# all global stores write-through (sc1) and the XCD leader's L2 write-back dropped from the grid barrier (payload + drain form of the release)
# speedup vs baseline: 1.0202x; 1.0102x over previous
.Lnb_loc_done_r:
	s_nop 0
	s_waitcnt vmcnt(0)
	v_mov_b32_e32 v6, 1
	v_mov_b32_e32 v12, 0x3400
	global_atomic_add v12, v6, s[6:7]

.LBB0_86:
	s_add_i32 s3, s6, s42
	s_cmpk_gt_i32 s3, 0x3fff
	s_cselect_b64 s[10:11], -1, 0
	s_ashr_i32 s7, s6, 31
	s_lshl_b64 s[8:9], s[6:7], 12
	v_lshl_add_u64 v[48:49], v[46:47], 0, s[8:9]
	global_load_dwordx4 v[64:67], v[48:49], off
	global_load_dwordx4 v[38:41], v[48:49], off offset:1024
	global_load_dwordx4 v[22:25], v[48:49], off offset:3072
	global_load_dwordx4 v[30:33], v[48:49], off offset:2048
	s_cmpk_lt_i32 s3, 0x4000
	s_cselect_b32 s6, s3, s6
	s_ashr_i32 s7, s6, 31
	s_lshl_b64 s[6:7], s[6:7], 12
	v_lshl_add_u64 v[50:51], v[46:47], 0, s[6:7]
	global_load_dwordx4 v[42:45], v[50:51], off
	global_load_dwordx4 v[34:37], v[50:51], off offset:1024
	global_load_dwordx4 v[18:21], v[50:51], off offset:3072
	global_load_dwordx4 v[26:29], v[50:51], off offset:2048
	s_mov_b32 s6, 0x3a800000
	s_and_b64 s[8:9], exec, s[10:11]
	s_mov_b64 s[12:13], -1
	s_waitcnt vmcnt(7)
	v_pk_mul_f32 v[52:53], v[66:67], v[66:67]
	v_pk_mul_f32 v[54:55], v[64:65], v[64:65]
	s_waitcnt vmcnt(6)
	v_pk_mul_f32 v[56:57], v[40:41], v[40:41]
	v_pk_mul_f32 v[68:69], v[38:39], v[38:39]
	s_waitcnt vmcnt(4)
	v_mul_f32_e32 v0, v31, v31
	v_mul_f32_e32 v70, v33, v33
	v_mul_f32_e32 v74, v24, v24
	v_mul_f32_e32 v75, v25, v25
	v_pk_mov_b32 v[72:73], v[54:55], v[52:53] op_sel:[1,0]
	v_mov_b32_e32 v55, v53
	v_pk_mov_b32 v[52:53], v[68:69], v[56:57] op_sel:[1,0]
	v_mov_b32_e32 v69, v57
	v_pk_fma_f32 v[56:57], v[30:31], v[30:31], v[0:1] op_sel_hi:[1,1,0]
	v_pk_fma_f32 v[70:71], v[32:33], v[32:33], v[70:71] op_sel_hi:[1,1,0]
	v_pk_add_f32 v[54:55], v[72:73], v[54:55]
	v_pk_add_f32 v[52:53], v[52:53], v[68:69]
	v_mov_b32_e32 v57, v74
	v_mov_b32_e32 v71, v75
	v_mul_f32_e32 v76, v22, v22
	v_mul_f32_e32 v77, v23, v23
	v_pk_add_f32 v[54:55], v[54:55], v[54:55] op_sel:[0,1] op_sel_hi:[1,0]
	v_pk_add_f32 v[52:53], v[52:53], v[52:53] op_sel:[0,1] op_sel_hi:[1,0]
	v_pk_add_f32 v[56:57], v[56:57], v[70:71]
	s_waitcnt vmcnt(3)
	v_pk_mul_f32 v[68:69], v[44:45], v[44:45]
	v_pk_mul_f32 v[70:71], v[42:43], v[42:43]
	s_waitcnt vmcnt(2)
	v_pk_mul_f32 v[72:73], v[36:37], v[36:37]
	v_pk_mul_f32 v[74:75], v[34:35], v[34:35]
	v_mov_b32_e32 v55, v76
	v_mov_b32_e32 v53, v77
	v_pk_mov_b32 v[78:79], v[70:71], v[68:69] op_sel:[1,0]
	v_mov_b32_e32 v71, v69
	v_pk_mov_b32 v[68:69], v[74:75], v[72:73] op_sel:[1,0]
	v_mov_b32_e32 v75, v73
	s_waitcnt vmcnt(1)
	v_mul_f32_e32 v77, v18, v18
	s_waitcnt vmcnt(0)
	v_mul_f32_e32 v0, v27, v27
	v_mul_f32_e32 v76, v29, v29
	v_pk_add_f32 v[52:53], v[54:55], v[52:53]
	v_pk_add_f32 v[70:71], v[78:79], v[70:71]
	v_pk_add_f32 v[68:69], v[68:69], v[74:75]
	v_mul_f32_e32 v80, v19, v19
	v_mul_f32_e32 v81, v20, v20
	v_mul_f32_e32 v82, v21, v21
	v_pk_fma_f32 v[54:55], v[26:27], v[26:27], v[0:1] op_sel_hi:[1,1,0]
	v_pk_fma_f32 v[72:73], v[28:29], v[28:29], v[76:77] op_sel_hi:[1,1,0]
	v_pk_add_f32 v[52:53], v[52:53], v[56:57]
	v_pk_add_f32 v[56:57], v[70:71], v[70:71] op_sel:[0,1] op_sel_hi:[1,0]
	v_pk_add_f32 v[68:69], v[68:69], v[68:69] op_sel:[0,1] op_sel_hi:[1,0]
	v_mov_b32_e32 v55, v81
	v_mov_b32_e32 v73, v82
	v_mov_b32_e32 v57, v77
	v_mov_b32_e32 v69, v80
	v_pk_add_f32 v[54:55], v[54:55], v[72:73]
	v_pk_add_f32 v[56:57], v[56:57], v[68:69]
	v_mov_b32_e32 v71, v52
	v_pk_add_f32 v[54:55], v[56:57], v[54:55]
	s_nop 0
	v_mov_b32_e32 v70, v54
	v_mov_b32_e32 v52, v55
	v_pk_add_f32 v[52:53], v[70:71], v[52:53]
	ds_bpermute_b32 v55, v58, v53
	ds_bpermute_b32 v54, v58, v52
	s_waitcnt lgkmcnt(0)
	v_pk_add_f32 v[52:53], v[52:53], v[54:55]
	ds_bpermute_b32 v55, v59, v53
	ds_bpermute_b32 v54, v59, v52
	s_waitcnt lgkmcnt(0)
	v_pk_add_f32 v[52:53], v[52:53], v[54:55]
	ds_bpermute_b32 v55, v60, v53
	ds_bpermute_b32 v54, v60, v52
	s_waitcnt lgkmcnt(0)
	v_pk_add_f32 v[52:53], v[52:53], v[54:55]
	ds_bpermute_b32 v55, v61, v53
	ds_bpermute_b32 v54, v61, v52
	s_waitcnt lgkmcnt(0)
	v_pk_add_f32 v[52:53], v[52:53], v[54:55]
	ds_bpermute_b32 v55, v62, v53
	ds_bpermute_b32 v54, v62, v52
	s_waitcnt lgkmcnt(0)
	v_pk_add_f32 v[52:53], v[52:53], v[54:55]
	ds_bpermute_b32 v55, v63, v53
	ds_bpermute_b32 v54, v63, v52
	s_waitcnt lgkmcnt(0)
	v_pk_add_f32 v[52:53], v[52:53], v[54:55]
	s_nop 0
	v_pk_fma_f32 v[56:57], v[52:53], s[6:7], v[190:191] op_sel_hi:[1,0,0]
	s_nop 0
	v_mul_f32_e32 v0, 0x4b800000, v57
	v_cmp_gt_f32_e32 vcc, s96, v57
	v_cmp_gt_f32_e64 s[6:7], s96, v56
	s_nop 0
	v_cndmask_b32_e32 v0, v57, v0, vcc
	v_rsq_f32_e32 v0, v0
	s_nop 0
	v_mul_f32_e32 v52, 0x45800000, v0
	v_cndmask_b32_e32 v52, v0, v52, vcc
	v_mov_b32_e32 v53, v52
	v_pk_mul_f32 v[64:65], v[64:65], v[52:53] op_sel_hi:[1,0]
	v_pk_mul_f32 v[66:67], v[66:67], v[52:53] op_sel_hi:[1,0]
	v_pk_mul_f32 v[54:55], v[38:39], v[52:53]
	v_pk_mul_f32 v[66:67], v[4:5], v[66:67]
	v_pk_mul_f32 v[64:65], v[2:3], v[64:65]
	s_mov_b64 vcc, s[8:9]
	global_store_dwordx4 v[48:49], v[64:67], off nt sc1
	s_cbranch_vccz .LBB0_88
	v_mov_b32_e32 v38, v52
	v_mov_b32_e32 v39, v52
	v_pk_mul_f32 v[38:39], v[40:41], v[38:39]
	v_pk_mul_f32 v[64:65], v[6:7], v[54:55]
	v_pk_mul_f32 v[66:67], v[8:9], v[38:39]
	global_store_dwordx4 v[48:49], v[64:67], off offset:1024 nt sc1
	s_mov_b64 s[12:13], 0
.LBB0_88:
	v_mul_f32_e32 v0, 0x4b800000, v56
	v_cndmask_b32_e64 v0, v56, v0, s[6:7]
	v_rsq_f32_e32 v0, v0
	s_andn2_b64 vcc, exec, s[12:13]
	v_mul_f32_e32 v38, 0x45800000, v0
	v_cndmask_b32_e64 v38, v0, v38, s[6:7]
	v_mov_b32_e32 v39, v38
	s_cbranch_vccnz .LBB0_90
	v_mov_b32_e32 v56, v38
	v_mov_b32_e32 v57, v38
	v_pk_mul_f32 v[44:45], v[44:45], v[56:57]
	v_pk_mul_f32 v[42:43], v[42:43], v[38:39]
	v_pk_mul_f32 v[44:45], v[4:5], v[44:45]
	v_pk_mul_f32 v[42:43], v[2:3], v[42:43]
	global_store_dwordx4 v[50:51], v[42:45], off nt sc1
	v_pk_mul_f32 v[36:37], v[36:37], v[56:57]
	v_pk_mul_f32 v[34:35], v[34:35], v[38:39]
	v_mov_b32_e32 v42, v52
	v_mov_b32_e32 v43, v52
	v_pk_mul_f32 v[40:41], v[40:41], v[42:43]
	v_pk_mul_f32 v[36:37], v[8:9], v[36:37]
	v_pk_mul_f32 v[42:43], v[8:9], v[40:41]
	v_pk_mul_f32 v[40:41], v[6:7], v[54:55]
	v_pk_mul_f32 v[34:35], v[6:7], v[34:35]
	global_store_dwordx4 v[48:49], v[40:43], off offset:1024 nt sc1
	global_store_dwordx4 v[50:51], v[34:37], off offset:1024 nt sc1
.LBB0_90:
	s_nop 1
	v_mov_b32_e32 v34, v52
	v_mov_b32_e32 v35, v52
	v_pk_mul_f32 v[32:33], v[32:33], v[34:35]
	v_pk_mul_f32 v[30:31], v[30:31], v[52:53]
	v_pk_mul_f32 v[32:33], v[12:13], v[32:33]
	v_pk_mul_f32 v[30:31], v[10:11], v[30:31]
	s_mov_b64 s[6:7], -1
	s_and_b64 vcc, exec, s[10:11]
	v_pk_mul_f32 v[22:23], v[22:23], v[52:53]
	global_store_dwordx4 v[48:49], v[30:33], off offset:2048 nt sc1
	s_cbranch_vccnz .LBB0_92
	s_andn2_b64 vcc, exec, s[6:7]
	s_cbranch_vccnz .LBB0_85
	s_branch .LBB0_93
.LBB0_92:
	s_nop 0
	v_pk_mul_f32 v[30:31], v[24:25], v[34:35]
	s_nop 0
	v_pk_mul_f32 v[32:33], v[16:17], v[30:31]
	v_pk_mul_f32 v[30:31], v[14:15], v[22:23]
	global_store_dwordx4 v[48:49], v[30:33], off offset:3072 nt sc1
	s_cbranch_execnz .LBB0_85
.LBB0_93:
	s_nop 0
	v_mov_b32_e32 v30, v38
	v_mov_b32_e32 v31, v38
	v_mov_b32_e32 v53, v52
	v_pk_mul_f32 v[28:29], v[28:29], v[30:31]
	v_pk_mul_f32 v[26:27], v[26:27], v[38:39]
	v_pk_mul_f32 v[24:25], v[24:25], v[52:53]
	v_pk_mul_f32 v[20:21], v[20:21], v[30:31]
	v_pk_mul_f32 v[18:19], v[18:19], v[38:39]
	v_pk_mul_f32 v[28:29], v[12:13], v[28:29]
	v_pk_mul_f32 v[26:27], v[10:11], v[26:27]
	v_pk_mul_f32 v[24:25], v[16:17], v[24:25]
	v_pk_mul_f32 v[22:23], v[14:15], v[22:23]
	v_pk_mul_f32 v[20:21], v[16:17], v[20:21]
	v_pk_mul_f32 v[18:19], v[14:15], v[18:19]
	global_store_dwordx4 v[50:51], v[26:29], off offset:2048 nt sc1
	global_store_dwordx4 v[48:49], v[22:25], off offset:3072 nt sc1
	global_store_dwordx4 v[50:51], v[18:21], off offset:3072 nt sc1
	s_branch .LBB0_85

.LBB0_122:
	s_ashr_i32 s18, s57, 31
	s_sub_i32 s20, s57, 64
	s_cmp_gt_i32 s57, 63
	v_readlane_b32 s22, v255, 52
	s_cselect_b32 s19, 0, s18
	s_cselect_b32 s18, s20, s57
	v_readlane_b32 s23, v255, 53
	s_cselect_b32 s20, s23, s11
	s_cselect_b32 s21, s22, s10
	s_lshl_b64 s[18:19], s[18:19], 20
	s_add_u32 s18, s21, s18
	s_addc_u32 s19, s20, s19
	s_min_i32 s20, s57, 64
	s_lshr_b32 s20, s20, 4
	s_mulk_i32 s20, 0x1800
	s_ashr_i32 s21, s20, 31
	s_lshl_b64 s[20:21], s[20:21], 2
	v_mov_b32_e32 v156, v191
	s_add_u32 s20, s39, s20
	s_addc_u32 s21, s40, s21
	s_lshl_b32 s22, s56, 8
	v_lshrrev_b32_e32 v130, 2, v156
	v_and_or_b32 v130, v130, 12, s22
	v_or_b32_e32 v130, s43, v130
	v_and_or_b32 v188, v156, 15, s42
	v_ashrrev_i32_e32 v131, 31, v130
	v_or_b32_e32 v172, 16, v188
	v_lshlrev_b64 v[152:153], 2, v[130:131]
	v_ashrrev_i32_e32 v189, 31, v188
	v_ashrrev_i32_e32 v173, 31, v172
	v_lshl_add_u64 v[130:131], s[20:21], 0, v[152:153]
	v_lshl_add_u64 v[192:193], s[18:19], 0, v[152:153]
	v_lshlrev_b64 v[152:153], 12, v[188:189]
	v_lshlrev_b64 v[172:173], 12, v[172:173]
	v_lshl_add_u64 v[152:153], v[192:193], 0, v[152:153]
	v_lshl_add_u64 v[194:195], v[192:193], 0, v[172:173]
	global_load_dwordx4 v[142:145], v[130:131], off
	global_load_dwordx4 v[138:141], v[130:131], off offset:64
	global_load_dwordx4 v[134:137], v[130:131], off offset:512
	s_nop 0
	global_load_dwordx4 v[130:133], v[130:131], off offset:576
	s_nop 0
	global_load_dwordx4 v[156:159], v[152:153], off
	global_load_dwordx4 v[160:163], v[152:153], off offset:64
	global_load_dwordx4 v[164:167], v[152:153], off offset:512
	global_load_dwordx4 v[168:171], v[152:153], off offset:576
	global_load_dwordx4 v[172:175], v[194:195], off
	global_load_dwordx4 v[176:179], v[194:195], off offset:64
	global_load_dwordx4 v[180:183], v[194:195], off offset:512
	global_load_dwordx4 v[184:187], v[194:195], off offset:576
	s_waitcnt vmcnt(0)
	v_pk_fma_f32 v[108:109], v[108:109], v[132:133], v[170:171]
	v_pk_fma_f32 v[106:107], v[106:107], v[130:131], v[168:169]
	global_store_dwordx4 v[152:153], v[106:109], off offset:576 sc1
	v_pk_fma_f32 v[128:129], v[128:129], v[144:145], v[158:159]
	v_pk_fma_f32 v[126:127], v[126:127], v[142:143], v[156:157]
	v_pk_fma_f32 v[108:109], v[120:121], v[144:145], v[174:175]
	v_pk_fma_f32 v[106:107], v[118:119], v[142:143], v[172:173]
	v_pk_fma_f32 v[124:125], v[124:125], v[140:141], v[162:163]
	v_pk_fma_f32 v[122:123], v[122:123], v[138:139], v[160:161]
	v_pk_fma_f32 v[116:117], v[116:117], v[136:137], v[166:167]
	v_pk_fma_f32 v[114:115], v[114:115], v[134:135], v[164:165]
	global_store_dwordx4 v[194:195], v[106:109], off sc1
	v_pk_fma_f32 v[104:105], v[104:105], v[136:137], v[182:183]
	v_pk_fma_f32 v[102:103], v[102:103], v[134:135], v[180:181]
	v_pk_fma_f32 v[108:109], v[112:113], v[140:141], v[178:179]
	v_pk_fma_f32 v[106:107], v[110:111], v[138:139], v[176:177]
	v_pk_fma_f32 v[100:101], v[100:101], v[132:133], v[186:187]
	v_pk_fma_f32 v[98:99], v[98:99], v[130:131], v[184:185]
	global_store_dwordx4 v[152:153], v[126:129], off sc1
	global_store_dwordx4 v[152:153], v[122:125], off offset:64 sc1
	global_store_dwordx4 v[152:153], v[114:117], off offset:512 sc1
	global_store_dwordx4 v[194:195], v[106:109], off offset:64 sc1
	global_store_dwordx4 v[194:195], v[102:105], off offset:512 sc1
	global_store_dwordx4 v[194:195], v[98:101], off offset:576 sc1
	s_nop 1
	v_or_b32_e32 v98, 32, v188
	v_or_b32_e32 v114, 48, v188
	v_ashrrev_i32_e32 v99, 31, v98
	v_ashrrev_i32_e32 v115, 31, v114
	v_lshlrev_b64 v[98:99], 12, v[98:99]
	v_lshlrev_b64 v[114:115], 12, v[114:115]
	v_lshl_add_u64 v[156:157], v[192:193], 0, v[98:99]
	v_lshl_add_u64 v[158:159], v[192:193], 0, v[114:115]
	global_load_dwordx4 v[98:101], v[156:157], off
	global_load_dwordx4 v[102:105], v[156:157], off offset:64
	global_load_dwordx4 v[106:109], v[156:157], off offset:512
	global_load_dwordx4 v[110:113], v[156:157], off offset:576
	global_load_dwordx4 v[114:117], v[158:159], off
	global_load_dwordx4 v[118:121], v[158:159], off offset:64
	global_load_dwordx4 v[122:125], v[158:159], off offset:512
	global_load_dwordx4 v[126:129], v[158:159], off offset:576
	s_waitcnt vmcnt(4)
	v_pk_fma_f32 v[76:77], v[76:77], v[132:133], v[112:113]
	v_pk_fma_f32 v[74:75], v[74:75], v[130:131], v[110:111]
	global_store_dwordx4 v[156:157], v[74:77], off offset:576 sc1
	v_pk_fma_f32 v[96:97], v[96:97], v[144:145], v[100:101]
	v_pk_fma_f32 v[94:95], v[94:95], v[142:143], v[98:99]
	s_waitcnt vmcnt(4)
	v_pk_fma_f32 v[76:77], v[88:89], v[144:145], v[116:117]
	v_pk_fma_f32 v[74:75], v[86:87], v[142:143], v[114:115]
	v_pk_fma_f32 v[92:93], v[92:93], v[140:141], v[104:105]
	v_pk_fma_f32 v[90:91], v[90:91], v[138:139], v[102:103]
	v_pk_fma_f32 v[84:85], v[84:85], v[136:137], v[108:109]
	v_pk_fma_f32 v[82:83], v[82:83], v[134:135], v[106:107]
	global_store_dwordx4 v[158:159], v[74:77], off sc1
	s_waitcnt vmcnt(3)
	v_pk_fma_f32 v[72:73], v[72:73], v[136:137], v[124:125]
	v_pk_fma_f32 v[70:71], v[70:71], v[134:135], v[122:123]
	v_pk_fma_f32 v[76:77], v[80:81], v[140:141], v[120:121]
	v_pk_fma_f32 v[74:75], v[78:79], v[138:139], v[118:119]
	s_waitcnt vmcnt(2)
	v_pk_fma_f32 v[68:69], v[68:69], v[132:133], v[128:129]
	v_pk_fma_f32 v[66:67], v[66:67], v[130:131], v[126:127]
	global_store_dwordx4 v[156:157], v[94:97], off sc1
	global_store_dwordx4 v[156:157], v[90:93], off offset:64 sc1
	global_store_dwordx4 v[156:157], v[82:85], off offset:512 sc1
	global_store_dwordx4 v[158:159], v[74:77], off offset:64 sc1
	global_store_dwordx4 v[158:159], v[70:73], off offset:512 sc1
	global_store_dwordx4 v[158:159], v[66:69], off offset:576 sc1
	s_mov_b64 s[18:19], 0x80000
	v_lshl_add_u64 v[98:99], v[152:153], 0, s[18:19]
	s_mov_b32 s18, 0x80000
	v_add_co_u32_e32 v100, vcc, s18, v152
	s_mov_b64 s[18:19], 0x90000
	s_nop 0
	v_addc_co_u32_e32 v101, vcc, 0, v153, vcc
	v_lshl_add_u64 v[102:103], v[152:153], 0, s[18:19]
	v_add_co_u32_e32 v104, vcc, s80, v152
	global_load_dwordx4 v[66:69], v[98:99], off offset:64
	global_load_dwordx4 v[70:73], v[98:99], off offset:512
	global_load_dwordx4 v[74:77], v[100:101], off
	global_load_dwordx4 v[78:81], v[98:99], off offset:576
	v_addc_co_u32_e32 v105, vcc, 0, v153, vcc
	global_load_dwordx4 v[82:85], v[102:103], off offset:64
	global_load_dwordx4 v[86:89], v[102:103], off offset:512
	global_load_dwordx4 v[90:93], v[104:105], off
	global_load_dwordx4 v[94:97], v[102:103], off offset:576
	s_waitcnt vmcnt(4)
	v_pk_fma_f32 v[44:45], v[44:45], v[132:133], v[80:81]
	v_pk_fma_f32 v[42:43], v[42:43], v[130:131], v[78:79]
	global_store_dwordx4 v[98:99], v[42:45], off offset:576 sc1
	v_pk_fma_f32 v[64:65], v[64:65], v[144:145], v[76:77]
	v_pk_fma_f32 v[62:63], v[62:63], v[142:143], v[74:75]
	s_waitcnt vmcnt(2)
	v_pk_fma_f32 v[44:45], v[56:57], v[144:145], v[92:93]
	v_pk_fma_f32 v[42:43], v[54:55], v[142:143], v[90:91]
	v_pk_fma_f32 v[60:61], v[60:61], v[140:141], v[68:69]
	v_pk_fma_f32 v[58:59], v[58:59], v[138:139], v[66:67]
	v_pk_fma_f32 v[52:53], v[52:53], v[136:137], v[72:73]
	v_pk_fma_f32 v[50:51], v[50:51], v[134:135], v[70:71]
	global_store_dwordx4 v[104:105], v[42:45], off sc1
	v_pk_fma_f32 v[40:41], v[40:41], v[136:137], v[88:89]
	v_pk_fma_f32 v[38:39], v[38:39], v[134:135], v[86:87]
	v_pk_fma_f32 v[44:45], v[48:49], v[140:141], v[84:85]
	v_pk_fma_f32 v[42:43], v[46:47], v[138:139], v[82:83]
	s_waitcnt vmcnt(2)
	v_pk_fma_f32 v[36:37], v[36:37], v[132:133], v[96:97]
	v_pk_fma_f32 v[34:35], v[34:35], v[130:131], v[94:95]
	global_store_dwordx4 v[100:101], v[62:65], off sc1
	global_store_dwordx4 v[98:99], v[58:61], off offset:64 sc1
	global_store_dwordx4 v[98:99], v[50:53], off offset:512 sc1
	global_store_dwordx4 v[102:103], v[42:45], off offset:64 sc1
	global_store_dwordx4 v[102:103], v[38:41], off offset:512 sc1
	global_store_dwordx4 v[102:103], v[34:37], off offset:576 sc1
	s_mov_b64 s[18:19], 0xa0000
	v_lshl_add_u64 v[66:67], v[152:153], 0, s[18:19]
	s_mov_b32 s18, 0xa0000
	v_add_co_u32_e32 v68, vcc, s18, v152
	s_mov_b64 s[18:19], 0xb0000
	s_nop 0
	v_addc_co_u32_e32 v69, vcc, 0, v153, vcc
	v_lshl_add_u64 v[70:71], v[152:153], 0, s[18:19]
	s_mov_b32 s18, 0xb0000
	v_add_co_u32_e32 v72, vcc, s18, v152
	global_load_dwordx4 v[34:37], v[66:67], off offset:64
	global_load_dwordx4 v[38:41], v[66:67], off offset:512
	global_load_dwordx4 v[42:45], v[68:69], off
	global_load_dwordx4 v[46:49], v[66:67], off offset:576
	v_addc_co_u32_e32 v73, vcc, 0, v153, vcc
	global_load_dwordx4 v[50:53], v[70:71], off offset:64
	global_load_dwordx4 v[54:57], v[70:71], off offset:512
	global_load_dwordx4 v[58:61], v[72:73], off
	global_load_dwordx4 v[62:65], v[70:71], off offset:576
	s_waitcnt vmcnt(4)
	v_pk_fma_f32 v[12:13], v[12:13], v[132:133], v[48:49]
	v_pk_fma_f32 v[10:11], v[10:11], v[130:131], v[46:47]
	global_store_dwordx4 v[66:67], v[10:13], off offset:576 sc1
	v_pk_fma_f32 v[32:33], v[32:33], v[144:145], v[44:45]
	v_pk_fma_f32 v[30:31], v[30:31], v[142:143], v[42:43]
	s_waitcnt vmcnt(2)
	v_pk_fma_f32 v[12:13], v[24:25], v[144:145], v[60:61]
	v_pk_fma_f32 v[10:11], v[22:23], v[142:143], v[58:59]
	v_pk_fma_f32 v[28:29], v[28:29], v[140:141], v[36:37]
	v_pk_fma_f32 v[26:27], v[26:27], v[138:139], v[34:35]
	v_pk_fma_f32 v[20:21], v[20:21], v[136:137], v[40:41]
	v_pk_fma_f32 v[18:19], v[18:19], v[134:135], v[38:39]
	global_store_dwordx4 v[72:73], v[10:13], off sc1
	v_pk_fma_f32 v[8:9], v[8:9], v[136:137], v[56:57]
	v_pk_fma_f32 v[6:7], v[6:7], v[134:135], v[54:55]
	v_pk_fma_f32 v[12:13], v[16:17], v[140:141], v[52:53]
	v_pk_fma_f32 v[10:11], v[14:15], v[138:139], v[50:51]
	s_waitcnt vmcnt(2)
	v_pk_fma_f32 v[4:5], v[4:5], v[132:133], v[64:65]
	v_pk_fma_f32 v[2:3], v[2:3], v[130:131], v[62:63]
	global_store_dwordx4 v[68:69], v[30:33], off sc1
	global_store_dwordx4 v[66:67], v[26:29], off offset:64 sc1
	global_store_dwordx4 v[66:67], v[18:21], off offset:512 sc1
	global_store_dwordx4 v[70:71], v[10:13], off offset:64 sc1
	global_store_dwordx4 v[70:71], v[6:9], off offset:512 sc1
	global_store_dwordx4 v[70:71], v[2:5], off offset:576 sc1
	v_readlane_b32 s66, v255, 2
	s_and_b64 vcc, exec, s[6:7]
	s_mov_b64 s[6:7], -1
	v_readlane_b32 s67, v255, 3
	s_cbranch_vccnz .LBB0_107
	s_andn2_b64 vcc, exec, s[12:13]
	s_cbranch_vccnz .LBB0_106
	s_barrier
	s_branch .LBB0_106

.LBB0_141:
	v_mov_b32_e32 v26, v191
	s_lshl_b32 s15, s21, 8
	v_and_b32_e32 v148, 15, v26
	v_bfe_u32 v26, v26, 4, 2
	s_or_b32 s15, s15, s43
	v_lshl_add_u32 v26, v26, 2, s15
	v_ashrrev_i32_e32 v27, 31, v26
	v_lshlrev_b64 v[152:153], 2, v[26:27]
	v_lshl_add_u64 v[26:27], s[12:13], 0, v[152:153]
	global_load_dwordx4 v[46:49], v[26:27], off
	global_load_dwordx4 v[42:45], v[26:27], off offset:64
	global_load_dwordx4 v[38:41], v[26:27], off offset:512
	s_nop 0
	global_load_dwordx4 v[26:29], v[26:27], off offset:576
	s_ashr_i32 s15, s48, 31
	s_lshr_b32 s15, s15, 24
	s_add_i32 s15, s48, s15
	s_ashr_i32 s22, s15, 8
	s_ashr_i32 s21, s20, 31
	s_ashr_i32 s23, s22, 31
	s_lshl_b64 s[20:21], s[20:21], 20
	s_lshl_b64 s[22:23], s[22:23], 22
	s_add_u32 s15, s39, s22
	s_addc_u32 s22, s40, s23
	s_add_u32 s20, s15, s20
	v_add_u32_e32 v148, s42, v148
	s_addc_u32 s21, s22, s21
	v_add_u32_e32 v158, 48, v148
	v_lshl_add_u64 v[152:153], s[20:21], 0, v[152:153]
	s_brev_b32 s20, 63
	v_ashrrev_i32_e32 v149, 31, v148
	v_add_u32_e32 v154, 16, v148
	v_add_u32_e32 v156, 32, v148
	v_ashrrev_i32_e32 v159, 31, v158
	s_mov_b32 s21, -1
	v_lshlrev_b64 v[160:161], 12, v[148:149]
	v_ashrrev_i32_e32 v155, 31, v154
	v_ashrrev_i32_e32 v157, 31, v156
	v_lshlrev_b64 v[158:159], 12, v[158:159]
	v_lshl_add_u64 v[152:153], v[152:153], 0, s[20:21]
	v_lshlrev_b64 v[154:155], 12, v[154:155]
	v_lshlrev_b64 v[156:157], 12, v[156:157]
	v_lshl_add_u64 v[160:161], v[152:153], 0, v[160:161]
	v_lshl_add_u64 v[158:159], v[152:153], 0, v[158:159]
	v_lshl_add_u64 v[154:155], v[152:153], 0, v[154:155]
	v_lshl_add_u64 v[156:157], v[152:153], 0, v[156:157]
	v_readlane_b32 s66, v255, 2
	s_and_b64 vcc, exec, s[6:7]
	s_mov_b64 s[6:7], -1
	s_movk_i32 s49, 0x4000
	s_mov_b32 s56, 0xa000
	s_movk_i32 s57, 0x1ff
	v_readlane_b32 s67, v255, 3
	v_mov_b64_e32 v[230:231], v[242:243]
	v_mov_b32_e32 v238, v232
	v_mov_b32_e32 v232, v229
	v_mov_b64_e32 v[240:241], 0xff
	v_not_b32_e32 v229, 63
	v_not_b32_e32 v239, 31
	v_mov_b32_e32 v242, 0x7fc00000
	v_mov_b32_e32 v243, 0x68
	v_mov_b32_e32 v244, 0x58
	s_waitcnt vmcnt(0)
	v_pk_mul_f32 v[116:117], v[116:117], v[48:49]
	v_pk_mul_f32 v[114:115], v[114:115], v[46:47]
	v_pk_mul_f32 v[120:121], v[120:121], v[44:45]
	v_pk_mul_f32 v[68:69], v[68:69], v[28:29]
	v_pk_mul_f32 v[66:67], v[66:67], v[26:27]
	v_pk_mul_f32 v[118:119], v[118:119], v[42:43]
	v_pk_mul_f32 v[140:141], v[140:141], v[40:41]
	v_pk_mul_f32 v[138:139], v[138:139], v[38:39]
	v_pk_mul_f32 v[144:145], v[144:145], v[28:29]
	v_pk_mul_f32 v[142:143], v[142:143], v[26:27]
	v_pk_mul_f32 v[108:109], v[108:109], v[48:49]
	v_pk_mul_f32 v[106:107], v[106:107], v[46:47]
	v_pk_mul_f32 v[112:113], v[112:113], v[44:45]
	v_pk_mul_f32 v[110:111], v[110:111], v[42:43]
	v_pk_mul_f32 v[132:133], v[132:133], v[40:41]
	v_pk_mul_f32 v[130:131], v[130:131], v[38:39]
	v_pk_mul_f32 v[136:137], v[136:137], v[28:29]
	v_pk_mul_f32 v[134:135], v[134:135], v[26:27]
	v_pk_mul_f32 v[100:101], v[100:101], v[48:49]
	v_pk_mul_f32 v[98:99], v[98:99], v[46:47]
	v_pk_mul_f32 v[104:105], v[104:105], v[44:45]
	v_pk_mul_f32 v[102:103], v[102:103], v[42:43]
	v_pk_mul_f32 v[124:125], v[124:125], v[40:41]
	v_pk_mul_f32 v[122:123], v[122:123], v[38:39]
	v_pk_mul_f32 v[128:129], v[128:129], v[28:29]
	v_pk_mul_f32 v[126:127], v[126:127], v[26:27]
	v_pk_mul_f32 v[84:85], v[84:85], v[48:49]
	v_pk_mul_f32 v[82:83], v[82:83], v[46:47]
	v_pk_mul_f32 v[72:73], v[72:73], v[44:45]
	v_pk_mul_f32 v[70:71], v[70:71], v[42:43]
	v_pk_mul_f32 v[88:89], v[88:89], v[40:41]
	v_pk_mul_f32 v[86:87], v[86:87], v[38:39]
	global_store_dwordx4 v[160:161], v[114:117], off sc1
	global_store_dwordx4 v[160:161], v[118:121], off offset:64 sc1
	global_store_dwordx4 v[160:161], v[138:141], off offset:512 sc1
	global_store_dwordx4 v[160:161], v[142:145], off offset:576 sc1
	global_store_dwordx4 v[154:155], v[106:109], off sc1
	global_store_dwordx4 v[154:155], v[110:113], off offset:64 sc1
	global_store_dwordx4 v[154:155], v[130:133], off offset:512 sc1
	global_store_dwordx4 v[154:155], v[134:137], off offset:576 sc1
	global_store_dwordx4 v[156:157], v[98:101], off sc1
	global_store_dwordx4 v[156:157], v[102:105], off offset:64 sc1
	global_store_dwordx4 v[156:157], v[122:125], off offset:512 sc1
	global_store_dwordx4 v[156:157], v[126:129], off offset:576 sc1
	global_store_dwordx4 v[158:159], v[82:85], off sc1
	global_store_dwordx4 v[158:159], v[70:73], off offset:64 sc1
	global_store_dwordx4 v[158:159], v[86:89], off offset:512 sc1
	global_store_dwordx4 v[158:159], v[66:69], off offset:576 sc1
	v_pk_mul_f32 v[52:53], v[52:53], v[44:45]
	v_pk_mul_f32 v[50:51], v[50:51], v[42:43]
	v_add_u32_e32 v66, 0x80, v148
	v_ashrrev_i32_e32 v67, 31, v66
	v_lshlrev_b64 v[66:67], 12, v[66:67]
	v_lshl_add_u64 v[70:71], v[152:153], 0, v[66:67]
	v_pk_mul_f32 v[68:69], v[92:93], v[48:49]
	v_pk_mul_f32 v[66:67], v[90:91], v[46:47]
	global_store_dwordx4 v[70:71], v[66:69], off sc1
	v_pk_mul_f32 v[20:21], v[20:21], v[44:45]
	v_pk_mul_f32 v[18:19], v[18:19], v[42:43]
	v_pk_mul_f32 v[68:69], v[76:77], v[44:45]
	v_pk_mul_f32 v[66:67], v[74:75], v[42:43]
	global_store_dwordx4 v[70:71], v[66:69], off offset:64 sc1
	v_pk_mul_f32 v[4:5], v[4:5], v[44:45]
	v_pk_mul_f32 v[2:3], v[2:3], v[42:43]
	v_pk_mul_f32 v[68:69], v[96:97], v[40:41]
	v_pk_mul_f32 v[66:67], v[94:95], v[38:39]
	global_store_dwordx4 v[70:71], v[66:69], off offset:512 sc1
	v_pk_mul_f32 v[60:61], v[60:61], v[48:49]
	v_pk_mul_f32 v[58:59], v[58:59], v[46:47]
	v_pk_mul_f32 v[68:69], v[80:81], v[28:29]
	v_pk_mul_f32 v[66:67], v[78:79], v[26:27]
	global_store_dwordx4 v[70:71], v[66:69], off offset:576 sc1
	v_pk_mul_f32 v[32:33], v[32:33], v[48:49]
	v_pk_mul_f32 v[30:31], v[30:31], v[46:47]
	v_add_u32_e32 v66, 0x90, v148
	v_ashrrev_i32_e32 v67, 31, v66
	v_lshlrev_b64 v[66:67], 12, v[66:67]
	v_lshl_add_u64 v[66:67], v[152:153], 0, v[66:67]
	global_store_dwordx4 v[66:67], v[50:53], off offset:64 sc1
	v_pk_mul_f32 v[12:13], v[12:13], v[48:49]
	v_pk_mul_f32 v[10:11], v[10:11], v[46:47]
	v_pk_mul_f32 v[52:53], v[64:65], v[40:41]
	v_pk_mul_f32 v[50:51], v[62:63], v[38:39]
	global_store_dwordx4 v[66:67], v[50:53], off offset:512 sc1
	global_store_dwordx4 v[66:67], v[58:61], off sc1
	s_nop 0
	v_pk_mul_f32 v[52:53], v[56:57], v[28:29]
	v_pk_mul_f32 v[50:51], v[54:55], v[26:27]
	global_store_dwordx4 v[66:67], v[50:53], off offset:576 sc1
	s_nop 1
	v_add_u32_e32 v50, 0xa0, v148
	v_ashrrev_i32_e32 v51, 31, v50
	v_lshlrev_b64 v[50:51], 12, v[50:51]
	v_lshl_add_u64 v[50:51], v[152:153], 0, v[50:51]
	global_store_dwordx4 v[50:51], v[18:21], off offset:64 sc1
	global_store_dwordx4 v[50:51], v[30:33], off sc1
	s_nop 0
	v_pk_mul_f32 v[20:21], v[36:37], v[40:41]
	v_pk_mul_f32 v[18:19], v[34:35], v[38:39]
	global_store_dwordx4 v[50:51], v[18:21], off offset:512 sc1
	s_nop 1
	v_pk_mul_f32 v[20:21], v[24:25], v[28:29]
	v_pk_mul_f32 v[18:19], v[22:23], v[26:27]
	global_store_dwordx4 v[50:51], v[18:21], off offset:576 sc1
	s_nop 1
	v_add_u32_e32 v18, 0xb0, v148
	v_ashrrev_i32_e32 v19, 31, v18
	v_lshlrev_b64 v[18:19], 12, v[18:19]
	v_lshl_add_u64 v[18:19], v[152:153], 0, v[18:19]
	global_store_dwordx4 v[18:19], v[2:5], off offset:64 sc1
	global_store_dwordx4 v[18:19], v[10:13], off sc1
	s_nop 0
	v_pk_mul_f32 v[4:5], v[16:17], v[40:41]
	v_pk_mul_f32 v[2:3], v[14:15], v[38:39]
	global_store_dwordx4 v[18:19], v[2:5], off offset:512 sc1
	s_nop 1
	v_pk_mul_f32 v[4:5], v[8:9], v[28:29]
	v_pk_mul_f32 v[2:3], v[6:7], v[26:27]
	global_store_dwordx4 v[18:19], v[2:5], off offset:576 sc1
	s_cbranch_vccnz .LBB0_132
	s_andn2_b64 vcc, exec, s[8:9]
	s_cbranch_vccnz .LBB0_131
	s_barrier
	s_branch .LBB0_131

.Luc_fast0:
	v_pk_fma_f32 v[18:19], v[150:151], v[82:83], v[208:209]
	v_pk_fma_f32 v[26:27], v[158:159], v[90:91], v[216:217]
	v_pk_fma_f32 v[20:21], v[152:153], v[84:85], v[210:211]
	v_pk_fma_f32 v[28:29], v[160:161], v[92:93], v[218:219]
	v_pk_fma_f32 v[22:23], v[154:155], v[86:87], v[212:213]
	v_pk_fma_f32 v[30:31], v[162:163], v[94:95], v[220:221]
	v_pk_fma_f32 v[24:25], v[156:157], v[88:89], v[214:215]
	v_pk_fma_f32 v[32:33], v[164:165], v[96:97], v[222:223]
	v_pk_fma_f32 v[18:19], v[174:175], v[66:67], v[18:19]
	v_pk_fma_f32 v[26:27], v[142:143], v[74:75], v[26:27]
	v_pk_fma_f32 v[20:21], v[176:177], v[68:69], v[20:21]
	v_pk_fma_f32 v[28:29], v[144:145], v[76:77], v[28:29]
	v_pk_fma_f32 v[22:23], v[182:183], v[70:71], v[22:23]
	v_pk_fma_f32 v[30:31], v[146:147], v[78:79], v[30:31]
	v_pk_fma_f32 v[24:25], v[184:185], v[72:73], v[24:25]
	v_pk_fma_f32 v[32:33], v[148:149], v[80:81], v[32:33]
	v_pk_fma_f32 v[18:19], v[192:193], v[98:99], v[18:19]
	v_pk_fma_f32 v[26:27], v[200:201], v[106:107], v[26:27]
	v_pk_fma_f32 v[20:21], v[194:195], v[100:101], v[20:21]
	v_pk_fma_f32 v[28:29], v[202:203], v[108:109], v[28:29]
	v_pk_fma_f32 v[22:23], v[196:197], v[102:103], v[22:23]
	v_pk_fma_f32 v[30:31], v[204:205], v[110:111], v[30:31]
	v_pk_fma_f32 v[24:25], v[198:199], v[104:105], v[24:25]
	v_pk_fma_f32 v[32:33], v[206:207], v[112:113], v[32:33]
	v_pk_mul_f32 v[34:35], v[18:19], v[42:43] op_sel_hi:[1,0]
	v_pk_mul_f32 v[36:37], v[20:21], v[42:43] op_sel_hi:[1,0]
	v_pk_mul_f32 v[38:39], v[22:23], v[42:43] op_sel_hi:[1,0]
	v_pk_mul_f32 v[40:41], v[24:25], v[42:43] op_sel_hi:[1,0]
	v_exp_f32_e32 v34, v34
	v_exp_f32_e32 v35, v35
	v_exp_f32_e32 v36, v36
	v_exp_f32_e32 v37, v37
	v_exp_f32_e32 v38, v38
	v_exp_f32_e32 v39, v39
	v_exp_f32_e32 v40, v40
	v_exp_f32_e32 v41, v41
	v_pk_add_f32 v[34:35], v[34:35], 1.0 op_sel_hi:[1,0]
	v_pk_add_f32 v[36:37], v[36:37], 1.0 op_sel_hi:[1,0]
	v_pk_add_f32 v[38:39], v[38:39], 1.0 op_sel_hi:[1,0]
	v_pk_add_f32 v[40:41], v[40:41], 1.0 op_sel_hi:[1,0]
	v_rcp_f32_e32 v34, v34
	v_rcp_f32_e32 v35, v35
	v_rcp_f32_e32 v36, v36
	v_rcp_f32_e32 v37, v37
	v_rcp_f32_e32 v38, v38
	v_rcp_f32_e32 v39, v39
	v_rcp_f32_e32 v40, v40
	v_rcp_f32_e32 v41, v41
	v_pk_mul_f32 v[18:19], v[18:19], v[34:35]
	v_pk_mul_f32 v[20:21], v[20:21], v[36:37]
	v_pk_mul_f32 v[22:23], v[22:23], v[38:39]
	v_pk_mul_f32 v[24:25], v[24:25], v[40:41]
	v_pk_mul_f32 v[18:19], v[26:27], v[18:19]
	v_pk_mul_f32 v[20:21], v[28:29], v[20:21]
	v_pk_mul_f32 v[22:23], v[30:31], v[22:23]
	v_pk_mul_f32 v[24:25], v[32:33], v[24:25]
	v_cvt_pk_bf16_f32 v34, v18, v19
	v_cvt_pk_bf16_f32 v35, v20, v21
	v_cvt_pk_bf16_f32 v36, v22, v23
	v_cvt_pk_bf16_f32 v37, v24, v25
	global_store_dwordx4 v[50:51], v[34:37], off nt sc1
	s_and_b64 vcc, exec, s[78:79]
	s_cbranch_vccz .Luc_skip0
	v_mov_b64_e32 v[98:99], v[2:3]
	v_mov_b64_e32 v[100:101], v[4:5]
	v_mov_b64_e32 v[102:103], v[6:7]
	v_mov_b64_e32 v[104:105], v[8:9]
	v_mov_b64_e32 v[106:107], v[10:11]
	v_mov_b64_e32 v[108:109], v[12:13]
	v_mov_b64_e32 v[110:111], v[14:15]
	v_mov_b64_e32 v[112:113], v[16:17]

.Luc_fast1:
	v_pk_fma_f32 v[18:19], v[150:151], v[98:99], v[208:209]
	v_pk_fma_f32 v[26:27], v[158:159], v[106:107], v[216:217]
	v_pk_fma_f32 v[20:21], v[152:153], v[100:101], v[210:211]
	v_pk_fma_f32 v[28:29], v[160:161], v[108:109], v[218:219]
	v_pk_fma_f32 v[22:23], v[154:155], v[102:103], v[212:213]
	v_pk_fma_f32 v[30:31], v[162:163], v[110:111], v[220:221]
	v_pk_fma_f32 v[24:25], v[156:157], v[104:105], v[214:215]
	v_pk_fma_f32 v[32:33], v[164:165], v[112:113], v[222:223]
	v_pk_fma_f32 v[18:19], v[174:175], v[82:83], v[18:19]
	v_pk_fma_f32 v[26:27], v[142:143], v[90:91], v[26:27]
	v_pk_fma_f32 v[20:21], v[176:177], v[84:85], v[20:21]
	v_pk_fma_f32 v[28:29], v[144:145], v[92:93], v[28:29]
	v_pk_fma_f32 v[22:23], v[182:183], v[86:87], v[22:23]
	v_pk_fma_f32 v[30:31], v[146:147], v[94:95], v[30:31]
	v_pk_fma_f32 v[24:25], v[184:185], v[88:89], v[24:25]
	v_pk_fma_f32 v[32:33], v[148:149], v[96:97], v[32:33]
	v_pk_fma_f32 v[18:19], v[192:193], v[66:67], v[18:19]
	v_pk_fma_f32 v[26:27], v[200:201], v[74:75], v[26:27]
	v_pk_fma_f32 v[20:21], v[194:195], v[68:69], v[20:21]
	v_pk_fma_f32 v[28:29], v[202:203], v[76:77], v[28:29]
	v_pk_fma_f32 v[22:23], v[196:197], v[70:71], v[22:23]
	v_pk_fma_f32 v[30:31], v[204:205], v[78:79], v[30:31]
	v_pk_fma_f32 v[24:25], v[198:199], v[72:73], v[24:25]
	v_pk_fma_f32 v[32:33], v[206:207], v[80:81], v[32:33]
	v_pk_mul_f32 v[34:35], v[18:19], v[42:43] op_sel_hi:[1,0]
	v_pk_mul_f32 v[36:37], v[20:21], v[42:43] op_sel_hi:[1,0]
	v_pk_mul_f32 v[38:39], v[22:23], v[42:43] op_sel_hi:[1,0]
	v_pk_mul_f32 v[40:41], v[24:25], v[42:43] op_sel_hi:[1,0]
	v_exp_f32_e32 v34, v34
	v_exp_f32_e32 v35, v35
	v_exp_f32_e32 v36, v36
	v_exp_f32_e32 v37, v37
	v_exp_f32_e32 v38, v38
	v_exp_f32_e32 v39, v39
	v_exp_f32_e32 v40, v40
	v_exp_f32_e32 v41, v41
	v_pk_add_f32 v[34:35], v[34:35], 1.0 op_sel_hi:[1,0]
	v_pk_add_f32 v[36:37], v[36:37], 1.0 op_sel_hi:[1,0]
	v_pk_add_f32 v[38:39], v[38:39], 1.0 op_sel_hi:[1,0]
	v_pk_add_f32 v[40:41], v[40:41], 1.0 op_sel_hi:[1,0]
	v_rcp_f32_e32 v34, v34
	v_rcp_f32_e32 v35, v35
	v_rcp_f32_e32 v36, v36
	v_rcp_f32_e32 v37, v37
	v_rcp_f32_e32 v38, v38
	v_rcp_f32_e32 v39, v39
	v_rcp_f32_e32 v40, v40
	v_rcp_f32_e32 v41, v41
	v_pk_mul_f32 v[18:19], v[18:19], v[34:35]
	v_pk_mul_f32 v[20:21], v[20:21], v[36:37]
	v_pk_mul_f32 v[22:23], v[22:23], v[38:39]
	v_pk_mul_f32 v[24:25], v[24:25], v[40:41]
	v_pk_mul_f32 v[18:19], v[26:27], v[18:19]
	v_pk_mul_f32 v[20:21], v[28:29], v[20:21]
	v_pk_mul_f32 v[22:23], v[30:31], v[22:23]
	v_pk_mul_f32 v[24:25], v[32:33], v[24:25]
	v_cvt_pk_bf16_f32 v34, v18, v19
	v_cvt_pk_bf16_f32 v35, v20, v21
	v_cvt_pk_bf16_f32 v36, v22, v23
	v_cvt_pk_bf16_f32 v37, v24, v25
	global_store_dwordx4 v[50:51], v[34:37], off nt sc1
	s_and_b64 vcc, exec, s[78:79]
	s_cbranch_vccz .Luc_skip1
	v_mov_b64_e32 v[66:67], v[2:3]
	v_mov_b64_e32 v[68:69], v[4:5]
	v_mov_b64_e32 v[70:71], v[6:7]
	v_mov_b64_e32 v[72:73], v[8:9]
	v_mov_b64_e32 v[74:75], v[10:11]
	v_mov_b64_e32 v[76:77], v[12:13]
	v_mov_b64_e32 v[78:79], v[14:15]
	v_mov_b64_e32 v[80:81], v[16:17]

.Luc_fast2:
	v_pk_fma_f32 v[18:19], v[150:151], v[66:67], v[208:209]
	v_pk_fma_f32 v[26:27], v[158:159], v[74:75], v[216:217]
	v_pk_fma_f32 v[20:21], v[152:153], v[68:69], v[210:211]
	v_pk_fma_f32 v[28:29], v[160:161], v[76:77], v[218:219]
	v_pk_fma_f32 v[22:23], v[154:155], v[70:71], v[212:213]
	v_pk_fma_f32 v[30:31], v[162:163], v[78:79], v[220:221]
	v_pk_fma_f32 v[24:25], v[156:157], v[72:73], v[214:215]
	v_pk_fma_f32 v[32:33], v[164:165], v[80:81], v[222:223]
	v_pk_fma_f32 v[18:19], v[174:175], v[98:99], v[18:19]
	v_pk_fma_f32 v[26:27], v[142:143], v[106:107], v[26:27]
	v_pk_fma_f32 v[20:21], v[176:177], v[100:101], v[20:21]
	v_pk_fma_f32 v[28:29], v[144:145], v[108:109], v[28:29]
	v_pk_fma_f32 v[22:23], v[182:183], v[102:103], v[22:23]
	v_pk_fma_f32 v[30:31], v[146:147], v[110:111], v[30:31]
	v_pk_fma_f32 v[24:25], v[184:185], v[104:105], v[24:25]
	v_pk_fma_f32 v[32:33], v[148:149], v[112:113], v[32:33]
	v_pk_fma_f32 v[18:19], v[192:193], v[82:83], v[18:19]
	v_pk_fma_f32 v[26:27], v[200:201], v[90:91], v[26:27]
	v_pk_fma_f32 v[20:21], v[194:195], v[84:85], v[20:21]
	v_pk_fma_f32 v[28:29], v[202:203], v[92:93], v[28:29]
	v_pk_fma_f32 v[22:23], v[196:197], v[86:87], v[22:23]
	v_pk_fma_f32 v[30:31], v[204:205], v[94:95], v[30:31]
	v_pk_fma_f32 v[24:25], v[198:199], v[88:89], v[24:25]
	v_pk_fma_f32 v[32:33], v[206:207], v[96:97], v[32:33]
	v_pk_mul_f32 v[34:35], v[18:19], v[42:43] op_sel_hi:[1,0]
	v_pk_mul_f32 v[36:37], v[20:21], v[42:43] op_sel_hi:[1,0]
	v_pk_mul_f32 v[38:39], v[22:23], v[42:43] op_sel_hi:[1,0]
	v_pk_mul_f32 v[40:41], v[24:25], v[42:43] op_sel_hi:[1,0]
	v_exp_f32_e32 v34, v34
	v_exp_f32_e32 v35, v35
	v_exp_f32_e32 v36, v36
	v_exp_f32_e32 v37, v37
	v_exp_f32_e32 v38, v38
	v_exp_f32_e32 v39, v39
	v_exp_f32_e32 v40, v40
	v_exp_f32_e32 v41, v41
	v_pk_add_f32 v[34:35], v[34:35], 1.0 op_sel_hi:[1,0]
	v_pk_add_f32 v[36:37], v[36:37], 1.0 op_sel_hi:[1,0]
	v_pk_add_f32 v[38:39], v[38:39], 1.0 op_sel_hi:[1,0]
	v_pk_add_f32 v[40:41], v[40:41], 1.0 op_sel_hi:[1,0]
	v_rcp_f32_e32 v34, v34
	v_rcp_f32_e32 v35, v35
	v_rcp_f32_e32 v36, v36
	v_rcp_f32_e32 v37, v37
	v_rcp_f32_e32 v38, v38
	v_rcp_f32_e32 v39, v39
	v_rcp_f32_e32 v40, v40
	v_rcp_f32_e32 v41, v41
	v_pk_mul_f32 v[18:19], v[18:19], v[34:35]
	v_pk_mul_f32 v[20:21], v[20:21], v[36:37]
	v_pk_mul_f32 v[22:23], v[22:23], v[38:39]
	v_pk_mul_f32 v[24:25], v[24:25], v[40:41]
	v_pk_mul_f32 v[18:19], v[26:27], v[18:19]
	v_pk_mul_f32 v[20:21], v[28:29], v[20:21]
	v_pk_mul_f32 v[22:23], v[30:31], v[22:23]
	v_pk_mul_f32 v[24:25], v[32:33], v[24:25]
	v_cvt_pk_bf16_f32 v34, v18, v19
	v_cvt_pk_bf16_f32 v35, v20, v21
	v_cvt_pk_bf16_f32 v36, v22, v23
	v_cvt_pk_bf16_f32 v37, v24, v25
	global_store_dwordx4 v[50:51], v[34:37], off nt sc1
	s_and_b64 vcc, exec, s[78:79]
	s_cbranch_vccz .Luc_skip2
	v_mov_b64_e32 v[82:83], v[2:3]
	v_mov_b64_e32 v[84:85], v[4:5]
	v_mov_b64_e32 v[86:87], v[6:7]
	v_mov_b64_e32 v[88:89], v[8:9]
	v_mov_b64_e32 v[90:91], v[10:11]
	v_mov_b64_e32 v[92:93], v[12:13]
	v_mov_b64_e32 v[94:95], v[14:15]
	v_mov_b64_e32 v[96:97], v[16:17]

.LBB0_202:
	s_add_i32 s6, s42, s74
	s_add_i32 s17, s74, 0x4000
	s_add_i32 s16, s6, 0x4000
	s_cmp_lt_i32 s16, s28
	s_cselect_b64 s[14:15], -1, 0
	s_and_b64 s[18:19], s[14:15], exec
	s_cselect_b32 s5, s16, s17
	s_cmpk_lt_i32 s17, 0x4000
	s_cselect_b32 s19, s11, 0
	s_cselect_b32 s18, s10, s74
	s_cselect_b32 s7, s13, s9
	s_cselect_b32 s20, s12, s8
	s_lshl_b64 s[18:19], s[18:19], 12
	s_add_u32 s18, s20, s18
	s_addc_u32 s19, s7, s19
	s_add_i32 s7, s5, 0xffffc000
	s_ashr_i32 s20, s5, 31
	s_cmpk_lt_i32 s5, 0x4000
	s_cselect_b32 s21, s20, 0
	s_cselect_b32 s20, s5, s7
	s_cselect_b32 s7, s13, s9
	s_cselect_b32 s22, s12, s8
	s_lshl_b64 s[20:21], s[20:21], 12
	s_add_u32 s20, s22, s20
	s_addc_u32 s21, s7, s21
	s_cmp_eq_u32 s100, 1
	s_mov_b64 s[100:101], s[18:19]
	s_cbranch_scc1 .Lpn1_pf_top
	global_load_dwordx4 v[18:21], v0, s[18:19] nt
	global_load_dwordx4 v[22:25], v0, s[18:19] offset:1024 nt
	global_load_dwordx4 v[62:65], v0, s[20:21] nt
	global_load_dwordx4 v[54:57], v0, s[20:21] offset:1024 nt
	global_load_dwordx4 v[26:29], v0, s[18:19] offset:2048 nt
	global_load_dwordx4 v[30:33], v0, s[18:19] offset:3072 nt
	global_load_dwordx4 v[58:61], v0, s[20:21] offset:2048 nt
	global_load_dwordx4 v[50:53], v0, s[20:21] offset:3072 nt
	v_readlane_b32 s20, v255, 10
	v_readlane_b32 s21, v255, 11
	s_mov_b64 s[18:19], -1
	s_and_b64 vcc, exec, s[20:21]
	s_cbranch_vccz .LBB0_208
	s_cmpk_lt_i32 s17, 0x4000
	s_waitcnt vmcnt(7)
	v_mov_b32_e32 v2, v18
	v_mov_b32_e32 v3, v19
	v_mov_b32_e32 v4, v20
	v_mov_b32_e32 v5, v21
	s_waitcnt vmcnt(6)
	v_mov_b32_e32 v6, v22
	v_mov_b32_e32 v7, v23
	v_mov_b32_e32 v8, v24
	v_mov_b32_e32 v9, v25
	s_waitcnt vmcnt(3)
	v_mov_b32_e32 v10, v26
	v_mov_b32_e32 v11, v27
	v_mov_b32_e32 v12, v28
	v_mov_b32_e32 v13, v29
	s_waitcnt vmcnt(2)
	v_mov_b32_e32 v14, v30
	v_mov_b32_e32 v15, v31
	v_mov_b32_e32 v16, v32
	v_mov_b32_e32 v17, v33
	s_cbranch_scc1 .LBB0_205
	s_lshl_b64 s[18:19], s[74:75], 12
	v_lshl_add_u64 v[98:99], v[68:69], 0, s[18:19]
	v_add_co_u32_e32 v46, vcc, 0x400000, v98
	global_load_dwordx4 v[2:5], v[98:99], off
	global_load_dwordx4 v[6:9], v[98:99], off offset:1024
	global_load_dwordx4 v[10:13], v[98:99], off offset:2048
	global_load_dwordx4 v[14:17], v[98:99], off offset:3072
	v_addc_co_u32_e32 v47, vcc, 0, v99, vcc
	v_add_co_u32_e32 v94, vcc, 0x800000, v98
	global_load_dwordx4 v[34:37], v[46:47], off
	global_load_dwordx4 v[38:41], v[46:47], off offset:1024
	global_load_dwordx4 v[42:45], v[46:47], off offset:2048
	s_nop 0
	global_load_dwordx4 v[46:49], v[46:47], off offset:3072
	v_addc_co_u32_e32 v95, vcc, 0, v99, vcc
	v_add_co_u32_e32 v110, vcc, 0xc00000, v98
	global_load_dwordx4 v[82:85], v[94:95], off
	global_load_dwordx4 v[86:89], v[94:95], off offset:1024
	global_load_dwordx4 v[90:93], v[94:95], off offset:2048
	s_nop 0
	global_load_dwordx4 v[94:97], v[94:95], off offset:3072
	v_addc_co_u32_e32 v111, vcc, 0, v99, vcc
	global_load_dwordx4 v[98:101], v[110:111], off
	global_load_dwordx4 v[102:105], v[110:111], off offset:1024
	global_load_dwordx4 v[106:109], v[110:111], off offset:2048
	s_nop 0
	global_load_dwordx4 v[110:113], v[110:111], off offset:3072
	s_waitcnt vmcnt(15)
	v_pk_add_f32 v[4:5], v[20:21], v[4:5]
	v_pk_add_f32 v[2:3], v[18:19], v[2:3]
	s_waitcnt vmcnt(14)
	v_pk_add_f32 v[8:9], v[24:25], v[8:9]
	v_pk_add_f32 v[6:7], v[22:23], v[6:7]
	s_waitcnt vmcnt(13)
	v_pk_add_f32 v[12:13], v[28:29], v[12:13]
	v_pk_add_f32 v[10:11], v[26:27], v[10:11]
	s_waitcnt vmcnt(12)
	v_pk_add_f32 v[16:17], v[32:33], v[16:17]
	v_pk_add_f32 v[14:15], v[30:31], v[14:15]
	s_waitcnt vmcnt(11)
	v_pk_add_f32 v[4:5], v[4:5], v[36:37]
	v_pk_add_f32 v[2:3], v[2:3], v[34:35]
	s_waitcnt vmcnt(10)
	v_pk_add_f32 v[8:9], v[8:9], v[40:41]
	v_pk_add_f32 v[6:7], v[6:7], v[38:39]
	s_waitcnt vmcnt(9)
	v_pk_add_f32 v[12:13], v[12:13], v[44:45]
	v_pk_add_f32 v[10:11], v[10:11], v[42:43]
	s_waitcnt vmcnt(8)
	v_pk_add_f32 v[16:17], v[16:17], v[48:49]
	v_pk_add_f32 v[14:15], v[14:15], v[46:47]
	s_waitcnt vmcnt(7)
	v_pk_add_f32 v[4:5], v[4:5], v[84:85]
	v_pk_add_f32 v[2:3], v[2:3], v[82:83]
	s_waitcnt vmcnt(6)
	v_pk_add_f32 v[8:9], v[8:9], v[88:89]
	v_pk_add_f32 v[6:7], v[6:7], v[86:87]
	s_waitcnt vmcnt(5)
	v_pk_add_f32 v[12:13], v[12:13], v[92:93]
	v_pk_add_f32 v[10:11], v[10:11], v[90:91]
	s_waitcnt vmcnt(4)
	v_pk_add_f32 v[16:17], v[16:17], v[96:97]
	v_pk_add_f32 v[14:15], v[14:15], v[94:95]
	s_waitcnt vmcnt(3)
	v_pk_add_f32 v[4:5], v[4:5], v[100:101]
	v_pk_add_f32 v[2:3], v[2:3], v[98:99]
	s_waitcnt vmcnt(2)
	v_pk_add_f32 v[8:9], v[8:9], v[104:105]
	v_pk_add_f32 v[6:7], v[6:7], v[102:103]
	s_waitcnt vmcnt(1)
	v_pk_add_f32 v[12:13], v[12:13], v[108:109]
	v_pk_add_f32 v[10:11], v[10:11], v[106:107]
	s_waitcnt vmcnt(0)
	v_pk_add_f32 v[16:17], v[16:17], v[112:113]
	v_pk_add_f32 v[14:15], v[14:15], v[110:111]
	v_lshl_add_u64 v[34:35], v[76:77], 0, s[18:19]
	global_store_dwordx4 v[34:35], v[2:5], off sc1
	global_store_dwordx4 v[34:35], v[6:9], off offset:1024 sc1
	global_store_dwordx4 v[34:35], v[10:13], off offset:2048 sc1
	global_store_dwordx4 v[34:35], v[14:17], off offset:3072 sc1
.LBB0_205:
	s_cmpk_lt_i32 s16, 0x4000
	s_cselect_b64 s[18:19], -1, 0
	s_xor_b64 s[20:21], s[14:15], -1
	s_or_b64 s[18:19], s[20:21], s[18:19]
	s_and_b64 vcc, exec, s[18:19]
	s_waitcnt vmcnt(0)
	v_mov_b32_e32 v37, v53
	v_mov_b32_e32 v36, v52
	v_mov_b32_e32 v35, v51
	v_mov_b32_e32 v34, v50
	v_mov_b32_e32 v41, v61
	v_mov_b32_e32 v40, v60
	v_mov_b32_e32 v39, v59
	v_mov_b32_e32 v38, v58
	v_mov_b32_e32 v45, v57
	v_mov_b32_e32 v44, v56
	v_mov_b32_e32 v43, v55
	v_mov_b32_e32 v42, v54
	v_mov_b32_e32 v49, v65
	v_mov_b32_e32 v48, v64
	v_mov_b32_e32 v47, v63
	v_mov_b32_e32 v46, v62
	s_cbranch_vccnz .LBB0_207
	s_mov_b32 s7, s75
	s_lshl_b64 s[6:7], s[6:7], 12
	v_lshl_add_u64 v[114:115], v[68:69], 0, s[6:7]
	v_add_co_u32_e32 v94, vcc, 0x400000, v114
	s_mov_b32 s18, 0xc00000
	s_nop 0
	v_addc_co_u32_e32 v95, vcc, 0, v115, vcc
	v_add_co_u32_e32 v110, vcc, s96, v114
	global_load_dwordx4 v[34:37], v[114:115], off
	global_load_dwordx4 v[38:41], v[114:115], off offset:1024
	global_load_dwordx4 v[42:45], v[114:115], off offset:2048
	global_load_dwordx4 v[46:49], v[114:115], off offset:3072
	v_addc_co_u32_e32 v111, vcc, 0, v115, vcc
	v_add_co_u32_e32 v126, vcc, s18, v114
	global_load_dwordx4 v[82:85], v[94:95], off
	global_load_dwordx4 v[86:89], v[94:95], off offset:1024
	global_load_dwordx4 v[90:93], v[94:95], off offset:2048
	s_nop 0
	global_load_dwordx4 v[94:97], v[94:95], off offset:3072
	v_addc_co_u32_e32 v127, vcc, 0, v115, vcc
	global_load_dwordx4 v[98:101], v[110:111], off
	global_load_dwordx4 v[102:105], v[110:111], off offset:1024
	global_load_dwordx4 v[106:109], v[110:111], off offset:2048
	s_nop 0
	global_load_dwordx4 v[110:113], v[110:111], off offset:3072
	s_nop 0
	global_load_dwordx4 v[114:117], v[126:127], off
	global_load_dwordx4 v[118:121], v[126:127], off offset:1024
	global_load_dwordx4 v[122:125], v[126:127], off offset:2048
	s_nop 0
	global_load_dwordx4 v[126:129], v[126:127], off offset:3072
	s_waitcnt vmcnt(15)
	v_pk_add_f32 v[36:37], v[64:65], v[36:37]
	v_pk_add_f32 v[34:35], v[62:63], v[34:35]
	s_waitcnt vmcnt(14)
	v_pk_add_f32 v[40:41], v[56:57], v[40:41]
	v_pk_add_f32 v[38:39], v[54:55], v[38:39]
	s_waitcnt vmcnt(13)
	v_pk_add_f32 v[44:45], v[60:61], v[44:45]
	v_pk_add_f32 v[42:43], v[58:59], v[42:43]
	s_waitcnt vmcnt(12)
	v_pk_add_f32 v[48:49], v[52:53], v[48:49]
	v_pk_add_f32 v[46:47], v[50:51], v[46:47]
	s_waitcnt vmcnt(11)
	v_pk_add_f32 v[36:37], v[36:37], v[84:85]
	v_pk_add_f32 v[34:35], v[34:35], v[82:83]
	s_waitcnt vmcnt(10)
	v_pk_add_f32 v[40:41], v[40:41], v[88:89]
	v_pk_add_f32 v[38:39], v[38:39], v[86:87]
	s_waitcnt vmcnt(9)
	v_pk_add_f32 v[44:45], v[44:45], v[92:93]
	v_pk_add_f32 v[42:43], v[42:43], v[90:91]
	s_waitcnt vmcnt(8)
	v_pk_add_f32 v[48:49], v[48:49], v[96:97]
	v_pk_add_f32 v[46:47], v[46:47], v[94:95]
	s_waitcnt vmcnt(7)
	v_pk_add_f32 v[36:37], v[36:37], v[100:101]
	v_pk_add_f32 v[34:35], v[34:35], v[98:99]
	s_waitcnt vmcnt(6)
	v_pk_add_f32 v[40:41], v[40:41], v[104:105]
	v_pk_add_f32 v[38:39], v[38:39], v[102:103]
	s_waitcnt vmcnt(5)
	v_pk_add_f32 v[82:83], v[44:45], v[108:109]
	v_pk_add_f32 v[84:85], v[42:43], v[106:107]
	s_waitcnt vmcnt(4)
	v_pk_add_f32 v[86:87], v[48:49], v[112:113]
	v_pk_add_f32 v[88:89], v[46:47], v[110:111]
	s_waitcnt vmcnt(3)
	v_pk_add_f32 v[48:49], v[36:37], v[116:117]
	v_pk_add_f32 v[46:47], v[34:35], v[114:115]
	s_waitcnt vmcnt(2)
	v_pk_add_f32 v[44:45], v[40:41], v[120:121]
	v_pk_add_f32 v[42:43], v[38:39], v[118:119]
	s_waitcnt vmcnt(1)
	v_pk_add_f32 v[40:41], v[82:83], v[124:125]
	v_pk_add_f32 v[38:39], v[84:85], v[122:123]
	s_waitcnt vmcnt(0)
	v_pk_add_f32 v[36:37], v[86:87], v[128:129]
	v_pk_add_f32 v[34:35], v[88:89], v[126:127]
	v_lshl_add_u64 v[82:83], v[76:77], 0, s[6:7]
	global_store_dwordx4 v[82:83], v[46:49], off sc1
	global_store_dwordx4 v[82:83], v[42:45], off offset:1024 sc1
	global_store_dwordx4 v[82:83], v[38:41], off offset:2048 sc1
	global_store_dwordx4 v[82:83], v[34:37], off offset:3072 sc1

.Lpn1_wj:
	v_mul_f32_e32 v132, 0x4b800000, v131
	v_cmp_gt_f32_e32 vcc, s96, v131
	v_cmp_gt_f32_e64 s[6:7], s96, v130
	v_pk_add_f32 v[140:141], v[140:141], 1.0 op_sel_hi:[1,0]
	v_pk_add_f32 v[138:139], v[138:139], 1.0 op_sel_hi:[1,0]
	v_cndmask_b32_e32 v131, v131, v132, vcc
	v_rsq_f32_e32 v131, v131
	v_mul_f32_e32 v132, 0x4b800000, v130
	v_cndmask_b32_e64 v130, v130, v132, s[6:7]
	v_rsq_f32_e32 v130, v130
	v_mul_f32_e32 v132, 0x45800000, v131
	v_cndmask_b32_e32 v132, v131, v132, vcc
	v_mul_f32_e32 v131, 0x45800000, v130
	v_cndmask_b32_e64 v130, v130, v131, s[6:7]
	v_pk_add_f32 v[88:89], v[88:89], 1.0 op_sel_hi:[1,0]
	v_pk_add_f32 v[86:87], v[86:87], 1.0 op_sel_hi:[1,0]
	v_pk_add_f32 v[96:97], v[96:97], 1.0 op_sel_hi:[1,0]
	v_pk_add_f32 v[94:95], v[94:95], 1.0 op_sel_hi:[1,0]
	v_pk_add_f32 v[104:105], v[104:105], 1.0 op_sel_hi:[1,0]
	v_pk_add_f32 v[102:103], v[102:103], 1.0 op_sel_hi:[1,0]
	v_pk_mul_f32 v[2:3], v[2:3], v[132:133] op_sel_hi:[1,0]
	v_pk_mul_f32 v[4:5], v[4:5], v[132:133] op_sel_hi:[1,0]
	v_pk_mul_f32 v[6:7], v[6:7], v[132:133] op_sel_hi:[1,0]
	v_pk_mul_f32 v[8:9], v[8:9], v[132:133] op_sel_hi:[1,0]
	v_pk_mul_f32 v[10:11], v[10:11], v[132:133] op_sel_hi:[1,0]
	v_pk_mul_f32 v[12:13], v[12:13], v[132:133] op_sel_hi:[1,0]
	v_pk_mul_f32 v[14:15], v[14:15], v[132:133] op_sel_hi:[1,0]
	v_pk_mul_f32 v[16:17], v[16:17], v[132:133] op_sel_hi:[1,0]
	v_pk_fma_f32 v[2:3], v[138:139], v[2:3], v[134:135]
	v_pk_fma_f32 v[4:5], v[140:141], v[4:5], v[136:137]
	v_pk_fma_f32 v[6:7], v[86:87], v[6:7], v[82:83]
	v_pk_fma_f32 v[8:9], v[88:89], v[8:9], v[84:85]
	v_pk_fma_f32 v[10:11], v[94:95], v[10:11], v[90:91]
	v_pk_fma_f32 v[12:13], v[96:97], v[12:13], v[92:93]
	v_pk_fma_f32 v[14:15], v[102:103], v[14:15], v[98:99]
	v_pk_fma_f32 v[16:17], v[104:105], v[16:17], v[100:101]
	v_cvt_pk_bf16_f32 v2, v2, v3
	v_cvt_pk_bf16_f32 v3, v4, v5
	v_cvt_pk_bf16_f32 v6, v6, v7
	v_cvt_pk_bf16_f32 v7, v8, v9
	v_cvt_pk_bf16_f32 v10, v10, v11
	v_cvt_pk_bf16_f32 v11, v12, v13
	v_cvt_pk_bf16_f32 v14, v14, v15
	v_cvt_pk_bf16_f32 v15, v16, v17
	global_store_dwordx2 v[78:79], v[2:3], off sc1
	global_store_dwordx2 v[78:79], v[6:7], off offset:512 sc1
	global_store_dwordx2 v[78:79], v[10:11], off offset:1024 sc1
	global_store_dwordx2 v[78:79], v[14:15], off offset:1536 sc1
	s_andn2_b64 vcc, exec, s[14:15]
	s_cbranch_vccnz .Lpn1_row1_done
	v_pk_add_f32 v[112:113], v[112:113], 1.0 op_sel_hi:[1,0]
	v_pk_add_f32 v[110:111], v[110:111], 1.0 op_sel_hi:[1,0]
	v_pk_add_f32 v[120:121], v[120:121], 1.0 op_sel_hi:[1,0]
	v_pk_add_f32 v[118:119], v[118:119], 1.0 op_sel_hi:[1,0]
	v_pk_add_f32 v[128:129], v[128:129], 1.0 op_sel_hi:[1,0]
	v_pk_add_f32 v[126:127], v[126:127], 1.0 op_sel_hi:[1,0]
	v_pk_add_f32 v[152:153], v[152:153], 1.0 op_sel_hi:[1,0]
	v_pk_add_f32 v[150:151], v[150:151], 1.0 op_sel_hi:[1,0]
	v_pk_mul_f32 v[46:47], v[46:47], v[130:131] op_sel_hi:[1,0]
	v_pk_mul_f32 v[48:49], v[48:49], v[130:131] op_sel_hi:[1,0]
	v_pk_mul_f32 v[42:43], v[42:43], v[130:131] op_sel_hi:[1,0]
	v_pk_mul_f32 v[44:45], v[44:45], v[130:131] op_sel_hi:[1,0]
	v_pk_mul_f32 v[38:39], v[38:39], v[130:131] op_sel_hi:[1,0]
	v_pk_mul_f32 v[40:41], v[40:41], v[130:131] op_sel_hi:[1,0]
	v_pk_mul_f32 v[34:35], v[34:35], v[130:131] op_sel_hi:[1,0]
	v_pk_mul_f32 v[36:37], v[36:37], v[130:131] op_sel_hi:[1,0]
	v_pk_fma_f32 v[46:47], v[46:47], v[110:111], v[106:107]
	v_pk_fma_f32 v[48:49], v[48:49], v[112:113], v[108:109]
	v_pk_fma_f32 v[42:43], v[42:43], v[118:119], v[114:115]
	v_pk_fma_f32 v[44:45], v[44:45], v[120:121], v[116:117]
	v_pk_fma_f32 v[38:39], v[38:39], v[126:127], v[122:123]
	v_pk_fma_f32 v[40:41], v[40:41], v[128:129], v[124:125]
	v_pk_fma_f32 v[34:35], v[34:35], v[150:151], v[146:147]
	v_pk_fma_f32 v[36:37], v[36:37], v[152:153], v[148:149]
	v_cvt_pk_bf16_f32 v46, v46, v47
	v_cvt_pk_bf16_f32 v47, v48, v49
	v_cvt_pk_bf16_f32 v42, v42, v43
	v_cvt_pk_bf16_f32 v43, v44, v45
	v_cvt_pk_bf16_f32 v38, v38, v39
	v_cvt_pk_bf16_f32 v39, v40, v41
	v_cvt_pk_bf16_f32 v34, v34, v35
	v_cvt_pk_bf16_f32 v35, v36, v37
	global_store_dwordx2 v142, v[46:47], s[16:17] sc1
	global_store_dwordx2 v142, v[42:43], s[16:17] offset:512 sc1
	global_store_dwordx2 v142, v[38:39], s[16:17] offset:1024 sc1
	global_store_dwordx2 v142, v[34:35], s[16:17] offset:1536 sc1

.LBB0_238:
	s_ashr_i32 s21, s76, 31
	s_sub_i32 s23, s76, 64
	s_cmp_gt_i32 s76, 63
	v_readlane_b32 s38, v255, 52
	s_cselect_b32 s29, 0, s21
	s_cselect_b32 s28, s23, s76
	v_readlane_b32 s39, v255, 53
	s_cselect_b32 s21, s11, s13
	s_cselect_b32 s23, s10, s12
	s_cselect_b32 s44, s39, s15
	s_cselect_b32 s45, s38, s14
	s_lshl_b64 s[28:29], s[28:29], 20
	s_add_u32 s38, s23, s28
	s_addc_u32 s39, s21, s29
	s_add_u32 s28, s45, s28
	s_addc_u32 s29, s44, s29
	s_min_i32 s21, s76, 64
	s_lshr_b32 s21, s21, 4
	s_mul_i32 s44, s21, 0x1800
	s_ashr_i32 s45, s44, 31
	s_lshl_b64 s[44:45], s[44:45], 2
	v_mov_b32_e32 v154, v191
	s_add_u32 s44, s49, s44
	s_addc_u32 s45, s56, s45
	s_lshl_b32 s21, s74, 8
	v_lshrrev_b32_e32 v130, 2, v154
	v_and_or_b32 v130, v130, 12, s21
	v_or_b32_e32 v130, s66, v130
	v_and_or_b32 v188, v154, 15, s57
	v_ashrrev_i32_e32 v131, 31, v130
	v_or_b32_e32 v176, 16, v188
	v_lshlrev_b64 v[152:153], 2, v[130:131]
	v_ashrrev_i32_e32 v189, 31, v188
	v_ashrrev_i32_e32 v177, 31, v176
	v_lshl_add_u64 v[154:155], s[38:39], 0, v[152:153]
	v_lshlrev_b64 v[156:157], 12, v[188:189]
	v_lshlrev_b64 v[192:193], 12, v[176:177]
	v_lshl_add_u64 v[130:131], s[44:45], 0, v[152:153]
	v_lshl_add_u64 v[172:173], v[154:155], 0, v[156:157]
	v_lshl_add_u64 v[194:195], v[154:155], 0, v[192:193]
	global_load_dwordx4 v[142:145], v[130:131], off
	global_load_dwordx4 v[138:141], v[130:131], off offset:64
	global_load_dwordx4 v[134:137], v[130:131], off offset:512
	s_nop 0
	global_load_dwordx4 v[130:133], v[130:131], off offset:576
	s_nop 0
	global_load_dwordx4 v[160:163], v[172:173], off
	global_load_dwordx4 v[164:167], v[172:173], off offset:64
	global_load_dwordx4 v[168:171], v[172:173], off offset:512
	s_nop 0
	global_load_dwordx4 v[172:175], v[172:173], off offset:576
	s_nop 0
	global_load_dwordx4 v[176:179], v[194:195], off
	global_load_dwordx4 v[180:183], v[194:195], off offset:64
	global_load_dwordx4 v[184:187], v[194:195], off offset:512
	global_load_dwordx4 v[196:199], v[194:195], off offset:576
	v_lshl_add_u64 v[152:153], s[28:29], 0, v[152:153]
	v_lshl_add_u64 v[194:195], v[152:153], 0, v[156:157]
	s_waitcnt vmcnt(0)
	v_pk_fma_f32 v[120:121], v[120:121], v[136:137], v[170:171]
	v_pk_fma_f32 v[118:119], v[118:119], v[134:135], v[168:169]
	v_pk_fma_f32 v[108:109], v[108:109], v[132:133], v[174:175]
	v_pk_fma_f32 v[106:107], v[106:107], v[130:131], v[172:173]
	global_store_dwordx4 v[194:195], v[118:121], off offset:512 sc1
	global_store_dwordx4 v[194:195], v[106:109], off offset:576 sc1
	v_pk_fma_f32 v[128:129], v[128:129], v[144:145], v[162:163]
	v_lshl_add_u64 v[118:119], v[152:153], 0, v[192:193]
	v_pk_fma_f32 v[108:109], v[116:117], v[144:145], v[178:179]
	v_pk_fma_f32 v[106:107], v[114:115], v[142:143], v[176:177]
	v_pk_fma_f32 v[126:127], v[126:127], v[142:143], v[160:161]
	v_pk_fma_f32 v[124:125], v[124:125], v[140:141], v[166:167]
	v_pk_fma_f32 v[122:123], v[122:123], v[138:139], v[164:165]
	global_store_dwordx4 v[118:119], v[106:109], off sc1
	v_pk_fma_f32 v[104:105], v[104:105], v[136:137], v[186:187]
	v_pk_fma_f32 v[102:103], v[102:103], v[134:135], v[184:185]
	v_pk_fma_f32 v[108:109], v[112:113], v[140:141], v[182:183]
	v_pk_fma_f32 v[106:107], v[110:111], v[138:139], v[180:181]
	v_pk_fma_f32 v[100:101], v[100:101], v[132:133], v[198:199]
	v_pk_fma_f32 v[98:99], v[98:99], v[130:131], v[196:197]
	global_store_dwordx4 v[194:195], v[126:129], off sc1
	global_store_dwordx4 v[194:195], v[122:125], off offset:64 sc1
	global_store_dwordx4 v[118:119], v[106:109], off offset:64 sc1
	global_store_dwordx4 v[118:119], v[102:105], off offset:512 sc1
	global_store_dwordx4 v[118:119], v[98:101], off offset:576 sc1
	s_nop 1
	v_or_b32_e32 v98, 32, v188
	v_or_b32_e32 v114, 48, v188
	v_ashrrev_i32_e32 v99, 31, v98
	v_ashrrev_i32_e32 v115, 31, v114
	v_lshlrev_b64 v[160:161], 12, v[98:99]
	v_lshlrev_b64 v[162:163], 12, v[114:115]
	v_lshl_add_u64 v[110:111], v[154:155], 0, v[160:161]
	v_lshl_add_u64 v[126:127], v[154:155], 0, v[162:163]
	global_load_dwordx4 v[98:101], v[110:111], off
	global_load_dwordx4 v[102:105], v[110:111], off offset:64
	global_load_dwordx4 v[106:109], v[110:111], off offset:512
	s_nop 0
	global_load_dwordx4 v[110:113], v[110:111], off offset:576
	s_nop 0
	global_load_dwordx4 v[114:117], v[126:127], off
	global_load_dwordx4 v[118:121], v[126:127], off offset:64
	global_load_dwordx4 v[122:125], v[126:127], off offset:512
	s_nop 0
	global_load_dwordx4 v[126:129], v[126:127], off offset:576
	v_lshl_add_u64 v[160:161], v[152:153], 0, v[160:161]
	s_waitcnt vmcnt(5)
	v_pk_fma_f32 v[84:85], v[84:85], v[136:137], v[108:109]
	v_pk_fma_f32 v[82:83], v[82:83], v[134:135], v[106:107]
	s_waitcnt vmcnt(4)
	v_pk_fma_f32 v[76:77], v[76:77], v[132:133], v[112:113]
	v_pk_fma_f32 v[74:75], v[74:75], v[130:131], v[110:111]
	global_store_dwordx4 v[160:161], v[82:85], off offset:512 sc1
	global_store_dwordx4 v[160:161], v[74:77], off offset:576 sc1
	v_pk_fma_f32 v[96:97], v[96:97], v[144:145], v[100:101]
	v_lshl_add_u64 v[82:83], v[152:153], 0, v[162:163]
	s_waitcnt vmcnt(5)
	v_pk_fma_f32 v[76:77], v[88:89], v[144:145], v[116:117]
	v_pk_fma_f32 v[74:75], v[86:87], v[142:143], v[114:115]
	v_pk_fma_f32 v[94:95], v[94:95], v[142:143], v[98:99]
	v_pk_fma_f32 v[92:93], v[92:93], v[140:141], v[104:105]
	v_pk_fma_f32 v[90:91], v[90:91], v[138:139], v[102:103]
	global_store_dwordx4 v[82:83], v[74:77], off sc1
	s_waitcnt vmcnt(4)
	v_pk_fma_f32 v[72:73], v[72:73], v[136:137], v[124:125]
	v_pk_fma_f32 v[70:71], v[70:71], v[134:135], v[122:123]
	v_pk_fma_f32 v[76:77], v[80:81], v[140:141], v[120:121]
	v_pk_fma_f32 v[74:75], v[78:79], v[138:139], v[118:119]
	s_waitcnt vmcnt(3)
	v_pk_fma_f32 v[68:69], v[68:69], v[132:133], v[128:129]
	v_pk_fma_f32 v[66:67], v[66:67], v[130:131], v[126:127]
	global_store_dwordx4 v[160:161], v[94:97], off sc1
	global_store_dwordx4 v[160:161], v[90:93], off offset:64 sc1
	global_store_dwordx4 v[82:83], v[74:77], off offset:64 sc1
	global_store_dwordx4 v[82:83], v[70:73], off offset:512 sc1
	global_store_dwordx4 v[82:83], v[66:69], off offset:576 sc1
	s_mov_b64 s[28:29], 0x80000
	v_lshl_add_u64 v[98:99], v[156:157], 0, s[28:29]
	s_mov_b64 s[28:29], 0x90000
	v_lshl_add_u64 v[100:101], v[156:157], 0, s[28:29]
	v_lshl_add_u64 v[78:79], v[154:155], 0, v[98:99]
	v_lshl_add_u64 v[94:95], v[154:155], 0, v[100:101]
	global_load_dwordx4 v[66:69], v[78:79], off
	global_load_dwordx4 v[70:73], v[78:79], off offset:64
	global_load_dwordx4 v[74:77], v[78:79], off offset:512
	s_nop 0
	global_load_dwordx4 v[78:81], v[78:79], off offset:576
	s_nop 0
	global_load_dwordx4 v[82:85], v[94:95], off
	global_load_dwordx4 v[86:89], v[94:95], off offset:64
	global_load_dwordx4 v[90:93], v[94:95], off offset:512
	s_nop 0
	global_load_dwordx4 v[94:97], v[94:95], off offset:576
	v_lshl_add_u64 v[98:99], v[152:153], 0, v[98:99]
	s_waitcnt vmcnt(5)
	v_pk_fma_f32 v[52:53], v[52:53], v[136:137], v[76:77]
	v_pk_fma_f32 v[50:51], v[50:51], v[134:135], v[74:75]
	s_waitcnt vmcnt(4)
	v_pk_fma_f32 v[44:45], v[44:45], v[132:133], v[80:81]
	v_pk_fma_f32 v[42:43], v[42:43], v[130:131], v[78:79]
	global_store_dwordx4 v[98:99], v[50:53], off offset:512 sc1
	global_store_dwordx4 v[98:99], v[42:45], off offset:576 sc1
	v_pk_fma_f32 v[64:65], v[64:65], v[144:145], v[68:69]
	v_lshl_add_u64 v[50:51], v[152:153], 0, v[100:101]
	s_waitcnt vmcnt(5)
	v_pk_fma_f32 v[44:45], v[56:57], v[144:145], v[84:85]
	v_pk_fma_f32 v[42:43], v[54:55], v[142:143], v[82:83]
	v_pk_fma_f32 v[62:63], v[62:63], v[142:143], v[66:67]
	v_pk_fma_f32 v[60:61], v[60:61], v[140:141], v[72:73]
	v_pk_fma_f32 v[58:59], v[58:59], v[138:139], v[70:71]
	global_store_dwordx4 v[50:51], v[42:45], off sc1
	s_waitcnt vmcnt(4)
	v_pk_fma_f32 v[40:41], v[40:41], v[136:137], v[92:93]
	v_pk_fma_f32 v[38:39], v[38:39], v[134:135], v[90:91]
	v_pk_fma_f32 v[44:45], v[48:49], v[140:141], v[88:89]
	v_pk_fma_f32 v[42:43], v[46:47], v[138:139], v[86:87]
	s_waitcnt vmcnt(3)
	v_pk_fma_f32 v[32:33], v[32:33], v[132:133], v[96:97]
	v_pk_fma_f32 v[30:31], v[30:31], v[130:131], v[94:95]
	global_store_dwordx4 v[98:99], v[62:65], off sc1
	global_store_dwordx4 v[98:99], v[58:61], off offset:64 sc1
	global_store_dwordx4 v[50:51], v[42:45], off offset:64 sc1
	global_store_dwordx4 v[50:51], v[38:41], off offset:512 sc1
	global_store_dwordx4 v[50:51], v[30:33], off offset:576 sc1
	s_mov_b64 s[28:29], 0xa0000
	v_lshl_add_u64 v[66:67], v[156:157], 0, s[28:29]
	s_mov_b64 s[28:29], 0xb0000
	v_lshl_add_u64 v[68:69], v[156:157], 0, s[28:29]
	v_lshl_add_u64 v[46:47], v[154:155], 0, v[66:67]
	v_lshl_add_u64 v[62:63], v[154:155], 0, v[68:69]
	global_load_dwordx4 v[30:33], v[46:47], off
	global_load_dwordx4 v[38:41], v[46:47], off offset:64
	global_load_dwordx4 v[42:45], v[46:47], off offset:512
	s_nop 0
	global_load_dwordx4 v[46:49], v[46:47], off offset:576
	s_nop 0
	global_load_dwordx4 v[50:53], v[62:63], off
	global_load_dwordx4 v[54:57], v[62:63], off offset:64
	global_load_dwordx4 v[58:61], v[62:63], off offset:512
	s_nop 0
	global_load_dwordx4 v[62:65], v[62:63], off offset:576
	v_lshl_add_u64 v[66:67], v[152:153], 0, v[66:67]
	s_waitcnt vmcnt(5)
	v_pk_fma_f32 v[20:21], v[20:21], v[136:137], v[44:45]
	v_pk_fma_f32 v[18:19], v[18:19], v[134:135], v[42:43]
	s_waitcnt vmcnt(4)
	v_pk_fma_f32 v[12:13], v[12:13], v[132:133], v[48:49]
	v_pk_fma_f32 v[10:11], v[10:11], v[130:131], v[46:47]
	global_store_dwordx4 v[66:67], v[18:21], off offset:512 sc1
	global_store_dwordx4 v[66:67], v[10:13], off offset:576 sc1
	v_pk_fma_f32 v[32:33], v[36:37], v[144:145], v[32:33]
	v_lshl_add_u64 v[18:19], v[152:153], 0, v[68:69]
	s_waitcnt vmcnt(5)
	v_pk_fma_f32 v[12:13], v[24:25], v[144:145], v[52:53]
	v_pk_fma_f32 v[10:11], v[22:23], v[142:143], v[50:51]
	v_pk_fma_f32 v[30:31], v[34:35], v[142:143], v[30:31]
	v_pk_fma_f32 v[28:29], v[28:29], v[140:141], v[40:41]
	v_pk_fma_f32 v[26:27], v[26:27], v[138:139], v[38:39]
	global_store_dwordx4 v[18:19], v[10:13], off sc1
	s_waitcnt vmcnt(4)
	v_pk_fma_f32 v[8:9], v[8:9], v[136:137], v[60:61]
	v_pk_fma_f32 v[6:7], v[6:7], v[134:135], v[58:59]
	v_pk_fma_f32 v[12:13], v[16:17], v[140:141], v[56:57]
	v_pk_fma_f32 v[10:11], v[14:15], v[138:139], v[54:55]
	s_waitcnt vmcnt(3)
	v_pk_fma_f32 v[4:5], v[4:5], v[132:133], v[64:65]
	v_pk_fma_f32 v[2:3], v[2:3], v[130:131], v[62:63]
	global_store_dwordx4 v[66:67], v[30:33], off sc1
	global_store_dwordx4 v[66:67], v[26:29], off offset:64 sc1
	global_store_dwordx4 v[18:19], v[10:13], off offset:64 sc1
	global_store_dwordx4 v[18:19], v[6:9], off offset:512 sc1
	global_store_dwordx4 v[18:19], v[2:5], off offset:576 sc1
	s_andn2_b64 vcc, exec, s[8:9]
	s_mov_b64 s[8:9], -1
	v_readlane_b32 s81, v254, 62
	s_mov_b32 s93, 0x38000
	s_cbranch_vccnz .LBB0_227
	s_andn2_b64 vcc, exec, s[16:17]
	s_cbranch_vccnz .LBB0_226
	s_barrier
	s_branch .LBB0_226

.LBB0_257:
	v_mov_b32_e32 v26, v191
	s_lshl_b32 s15, s25, 8
	v_and_b32_e32 v148, 15, v26
	v_bfe_u32 v26, v26, 4, 2
	s_or_b32 s15, s15, s48
	v_lshl_add_u32 v26, v26, 2, s15
	v_ashrrev_i32_e32 v27, 31, v26
	v_lshlrev_b64 v[152:153], 2, v[26:27]
	v_lshl_add_u64 v[26:27], s[12:13], 0, v[152:153]
	global_load_dwordx4 v[46:49], v[26:27], off
	global_load_dwordx4 v[42:45], v[26:27], off offset:64
	global_load_dwordx4 v[38:41], v[26:27], off offset:512
	s_nop 0
	global_load_dwordx4 v[26:29], v[26:27], off offset:576
	s_ashr_i32 s15, s33, 31
	s_lshr_b32 s15, s15, 24
	s_add_i32 s15, s33, s15
	s_ashr_i32 s26, s15, 8
	s_ashr_i32 s25, s24, 31
	s_ashr_i32 s27, s26, 31
	s_lshl_b64 s[24:25], s[24:25], 20
	s_lshl_b64 s[26:27], s[26:27], 22
	s_add_u32 s15, s44, s26
	s_addc_u32 s17, s45, s27
	s_add_u32 s24, s15, s24
	v_add_u32_e32 v148, s46, v148
	s_addc_u32 s25, s17, s25
	v_add_u32_e32 v158, 48, v148
	v_lshl_add_u64 v[152:153], s[24:25], 0, v[152:153]
	s_brev_b32 s24, 63
	v_ashrrev_i32_e32 v149, 31, v148
	v_add_u32_e32 v154, 16, v148
	v_add_u32_e32 v156, 32, v148
	v_ashrrev_i32_e32 v159, 31, v158
	s_mov_b32 s25, -1
	v_lshlrev_b64 v[160:161], 12, v[148:149]
	v_ashrrev_i32_e32 v155, 31, v154
	v_ashrrev_i32_e32 v157, 31, v156
	v_lshlrev_b64 v[158:159], 12, v[158:159]
	v_lshl_add_u64 v[152:153], v[152:153], 0, s[24:25]
	v_lshlrev_b64 v[154:155], 12, v[154:155]
	v_lshlrev_b64 v[156:157], 12, v[156:157]
	v_lshl_add_u64 v[160:161], v[152:153], 0, v[160:161]
	v_lshl_add_u64 v[158:159], v[152:153], 0, v[158:159]
	v_lshl_add_u64 v[154:155], v[152:153], 0, v[154:155]
	v_lshl_add_u64 v[156:157], v[152:153], 0, v[156:157]
	v_readlane_b32 s66, v255, 2
	s_and_b64 vcc, exec, s[6:7]
	s_mov_b64 s[6:7], -1
	s_movk_i32 s57, 0x1ff
	v_readlane_b32 s67, v255, 3
	v_mov_b64_e32 v[230:231], v[242:243]
	v_mov_b32_e32 v238, v232
	v_mov_b32_e32 v232, v229
	v_mov_b64_e32 v[240:241], 0xff
	v_not_b32_e32 v229, 63
	v_not_b32_e32 v239, 31
	v_mov_b32_e32 v242, 0x7fc00000
	v_mov_b32_e32 v243, 0x68
	v_mov_b32_e32 v244, 0x58
	s_waitcnt vmcnt(0)
	v_pk_mul_f32 v[116:117], v[116:117], v[48:49]
	v_pk_mul_f32 v[114:115], v[114:115], v[46:47]
	v_pk_mul_f32 v[120:121], v[120:121], v[44:45]
	v_pk_mul_f32 v[68:69], v[68:69], v[28:29]
	v_pk_mul_f32 v[66:67], v[66:67], v[26:27]
	v_pk_mul_f32 v[118:119], v[118:119], v[42:43]
	v_pk_mul_f32 v[140:141], v[140:141], v[40:41]
	v_pk_mul_f32 v[138:139], v[138:139], v[38:39]
	v_pk_mul_f32 v[144:145], v[144:145], v[28:29]
	v_pk_mul_f32 v[142:143], v[142:143], v[26:27]
	v_pk_mul_f32 v[108:109], v[108:109], v[48:49]
	v_pk_mul_f32 v[106:107], v[106:107], v[46:47]
	v_pk_mul_f32 v[112:113], v[112:113], v[44:45]
	v_pk_mul_f32 v[110:111], v[110:111], v[42:43]
	v_pk_mul_f32 v[132:133], v[132:133], v[40:41]
	v_pk_mul_f32 v[130:131], v[130:131], v[38:39]
	v_pk_mul_f32 v[136:137], v[136:137], v[28:29]
	v_pk_mul_f32 v[134:135], v[134:135], v[26:27]
	v_pk_mul_f32 v[100:101], v[100:101], v[48:49]
	v_pk_mul_f32 v[98:99], v[98:99], v[46:47]
	v_pk_mul_f32 v[104:105], v[104:105], v[44:45]
	v_pk_mul_f32 v[102:103], v[102:103], v[42:43]
	v_pk_mul_f32 v[124:125], v[124:125], v[40:41]
	v_pk_mul_f32 v[122:123], v[122:123], v[38:39]
	v_pk_mul_f32 v[128:129], v[128:129], v[28:29]
	v_pk_mul_f32 v[126:127], v[126:127], v[26:27]
	v_pk_mul_f32 v[84:85], v[84:85], v[48:49]
	v_pk_mul_f32 v[82:83], v[82:83], v[46:47]
	v_pk_mul_f32 v[72:73], v[72:73], v[44:45]
	v_pk_mul_f32 v[70:71], v[70:71], v[42:43]
	v_pk_mul_f32 v[88:89], v[88:89], v[40:41]
	v_pk_mul_f32 v[86:87], v[86:87], v[38:39]
	global_store_dwordx4 v[160:161], v[114:117], off sc1
	global_store_dwordx4 v[160:161], v[118:121], off offset:64 sc1
	global_store_dwordx4 v[160:161], v[138:141], off offset:512 sc1
	global_store_dwordx4 v[160:161], v[142:145], off offset:576 sc1
	global_store_dwordx4 v[154:155], v[106:109], off sc1
	global_store_dwordx4 v[154:155], v[110:113], off offset:64 sc1
	global_store_dwordx4 v[154:155], v[130:133], off offset:512 sc1
	global_store_dwordx4 v[154:155], v[134:137], off offset:576 sc1
	global_store_dwordx4 v[156:157], v[98:101], off sc1
	global_store_dwordx4 v[156:157], v[102:105], off offset:64 sc1
	global_store_dwordx4 v[156:157], v[122:125], off offset:512 sc1
	global_store_dwordx4 v[156:157], v[126:129], off offset:576 sc1
	global_store_dwordx4 v[158:159], v[82:85], off sc1
	global_store_dwordx4 v[158:159], v[70:73], off offset:64 sc1
	global_store_dwordx4 v[158:159], v[86:89], off offset:512 sc1
	global_store_dwordx4 v[158:159], v[66:69], off offset:576 sc1
	v_pk_mul_f32 v[52:53], v[52:53], v[44:45]
	v_pk_mul_f32 v[50:51], v[50:51], v[42:43]
	v_add_u32_e32 v66, 0x80, v148
	v_ashrrev_i32_e32 v67, 31, v66
	v_lshlrev_b64 v[66:67], 12, v[66:67]
	v_lshl_add_u64 v[70:71], v[152:153], 0, v[66:67]
	v_pk_mul_f32 v[68:69], v[92:93], v[48:49]
	v_pk_mul_f32 v[66:67], v[90:91], v[46:47]
	global_store_dwordx4 v[70:71], v[66:69], off sc1
	v_pk_mul_f32 v[20:21], v[20:21], v[44:45]
	v_pk_mul_f32 v[18:19], v[18:19], v[42:43]
	v_pk_mul_f32 v[68:69], v[76:77], v[44:45]
	v_pk_mul_f32 v[66:67], v[74:75], v[42:43]
	global_store_dwordx4 v[70:71], v[66:69], off offset:64 sc1
	v_pk_mul_f32 v[4:5], v[4:5], v[44:45]
	v_pk_mul_f32 v[2:3], v[2:3], v[42:43]
	v_pk_mul_f32 v[68:69], v[96:97], v[40:41]
	v_pk_mul_f32 v[66:67], v[94:95], v[38:39]
	global_store_dwordx4 v[70:71], v[66:69], off offset:512 sc1
	v_pk_mul_f32 v[60:61], v[60:61], v[48:49]
	v_pk_mul_f32 v[58:59], v[58:59], v[46:47]
	v_pk_mul_f32 v[68:69], v[80:81], v[28:29]
	v_pk_mul_f32 v[66:67], v[78:79], v[26:27]
	global_store_dwordx4 v[70:71], v[66:69], off offset:576 sc1
	v_pk_mul_f32 v[32:33], v[32:33], v[48:49]
	v_pk_mul_f32 v[30:31], v[30:31], v[46:47]
	v_add_u32_e32 v66, 0x90, v148
	v_ashrrev_i32_e32 v67, 31, v66
	v_lshlrev_b64 v[66:67], 12, v[66:67]
	v_lshl_add_u64 v[66:67], v[152:153], 0, v[66:67]
	global_store_dwordx4 v[66:67], v[50:53], off offset:64 sc1
	v_pk_mul_f32 v[12:13], v[12:13], v[48:49]
	v_pk_mul_f32 v[10:11], v[10:11], v[46:47]
	v_pk_mul_f32 v[52:53], v[64:65], v[40:41]
	v_pk_mul_f32 v[50:51], v[62:63], v[38:39]
	global_store_dwordx4 v[66:67], v[50:53], off offset:512 sc1
	global_store_dwordx4 v[66:67], v[58:61], off sc1
	s_nop 0
	v_pk_mul_f32 v[52:53], v[56:57], v[28:29]
	v_pk_mul_f32 v[50:51], v[54:55], v[26:27]
	global_store_dwordx4 v[66:67], v[50:53], off offset:576 sc1
	s_nop 1
	v_add_u32_e32 v50, 0xa0, v148
	v_ashrrev_i32_e32 v51, 31, v50
	v_lshlrev_b64 v[50:51], 12, v[50:51]
	v_lshl_add_u64 v[50:51], v[152:153], 0, v[50:51]
	global_store_dwordx4 v[50:51], v[18:21], off offset:64 sc1
	global_store_dwordx4 v[50:51], v[30:33], off sc1
	s_nop 0
	v_pk_mul_f32 v[20:21], v[36:37], v[40:41]
	v_pk_mul_f32 v[18:19], v[34:35], v[38:39]
	global_store_dwordx4 v[50:51], v[18:21], off offset:512 sc1
	s_nop 1
	v_pk_mul_f32 v[20:21], v[24:25], v[28:29]
	v_pk_mul_f32 v[18:19], v[22:23], v[26:27]
	global_store_dwordx4 v[50:51], v[18:21], off offset:576 sc1
	s_nop 1
	v_add_u32_e32 v18, 0xb0, v148
	v_ashrrev_i32_e32 v19, 31, v18
	v_lshlrev_b64 v[18:19], 12, v[18:19]
	v_lshl_add_u64 v[18:19], v[152:153], 0, v[18:19]
	global_store_dwordx4 v[18:19], v[2:5], off offset:64 sc1
	global_store_dwordx4 v[18:19], v[10:13], off sc1
	s_nop 0
	v_pk_mul_f32 v[4:5], v[16:17], v[40:41]
	v_pk_mul_f32 v[2:3], v[14:15], v[38:39]
	global_store_dwordx4 v[18:19], v[2:5], off offset:512 sc1
	s_nop 1
	v_pk_mul_f32 v[4:5], v[8:9], v[28:29]
	v_pk_mul_f32 v[2:3], v[6:7], v[26:27]
	global_store_dwordx4 v[18:19], v[2:5], off offset:576 sc1
	s_cbranch_vccnz .LBB0_248
	s_andn2_b64 vcc, exec, s[8:9]
	s_cbranch_vccnz .LBB0_247
	s_barrier
	s_branch .LBB0_247

.LBB0_290:
	v_add_u32_e32 v5, s6, v0
	ds_read2st64_b32 v[8:9], v5 offset1:1
	ds_read2st64_b32 v[12:13], v6 offset1:1
	ds_read2st64_b32 v[14:15], v6 offset0:2 offset1:3
	s_add_i32 s6, s6, 64
	s_cmpk_lg_i32 s6, 0x100
	s_waitcnt lgkmcnt(2)
	v_add_f32_e32 v7, 0, v8
	v_add_f32_e32 v7, v7, v9
	ds_read2st64_b32 v[8:9], v5 offset0:2 offset1:3
	s_waitcnt lgkmcnt(0)
	v_add_f32_e32 v7, v7, v8
	v_add_f32_e32 v7, v7, v9
	ds_read2st64_b32 v[8:9], v5 offset0:4 offset1:5
	s_waitcnt lgkmcnt(0)
	v_add_f32_e32 v7, v7, v8
	v_add_f32_e32 v7, v7, v9
	ds_read2st64_b32 v[8:9], v5 offset0:6 offset1:7
	s_waitcnt lgkmcnt(0)
	v_add_f32_e32 v5, v7, v8
	v_add_f32_e32 v5, v5, v9
	v_fmamk_f32 v5, v5, 0x3b000000, v190
	v_cmp_gt_f32_e32 vcc, s96, v5
	v_mul_f32_e32 v7, 0x4b800000, v5
	s_nop 0
	v_cndmask_b32_e32 v5, v5, v7, vcc
	v_rsq_f32_e32 v5, v5
	s_nop 0
	v_mul_f32_e32 v7, 0x45800000, v5
	v_cndmask_b32_e32 v8, v5, v7, vcc
	v_ashrrev_i32_e32 v5, 31, v4
	v_lshlrev_b64 v[10:11], 11, v[4:5]
	v_pk_mul_f32 v[12:13], v[12:13], v[8:9] op_sel_hi:[1,0]
	v_pk_mul_f32 v[14:15], v[14:15], v[8:9] op_sel_hi:[1,0]
	v_lshl_add_u64 v[10:11], v[2:3], 0, v[10:11]
	v_cvt_pk_bf16_f32 v12, v12, v13
	v_cvt_pk_bf16_f32 v13, v14, v15
	global_store_dwordx2 v[10:11], v[12:13], off offset:1024 sc1
	ds_read2st64_b32 v[12:13], v6 offset0:4 offset1:5
	ds_read2st64_b32 v[14:15], v6 offset0:6 offset1:7
	v_add_u32_e32 v4, 16, v4
	s_waitcnt lgkmcnt(1)
	v_pk_mul_f32 v[12:13], v[12:13], v[8:9] op_sel_hi:[1,0]
	s_waitcnt lgkmcnt(0)
	v_pk_mul_f32 v[14:15], v[8:9], v[14:15] op_sel_hi:[0,1]
	v_cvt_pk_bf16_f32 v12, v12, v13
	v_cvt_pk_bf16_f32 v13, v14, v15
	global_store_dwordx2 v[10:11], v[12:13], off offset:1056 sc1
	ds_read2st64_b32 v[12:13], v6 offset0:8 offset1:9
	ds_read2st64_b32 v[14:15], v6 offset0:10 offset1:11
	s_waitcnt lgkmcnt(1)
	v_pk_mul_f32 v[12:13], v[8:9], v[12:13] op_sel_hi:[0,1]
	s_waitcnt lgkmcnt(0)
	v_pk_mul_f32 v[14:15], v[8:9], v[14:15] op_sel_hi:[0,1]
	v_cvt_pk_bf16_f32 v12, v12, v13
	v_cvt_pk_bf16_f32 v13, v14, v15
	global_store_dwordx2 v[10:11], v[12:13], off offset:1088 sc1
	ds_read2st64_b32 v[12:13], v6 offset0:12 offset1:13
	ds_read2st64_b32 v[14:15], v6 offset0:14 offset1:15
	v_add_u32_e32 v6, 0x1000, v6
	s_waitcnt lgkmcnt(1)
	v_pk_mul_f32 v[12:13], v[8:9], v[12:13] op_sel_hi:[0,1]
	s_waitcnt lgkmcnt(0)
	v_pk_mul_f32 v[8:9], v[8:9], v[14:15] op_sel_hi:[0,1]
	v_cvt_pk_bf16_f32 v12, v12, v13
	v_cvt_pk_bf16_f32 v13, v8, v9
	global_store_dwordx2 v[10:11], v[12:13], off offset:1120 sc1
	s_cbranch_scc1 .LBB0_290
	s_add_i32 s6, s10, s43
	s_ashr_i32 s7, s6, 31
	v_lshrrev_b32_e32 v2, 4, v228
	v_and_b32_e32 v3, 15, v228
	v_lshlrev_b32_e32 v3, 4, v3
	s_lshl_b64 s[6:7], s[6:7], 11
	v_lshl_add_u32 v5, v2, 11, v3
	s_add_u32 s6, s33, s6
	s_addc_u32 s7, s42, s7
	v_add_u32_e32 v7, 0x2000, v5
	s_mov_b32 s10, 0xffff0000
	s_waitcnt vmcnt(20)
	v_lshlrev_b32_e32 v40, 16, v130
	v_lshlrev_b32_e32 v41, 16, v131
	v_lshlrev_b32_e32 v42, 16, v132
	v_lshlrev_b32_e32 v43, 16, v133
	v_lshlrev_b32_e32 v44, 16, v134
	v_lshlrev_b32_e32 v45, 16, v135
	v_lshlrev_b32_e32 v46, 16, v136
	v_lshlrev_b32_e32 v47, 16, v137
	v_lshlrev_b32_e32 v48, 16, v138
	v_lshlrev_b32_e32 v49, 16, v139
	v_lshlrev_b32_e32 v50, 16, v140
	v_lshlrev_b32_e32 v51, 16, v141
	v_lshlrev_b32_e32 v52, 16, v142
	v_lshlrev_b32_e32 v53, 16, v143
	v_lshlrev_b32_e32 v54, 16, v144
	v_lshlrev_b32_e32 v55, 16, v145
	v_and_b32_e32 v130, s10, v130
	v_and_b32_e32 v131, s10, v131
	v_and_b32_e32 v132, s10, v132
	v_and_b32_e32 v133, s10, v133
	v_and_b32_e32 v134, s10, v134
	v_and_b32_e32 v135, s10, v135
	v_and_b32_e32 v136, s10, v136
	v_and_b32_e32 v137, s10, v137
	v_and_b32_e32 v138, s10, v138
	v_and_b32_e32 v139, s10, v139
	v_and_b32_e32 v140, s10, v140
	v_and_b32_e32 v141, s10, v141
	v_and_b32_e32 v142, s10, v142
	v_and_b32_e32 v143, s10, v143
	v_and_b32_e32 v144, s10, v144
	v_and_b32_e32 v145, s10, v145
	v_mul_f32_e32 v72, v40, v40
	v_mul_f32_e32 v73, v41, v41
	v_mul_f32_e32 v74, v42, v42
	v_mul_f32_e32 v75, v43, v43
	v_fmac_f32_e32 v72, v130, v130
	v_fmac_f32_e32 v73, v131, v131
	v_fmac_f32_e32 v74, v132, v132
	v_fmac_f32_e32 v75, v133, v133
	v_fmac_f32_e32 v72, v44, v44
	v_fmac_f32_e32 v73, v45, v45
	v_fmac_f32_e32 v74, v46, v46
	v_fmac_f32_e32 v75, v47, v47
	v_fmac_f32_e32 v72, v48, v48
	v_fmac_f32_e32 v73, v49, v49
	v_fmac_f32_e32 v74, v50, v50
	v_fmac_f32_e32 v75, v51, v51
	v_fmac_f32_e32 v72, v52, v52
	v_fmac_f32_e32 v73, v53, v53
	v_fmac_f32_e32 v74, v54, v54
	v_fmac_f32_e32 v75, v55, v55
	v_fmac_f32_e32 v72, v134, v134
	v_fmac_f32_e32 v73, v135, v135
	v_fmac_f32_e32 v74, v136, v136
	v_fmac_f32_e32 v75, v137, v137
	v_fmac_f32_e32 v72, v138, v138
	v_fmac_f32_e32 v73, v139, v139
	v_fmac_f32_e32 v74, v140, v140
	v_fmac_f32_e32 v75, v141, v141
	v_fmac_f32_e32 v72, v142, v142
	v_fmac_f32_e32 v73, v143, v143
	v_fmac_f32_e32 v74, v144, v144
	v_fmac_f32_e32 v75, v145, v145
	v_add_f32_e32 v72, v72, v73
	v_add_f32_e32 v74, v74, v75
	s_nop 0
	v_add_f32_e32 v72, v72, v74
	s_waitcnt vmcnt(16)
	v_lshlrev_b32_e32 v56, 16, v146
	v_lshlrev_b32_e32 v57, 16, v147
	v_lshlrev_b32_e32 v58, 16, v148
	v_lshlrev_b32_e32 v59, 16, v149
	v_lshlrev_b32_e32 v60, 16, v150
	v_lshlrev_b32_e32 v61, 16, v151
	v_lshlrev_b32_e32 v62, 16, v152
	v_lshlrev_b32_e32 v63, 16, v153
	v_lshlrev_b32_e32 v64, 16, v154
	v_lshlrev_b32_e32 v65, 16, v155
	v_lshlrev_b32_e32 v66, 16, v156
	v_lshlrev_b32_e32 v67, 16, v157
	v_lshlrev_b32_e32 v68, 16, v158
	v_lshlrev_b32_e32 v69, 16, v159
	v_lshlrev_b32_e32 v70, 16, v160
	v_lshlrev_b32_e32 v71, 16, v161
	v_and_b32_e32 v146, s10, v146
	v_and_b32_e32 v147, s10, v147
	v_and_b32_e32 v148, s10, v148
	v_and_b32_e32 v149, s10, v149
	v_and_b32_e32 v150, s10, v150
	v_and_b32_e32 v151, s10, v151
	v_and_b32_e32 v152, s10, v152
	v_and_b32_e32 v153, s10, v153
	v_and_b32_e32 v154, s10, v154
	v_and_b32_e32 v155, s10, v155
	v_and_b32_e32 v156, s10, v156
	v_and_b32_e32 v157, s10, v157
	v_and_b32_e32 v158, s10, v158
	v_and_b32_e32 v159, s10, v159
	v_and_b32_e32 v160, s10, v160
	v_and_b32_e32 v161, s10, v161
	v_mul_f32_e32 v76, v56, v56
	v_mul_f32_e32 v77, v57, v57
	v_mul_f32_e32 v78, v58, v58
	v_mul_f32_e32 v79, v59, v59
	v_fmac_f32_e32 v76, v146, v146
	v_fmac_f32_e32 v77, v147, v147
	v_fmac_f32_e32 v78, v148, v148
	v_fmac_f32_e32 v79, v149, v149
	v_fmac_f32_e32 v76, v60, v60
	v_fmac_f32_e32 v77, v61, v61
	v_fmac_f32_e32 v78, v62, v62
	v_fmac_f32_e32 v79, v63, v63
	v_fmac_f32_e32 v76, v64, v64
	v_fmac_f32_e32 v77, v65, v65
	v_fmac_f32_e32 v78, v66, v66
	v_fmac_f32_e32 v79, v67, v67
	v_fmac_f32_e32 v76, v68, v68
	v_fmac_f32_e32 v77, v69, v69
	v_fmac_f32_e32 v78, v70, v70
	v_fmac_f32_e32 v79, v71, v71
	v_fmac_f32_e32 v76, v150, v150
	v_fmac_f32_e32 v77, v151, v151
	v_fmac_f32_e32 v78, v152, v152
	v_fmac_f32_e32 v79, v153, v153
	v_fmac_f32_e32 v76, v154, v154
	v_fmac_f32_e32 v77, v155, v155
	v_fmac_f32_e32 v78, v156, v156
	v_fmac_f32_e32 v79, v157, v157
	v_fmac_f32_e32 v76, v158, v158
	v_fmac_f32_e32 v77, v159, v159
	v_fmac_f32_e32 v78, v160, v160
	v_fmac_f32_e32 v79, v161, v161
	v_add_f32_e32 v76, v76, v77
	v_add_f32_e32 v78, v78, v79
	s_nop 0
	v_add_f32_e32 v76, v76, v78
	s_nop 1
	v_add_f32_dpp v73, v72, v72 quad_perm:[1,0,3,2] row_mask:0xf bank_mask:0xf
	v_add_f32_dpp v77, v76, v76 quad_perm:[1,0,3,2] row_mask:0xf bank_mask:0xf
	s_nop 0
	v_add_f32_dpp v72, v73, v73 quad_perm:[2,3,0,1] row_mask:0xf bank_mask:0xf
	v_add_f32_dpp v76, v77, v77 quad_perm:[2,3,0,1] row_mask:0xf bank_mask:0xf
	s_nop 0
	v_add_f32_dpp v73, v72, v72 row_half_mirror row_mask:0xf bank_mask:0xf
	v_add_f32_dpp v77, v76, v76 row_half_mirror row_mask:0xf bank_mask:0xf
	s_nop 0
	v_add_f32_dpp v72, v73, v73 row_mirror row_mask:0xf bank_mask:0xf
	v_add_f32_dpp v76, v77, v77 row_mirror row_mask:0xf bank_mask:0xf
	s_nop 0
	v_fmamk_f32 v72, v72, 0x3b000000, v190
	v_fmamk_f32 v76, v76, 0x3b000000, v190
	v_cmp_gt_f32_e32 vcc, s96, v72
	v_cmp_gt_f32_e64 s[8:9], s96, v76
	v_mul_f32_e32 v73, 0x4b800000, v72
	v_mul_f32_e32 v77, 0x4b800000, v76
	v_cndmask_b32_e32 v72, v72, v73, vcc
	v_cndmask_b32_e64 v76, v76, v77, s[8:9]
	v_rsq_f32_e32 v72, v72
	v_rsq_f32_e32 v76, v76
	s_nop 0
	v_mul_f32_e32 v73, 0x45800000, v72
	v_mul_f32_e32 v77, 0x45800000, v76
	v_cndmask_b32_e32 v72, v72, v73, vcc
	v_cndmask_b32_e64 v76, v76, v77, s[8:9]
	v_mul_f32_e32 v40, v72, v40
	v_mul_f32_e32 v41, v72, v41
	v_mul_f32_e32 v42, v72, v42
	v_mul_f32_e32 v43, v72, v43
	v_mul_f32_e32 v44, v72, v44
	v_mul_f32_e32 v45, v72, v45
	v_mul_f32_e32 v46, v72, v46
	v_mul_f32_e32 v47, v72, v47
	v_mul_f32_e32 v48, v72, v48
	v_mul_f32_e32 v49, v72, v49
	v_mul_f32_e32 v50, v72, v50
	v_mul_f32_e32 v51, v72, v51
	v_mul_f32_e32 v52, v72, v52
	v_mul_f32_e32 v53, v72, v53
	v_mul_f32_e32 v54, v72, v54
	v_mul_f32_e32 v55, v72, v55
	v_mul_f32_e32 v130, v72, v130
	v_mul_f32_e32 v131, v72, v131
	v_mul_f32_e32 v132, v72, v132
	v_mul_f32_e32 v133, v72, v133
	v_mul_f32_e32 v134, v72, v134
	v_mul_f32_e32 v135, v72, v135
	v_mul_f32_e32 v136, v72, v136
	v_mul_f32_e32 v137, v72, v137
	v_mul_f32_e32 v138, v72, v138
	v_mul_f32_e32 v139, v72, v139
	v_mul_f32_e32 v140, v72, v140
	v_mul_f32_e32 v141, v72, v141
	v_mul_f32_e32 v142, v72, v142
	v_mul_f32_e32 v143, v72, v143
	v_mul_f32_e32 v144, v72, v144
	v_mul_f32_e32 v145, v72, v145
	v_cvt_pk_bf16_f32 v130, v40, v130
	v_cvt_pk_bf16_f32 v131, v41, v131
	v_cvt_pk_bf16_f32 v132, v42, v132
	v_cvt_pk_bf16_f32 v133, v43, v133
	v_cvt_pk_bf16_f32 v134, v44, v134
	v_cvt_pk_bf16_f32 v135, v45, v135
	v_cvt_pk_bf16_f32 v136, v46, v136
	v_cvt_pk_bf16_f32 v137, v47, v137
	v_cvt_pk_bf16_f32 v138, v48, v138
	v_cvt_pk_bf16_f32 v139, v49, v139
	v_cvt_pk_bf16_f32 v140, v50, v140
	v_cvt_pk_bf16_f32 v141, v51, v141
	v_cvt_pk_bf16_f32 v142, v52, v142
	v_cvt_pk_bf16_f32 v143, v53, v143
	v_cvt_pk_bf16_f32 v144, v54, v144
	v_cvt_pk_bf16_f32 v145, v55, v145
	v_mul_f32_e32 v56, v76, v56
	v_mul_f32_e32 v57, v76, v57
	v_mul_f32_e32 v58, v76, v58
	v_mul_f32_e32 v59, v76, v59
	v_mul_f32_e32 v60, v76, v60
	v_mul_f32_e32 v61, v76, v61
	v_mul_f32_e32 v62, v76, v62
	v_mul_f32_e32 v63, v76, v63
	v_mul_f32_e32 v64, v76, v64
	v_mul_f32_e32 v65, v76, v65
	v_mul_f32_e32 v66, v76, v66
	v_mul_f32_e32 v67, v76, v67
	v_mul_f32_e32 v68, v76, v68
	v_mul_f32_e32 v69, v76, v69
	v_mul_f32_e32 v70, v76, v70
	v_mul_f32_e32 v71, v76, v71
	v_mul_f32_e32 v146, v76, v146
	v_mul_f32_e32 v147, v76, v147
	v_mul_f32_e32 v148, v76, v148
	v_mul_f32_e32 v149, v76, v149
	v_mul_f32_e32 v150, v76, v150
	v_mul_f32_e32 v151, v76, v151
	v_mul_f32_e32 v152, v76, v152
	v_mul_f32_e32 v153, v76, v153
	v_mul_f32_e32 v154, v76, v154
	v_mul_f32_e32 v155, v76, v155
	v_mul_f32_e32 v156, v76, v156
	v_mul_f32_e32 v157, v76, v157
	v_mul_f32_e32 v158, v76, v158
	v_mul_f32_e32 v159, v76, v159
	v_mul_f32_e32 v160, v76, v160
	v_mul_f32_e32 v161, v76, v161
	v_cvt_pk_bf16_f32 v146, v56, v146
	v_cvt_pk_bf16_f32 v147, v57, v147
	v_cvt_pk_bf16_f32 v148, v58, v148
	v_cvt_pk_bf16_f32 v149, v59, v149
	v_cvt_pk_bf16_f32 v150, v60, v150
	v_cvt_pk_bf16_f32 v151, v61, v151
	v_cvt_pk_bf16_f32 v152, v62, v152
	v_cvt_pk_bf16_f32 v153, v63, v153
	v_cvt_pk_bf16_f32 v154, v64, v154
	v_cvt_pk_bf16_f32 v155, v65, v155
	v_cvt_pk_bf16_f32 v156, v66, v156
	v_cvt_pk_bf16_f32 v157, v67, v157
	v_cvt_pk_bf16_f32 v158, v68, v158
	v_cvt_pk_bf16_f32 v159, v69, v159
	v_cvt_pk_bf16_f32 v160, v70, v160
	v_cvt_pk_bf16_f32 v161, v71, v161
	global_store_dwordx4 v5, v[130:133], s[6:7] sc1
	global_store_dwordx4 v5, v[134:137], s[6:7] offset:256 sc1
	global_store_dwordx4 v5, v[138:141], s[6:7] offset:512 sc1
	global_store_dwordx4 v5, v[142:145], s[6:7] offset:768 sc1
	global_store_dwordx4 v7, v[146:149], s[6:7] sc1
	global_store_dwordx4 v7, v[150:153], s[6:7] offset:256 sc1
	global_store_dwordx4 v7, v[154:157], s[6:7] offset:512 sc1
	global_store_dwordx4 v7, v[158:161], s[6:7] offset:768 sc1
	s_waitcnt lgkmcnt(0)
	s_add_i32 s57, s57, s81
	v_readlane_b32 s6, v255, 31
	s_cmp_ge_i32 s57, s6
	s_barrier
	s_cbranch_scc0 .LBB0_268

.LBB0_324:
	s_or_b64 exec, exec, s[8:9]
	s_waitcnt lgkmcnt(0)
	v_add_u32_e32 v34, 0xc080, v50
	ds_read2_b32 v[52:53], v34 offset0:0 offset1:1
	ds_read2_b32 v[54:55], v34 offset0:2 offset1:3
	ds_read2_b32 v[56:57], v34 offset0:8 offset1:9
	ds_read2_b32 v[58:59], v34 offset0:10 offset1:11
	ds_read2_b32 v[60:61], v34 offset0:16 offset1:17
	ds_read2_b32 v[62:63], v34 offset0:18 offset1:19
	ds_read2_b32 v[64:65], v34 offset0:24 offset1:25
	ds_read2_b32 v[66:67], v34 offset0:26 offset1:27
	v_readlane_b32 s3, v255, 54
	s_add_u32 s3, s3, s12
	v_readlane_b32 s8, v255, 55
	s_addc_u32 s8, s8, s13
	s_lshl_b32 s9, s37, 12
	s_add_i32 s9, s66, s9
	v_lshlrev_b32_e32 v0, 1, v0
	s_lshl_b64 s[10:11], s[14:15], 1
	s_add_u32 s10, s3, s10
	s_addc_u32 s11, s8, s11
	v_lshlrev_b32_e32 v50, 1, v204
	v_add3_u32 v0, s9, v0, v50
	s_waitcnt lgkmcnt(0)
	v_rcp_f32_e32 v36, v52
	v_rcp_f32_e32 v37, v53
	v_rcp_f32_e32 v38, v54
	v_rcp_f32_e32 v39, v55
	v_rcp_f32_e32 v40, v56
	v_rcp_f32_e32 v41, v57
	v_rcp_f32_e32 v42, v58
	v_rcp_f32_e32 v43, v59
	v_rcp_f32_e32 v44, v60
	v_rcp_f32_e32 v45, v61
	v_rcp_f32_e32 v46, v62
	v_rcp_f32_e32 v47, v63
	v_rcp_f32_e32 v48, v64
	v_rcp_f32_e32 v49, v65
	v_rcp_f32_e32 v34, v66
	v_rcp_f32_e32 v35, v67
	v_mul_f32_e32 v2, v2, v36
	v_cvt_pk_bf16_f32 v2, v2, s0
	v_mul_f32_e32 v18, v18, v36
	v_cvt_pk_bf16_f32 v18, v18, s0
	ds_write_b16 v0, v2 offset:51264
	v_mul_f32_e32 v2, v19, v37
	v_cvt_pk_bf16_f32 v2, v2, s0
	ds_write_b16 v0, v2 offset:51328
	v_mul_f32_e32 v2, v3, v37
	v_cvt_pk_bf16_f32 v2, v2, s0
	ds_write_b16 v0, v2 offset:51392
	v_mul_f32_e32 v2, v20, v38
	v_cvt_pk_bf16_f32 v2, v2, s0
	ds_write_b16 v0, v2 offset:51456
	v_mul_f32_e32 v2, v4, v38
	v_cvt_pk_bf16_f32 v2, v2, s0
	ds_write_b16 v0, v2 offset:51520
	v_mul_f32_e32 v2, v21, v39
	v_cvt_pk_bf16_f32 v2, v2, s0
	ds_write_b16 v0, v2 offset:51584
	v_mul_f32_e32 v2, v5, v39
	v_cvt_pk_bf16_f32 v2, v2, s0
	ds_write_b16 v0, v2 offset:51648
	v_mul_f32_e32 v2, v22, v40
	v_cvt_pk_bf16_f32 v2, v2, s0
	ds_write_b16 v0, v2 offset:52224
	v_mul_f32_e32 v2, v6, v40
	v_cvt_pk_bf16_f32 v2, v2, s0
	ds_write_b16 v0, v2 offset:52288
	v_mul_f32_e32 v2, v23, v41
	v_cvt_pk_bf16_f32 v2, v2, s0
	ds_write_b16 v0, v2 offset:52352
	v_mul_f32_e32 v2, v7, v41
	v_cvt_pk_bf16_f32 v2, v2, s0
	ds_write_b16 v0, v2 offset:52416
	v_mul_f32_e32 v2, v24, v42
	v_cvt_pk_bf16_f32 v2, v2, s0
	ds_write_b16 v0, v2 offset:52480
	v_mul_f32_e32 v2, v8, v42
	v_cvt_pk_bf16_f32 v2, v2, s0
	ds_write_b16 v0, v2 offset:52544
	v_mul_f32_e32 v2, v25, v43
	v_cvt_pk_bf16_f32 v2, v2, s0
	ds_write_b16 v0, v2 offset:52608
	v_mul_f32_e32 v2, v9, v43
	v_cvt_pk_bf16_f32 v2, v2, s0
	ds_write_b16 v0, v2 offset:52672
	v_mul_f32_e32 v2, v26, v44
	v_cvt_pk_bf16_f32 v2, v2, s0
	ds_write_b16 v0, v2 offset:53248
	v_mul_f32_e32 v2, v10, v44
	v_cvt_pk_bf16_f32 v2, v2, s0
	ds_write_b16 v0, v2 offset:53312
	v_mul_f32_e32 v2, v27, v45
	v_cvt_pk_bf16_f32 v2, v2, s0
	ds_write_b16 v0, v2 offset:53376
	v_mul_f32_e32 v2, v11, v45
	v_cvt_pk_bf16_f32 v2, v2, s0
	ds_write_b16 v0, v2 offset:53440
	v_mul_f32_e32 v2, v28, v46
	v_cvt_pk_bf16_f32 v2, v2, s0
	ds_write_b16 v0, v2 offset:53504
	v_mul_f32_e32 v2, v12, v46
	v_cvt_pk_bf16_f32 v2, v2, s0
	ds_write_b16 v0, v2 offset:53568
	v_mul_f32_e32 v2, v29, v47
	v_cvt_pk_bf16_f32 v2, v2, s0
	ds_write_b16 v0, v2 offset:53632
	v_mul_f32_e32 v2, v13, v47
	v_cvt_pk_bf16_f32 v2, v2, s0
	ds_write_b16 v0, v2 offset:53696
	v_mul_f32_e32 v2, v30, v48
	v_cvt_pk_bf16_f32 v2, v2, s0
	ds_write_b16 v0, v2 offset:54272
	v_mul_f32_e32 v2, v14, v48
	v_cvt_pk_bf16_f32 v2, v2, s0
	ds_write_b16 v0, v2 offset:54336
	v_mul_f32_e32 v2, v31, v49
	v_cvt_pk_bf16_f32 v2, v2, s0
	ds_write_b16 v0, v2 offset:54400
	v_mul_f32_e32 v2, v15, v49
	v_cvt_pk_bf16_f32 v2, v2, s0
	ds_write_b16 v0, v2 offset:54464
	v_mul_f32_e32 v2, v32, v34
	v_cvt_pk_bf16_f32 v2, v2, s0
	ds_write_b16 v0, v2 offset:54528
	v_mul_f32_e32 v2, v16, v34
	v_cvt_pk_bf16_f32 v2, v2, s0
	ds_write_b16 v0, v2 offset:54592
	v_mul_f32_e32 v2, v33, v35
	v_cvt_pk_bf16_f32 v2, v2, s0
	ds_write_b16 v0, v2 offset:54656
	v_mul_f32_e32 v2, v17, v35
	v_cvt_pk_bf16_f32 v2, v2, s0
	ds_write_b16 v0, v18 offset:51200
	ds_write_b16 v0, v2 offset:54720
	v_lshlrev_b32_e32 v0, 1, v203
	v_and_b32_e32 v0, 0x70, v0
	v_lshrrev_b32_e32 v10, 3, v202
	v_add_u32_e32 v11, s9, v0
	s_waitcnt lgkmcnt(0)
	v_lshl_add_u64 v[6:7], s[10:11], 0, v[0:1]
	v_lshl_add_u32 v0, v10, 7, v11
	ds_read_b128 v[2:5], v0 offset:51200
	ds_read_b128 v[52:55], v0 offset:52224
	ds_read_b128 v[56:59], v0 offset:53248
	ds_read_b128 v[60:63], v0 offset:54272
	v_lshlrev_b32_e32 v0, 10, v10
	v_lshl_add_u64 v[8:9], v[6:7], 0, v[0:1]
	s_mov_b32 s8, 0x2000
	s_mov_b32 s9, 0
	v_lshl_add_u64 v[12:13], v[8:9], 0, s[8:9]
	v_lshl_add_u64 v[14:15], v[12:13], 0, s[8:9]
	v_lshl_add_u64 v[16:17], v[14:15], 0, s[8:9]
	s_waitcnt lgkmcnt(3)
	global_store_dwordx4 v[8:9], v[2:5], off sc1
	s_waitcnt lgkmcnt(2)
	global_store_dwordx4 v[12:13], v[52:55], off sc1
	s_waitcnt lgkmcnt(1)
	global_store_dwordx4 v[14:15], v[56:59], off sc1
	s_waitcnt lgkmcnt(0)
	global_store_dwordx4 v[16:17], v[60:63], off sc1
	s_waitcnt lgkmcnt(0)
	s_barrier

.Lconv_nopf:
	ds_read_b128 v[158:161], v197
	ds_read_b128 v[162:165], v198
	ds_read_b128 v[166:169], v199
	v_mfma_f32_16x16x32_bf16 v[10:13], v[34:37], v[134:137], 0
	s_mov_b64 s[10:11], -1
	v_mfma_f32_16x16x32_bf16 v[18:21], v[42:45], v[134:137], 0
	v_mfma_f32_16x16x32_bf16 v[146:149], v[38:41], v[6:9], v[10:13]
	v_mfma_f32_16x16x32_bf16 v[10:13], v[50:53], v[134:137], 0
	v_mfma_f32_16x16x32_bf16 v[154:157], v[46:49], v[6:9], v[18:21]
	v_mfma_f32_16x16x32_bf16 v[18:21], v[58:61], v[134:137], 0
	v_mfma_f32_16x16x32_bf16 v[130:133], v[54:57], v[6:9], v[10:13]
	v_mfma_f32_16x16x32_bf16 v[10:13], v[66:69], v[134:137], 0
	v_mfma_f32_16x16x32_bf16 v[30:33], v[62:65], v[6:9], v[18:21]
	v_mfma_f32_16x16x32_bf16 v[18:21], v[70:73], v[134:137], 0
	v_mfma_f32_16x16x32_bf16 v[22:25], v[74:77], v[6:9], v[10:13]
	v_mfma_f32_16x16x32_bf16 v[10:13], v[82:85], v[134:137], 0
	v_mfma_f32_16x16x32_bf16 v[134:137], v[86:89], v[134:137], 0
	v_mfma_f32_16x16x32_bf16 v[18:21], v[78:81], v[6:9], v[18:21]
	v_mfma_f32_16x16x32_bf16 v[10:13], v[90:93], v[6:9], v[10:13]
	v_mfma_f32_16x16x32_bf16 v[6:9], v[94:97], v[6:9], v[134:137]
	s_nop 4
	ds_read_b128 v[246:249], v202
	ds_read_b128 v[250:253], v203
	ds_read_b128 v[134:137], v204
	v_mov_b32_e32 v170, 0xbfb8aa3b
	v_mov_b32_e32 v226, 0x3fb17218
	s_waitcnt lgkmcnt(3)
	v_pk_fma_f32 v[146:147], v[146:147], v[170:171], v[158:159] op_sel_hi:[1,0,1]
	v_pk_fma_f32 v[148:149], v[148:149], v[170:171], v[160:161] op_sel_hi:[1,0,1]
	v_pk_fma_f32 v[154:155], v[154:155], v[170:171], v[162:163] op_sel_hi:[1,0,1]
	v_pk_fma_f32 v[156:157], v[156:157], v[170:171], v[164:165] op_sel_hi:[1,0,1]
	v_exp_f32_e32 v146, v146
	v_exp_f32_e32 v147, v147
	v_exp_f32_e32 v148, v148
	v_exp_f32_e32 v149, v149
	v_exp_f32_e32 v154, v154
	v_exp_f32_e32 v155, v155
	v_exp_f32_e32 v156, v156
	v_exp_f32_e32 v157, v157
	v_pk_add_f32 v[146:147], v[146:147], 1.0 op_sel_hi:[1,0]
	v_pk_add_f32 v[148:149], v[148:149], 1.0 op_sel_hi:[1,0]
	v_pk_add_f32 v[154:155], v[154:155], 1.0 op_sel_hi:[1,0]
	v_pk_add_f32 v[156:157], v[156:157], 1.0 op_sel_hi:[1,0]
	v_rcp_f32_e32 v146, v146
	v_rcp_f32_e32 v147, v147
	v_rcp_f32_e32 v148, v148
	v_rcp_f32_e32 v149, v149
	v_rcp_f32_e32 v154, v154
	v_rcp_f32_e32 v155, v155
	v_rcp_f32_e32 v156, v156
	v_rcp_f32_e32 v157, v157
	v_pk_mul_f32 v[166:167], v[166:167], v[146:147]
	v_pk_mul_f32 v[168:169], v[168:169], v[148:149]
	v_exp_f32_e32 v146, v166
	v_exp_f32_e32 v147, v167
	v_exp_f32_e32 v148, v168
	v_exp_f32_e32 v149, v169
	v_pk_mul_f32 v[158:159], v[166:167], v[226:227] op_sel_hi:[1,0]
	v_pk_mul_f32 v[160:161], v[168:169], v[226:227] op_sel_hi:[1,0]
	v_pk_fma_f32 v[162:163], v[158:159], 0.5, 1.0 op_sel_hi:[1,0,0]
	v_pk_fma_f32 v[164:165], v[160:161], 0.5, 1.0 op_sel_hi:[1,0,0]
	v_pk_mul_f32 v[162:163], v[162:163], v[158:159] neg_lo:[0,1] neg_hi:[0,1]
	v_pk_mul_f32 v[164:165], v[164:165], v[160:161] neg_lo:[0,1] neg_hi:[0,1]
	v_cmp_lt_f32_e32 vcc, s72, v158
	v_cmp_lt_f32_e64 s[12:13], s72, v159
	v_cmp_lt_f32_e64 s[14:15], s72, v160
	v_cmp_lt_f32_e64 s[16:17], s72, v161
	v_pk_fma_f32 v[158:159], v[146:147], v[146:147], 1.0 op_sel_hi:[1,1,0] neg_lo:[1,0,0] neg_hi:[1,0,0]
	v_pk_fma_f32 v[160:161], v[148:149], v[148:149], 1.0 op_sel_hi:[1,1,0] neg_lo:[1,0,0] neg_hi:[1,0,0]
	v_cndmask_b32_e32 v158, v158, v162, vcc
	v_cndmask_b32_e64 v159, v159, v163, s[12:13]
	v_cndmask_b32_e64 v160, v160, v164, s[14:15]
	v_cndmask_b32_e64 v161, v161, v165, s[16:17]
	v_sqrt_f32_e32 v158, v158
	v_sqrt_f32_e32 v159, v159
	v_sqrt_f32_e32 v160, v160
	v_sqrt_f32_e32 v161, v161
	v_pk_mul_f32 v[154:155], v[154:155], v[158:159]
	v_pk_mul_f32 v[156:157], v[156:157], v[160:161]
	v_pk_mul_f32 v[150:151], v[150:151], v[154:155]
	v_pk_mul_f32 v[152:153], v[152:153], v[156:157]
	v_cvt_pkrtz_f16_f32 v162, v166, v150
	v_cvt_pkrtz_f16_f32 v163, v167, v151
	v_cvt_pkrtz_f16_f32 v164, v168, v152
	v_cvt_pkrtz_f16_f32 v165, v169, v153
	global_store_dwordx4 v[142:143], v[162:165], off offset:-2048 sc1
	ds_read_b128 v[158:161], v205
	ds_read_b128 v[162:165], v206
	ds_read_b128 v[166:169], v207
	s_waitcnt lgkmcnt(3)
	v_pk_fma_f32 v[130:131], v[130:131], v[170:171], v[246:247] op_sel_hi:[1,0,1]
	v_pk_fma_f32 v[132:133], v[132:133], v[170:171], v[248:249] op_sel_hi:[1,0,1]
	v_pk_fma_f32 v[30:31], v[30:31], v[170:171], v[250:251] op_sel_hi:[1,0,1]
	v_pk_fma_f32 v[32:33], v[32:33], v[170:171], v[252:253] op_sel_hi:[1,0,1]
	v_exp_f32_e32 v130, v130
	v_exp_f32_e32 v131, v131
	v_exp_f32_e32 v132, v132
	v_exp_f32_e32 v133, v133
	v_exp_f32_e32 v30, v30
	v_exp_f32_e32 v31, v31
	v_exp_f32_e32 v32, v32
	v_exp_f32_e32 v33, v33
	v_pk_add_f32 v[130:131], v[130:131], 1.0 op_sel_hi:[1,0]
	v_pk_add_f32 v[132:133], v[132:133], 1.0 op_sel_hi:[1,0]
	v_pk_add_f32 v[30:31], v[30:31], 1.0 op_sel_hi:[1,0]
	v_pk_add_f32 v[32:33], v[32:33], 1.0 op_sel_hi:[1,0]
	v_rcp_f32_e32 v130, v130
	v_rcp_f32_e32 v131, v131
	v_rcp_f32_e32 v132, v132
	v_rcp_f32_e32 v133, v133
	v_rcp_f32_e32 v30, v30
	v_rcp_f32_e32 v31, v31
	v_rcp_f32_e32 v32, v32
	v_rcp_f32_e32 v33, v33
	v_pk_mul_f32 v[134:135], v[134:135], v[130:131]
	v_pk_mul_f32 v[136:137], v[136:137], v[132:133]
	v_exp_f32_e32 v130, v134
	v_exp_f32_e32 v131, v135
	v_exp_f32_e32 v132, v136
	v_exp_f32_e32 v133, v137
	v_pk_mul_f32 v[246:247], v[134:135], v[226:227] op_sel_hi:[1,0]
	v_pk_mul_f32 v[248:249], v[136:137], v[226:227] op_sel_hi:[1,0]
	v_pk_fma_f32 v[250:251], v[246:247], 0.5, 1.0 op_sel_hi:[1,0,0]
	v_pk_fma_f32 v[252:253], v[248:249], 0.5, 1.0 op_sel_hi:[1,0,0]
	v_pk_mul_f32 v[250:251], v[250:251], v[246:247] neg_lo:[0,1] neg_hi:[0,1]
	v_pk_mul_f32 v[252:253], v[252:253], v[248:249] neg_lo:[0,1] neg_hi:[0,1]
	v_cmp_lt_f32_e32 vcc, s72, v246
	v_cmp_lt_f32_e64 s[12:13], s72, v247
	v_cmp_lt_f32_e64 s[14:15], s72, v248
	v_cmp_lt_f32_e64 s[16:17], s72, v249
	v_pk_fma_f32 v[246:247], v[130:131], v[130:131], 1.0 op_sel_hi:[1,1,0] neg_lo:[1,0,0] neg_hi:[1,0,0]
	v_pk_fma_f32 v[248:249], v[132:133], v[132:133], 1.0 op_sel_hi:[1,1,0] neg_lo:[1,0,0] neg_hi:[1,0,0]
	v_cndmask_b32_e32 v246, v246, v250, vcc
	v_cndmask_b32_e64 v247, v247, v251, s[12:13]
	v_cndmask_b32_e64 v248, v248, v252, s[14:15]
	v_cndmask_b32_e64 v249, v249, v253, s[16:17]
	v_sqrt_f32_e32 v246, v246
	v_sqrt_f32_e32 v247, v247
	v_sqrt_f32_e32 v248, v248
	v_sqrt_f32_e32 v249, v249
	v_pk_mul_f32 v[30:31], v[30:31], v[246:247]
	v_pk_mul_f32 v[32:33], v[32:33], v[248:249]
	v_pk_mul_f32 v[26:27], v[26:27], v[30:31]
	v_pk_mul_f32 v[28:29], v[28:29], v[32:33]
	v_cvt_pkrtz_f16_f32 v250, v134, v26
	v_cvt_pkrtz_f16_f32 v251, v135, v27
	v_cvt_pkrtz_f16_f32 v252, v136, v28
	v_cvt_pkrtz_f16_f32 v253, v137, v29
	global_store_dwordx4 v[142:143], v[250:253], off offset:-1024 sc1
	ds_read_b128 v[246:249], v208
	ds_read_b128 v[250:253], v209
	ds_read_b128 v[134:137], v210
	s_waitcnt lgkmcnt(3)
	v_pk_fma_f32 v[22:23], v[22:23], v[170:171], v[158:159] op_sel_hi:[1,0,1]
	v_pk_fma_f32 v[24:25], v[24:25], v[170:171], v[160:161] op_sel_hi:[1,0,1]
	v_pk_fma_f32 v[18:19], v[18:19], v[170:171], v[162:163] op_sel_hi:[1,0,1]
	v_pk_fma_f32 v[20:21], v[20:21], v[170:171], v[164:165] op_sel_hi:[1,0,1]
	v_exp_f32_e32 v22, v22
	v_exp_f32_e32 v23, v23
	v_exp_f32_e32 v24, v24
	v_exp_f32_e32 v25, v25
	v_exp_f32_e32 v18, v18
	v_exp_f32_e32 v19, v19
	v_exp_f32_e32 v20, v20
	v_exp_f32_e32 v21, v21
	v_pk_add_f32 v[22:23], v[22:23], 1.0 op_sel_hi:[1,0]
	v_pk_add_f32 v[24:25], v[24:25], 1.0 op_sel_hi:[1,0]
	v_pk_add_f32 v[18:19], v[18:19], 1.0 op_sel_hi:[1,0]
	v_pk_add_f32 v[20:21], v[20:21], 1.0 op_sel_hi:[1,0]
	v_rcp_f32_e32 v22, v22
	v_rcp_f32_e32 v23, v23
	v_rcp_f32_e32 v24, v24
	v_rcp_f32_e32 v25, v25
	v_rcp_f32_e32 v18, v18
	v_rcp_f32_e32 v19, v19
	v_rcp_f32_e32 v20, v20
	v_rcp_f32_e32 v21, v21
	v_pk_mul_f32 v[166:167], v[166:167], v[22:23]
	v_pk_mul_f32 v[168:169], v[168:169], v[24:25]
	v_exp_f32_e32 v22, v166
	v_exp_f32_e32 v23, v167
	v_exp_f32_e32 v24, v168
	v_exp_f32_e32 v25, v169
	v_pk_mul_f32 v[158:159], v[166:167], v[226:227] op_sel_hi:[1,0]
	v_pk_mul_f32 v[160:161], v[168:169], v[226:227] op_sel_hi:[1,0]
	v_pk_fma_f32 v[162:163], v[158:159], 0.5, 1.0 op_sel_hi:[1,0,0]
	v_pk_fma_f32 v[164:165], v[160:161], 0.5, 1.0 op_sel_hi:[1,0,0]
	v_pk_mul_f32 v[162:163], v[162:163], v[158:159] neg_lo:[0,1] neg_hi:[0,1]
	v_pk_mul_f32 v[164:165], v[164:165], v[160:161] neg_lo:[0,1] neg_hi:[0,1]
	v_cmp_lt_f32_e32 vcc, s72, v158
	v_cmp_lt_f32_e64 s[12:13], s72, v159
	v_cmp_lt_f32_e64 s[14:15], s72, v160
	v_cmp_lt_f32_e64 s[16:17], s72, v161
	v_pk_fma_f32 v[158:159], v[22:23], v[22:23], 1.0 op_sel_hi:[1,1,0] neg_lo:[1,0,0] neg_hi:[1,0,0]
	v_pk_fma_f32 v[160:161], v[24:25], v[24:25], 1.0 op_sel_hi:[1,1,0] neg_lo:[1,0,0] neg_hi:[1,0,0]
	v_cndmask_b32_e32 v158, v158, v162, vcc
	v_cndmask_b32_e64 v159, v159, v163, s[12:13]
	v_cndmask_b32_e64 v160, v160, v164, s[14:15]
	v_cndmask_b32_e64 v161, v161, v165, s[16:17]
	v_sqrt_f32_e32 v158, v158
	v_sqrt_f32_e32 v159, v159
	v_sqrt_f32_e32 v160, v160
	v_sqrt_f32_e32 v161, v161
	v_pk_mul_f32 v[18:19], v[18:19], v[158:159]
	v_pk_mul_f32 v[20:21], v[20:21], v[160:161]
	v_pk_mul_f32 v[14:15], v[14:15], v[18:19]
	v_pk_mul_f32 v[16:17], v[16:17], v[20:21]
	v_cvt_pkrtz_f16_f32 v162, v166, v14
	v_cvt_pkrtz_f16_f32 v163, v167, v15
	v_cvt_pkrtz_f16_f32 v164, v168, v16
	v_cvt_pkrtz_f16_f32 v165, v169, v17
	global_store_dwordx4 v[142:143], v[162:165], off sc1
	s_waitcnt lgkmcnt(0)
	v_pk_fma_f32 v[10:11], v[10:11], v[170:171], v[246:247] op_sel_hi:[1,0,1]
	v_pk_fma_f32 v[12:13], v[12:13], v[170:171], v[248:249] op_sel_hi:[1,0,1]
	v_pk_fma_f32 v[6:7], v[6:7], v[170:171], v[250:251] op_sel_hi:[1,0,1]
	v_pk_fma_f32 v[8:9], v[8:9], v[170:171], v[252:253] op_sel_hi:[1,0,1]
	v_exp_f32_e32 v10, v10
	v_exp_f32_e32 v11, v11
	v_exp_f32_e32 v12, v12
	v_exp_f32_e32 v13, v13
	v_exp_f32_e32 v6, v6
	v_exp_f32_e32 v7, v7
	v_exp_f32_e32 v8, v8
	v_exp_f32_e32 v9, v9
	v_pk_add_f32 v[10:11], v[10:11], 1.0 op_sel_hi:[1,0]
	v_pk_add_f32 v[12:13], v[12:13], 1.0 op_sel_hi:[1,0]
	v_pk_add_f32 v[6:7], v[6:7], 1.0 op_sel_hi:[1,0]
	v_pk_add_f32 v[8:9], v[8:9], 1.0 op_sel_hi:[1,0]
	v_rcp_f32_e32 v10, v10
	v_rcp_f32_e32 v11, v11
	v_rcp_f32_e32 v12, v12
	v_rcp_f32_e32 v13, v13
	v_rcp_f32_e32 v6, v6
	v_rcp_f32_e32 v7, v7
	v_rcp_f32_e32 v8, v8
	v_rcp_f32_e32 v9, v9
	v_pk_mul_f32 v[134:135], v[134:135], v[10:11]
	v_pk_mul_f32 v[136:137], v[136:137], v[12:13]
	v_exp_f32_e32 v10, v134
	v_exp_f32_e32 v11, v135
	v_exp_f32_e32 v12, v136
	v_exp_f32_e32 v13, v137
	v_pk_mul_f32 v[246:247], v[134:135], v[226:227] op_sel_hi:[1,0]
	v_pk_mul_f32 v[248:249], v[136:137], v[226:227] op_sel_hi:[1,0]
	v_pk_fma_f32 v[250:251], v[246:247], 0.5, 1.0 op_sel_hi:[1,0,0]
	v_pk_fma_f32 v[252:253], v[248:249], 0.5, 1.0 op_sel_hi:[1,0,0]
	v_pk_mul_f32 v[250:251], v[250:251], v[246:247] neg_lo:[0,1] neg_hi:[0,1]
	v_pk_mul_f32 v[252:253], v[252:253], v[248:249] neg_lo:[0,1] neg_hi:[0,1]
	v_cmp_lt_f32_e32 vcc, s72, v246
	v_cmp_lt_f32_e64 s[12:13], s72, v247
	v_cmp_lt_f32_e64 s[14:15], s72, v248
	v_cmp_lt_f32_e64 s[16:17], s72, v249
	v_pk_fma_f32 v[246:247], v[10:11], v[10:11], 1.0 op_sel_hi:[1,1,0] neg_lo:[1,0,0] neg_hi:[1,0,0]
	v_pk_fma_f32 v[248:249], v[12:13], v[12:13], 1.0 op_sel_hi:[1,1,0] neg_lo:[1,0,0] neg_hi:[1,0,0]
	v_cndmask_b32_e32 v246, v246, v250, vcc
	v_cndmask_b32_e64 v247, v247, v251, s[12:13]
	v_cndmask_b32_e64 v248, v248, v252, s[14:15]
	v_cndmask_b32_e64 v249, v249, v253, s[16:17]
	v_sqrt_f32_e32 v246, v246
	v_sqrt_f32_e32 v247, v247
	v_sqrt_f32_e32 v248, v248
	v_sqrt_f32_e32 v249, v249
	v_pk_mul_f32 v[6:7], v[6:7], v[246:247]
	v_pk_mul_f32 v[8:9], v[8:9], v[248:249]
	v_pk_mul_f32 v[2:3], v[2:3], v[6:7]
	v_pk_mul_f32 v[4:5], v[4:5], v[8:9]
	v_cvt_pkrtz_f16_f32 v250, v134, v2
	v_cvt_pkrtz_f16_f32 v251, v135, v3
	v_cvt_pkrtz_f16_f32 v252, v136, v4
	v_cvt_pkrtz_f16_f32 v253, v137, v5
	global_store_dwordx4 v[142:143], v[250:253], off offset:1024 sc1
	s_and_b64 vcc, exec, s[44:45]
	s_cbranch_vccz .LBB0_341
	s_mov_b32 s10, 0x10001
	s_mov_b32 s11, 0x10001
	s_mov_b64 s[12:13], exec
	s_mov_b64 exec, s[10:11]
	v_fma_f32 v150, v172, v150, v214
	v_mul_f32_e32 v146, v146, v172
	v_fma_f32 v151, v173, v151, v215
	v_mul_f32_e32 v147, v147, v173
	v_fma_f32 v152, v174, v152, v216
	v_mul_f32_e32 v148, v148, v174
	v_fma_f32 v153, v175, v153, v217
	v_mul_f32_e32 v149, v149, v175
	v_fma_f32 v26, v176, v26, v218
	v_mul_f32_e32 v130, v130, v176
	v_fma_f32 v27, v177, v27, v219
	v_mul_f32_e32 v131, v131, v177
	v_fma_f32 v28, v178, v28, v220
	v_mul_f32_e32 v132, v132, v178
	v_fma_f32 v29, v179, v29, v221
	v_mul_f32_e32 v133, v133, v179
	v_fma_f32 v14, v180, v14, v222
	v_mul_f32_e32 v22, v22, v180
	v_fma_f32 v15, v181, v15, v223
	v_mul_f32_e32 v23, v23, v181
	v_fma_f32 v16, v182, v16, v224
	v_mul_f32_e32 v24, v24, v182
	v_fma_f32 v17, v183, v17, v225
	v_mul_f32_e32 v25, v25, v183
	v_fma_f32 v2, v192, v2, v234
	v_mul_f32_e32 v10, v10, v192
	v_fma_f32 v3, v193, v3, v235
	v_mul_f32_e32 v11, v11, v193
	v_fma_f32 v4, v194, v4, v236
	v_mul_f32_e32 v12, v12, v194
	v_fma_f32 v5, v195, v5, v237
	v_mul_f32_e32 v13, v13, v195
	s_mov_b64 exec, s[12:13]
	s_nop 4
	v_fmac_f32_dpp v150, v150, v146 row_shl:1 row_mask:0xf bank_mask:0xf bound_ctrl:1
	v_mul_f32_dpp v146, v146, v146 row_shl:1 row_mask:0xf bank_mask:0xf
	v_fmac_f32_dpp v151, v151, v147 row_shl:1 row_mask:0xf bank_mask:0xf bound_ctrl:1
	v_mul_f32_dpp v147, v147, v147 row_shl:1 row_mask:0xf bank_mask:0xf
	v_fmac_f32_dpp v152, v152, v148 row_shl:1 row_mask:0xf bank_mask:0xf bound_ctrl:1
	v_mul_f32_dpp v148, v148, v148 row_shl:1 row_mask:0xf bank_mask:0xf
	v_fmac_f32_dpp v153, v153, v149 row_shl:1 row_mask:0xf bank_mask:0xf bound_ctrl:1
	v_mul_f32_dpp v149, v149, v149 row_shl:1 row_mask:0xf bank_mask:0xf
	v_fmac_f32_dpp v26, v26, v130 row_shl:1 row_mask:0xf bank_mask:0xf bound_ctrl:1
	v_mul_f32_dpp v130, v130, v130 row_shl:1 row_mask:0xf bank_mask:0xf
	v_fmac_f32_dpp v27, v27, v131 row_shl:1 row_mask:0xf bank_mask:0xf bound_ctrl:1
	v_mul_f32_dpp v131, v131, v131 row_shl:1 row_mask:0xf bank_mask:0xf
	v_fmac_f32_dpp v28, v28, v132 row_shl:1 row_mask:0xf bank_mask:0xf bound_ctrl:1
	v_mul_f32_dpp v132, v132, v132 row_shl:1 row_mask:0xf bank_mask:0xf
	v_fmac_f32_dpp v29, v29, v133 row_shl:1 row_mask:0xf bank_mask:0xf bound_ctrl:1
	v_mul_f32_dpp v133, v133, v133 row_shl:1 row_mask:0xf bank_mask:0xf
	v_fmac_f32_dpp v14, v14, v22 row_shl:1 row_mask:0xf bank_mask:0xf bound_ctrl:1
	v_mul_f32_dpp v22, v22, v22 row_shl:1 row_mask:0xf bank_mask:0xf
	v_fmac_f32_dpp v15, v15, v23 row_shl:1 row_mask:0xf bank_mask:0xf bound_ctrl:1
	v_mul_f32_dpp v23, v23, v23 row_shl:1 row_mask:0xf bank_mask:0xf
	v_fmac_f32_dpp v16, v16, v24 row_shl:1 row_mask:0xf bank_mask:0xf bound_ctrl:1
	v_mul_f32_dpp v24, v24, v24 row_shl:1 row_mask:0xf bank_mask:0xf
	v_fmac_f32_dpp v17, v17, v25 row_shl:1 row_mask:0xf bank_mask:0xf bound_ctrl:1
	v_mul_f32_dpp v25, v25, v25 row_shl:1 row_mask:0xf bank_mask:0xf
	v_fmac_f32_dpp v2, v2, v10 row_shl:1 row_mask:0xf bank_mask:0xf bound_ctrl:1
	v_mul_f32_dpp v10, v10, v10 row_shl:1 row_mask:0xf bank_mask:0xf
	v_fmac_f32_dpp v3, v3, v11 row_shl:1 row_mask:0xf bank_mask:0xf bound_ctrl:1
	v_mul_f32_dpp v11, v11, v11 row_shl:1 row_mask:0xf bank_mask:0xf
	v_fmac_f32_dpp v4, v4, v12 row_shl:1 row_mask:0xf bank_mask:0xf bound_ctrl:1
	v_mul_f32_dpp v12, v12, v12 row_shl:1 row_mask:0xf bank_mask:0xf
	v_fmac_f32_dpp v5, v5, v13 row_shl:1 row_mask:0xf bank_mask:0xf bound_ctrl:1
	v_mul_f32_dpp v13, v13, v13 row_shl:1 row_mask:0xf bank_mask:0xf
	v_fmac_f32_dpp v150, v150, v146 row_shl:2 row_mask:0xf bank_mask:0xf bound_ctrl:1
	v_mul_f32_dpp v146, v146, v146 row_shl:2 row_mask:0xf bank_mask:0xf
	v_fmac_f32_dpp v151, v151, v147 row_shl:2 row_mask:0xf bank_mask:0xf bound_ctrl:1
	v_mul_f32_dpp v147, v147, v147 row_shl:2 row_mask:0xf bank_mask:0xf
	v_fmac_f32_dpp v152, v152, v148 row_shl:2 row_mask:0xf bank_mask:0xf bound_ctrl:1
	v_mul_f32_dpp v148, v148, v148 row_shl:2 row_mask:0xf bank_mask:0xf
	v_fmac_f32_dpp v153, v153, v149 row_shl:2 row_mask:0xf bank_mask:0xf bound_ctrl:1
	v_mul_f32_dpp v149, v149, v149 row_shl:2 row_mask:0xf bank_mask:0xf
	v_fmac_f32_dpp v26, v26, v130 row_shl:2 row_mask:0xf bank_mask:0xf bound_ctrl:1
	v_mul_f32_dpp v130, v130, v130 row_shl:2 row_mask:0xf bank_mask:0xf
	v_fmac_f32_dpp v27, v27, v131 row_shl:2 row_mask:0xf bank_mask:0xf bound_ctrl:1
	v_mul_f32_dpp v131, v131, v131 row_shl:2 row_mask:0xf bank_mask:0xf
	v_fmac_f32_dpp v28, v28, v132 row_shl:2 row_mask:0xf bank_mask:0xf bound_ctrl:1
	v_mul_f32_dpp v132, v132, v132 row_shl:2 row_mask:0xf bank_mask:0xf
	v_fmac_f32_dpp v29, v29, v133 row_shl:2 row_mask:0xf bank_mask:0xf bound_ctrl:1
	v_mul_f32_dpp v133, v133, v133 row_shl:2 row_mask:0xf bank_mask:0xf
	v_fmac_f32_dpp v14, v14, v22 row_shl:2 row_mask:0xf bank_mask:0xf bound_ctrl:1
	v_mul_f32_dpp v22, v22, v22 row_shl:2 row_mask:0xf bank_mask:0xf
	v_fmac_f32_dpp v15, v15, v23 row_shl:2 row_mask:0xf bank_mask:0xf bound_ctrl:1
	v_mul_f32_dpp v23, v23, v23 row_shl:2 row_mask:0xf bank_mask:0xf
	v_fmac_f32_dpp v16, v16, v24 row_shl:2 row_mask:0xf bank_mask:0xf bound_ctrl:1
	v_mul_f32_dpp v24, v24, v24 row_shl:2 row_mask:0xf bank_mask:0xf
	v_fmac_f32_dpp v17, v17, v25 row_shl:2 row_mask:0xf bank_mask:0xf bound_ctrl:1
	v_mul_f32_dpp v25, v25, v25 row_shl:2 row_mask:0xf bank_mask:0xf
	v_fmac_f32_dpp v2, v2, v10 row_shl:2 row_mask:0xf bank_mask:0xf bound_ctrl:1
	v_mul_f32_dpp v10, v10, v10 row_shl:2 row_mask:0xf bank_mask:0xf
	v_fmac_f32_dpp v3, v3, v11 row_shl:2 row_mask:0xf bank_mask:0xf bound_ctrl:1
	v_mul_f32_dpp v11, v11, v11 row_shl:2 row_mask:0xf bank_mask:0xf
	v_fmac_f32_dpp v4, v4, v12 row_shl:2 row_mask:0xf bank_mask:0xf bound_ctrl:1
	v_mul_f32_dpp v12, v12, v12 row_shl:2 row_mask:0xf bank_mask:0xf
	v_fmac_f32_dpp v5, v5, v13 row_shl:2 row_mask:0xf bank_mask:0xf bound_ctrl:1
	v_mul_f32_dpp v13, v13, v13 row_shl:2 row_mask:0xf bank_mask:0xf
	v_fmac_f32_dpp v150, v150, v146 row_shl:4 row_mask:0xf bank_mask:0xf bound_ctrl:1
	v_mul_f32_dpp v146, v146, v146 row_shl:4 row_mask:0xf bank_mask:0xf
	v_fmac_f32_dpp v151, v151, v147 row_shl:4 row_mask:0xf bank_mask:0xf bound_ctrl:1
	v_mul_f32_dpp v147, v147, v147 row_shl:4 row_mask:0xf bank_mask:0xf
	v_fmac_f32_dpp v152, v152, v148 row_shl:4 row_mask:0xf bank_mask:0xf bound_ctrl:1
	v_mul_f32_dpp v148, v148, v148 row_shl:4 row_mask:0xf bank_mask:0xf
	v_fmac_f32_dpp v153, v153, v149 row_shl:4 row_mask:0xf bank_mask:0xf bound_ctrl:1
	v_mul_f32_dpp v149, v149, v149 row_shl:4 row_mask:0xf bank_mask:0xf
	v_fmac_f32_dpp v26, v26, v130 row_shl:4 row_mask:0xf bank_mask:0xf bound_ctrl:1
	v_mul_f32_dpp v130, v130, v130 row_shl:4 row_mask:0xf bank_mask:0xf
	v_fmac_f32_dpp v27, v27, v131 row_shl:4 row_mask:0xf bank_mask:0xf bound_ctrl:1
	v_mul_f32_dpp v131, v131, v131 row_shl:4 row_mask:0xf bank_mask:0xf
	v_fmac_f32_dpp v28, v28, v132 row_shl:4 row_mask:0xf bank_mask:0xf bound_ctrl:1
	v_mul_f32_dpp v132, v132, v132 row_shl:4 row_mask:0xf bank_mask:0xf
	v_fmac_f32_dpp v29, v29, v133 row_shl:4 row_mask:0xf bank_mask:0xf bound_ctrl:1
	v_mul_f32_dpp v133, v133, v133 row_shl:4 row_mask:0xf bank_mask:0xf
	v_fmac_f32_dpp v14, v14, v22 row_shl:4 row_mask:0xf bank_mask:0xf bound_ctrl:1
	v_mul_f32_dpp v22, v22, v22 row_shl:4 row_mask:0xf bank_mask:0xf
	v_fmac_f32_dpp v15, v15, v23 row_shl:4 row_mask:0xf bank_mask:0xf bound_ctrl:1
	v_mul_f32_dpp v23, v23, v23 row_shl:4 row_mask:0xf bank_mask:0xf
	v_fmac_f32_dpp v16, v16, v24 row_shl:4 row_mask:0xf bank_mask:0xf bound_ctrl:1
	v_mul_f32_dpp v24, v24, v24 row_shl:4 row_mask:0xf bank_mask:0xf
	v_fmac_f32_dpp v17, v17, v25 row_shl:4 row_mask:0xf bank_mask:0xf bound_ctrl:1
	v_mul_f32_dpp v25, v25, v25 row_shl:4 row_mask:0xf bank_mask:0xf
	v_fmac_f32_dpp v2, v2, v10 row_shl:4 row_mask:0xf bank_mask:0xf bound_ctrl:1
	v_mul_f32_dpp v10, v10, v10 row_shl:4 row_mask:0xf bank_mask:0xf
	v_fmac_f32_dpp v3, v3, v11 row_shl:4 row_mask:0xf bank_mask:0xf bound_ctrl:1
	v_mul_f32_dpp v11, v11, v11 row_shl:4 row_mask:0xf bank_mask:0xf
	v_fmac_f32_dpp v4, v4, v12 row_shl:4 row_mask:0xf bank_mask:0xf bound_ctrl:1
	v_mul_f32_dpp v12, v12, v12 row_shl:4 row_mask:0xf bank_mask:0xf
	v_fmac_f32_dpp v5, v5, v13 row_shl:4 row_mask:0xf bank_mask:0xf bound_ctrl:1
	v_mul_f32_dpp v13, v13, v13 row_shl:4 row_mask:0xf bank_mask:0xf
	v_fmac_f32_dpp v150, v150, v146 row_shl:8 row_mask:0xf bank_mask:0xf bound_ctrl:1
	v_mul_f32_dpp v146, v146, v146 row_shl:8 row_mask:0xf bank_mask:0xf
	v_fmac_f32_dpp v151, v151, v147 row_shl:8 row_mask:0xf bank_mask:0xf bound_ctrl:1
	v_mul_f32_dpp v147, v147, v147 row_shl:8 row_mask:0xf bank_mask:0xf
	v_fmac_f32_dpp v152, v152, v148 row_shl:8 row_mask:0xf bank_mask:0xf bound_ctrl:1
	v_mul_f32_dpp v148, v148, v148 row_shl:8 row_mask:0xf bank_mask:0xf
	v_fmac_f32_dpp v153, v153, v149 row_shl:8 row_mask:0xf bank_mask:0xf bound_ctrl:1
	v_mul_f32_dpp v149, v149, v149 row_shl:8 row_mask:0xf bank_mask:0xf
	v_fmac_f32_dpp v26, v26, v130 row_shl:8 row_mask:0xf bank_mask:0xf bound_ctrl:1
	v_mul_f32_dpp v130, v130, v130 row_shl:8 row_mask:0xf bank_mask:0xf
	v_fmac_f32_dpp v27, v27, v131 row_shl:8 row_mask:0xf bank_mask:0xf bound_ctrl:1
	v_mul_f32_dpp v131, v131, v131 row_shl:8 row_mask:0xf bank_mask:0xf
	v_fmac_f32_dpp v28, v28, v132 row_shl:8 row_mask:0xf bank_mask:0xf bound_ctrl:1
	v_mul_f32_dpp v132, v132, v132 row_shl:8 row_mask:0xf bank_mask:0xf
	v_fmac_f32_dpp v29, v29, v133 row_shl:8 row_mask:0xf bank_mask:0xf bound_ctrl:1
	v_mul_f32_dpp v133, v133, v133 row_shl:8 row_mask:0xf bank_mask:0xf
	v_fmac_f32_dpp v14, v14, v22 row_shl:8 row_mask:0xf bank_mask:0xf bound_ctrl:1
	v_mul_f32_dpp v22, v22, v22 row_shl:8 row_mask:0xf bank_mask:0xf
	v_fmac_f32_dpp v15, v15, v23 row_shl:8 row_mask:0xf bank_mask:0xf bound_ctrl:1
	v_mul_f32_dpp v23, v23, v23 row_shl:8 row_mask:0xf bank_mask:0xf
	v_fmac_f32_dpp v16, v16, v24 row_shl:8 row_mask:0xf bank_mask:0xf bound_ctrl:1
	v_mul_f32_dpp v24, v24, v24 row_shl:8 row_mask:0xf bank_mask:0xf
	v_fmac_f32_dpp v17, v17, v25 row_shl:8 row_mask:0xf bank_mask:0xf bound_ctrl:1
	v_mul_f32_dpp v25, v25, v25 row_shl:8 row_mask:0xf bank_mask:0xf
	v_fmac_f32_dpp v2, v2, v10 row_shl:8 row_mask:0xf bank_mask:0xf bound_ctrl:1
	v_mul_f32_dpp v10, v10, v10 row_shl:8 row_mask:0xf bank_mask:0xf
	v_fmac_f32_dpp v3, v3, v11 row_shl:8 row_mask:0xf bank_mask:0xf bound_ctrl:1
	v_mul_f32_dpp v11, v11, v11 row_shl:8 row_mask:0xf bank_mask:0xf
	v_fmac_f32_dpp v4, v4, v12 row_shl:8 row_mask:0xf bank_mask:0xf bound_ctrl:1
	v_mul_f32_dpp v12, v12, v12 row_shl:8 row_mask:0xf bank_mask:0xf
	v_fmac_f32_dpp v5, v5, v13 row_shl:8 row_mask:0xf bank_mask:0xf bound_ctrl:1
	v_mul_f32_dpp v13, v13, v13 row_shl:8 row_mask:0xf bank_mask:0xf
	v_mov_b64_e32 v[172:173], v[146:147]
	v_mov_b64_e32 v[214:215], v[150:151]
	v_mov_b64_e32 v[174:175], v[148:149]
	v_mov_b64_e32 v[216:217], v[152:153]
	v_mov_b64_e32 v[176:177], v[130:131]
	v_mov_b64_e32 v[218:219], v[26:27]
	v_mov_b64_e32 v[178:179], v[132:133]
	v_mov_b64_e32 v[220:221], v[28:29]
	v_mov_b64_e32 v[180:181], v[22:23]
	v_mov_b64_e32 v[222:223], v[14:15]
	v_mov_b64_e32 v[182:183], v[24:25]
	v_mov_b64_e32 v[224:225], v[16:17]
	v_mov_b64_e32 v[192:193], v[10:11]
	v_mov_b64_e32 v[234:235], v[2:3]
	v_mov_b64_e32 v[194:195], v[12:13]
	v_mov_b64_e32 v[236:237], v[4:5]
	s_mov_b64 s[10:11], 0

.LBB0_343:
	s_cmp_eq_u32 s43, 0
	s_cselect_b32 s3, 15, 0
	v_cmp_eq_u32_e32 vcc, s3, v184
	s_and_saveexec_b64 s[8:9], vcc
	s_cbranch_execz .LBB0_345
	s_lshl_b32 s3, s74, 1
	s_or_b32 s3, s3, s43
	s_mulk_i32 s3, 0x44
	s_ashr_i32 s11, s59, 31
	s_add_u32 s10, s3, s59
	s_addc_u32 s11, 0, s11
	s_lshl_b64 s[10:11], s[10:11], 9
	s_add_u32 s10, s10, s18
	s_addc_u32 s11, s11, s19
	v_lshl_add_u64 v[2:3], s[10:11], 0, v[138:139]
	v_lshlrev_b64 v[6:7], 2, v[2:3]
	v_lshl_add_u64 v[22:23], s[22:23], 0, v[6:7]
	v_lshl_add_u64 v[24:25], s[20:21], 0, v[6:7]
	global_store_dwordx4 v[22:23], v[172:175], off sc1
	global_store_dwordx4 v[24:25], v[214:217], off sc1
	global_store_dwordx4 v[22:23], v[176:179], off offset:64 sc1
	global_store_dwordx4 v[24:25], v[218:221], off offset:64 sc1
	global_store_dwordx4 v[22:23], v[180:183], off offset:128 sc1
	global_store_dwordx4 v[24:25], v[222:225], off offset:128 sc1
	global_store_dwordx4 v[22:23], v[192:195], off offset:192 sc1
	global_store_dwordx4 v[24:25], v[234:237], off offset:192 sc1

.LBB0_429:
	s_andn2_b64 vcc, exec, s[8:9]
	s_cbranch_vccnz .LBB0_434
	s_cmpk_lt_i32 s3, 0x4000
	s_cbranch_scc1 .LBB0_432
	s_lshl_b64 s[8:9], s[74:75], 12
	v_lshl_add_u64 v[48:49], v[36:37], 0, s[8:9]
	v_add_co_u32_e32 v50, vcc, 0x400000, v48
	global_load_dwordx4 v[54:57], v[48:49], off
	global_load_dwordx4 v[58:61], v[48:49], off offset:1024
	global_load_dwordx4 v[62:65], v[48:49], off offset:2048
	global_load_dwordx4 v[66:69], v[48:49], off offset:3072
	v_addc_co_u32_e32 v51, vcc, 0, v49, vcc
	global_load_dwordx4 v[70:73], v[50:51], off
	global_load_dwordx4 v[74:77], v[50:51], off offset:1024
	global_load_dwordx4 v[78:81], v[50:51], off offset:2048
	global_load_dwordx4 v[82:85], v[50:51], off offset:3072
	v_add_co_u32_e32 v50, vcc, 0x800000, v48
	s_nop 1
	v_addc_co_u32_e32 v51, vcc, 0, v49, vcc
	global_load_dwordx4 v[86:89], v[50:51], off
	global_load_dwordx4 v[90:93], v[50:51], off offset:1024
	global_load_dwordx4 v[94:97], v[50:51], off offset:2048
	global_load_dwordx4 v[98:101], v[50:51], off offset:3072
	v_add_co_u32_e32 v50, vcc, 0xc00000, v48
	s_nop 1
	v_addc_co_u32_e32 v51, vcc, 0, v49, vcc
	global_load_dwordx4 v[102:105], v[50:51], off
	global_load_dwordx4 v[106:109], v[50:51], off offset:1024
	global_load_dwordx4 v[110:113], v[50:51], off offset:2048
	global_load_dwordx4 v[114:117], v[50:51], off offset:3072
	s_waitcnt vmcnt(14)
	v_pk_add_f32 v[22:23], v[22:23], v[58:59]
	s_waitcnt vmcnt(13)
	v_pk_add_f32 v[16:17], v[16:17], v[64:65]
	s_waitcnt vmcnt(10)
	v_pk_add_f32 v[22:23], v[22:23], v[74:75]
	s_waitcnt vmcnt(9)
	v_pk_add_f32 v[16:17], v[16:17], v[80:81]
	v_pk_add_f32 v[32:33], v[32:33], v[56:57]
	v_pk_add_f32 v[30:31], v[30:31], v[54:55]
	v_pk_add_f32 v[24:25], v[24:25], v[60:61]
	v_pk_add_f32 v[14:15], v[14:15], v[62:63]
	v_pk_add_f32 v[8:9], v[8:9], v[68:69]
	v_pk_add_f32 v[6:7], v[6:7], v[66:67]
	s_waitcnt vmcnt(6)
	v_pk_add_f32 v[22:23], v[22:23], v[90:91]
	s_waitcnt vmcnt(5)
	v_pk_add_f32 v[50:51], v[16:17], v[96:97]
	s_mov_b32 s5, 0x1000000
	v_pk_add_f32 v[32:33], v[32:33], v[72:73]
	v_pk_add_f32 v[30:31], v[30:31], v[70:71]
	v_pk_add_f32 v[24:25], v[24:25], v[76:77]
	v_pk_add_f32 v[14:15], v[14:15], v[78:79]
	v_pk_add_f32 v[8:9], v[8:9], v[84:85]
	v_pk_add_f32 v[6:7], v[6:7], v[82:83]
	s_waitcnt vmcnt(2)
	v_pk_add_f32 v[16:17], v[22:23], v[106:107]
	s_waitcnt vmcnt(1)
	v_pk_add_f32 v[22:23], v[50:51], v[112:113]
	v_add_co_u32_e32 v50, vcc, s5, v48
	v_pk_add_f32 v[32:33], v[32:33], v[88:89]
	v_pk_add_f32 v[30:31], v[30:31], v[86:87]
	v_pk_add_f32 v[24:25], v[24:25], v[92:93]
	v_pk_add_f32 v[54:55], v[14:15], v[94:95]
	v_pk_add_f32 v[56:57], v[8:9], v[100:101]
	v_pk_add_f32 v[58:59], v[6:7], v[98:99]
	v_addc_co_u32_e32 v51, vcc, 0, v49, vcc
	s_mov_b32 s5, 0x1400000
	v_pk_add_f32 v[6:7], v[32:33], v[104:105]
	v_pk_add_f32 v[8:9], v[30:31], v[102:103]
	v_pk_add_f32 v[14:15], v[24:25], v[108:109]
	v_pk_add_f32 v[24:25], v[54:55], v[110:111]
	s_waitcnt vmcnt(0)
	v_pk_add_f32 v[30:31], v[56:57], v[116:117]
	v_pk_add_f32 v[32:33], v[58:59], v[114:115]
	global_load_dwordx4 v[54:57], v[50:51], off
	global_load_dwordx4 v[58:61], v[50:51], off offset:1024
	global_load_dwordx4 v[62:65], v[50:51], off offset:2048
	global_load_dwordx4 v[66:69], v[50:51], off offset:3072
	v_add_co_u32_e32 v50, vcc, s5, v48
	s_mov_b32 s5, 0x1800000
	s_nop 0
	v_addc_co_u32_e32 v51, vcc, 0, v49, vcc
	global_load_dwordx4 v[70:73], v[50:51], off
	global_load_dwordx4 v[74:77], v[50:51], off offset:1024
	global_load_dwordx4 v[78:81], v[50:51], off offset:2048
	global_load_dwordx4 v[82:85], v[50:51], off offset:3072
	v_add_co_u32_e32 v50, vcc, s5, v48
	s_mov_b32 s5, 0x1c00000
	s_nop 0
	v_addc_co_u32_e32 v51, vcc, 0, v49, vcc
	global_load_dwordx4 v[86:89], v[50:51], off
	global_load_dwordx4 v[90:93], v[50:51], off offset:1024
	global_load_dwordx4 v[94:97], v[50:51], off offset:2048
	global_load_dwordx4 v[98:101], v[50:51], off offset:3072
	v_add_co_u32_e32 v50, vcc, s5, v48
	s_nop 1
	v_addc_co_u32_e32 v51, vcc, 0, v49, vcc
	global_load_dwordx4 v[102:105], v[50:51], off
	global_load_dwordx4 v[106:109], v[50:51], off offset:1024
	global_load_dwordx4 v[110:113], v[50:51], off offset:2048
	global_load_dwordx4 v[114:117], v[50:51], off offset:3072
	s_waitcnt vmcnt(14)
	v_pk_add_f32 v[14:15], v[14:15], v[60:61]
	s_waitcnt vmcnt(13)
	v_pk_add_f32 v[22:23], v[22:23], v[64:65]
	s_waitcnt vmcnt(10)
	v_pk_add_f32 v[14:15], v[14:15], v[76:77]
	s_waitcnt vmcnt(9)
	v_pk_add_f32 v[22:23], v[22:23], v[80:81]
	v_pk_add_f32 v[6:7], v[6:7], v[56:57]
	v_pk_add_f32 v[8:9], v[8:9], v[54:55]
	v_pk_add_f32 v[16:17], v[16:17], v[58:59]
	v_pk_add_f32 v[24:25], v[24:25], v[62:63]
	v_pk_add_f32 v[30:31], v[30:31], v[68:69]
	v_pk_add_f32 v[32:33], v[32:33], v[66:67]
	s_waitcnt vmcnt(6)
	v_pk_add_f32 v[14:15], v[14:15], v[92:93]
	s_waitcnt vmcnt(5)
	v_pk_add_f32 v[50:51], v[22:23], v[96:97]
	s_brev_b32 s5, 64
	v_pk_add_f32 v[6:7], v[6:7], v[72:73]
	v_pk_add_f32 v[8:9], v[8:9], v[70:71]
	v_pk_add_f32 v[16:17], v[16:17], v[74:75]
	v_pk_add_f32 v[24:25], v[24:25], v[78:79]
	v_pk_add_f32 v[30:31], v[30:31], v[84:85]
	v_pk_add_f32 v[32:33], v[32:33], v[82:83]
	s_waitcnt vmcnt(2)
	v_pk_add_f32 v[22:23], v[14:15], v[108:109]
	s_waitcnt vmcnt(1)
	v_pk_add_f32 v[14:15], v[50:51], v[112:113]
	v_add_co_u32_e32 v50, vcc, s5, v48
	v_pk_add_f32 v[6:7], v[6:7], v[88:89]
	v_pk_add_f32 v[8:9], v[8:9], v[86:87]
	v_pk_add_f32 v[16:17], v[16:17], v[90:91]
	v_pk_add_f32 v[54:55], v[24:25], v[94:95]
	v_pk_add_f32 v[56:57], v[30:31], v[100:101]
	v_pk_add_f32 v[58:59], v[32:33], v[98:99]
	v_addc_co_u32_e32 v51, vcc, 0, v49, vcc
	s_mov_b32 s5, 0x2400000
	v_pk_add_f32 v[30:31], v[6:7], v[104:105]
	v_pk_add_f32 v[32:33], v[8:9], v[102:103]
	v_pk_add_f32 v[24:25], v[16:17], v[106:107]
	v_pk_add_f32 v[16:17], v[54:55], v[110:111]
	s_waitcnt vmcnt(0)
	v_pk_add_f32 v[6:7], v[56:57], v[116:117]
	v_pk_add_f32 v[8:9], v[58:59], v[114:115]
	global_load_dwordx4 v[54:57], v[50:51], off
	global_load_dwordx4 v[58:61], v[50:51], off offset:1024
	global_load_dwordx4 v[62:65], v[50:51], off offset:2048
	global_load_dwordx4 v[66:69], v[50:51], off offset:3072
	v_add_co_u32_e32 v50, vcc, s5, v48
	s_mov_b32 s5, 0x2800000
	s_nop 0
	v_addc_co_u32_e32 v51, vcc, 0, v49, vcc
	v_add_co_u32_e32 v94, vcc, s5, v48
	global_load_dwordx4 v[70:73], v[50:51], off
	global_load_dwordx4 v[74:77], v[50:51], off offset:1024
	global_load_dwordx4 v[78:81], v[50:51], off offset:2048
	global_load_dwordx4 v[82:85], v[50:51], off offset:3072
	v_addc_co_u32_e32 v95, vcc, 0, v49, vcc
	global_load_dwordx4 v[48:51], v[94:95], off
	global_load_dwordx4 v[86:89], v[94:95], off offset:1024
	global_load_dwordx4 v[90:93], v[94:95], off offset:2048
	s_nop 0
	global_load_dwordx4 v[94:97], v[94:95], off offset:3072
	s_waitcnt vmcnt(11)
	v_pk_add_f32 v[30:31], v[30:31], v[56:57]
	v_pk_add_f32 v[32:33], v[32:33], v[54:55]
	s_waitcnt vmcnt(10)
	v_pk_add_f32 v[22:23], v[22:23], v[60:61]
	v_pk_add_f32 v[24:25], v[24:25], v[58:59]
	s_waitcnt vmcnt(9)
	v_pk_add_f32 v[14:15], v[14:15], v[64:65]
	v_pk_add_f32 v[16:17], v[16:17], v[62:63]
	s_waitcnt vmcnt(8)
	v_pk_add_f32 v[6:7], v[6:7], v[68:69]
	v_pk_add_f32 v[8:9], v[8:9], v[66:67]
	s_waitcnt vmcnt(7)
	v_pk_add_f32 v[30:31], v[30:31], v[72:73]
	v_pk_add_f32 v[32:33], v[32:33], v[70:71]
	s_waitcnt vmcnt(6)
	v_pk_add_f32 v[22:23], v[22:23], v[76:77]
	v_pk_add_f32 v[24:25], v[24:25], v[74:75]
	s_waitcnt vmcnt(5)
	v_pk_add_f32 v[14:15], v[14:15], v[80:81]
	v_pk_add_f32 v[16:17], v[16:17], v[78:79]
	s_waitcnt vmcnt(4)
	v_pk_add_f32 v[6:7], v[6:7], v[84:85]
	v_pk_add_f32 v[8:9], v[8:9], v[82:83]
	s_waitcnt vmcnt(3)
	v_pk_add_f32 v[30:31], v[30:31], v[50:51]
	v_pk_add_f32 v[54:55], v[32:33], v[48:49]
	s_waitcnt vmcnt(2)
	v_pk_add_f32 v[22:23], v[22:23], v[88:89]
	v_pk_add_f32 v[56:57], v[24:25], v[86:87]
	s_waitcnt vmcnt(1)
	v_pk_add_f32 v[14:15], v[14:15], v[92:93]
	v_pk_add_f32 v[58:59], v[16:17], v[90:91]
	s_waitcnt vmcnt(0)
	v_pk_add_f32 v[6:7], v[6:7], v[96:97]
	v_pk_add_f32 v[60:61], v[8:9], v[94:95]
	v_pk_fma_f32 v[32:33], v[50:51], 0, v[30:31] op_sel_hi:[1,0,1]
	v_pk_fma_f32 v[30:31], v[48:49], 0, v[54:55] op_sel_hi:[1,0,1]
	v_pk_fma_f32 v[24:25], v[88:89], 0, v[22:23] op_sel_hi:[1,0,1]
	v_pk_fma_f32 v[22:23], v[86:87], 0, v[56:57] op_sel_hi:[1,0,1]
	v_pk_fma_f32 v[16:17], v[92:93], 0, v[14:15] op_sel_hi:[1,0,1]
	v_pk_fma_f32 v[14:15], v[90:91], 0, v[58:59] op_sel_hi:[1,0,1]
	v_pk_fma_f32 v[8:9], v[96:97], 0, v[6:7] op_sel_hi:[1,0,1]
	v_pk_fma_f32 v[6:7], v[94:95], 0, v[60:61] op_sel_hi:[1,0,1]
	v_lshl_add_u64 v[48:49], v[44:45], 0, s[8:9]
	global_store_dwordx4 v[48:49], v[30:33], off sc1
	global_store_dwordx4 v[48:49], v[22:25], off offset:1024 sc1
	global_store_dwordx4 v[48:49], v[14:17], off offset:2048 sc1
	global_store_dwordx4 v[48:49], v[6:9], off offset:3072 sc1
.LBB0_432:
	s_and_b32 s5, s20, 0xfffffc00
	s_cmpk_lg_i32 s5, 0x4000
	s_cbranch_scc1 .LBB0_434
	s_mov_b32 s5, s75
	s_lshl_b64 s[8:9], s[4:5], 2
	v_lshl_add_u64 v[48:49], v[36:37], 0, s[8:9]
	v_add_co_u32_e32 v50, vcc, 0x400000, v48
	global_load_dwordx4 v[54:57], v[48:49], off
	global_load_dwordx4 v[58:61], v[48:49], off offset:1024
	global_load_dwordx4 v[62:65], v[48:49], off offset:2048
	global_load_dwordx4 v[66:69], v[48:49], off offset:3072
	v_addc_co_u32_e32 v51, vcc, 0, v49, vcc
	global_load_dwordx4 v[70:73], v[50:51], off
	global_load_dwordx4 v[74:77], v[50:51], off offset:1024
	global_load_dwordx4 v[78:81], v[50:51], off offset:2048
	global_load_dwordx4 v[82:85], v[50:51], off offset:3072
	v_add_co_u32_e32 v50, vcc, s96, v48
	s_mov_b32 s5, 0xc00000
	s_nop 0
	v_addc_co_u32_e32 v51, vcc, 0, v49, vcc
	global_load_dwordx4 v[86:89], v[50:51], off
	global_load_dwordx4 v[90:93], v[50:51], off offset:1024
	global_load_dwordx4 v[94:97], v[50:51], off offset:2048
	global_load_dwordx4 v[98:101], v[50:51], off offset:3072
	v_add_co_u32_e32 v50, vcc, s5, v48
	s_nop 1
	v_addc_co_u32_e32 v51, vcc, 0, v49, vcc
	global_load_dwordx4 v[102:105], v[50:51], off
	global_load_dwordx4 v[106:109], v[50:51], off offset:1024
	global_load_dwordx4 v[110:113], v[50:51], off offset:2048
	global_load_dwordx4 v[114:117], v[50:51], off offset:3072
	s_waitcnt vmcnt(14)
	v_pk_add_f32 v[18:19], v[18:19], v[58:59]
	s_waitcnt vmcnt(13)
	v_pk_add_f32 v[12:13], v[12:13], v[64:65]
	s_waitcnt vmcnt(10)
	v_pk_add_f32 v[18:19], v[18:19], v[74:75]
	s_waitcnt vmcnt(9)
	v_pk_add_f32 v[12:13], v[12:13], v[80:81]
	v_pk_add_f32 v[28:29], v[28:29], v[56:57]
	v_pk_add_f32 v[26:27], v[26:27], v[54:55]
	v_pk_add_f32 v[20:21], v[20:21], v[60:61]
	v_pk_add_f32 v[10:11], v[10:11], v[62:63]
	v_pk_add_f32 v[4:5], v[4:5], v[68:69]
	v_pk_add_f32 v[2:3], v[2:3], v[66:67]
	s_waitcnt vmcnt(6)
	v_pk_add_f32 v[18:19], v[18:19], v[90:91]
	s_waitcnt vmcnt(5)
	v_pk_add_f32 v[50:51], v[12:13], v[96:97]
	s_mov_b32 s5, 0x1000000
	v_pk_add_f32 v[28:29], v[28:29], v[72:73]
	v_pk_add_f32 v[26:27], v[26:27], v[70:71]
	v_pk_add_f32 v[20:21], v[20:21], v[76:77]
	v_pk_add_f32 v[10:11], v[10:11], v[78:79]
	v_pk_add_f32 v[4:5], v[4:5], v[84:85]
	v_pk_add_f32 v[2:3], v[2:3], v[82:83]
	s_waitcnt vmcnt(2)
	v_pk_add_f32 v[12:13], v[18:19], v[106:107]
	s_waitcnt vmcnt(1)
	v_pk_add_f32 v[18:19], v[50:51], v[112:113]
	v_add_co_u32_e32 v50, vcc, s5, v48
	v_pk_add_f32 v[28:29], v[28:29], v[88:89]
	v_pk_add_f32 v[26:27], v[26:27], v[86:87]
	v_pk_add_f32 v[20:21], v[20:21], v[92:93]
	v_pk_add_f32 v[54:55], v[10:11], v[94:95]
	v_pk_add_f32 v[56:57], v[4:5], v[100:101]
	v_pk_add_f32 v[58:59], v[2:3], v[98:99]
	v_addc_co_u32_e32 v51, vcc, 0, v49, vcc
	s_mov_b32 s5, 0x1400000
	v_pk_add_f32 v[2:3], v[28:29], v[104:105]
	v_pk_add_f32 v[4:5], v[26:27], v[102:103]
	v_pk_add_f32 v[10:11], v[20:21], v[108:109]
	v_pk_add_f32 v[20:21], v[54:55], v[110:111]
	s_waitcnt vmcnt(0)
	v_pk_add_f32 v[26:27], v[56:57], v[116:117]
	v_pk_add_f32 v[28:29], v[58:59], v[114:115]
	global_load_dwordx4 v[54:57], v[50:51], off
	global_load_dwordx4 v[58:61], v[50:51], off offset:1024
	global_load_dwordx4 v[62:65], v[50:51], off offset:2048
	global_load_dwordx4 v[66:69], v[50:51], off offset:3072
	v_add_co_u32_e32 v50, vcc, s5, v48
	s_mov_b32 s5, 0x1800000
	s_nop 0
	v_addc_co_u32_e32 v51, vcc, 0, v49, vcc
	global_load_dwordx4 v[70:73], v[50:51], off
	global_load_dwordx4 v[74:77], v[50:51], off offset:1024
	global_load_dwordx4 v[78:81], v[50:51], off offset:2048
	global_load_dwordx4 v[82:85], v[50:51], off offset:3072
	v_add_co_u32_e32 v50, vcc, s5, v48
	s_mov_b32 s5, 0x1c00000
	s_nop 0
	v_addc_co_u32_e32 v51, vcc, 0, v49, vcc
	global_load_dwordx4 v[86:89], v[50:51], off
	global_load_dwordx4 v[90:93], v[50:51], off offset:1024
	global_load_dwordx4 v[94:97], v[50:51], off offset:2048
	global_load_dwordx4 v[98:101], v[50:51], off offset:3072
	v_add_co_u32_e32 v50, vcc, s5, v48
	s_nop 1
	v_addc_co_u32_e32 v51, vcc, 0, v49, vcc
	global_load_dwordx4 v[102:105], v[50:51], off
	global_load_dwordx4 v[106:109], v[50:51], off offset:1024
	global_load_dwordx4 v[110:113], v[50:51], off offset:2048
	global_load_dwordx4 v[114:117], v[50:51], off offset:3072
	s_waitcnt vmcnt(14)
	v_pk_add_f32 v[10:11], v[10:11], v[60:61]
	s_waitcnt vmcnt(13)
	v_pk_add_f32 v[18:19], v[18:19], v[64:65]
	s_waitcnt vmcnt(10)
	v_pk_add_f32 v[10:11], v[10:11], v[76:77]
	s_waitcnt vmcnt(9)
	v_pk_add_f32 v[18:19], v[18:19], v[80:81]
	v_pk_add_f32 v[2:3], v[2:3], v[56:57]
	v_pk_add_f32 v[4:5], v[4:5], v[54:55]
	v_pk_add_f32 v[12:13], v[12:13], v[58:59]
	v_pk_add_f32 v[20:21], v[20:21], v[62:63]
	v_pk_add_f32 v[26:27], v[26:27], v[68:69]
	v_pk_add_f32 v[28:29], v[28:29], v[66:67]
	s_waitcnt vmcnt(6)
	v_pk_add_f32 v[10:11], v[10:11], v[92:93]
	s_waitcnt vmcnt(5)
	v_pk_add_f32 v[50:51], v[18:19], v[96:97]
	s_brev_b32 s5, 64
	v_pk_add_f32 v[2:3], v[2:3], v[72:73]
	v_pk_add_f32 v[4:5], v[4:5], v[70:71]
	v_pk_add_f32 v[12:13], v[12:13], v[74:75]
	v_pk_add_f32 v[20:21], v[20:21], v[78:79]
	v_pk_add_f32 v[26:27], v[26:27], v[84:85]
	v_pk_add_f32 v[28:29], v[28:29], v[82:83]
	s_waitcnt vmcnt(2)
	v_pk_add_f32 v[18:19], v[10:11], v[108:109]
	s_waitcnt vmcnt(1)
	v_pk_add_f32 v[10:11], v[50:51], v[112:113]
	v_add_co_u32_e32 v50, vcc, s5, v48
	v_pk_add_f32 v[2:3], v[2:3], v[88:89]
	v_pk_add_f32 v[4:5], v[4:5], v[86:87]
	v_pk_add_f32 v[12:13], v[12:13], v[90:91]
	v_pk_add_f32 v[54:55], v[20:21], v[94:95]
	v_pk_add_f32 v[56:57], v[26:27], v[100:101]
	v_pk_add_f32 v[58:59], v[28:29], v[98:99]
	v_addc_co_u32_e32 v51, vcc, 0, v49, vcc
	s_mov_b32 s5, 0x2400000
	v_pk_add_f32 v[26:27], v[2:3], v[104:105]
	v_pk_add_f32 v[28:29], v[4:5], v[102:103]
	v_pk_add_f32 v[20:21], v[12:13], v[106:107]
	v_pk_add_f32 v[12:13], v[54:55], v[110:111]
	s_waitcnt vmcnt(0)
	v_pk_add_f32 v[2:3], v[56:57], v[116:117]
	v_pk_add_f32 v[4:5], v[58:59], v[114:115]
	global_load_dwordx4 v[54:57], v[50:51], off
	global_load_dwordx4 v[58:61], v[50:51], off offset:1024
	global_load_dwordx4 v[62:65], v[50:51], off offset:2048
	global_load_dwordx4 v[66:69], v[50:51], off offset:3072
	v_add_co_u32_e32 v50, vcc, s5, v48
	s_mov_b32 s5, 0x2800000
	s_nop 0
	v_addc_co_u32_e32 v51, vcc, 0, v49, vcc
	v_add_co_u32_e32 v94, vcc, s5, v48
	global_load_dwordx4 v[70:73], v[50:51], off
	global_load_dwordx4 v[74:77], v[50:51], off offset:1024
	global_load_dwordx4 v[78:81], v[50:51], off offset:2048
	global_load_dwordx4 v[82:85], v[50:51], off offset:3072
	v_addc_co_u32_e32 v95, vcc, 0, v49, vcc
	global_load_dwordx4 v[48:51], v[94:95], off
	global_load_dwordx4 v[86:89], v[94:95], off offset:1024
	global_load_dwordx4 v[90:93], v[94:95], off offset:2048
	s_nop 0
	global_load_dwordx4 v[94:97], v[94:95], off offset:3072
	s_waitcnt vmcnt(11)
	v_pk_add_f32 v[26:27], v[26:27], v[56:57]
	v_pk_add_f32 v[28:29], v[28:29], v[54:55]
	s_waitcnt vmcnt(10)
	v_pk_add_f32 v[18:19], v[18:19], v[60:61]
	v_pk_add_f32 v[20:21], v[20:21], v[58:59]
	s_waitcnt vmcnt(9)
	v_pk_add_f32 v[10:11], v[10:11], v[64:65]
	v_pk_add_f32 v[12:13], v[12:13], v[62:63]
	s_waitcnt vmcnt(8)
	v_pk_add_f32 v[2:3], v[2:3], v[68:69]
	v_pk_add_f32 v[4:5], v[4:5], v[66:67]
	s_waitcnt vmcnt(7)
	v_pk_add_f32 v[26:27], v[26:27], v[72:73]
	v_pk_add_f32 v[28:29], v[28:29], v[70:71]
	s_waitcnt vmcnt(6)
	v_pk_add_f32 v[18:19], v[18:19], v[76:77]
	v_pk_add_f32 v[20:21], v[20:21], v[74:75]
	s_waitcnt vmcnt(5)
	v_pk_add_f32 v[10:11], v[10:11], v[80:81]
	v_pk_add_f32 v[12:13], v[12:13], v[78:79]
	s_waitcnt vmcnt(4)
	v_pk_add_f32 v[2:3], v[2:3], v[84:85]
	v_pk_add_f32 v[4:5], v[4:5], v[82:83]
	s_waitcnt vmcnt(3)
	v_pk_add_f32 v[26:27], v[26:27], v[50:51]
	v_pk_add_f32 v[54:55], v[28:29], v[48:49]
	s_waitcnt vmcnt(2)
	v_pk_add_f32 v[18:19], v[18:19], v[88:89]
	v_pk_add_f32 v[56:57], v[20:21], v[86:87]
	s_waitcnt vmcnt(1)
	v_pk_add_f32 v[10:11], v[10:11], v[92:93]
	v_pk_add_f32 v[58:59], v[12:13], v[90:91]
	s_waitcnt vmcnt(0)
	v_pk_add_f32 v[2:3], v[2:3], v[96:97]
	v_pk_add_f32 v[60:61], v[4:5], v[94:95]
	v_pk_fma_f32 v[28:29], v[50:51], 0, v[26:27] op_sel_hi:[1,0,1]
	v_pk_fma_f32 v[26:27], v[48:49], 0, v[54:55] op_sel_hi:[1,0,1]
	v_pk_fma_f32 v[20:21], v[88:89], 0, v[18:19] op_sel_hi:[1,0,1]
	v_pk_fma_f32 v[18:19], v[86:87], 0, v[56:57] op_sel_hi:[1,0,1]
	v_pk_fma_f32 v[12:13], v[92:93], 0, v[10:11] op_sel_hi:[1,0,1]
	v_pk_fma_f32 v[10:11], v[90:91], 0, v[58:59] op_sel_hi:[1,0,1]
	v_pk_fma_f32 v[4:5], v[96:97], 0, v[2:3] op_sel_hi:[1,0,1]
	v_pk_fma_f32 v[2:3], v[94:95], 0, v[60:61] op_sel_hi:[1,0,1]
	v_lshl_add_u64 v[48:49], v[44:45], 0, s[8:9]
	global_store_dwordx4 v[48:49], v[26:29], off sc1
	global_store_dwordx4 v[48:49], v[18:21], off offset:1024 sc1
	global_store_dwordx4 v[48:49], v[10:13], off offset:2048 sc1
	global_store_dwordx4 v[48:49], v[2:5], off offset:3072 sc1
.LBB0_434:
	s_min_i32 s5, s3, 0x4000
	s_ashr_i32 s5, s5, 12
	v_readlane_b32 s22, v255, 30
	s_add_i32 s5, s5, s22
	s_mul_i32 s8, s5, 0x1800
	s_min_i32 s5, s21, 0x4000
	s_ashr_i32 s5, s5, 12
	s_add_i32 s5, s5, s22
	s_ashr_i32 s9, s8, 31
	s_mul_i32 s22, s5, 0x1800
	s_waitcnt vmcnt(7)
	v_pk_mul_f32 v[54:55], v[32:33], v[32:33]
	v_pk_mul_f32 v[56:57], v[30:31], v[30:31]
	s_ashr_i32 s23, s22, 31
	s_lshl_b64 s[8:9], s[8:9], 2
	v_readlane_b32 s26, v255, 48
	v_pk_mov_b32 v[58:59], v[56:57], v[54:55] op_sel:[1,0]
	v_mov_b32_e32 v57, v55
	v_readlane_b32 s27, v255, 49
	s_add_u32 s24, s26, s8
	v_pk_add_f32 v[54:55], v[58:59], v[56:57]
	s_waitcnt vmcnt(5)
	v_pk_mul_f32 v[58:59], v[28:29], v[28:29]
	v_pk_mul_f32 v[60:61], v[26:27], v[26:27]
	s_addc_u32 s25, s27, s9
	s_lshl_b64 s[8:9], s[22:23], 2
	v_pk_mov_b32 v[64:65], v[60:61], v[58:59] op_sel:[1,0]
	v_mov_b32_e32 v61, v59
	s_add_u32 s22, s26, s8
	v_pk_mul_f32 v[48:49], v[24:25], v[24:25]
	v_pk_mul_f32 v[50:51], v[22:23], v[22:23]
	v_pk_add_f32 v[58:59], v[64:65], v[60:61]
	s_addc_u32 s23, s27, s9
	v_pk_add_f32 v[62:63], v[54:55], v[54:55] op_sel_hi:[0,1]
	s_waitcnt vmcnt(4)
	v_pk_mul_f32 v[54:55], v[20:21], v[20:21]
	v_pk_mul_f32 v[56:57], v[18:19], v[18:19]
	v_pk_add_f32 v[64:65], v[58:59], v[58:59] op_sel_hi:[0,1]
	v_pk_mov_b32 v[58:59], v[50:51], v[48:49] op_sel:[1,0]
	v_mov_b32_e32 v51, v49
	v_pk_add_f32 v[48:49], v[58:59], v[50:51]
	v_pk_mov_b32 v[50:51], v[56:57], v[54:55] op_sel:[1,0]
	v_mov_b32_e32 v57, v55
	s_add_u32 s26, s24, 0x1000
	v_pk_add_f32 v[50:51], v[50:51], v[56:57]
	s_addc_u32 s27, s25, 0
	global_load_dwordx4 v[54:57], v0, s[24:25]
	global_load_dwordx4 v[58:61], v0, s[26:27]
	v_pk_add_f32 v[48:49], v[48:49], v[48:49] op_sel_hi:[0,1]
	s_waitcnt vmcnt(5)
	v_mul_f32_e32 v48, v14, v14
	v_pk_fma_f32 v[66:67], v[14:15], v[14:15], v[48:49] op_sel_hi:[1,1,0]
	v_mul_f32_e32 v48, v16, v16
	v_pk_fma_f32 v[68:69], v[16:17], v[16:17], v[48:49] op_sel_hi:[1,1,0]
	s_waitcnt vmcnt(3)
	v_mul_f32_e32 v48, v10, v10
	v_pk_fma_f32 v[70:71], v[10:11], v[10:11], v[48:49] op_sel_hi:[1,1,0]
	v_mul_f32_e32 v48, v12, v12
	v_pk_add_f32 v[50:51], v[50:51], v[50:51] op_sel_hi:[0,1]
	v_pk_fma_f32 v[72:73], v[12:13], v[12:13], v[48:49] op_sel_hi:[1,1,0]
	v_mul_f32_e32 v66, v6, v6
	v_mul_f32_e32 v68, v7, v7
	v_mul_f32_e32 v62, v8, v8
	v_mul_f32_e32 v48, v9, v9
	s_waitcnt vmcnt(2)
	v_mul_f32_e32 v70, v2, v2
	v_mul_f32_e32 v72, v3, v3
	v_mul_f32_e32 v64, v4, v4
	v_mul_f32_e32 v50, v5, v5
	v_pk_add_f32 v[66:67], v[66:67], v[68:69]
	v_pk_add_f32 v[48:49], v[62:63], v[48:49]
	v_pk_add_f32 v[62:63], v[70:71], v[72:73]
	v_pk_add_f32 v[50:51], v[64:65], v[50:51]
	v_pk_add_f32 v[48:49], v[66:67], v[48:49]
	v_pk_add_f32 v[50:51], v[62:63], v[50:51]
	v_mov_b32_e32 v63, v48
	v_mov_b32_e32 v62, v50
	v_mov_b32_e32 v48, v51
	v_pk_add_f32 v[48:49], v[62:63], v[48:49]
	s_add_u32 s28, s22, 0x1000
	s_addc_u32 s29, s23, 0
	global_load_dwordx4 v[62:65], v0, s[24:25] offset:1024
	global_load_dwordx4 v[66:69], v0, s[26:27] offset:1024
	global_load_dwordx4 v[70:73], v0, s[24:25] offset:2048
	global_load_dwordx4 v[74:77], v0, s[26:27] offset:2048
	global_load_dwordx4 v[78:81], v0, s[24:25] offset:3072
	global_load_dwordx4 v[82:85], v0, s[26:27] offset:3072
	global_load_dwordx4 v[86:89], v0, s[22:23]
	global_load_dwordx4 v[90:93], v0, s[28:29]
	global_load_dwordx4 v[94:97], v0, s[22:23] offset:1024
	global_load_dwordx4 v[98:101], v0, s[28:29] offset:1024
	global_load_dwordx4 v[102:105], v0, s[22:23] offset:2048
	global_load_dwordx4 v[106:109], v0, s[28:29] offset:2048
	global_load_dwordx4 v[110:113], v0, s[22:23] offset:3072
	global_load_dwordx4 v[114:117], v0, s[28:29] offset:3072
	s_ashr_i32 s21, s20, 31
	v_readlane_b32 s5, v255, 54
	s_lshl_b64 s[8:9], s[20:21], 11
	v_lshlrev_b32_e32 v118, 1, v34
	s_add_u32 s20, s5, s8
	v_readlane_b32 s5, v255, 55
	ds_bpermute_b32 v51, v35, v49
	ds_bpermute_b32 v50, v35, v48
	s_addc_u32 s21, s5, s9
	s_waitcnt lgkmcnt(0)
	v_pk_add_f32 v[48:49], v[48:49], v[50:51]
	ds_bpermute_b32 v51, v39, v49
	ds_bpermute_b32 v50, v39, v48
	s_mov_b32 s8, 0x3a800000
	s_waitcnt lgkmcnt(0)
	v_pk_add_f32 v[48:49], v[48:49], v[50:51]
	ds_bpermute_b32 v51, v41, v49
	ds_bpermute_b32 v50, v41, v48
	s_waitcnt lgkmcnt(0)
	v_pk_add_f32 v[48:49], v[48:49], v[50:51]
	ds_bpermute_b32 v51, v43, v49
	ds_bpermute_b32 v50, v43, v48
	s_waitcnt lgkmcnt(0)
	v_pk_add_f32 v[48:49], v[48:49], v[50:51]
	ds_bpermute_b32 v51, v52, v49
	ds_bpermute_b32 v50, v52, v48
	s_waitcnt lgkmcnt(0)
	v_pk_add_f32 v[48:49], v[48:49], v[50:51]
	ds_bpermute_b32 v51, v53, v49
	ds_bpermute_b32 v50, v53, v48
	s_waitcnt lgkmcnt(0)
	v_pk_add_f32 v[48:49], v[48:49], v[50:51]
	s_nop 0
	v_pk_fma_f32 v[48:49], v[48:49], s[8:9], v[190:191] op_sel_hi:[1,0,0]
	s_waitcnt vmcnt(0)
	v_mul_f32_e32 v50, 0x4b800000, v49
	v_cmp_gt_f32_e32 vcc, s96, v49
	v_cmp_gt_f32_e64 s[8:9], s96, v48
	v_pk_add_f32 v[60:61], v[60:61], 1.0 op_sel_hi:[1,0]
	v_pk_add_f32 v[58:59], v[58:59], 1.0 op_sel_hi:[1,0]
	v_cndmask_b32_e32 v49, v49, v50, vcc
	v_rsq_f32_e32 v49, v49
	v_mul_f32_e32 v50, 0x4b800000, v48
	v_cndmask_b32_e64 v48, v48, v50, s[8:9]
	v_rsq_f32_e32 v48, v48
	v_mul_f32_e32 v50, 0x45800000, v49
	v_cndmask_b32_e32 v50, v49, v50, vcc
	v_mul_f32_e32 v49, 0x45800000, v48
	v_cndmask_b32_e64 v48, v48, v49, s[8:9]
	v_pk_add_f32 v[68:69], v[68:69], 1.0 op_sel_hi:[1,0]
	v_pk_add_f32 v[66:67], v[66:67], 1.0 op_sel_hi:[1,0]
	v_pk_add_f32 v[76:77], v[76:77], 1.0 op_sel_hi:[1,0]
	v_pk_add_f32 v[74:75], v[74:75], 1.0 op_sel_hi:[1,0]
	v_pk_add_f32 v[84:85], v[84:85], 1.0 op_sel_hi:[1,0]
	v_pk_add_f32 v[82:83], v[82:83], 1.0 op_sel_hi:[1,0]
	v_pk_mul_f32 v[30:31], v[30:31], v[50:51] op_sel_hi:[1,0]
	v_pk_mul_f32 v[32:33], v[32:33], v[50:51] op_sel_hi:[1,0]
	v_pk_mul_f32 v[22:23], v[22:23], v[50:51] op_sel_hi:[1,0]
	v_pk_mul_f32 v[24:25], v[24:25], v[50:51] op_sel_hi:[1,0]
	v_pk_mul_f32 v[14:15], v[14:15], v[50:51] op_sel_hi:[1,0]
	v_pk_mul_f32 v[16:17], v[16:17], v[50:51] op_sel_hi:[1,0]
	v_pk_mul_f32 v[6:7], v[6:7], v[50:51] op_sel_hi:[1,0]
	v_pk_mul_f32 v[8:9], v[8:9], v[50:51] op_sel_hi:[1,0]
	v_pk_fma_f32 v[30:31], v[58:59], v[30:31], v[54:55]
	v_pk_fma_f32 v[32:33], v[60:61], v[32:33], v[56:57]
	v_pk_fma_f32 v[22:23], v[66:67], v[22:23], v[62:63]
	v_pk_fma_f32 v[24:25], v[68:69], v[24:25], v[64:65]
	v_pk_fma_f32 v[14:15], v[74:75], v[14:15], v[70:71]
	v_pk_fma_f32 v[16:17], v[76:77], v[16:17], v[72:73]
	v_pk_fma_f32 v[6:7], v[82:83], v[6:7], v[78:79]
	v_pk_fma_f32 v[8:9], v[84:85], v[8:9], v[80:81]
	v_cvt_pk_bf16_f32 v30, v30, v31
	v_cvt_pk_bf16_f32 v31, v32, v33
	v_cvt_pk_bf16_f32 v22, v22, v23
	v_cvt_pk_bf16_f32 v23, v24, v25
	v_cvt_pk_bf16_f32 v14, v14, v15
	v_cvt_pk_bf16_f32 v15, v16, v17
	v_cvt_pk_bf16_f32 v6, v6, v7
	v_cvt_pk_bf16_f32 v7, v8, v9
	global_store_dwordx2 v[46:47], v[30:31], off sc1
	global_store_dwordx2 v[46:47], v[22:23], off offset:512 sc1
	global_store_dwordx2 v[46:47], v[14:15], off offset:1024 sc1
	global_store_dwordx2 v[46:47], v[6:7], off offset:1536 sc1
	s_andn2_b64 vcc, exec, s[18:19]
	s_cbranch_vccnz .Lpn2_row1_done
	v_pk_add_f32 v[92:93], v[92:93], 1.0 op_sel_hi:[1,0]
	v_pk_add_f32 v[90:91], v[90:91], 1.0 op_sel_hi:[1,0]
	v_pk_add_f32 v[100:101], v[100:101], 1.0 op_sel_hi:[1,0]
	v_pk_add_f32 v[98:99], v[98:99], 1.0 op_sel_hi:[1,0]
	v_pk_add_f32 v[108:109], v[108:109], 1.0 op_sel_hi:[1,0]
	v_pk_add_f32 v[106:107], v[106:107], 1.0 op_sel_hi:[1,0]
	v_pk_add_f32 v[116:117], v[116:117], 1.0 op_sel_hi:[1,0]
	v_pk_add_f32 v[114:115], v[114:115], 1.0 op_sel_hi:[1,0]
	v_pk_mul_f32 v[26:27], v[26:27], v[48:49] op_sel_hi:[1,0]
	v_pk_mul_f32 v[28:29], v[28:29], v[48:49] op_sel_hi:[1,0]
	v_pk_mul_f32 v[18:19], v[18:19], v[48:49] op_sel_hi:[1,0]
	v_pk_mul_f32 v[20:21], v[20:21], v[48:49] op_sel_hi:[1,0]
	v_pk_mul_f32 v[10:11], v[10:11], v[48:49] op_sel_hi:[1,0]
	v_pk_mul_f32 v[12:13], v[12:13], v[48:49] op_sel_hi:[1,0]
	v_pk_mul_f32 v[2:3], v[2:3], v[48:49] op_sel_hi:[1,0]
	v_pk_mul_f32 v[4:5], v[4:5], v[48:49] op_sel_hi:[1,0]
	v_pk_fma_f32 v[26:27], v[26:27], v[90:91], v[86:87]
	v_pk_fma_f32 v[28:29], v[28:29], v[92:93], v[88:89]
	v_pk_fma_f32 v[18:19], v[18:19], v[98:99], v[94:95]
	v_pk_fma_f32 v[20:21], v[20:21], v[100:101], v[96:97]
	v_pk_fma_f32 v[10:11], v[10:11], v[106:107], v[102:103]
	v_pk_fma_f32 v[12:13], v[12:13], v[108:109], v[104:105]
	v_pk_fma_f32 v[2:3], v[2:3], v[114:115], v[110:111]
	v_pk_fma_f32 v[4:5], v[4:5], v[116:117], v[112:113]
	v_cvt_pk_bf16_f32 v26, v26, v27
	v_cvt_pk_bf16_f32 v27, v28, v29
	v_cvt_pk_bf16_f32 v18, v18, v19
	v_cvt_pk_bf16_f32 v19, v20, v21
	v_cvt_pk_bf16_f32 v10, v10, v11
	v_cvt_pk_bf16_f32 v11, v12, v13
	v_cvt_pk_bf16_f32 v2, v2, v3
	v_cvt_pk_bf16_f32 v3, v4, v5
	global_store_dwordx2 v118, v[26:27], s[20:21] sc1
	global_store_dwordx2 v118, v[18:19], s[20:21] offset:512 sc1
	global_store_dwordx2 v118, v[10:11], s[20:21] offset:1024 sc1
	global_store_dwordx2 v118, v[2:3], s[20:21] offset:1536 sc1

.Lwin_norope_0:
	v_cvt_pk_bf16_f32 v126, v126, v127
	v_cvt_pk_bf16_f32 v127, v128, v129
	v_cvt_pk_bf16_f32 v128, v122, v123
	v_cvt_pk_bf16_f32 v129, v124, v125
	v_cvt_pk_bf16_f32 v118, v118, v119
	v_cvt_pk_bf16_f32 v119, v120, v121
	v_cvt_pk_bf16_f32 v120, v114, v115
	v_cvt_pk_bf16_f32 v121, v116, v117
	global_store_dwordx4 v236, v[126:129], s[48:49] sc1
	global_store_dwordx4 v236, v[118:121], s[48:49] offset:64 sc1
	v_add_u32_e32 v234, 0x1800, v235
	global_load_dwordx4 v[114:117], v234, s[78:79] offset:0
	global_load_dwordx4 v[118:121], v234, s[78:79] offset:16
	global_load_dwordx4 v[122:125], v234, s[22:23] offset:0
	global_load_dwordx4 v[126:129], v234, s[22:23] offset:16
	s_waitcnt vmcnt(10)
	v_pk_mul_f32 v[110:111], v[110:111], v[178:179] op_sel:[0,1] op_sel_hi:[1,1]
	v_pk_mul_f32 v[112:113], v[112:113], v[178:179] op_sel:[0,1] op_sel_hi:[1,1]
	v_pk_mul_f32 v[106:107], v[106:107], v[178:179] op_sel:[0,1] op_sel_hi:[1,1]
	v_pk_mul_f32 v[108:109], v[108:109], v[178:179] op_sel:[0,1] op_sel_hi:[1,1]
	v_pk_mul_f32 v[102:103], v[102:103], v[178:179] op_sel:[0,1] op_sel_hi:[1,1]
	v_pk_mul_f32 v[104:105], v[104:105], v[178:179] op_sel:[0,1] op_sel_hi:[1,1]
	v_pk_mul_f32 v[98:99], v[98:99], v[178:179] op_sel:[0,1] op_sel_hi:[1,1]
	v_pk_mul_f32 v[100:101], v[100:101], v[178:179] op_sel:[0,1] op_sel_hi:[1,1]
	v_pk_mul_f32 v[110:111], v[110:111], v[142:143]
	v_pk_mul_f32 v[112:113], v[112:113], v[144:145]
	v_pk_mul_f32 v[106:107], v[106:107], v[138:139]
	v_pk_mul_f32 v[108:109], v[108:109], v[140:141]
	v_pk_mul_f32 v[102:103], v[102:103], v[134:135]
	v_pk_mul_f32 v[104:105], v[104:105], v[136:137]
	v_pk_mul_f32 v[98:99], v[98:99], v[130:131]
	v_pk_mul_f32 v[100:101], v[100:101], v[132:133]
	s_cmp_eq_u32 s20, 0
	s_cbranch_scc1 .Lwin_norope_1
	v_pk_mul_f32 v[192:193], v[102:103], v[170:171]
	v_pk_mul_f32 v[194:195], v[104:105], v[172:173]
	v_pk_mul_f32 v[102:103], v[102:103], v[162:163]
	v_pk_mul_f32 v[104:105], v[104:105], v[164:165]
	v_pk_fma_f32 v[102:103], v[110:111], v[170:171], v[102:103]
	v_pk_fma_f32 v[104:105], v[112:113], v[172:173], v[104:105]
	v_pk_fma_f32 v[110:111], v[110:111], v[162:163], v[192:193] neg_lo:[0,0,1] neg_hi:[0,0,1]
	v_pk_fma_f32 v[112:113], v[112:113], v[164:165], v[194:195] neg_lo:[0,0,1] neg_hi:[0,0,1]
	v_pk_mul_f32 v[192:193], v[98:99], v[174:175]
	v_pk_mul_f32 v[194:195], v[100:101], v[176:177]
	v_pk_mul_f32 v[98:99], v[98:99], v[166:167]
	v_pk_mul_f32 v[100:101], v[100:101], v[168:169]
	v_pk_fma_f32 v[98:99], v[106:107], v[174:175], v[98:99]
	v_pk_fma_f32 v[100:101], v[108:109], v[176:177], v[100:101]
	v_pk_fma_f32 v[106:107], v[106:107], v[166:167], v[192:193] neg_lo:[0,0,1] neg_hi:[0,0,1]
	v_pk_fma_f32 v[108:109], v[108:109], v[168:169], v[194:195] neg_lo:[0,0,1] neg_hi:[0,0,1]
.Lwin_norope_1:
	v_cvt_pk_bf16_f32 v110, v110, v111
	v_cvt_pk_bf16_f32 v111, v112, v113
	v_cvt_pk_bf16_f32 v112, v106, v107
	v_cvt_pk_bf16_f32 v113, v108, v109
	v_cvt_pk_bf16_f32 v102, v102, v103
	v_cvt_pk_bf16_f32 v103, v104, v105
	v_cvt_pk_bf16_f32 v104, v98, v99
	v_cvt_pk_bf16_f32 v105, v100, v101
	s_lshl_b32 s27, 16, s13
	v_add_u32_e32 v237, s27, v236
	global_store_dwordx4 v237, v[110:113], s[48:49] sc1
	global_store_dwordx4 v237, v[102:105], s[48:49] offset:64 sc1
	v_add_u32_e32 v234, 0x4000, v235
	global_load_dwordx4 v[98:101], v234, s[78:79] offset:0
	global_load_dwordx4 v[102:105], v234, s[78:79] offset:16
	global_load_dwordx4 v[106:109], v234, s[22:23] offset:0
	global_load_dwordx4 v[110:113], v234, s[22:23] offset:16
	s_waitcnt vmcnt(12)
	v_pk_mul_f32 v[94:95], v[94:95], v[180:181] op_sel_hi:[1,0]
	v_pk_mul_f32 v[96:97], v[96:97], v[180:181] op_sel_hi:[1,0]
	v_pk_mul_f32 v[90:91], v[90:91], v[180:181] op_sel_hi:[1,0]
	v_pk_mul_f32 v[92:93], v[92:93], v[180:181] op_sel_hi:[1,0]
	v_pk_mul_f32 v[86:87], v[86:87], v[180:181] op_sel_hi:[1,0]
	v_pk_mul_f32 v[88:89], v[88:89], v[180:181] op_sel_hi:[1,0]
	v_pk_mul_f32 v[82:83], v[82:83], v[180:181] op_sel_hi:[1,0]
	v_pk_mul_f32 v[84:85], v[84:85], v[180:181] op_sel_hi:[1,0]
	v_pk_mul_f32 v[94:95], v[94:95], v[142:143]
	v_pk_mul_f32 v[96:97], v[96:97], v[144:145]
	v_pk_mul_f32 v[90:91], v[90:91], v[138:139]
	v_pk_mul_f32 v[92:93], v[92:93], v[140:141]
	v_pk_mul_f32 v[86:87], v[86:87], v[134:135]
	v_pk_mul_f32 v[88:89], v[88:89], v[136:137]
	v_pk_mul_f32 v[82:83], v[82:83], v[130:131]
	v_pk_mul_f32 v[84:85], v[84:85], v[132:133]
	s_cmp_eq_u32 s20, 0
	s_cbranch_scc1 .Lwin_norope_2
	v_pk_mul_f32 v[192:193], v[86:87], v[214:215]
	v_pk_mul_f32 v[194:195], v[88:89], v[216:217]
	v_pk_mul_f32 v[86:87], v[86:87], v[206:207]
	v_pk_mul_f32 v[88:89], v[88:89], v[208:209]
	v_pk_fma_f32 v[86:87], v[94:95], v[214:215], v[86:87]
	v_pk_fma_f32 v[88:89], v[96:97], v[216:217], v[88:89]
	v_pk_fma_f32 v[94:95], v[94:95], v[206:207], v[192:193] neg_lo:[0,0,1] neg_hi:[0,0,1]
	v_pk_fma_f32 v[96:97], v[96:97], v[208:209], v[194:195] neg_lo:[0,0,1] neg_hi:[0,0,1]
	v_pk_mul_f32 v[192:193], v[82:83], v[218:219]
	v_pk_mul_f32 v[194:195], v[84:85], v[220:221]
	v_pk_mul_f32 v[82:83], v[82:83], v[210:211]
	v_pk_mul_f32 v[84:85], v[84:85], v[212:213]
	v_pk_fma_f32 v[82:83], v[90:91], v[218:219], v[82:83]
	v_pk_fma_f32 v[84:85], v[92:93], v[220:221], v[84:85]
	v_pk_fma_f32 v[90:91], v[90:91], v[210:211], v[192:193] neg_lo:[0,0,1] neg_hi:[0,0,1]
	v_pk_fma_f32 v[92:93], v[92:93], v[212:213], v[194:195] neg_lo:[0,0,1] neg_hi:[0,0,1]
.Lwin_norope_2:
	v_cvt_pk_bf16_f32 v94, v94, v95
	v_cvt_pk_bf16_f32 v95, v96, v97
	v_cvt_pk_bf16_f32 v96, v90, v91
	v_cvt_pk_bf16_f32 v97, v92, v93
	v_cvt_pk_bf16_f32 v86, v86, v87
	v_cvt_pk_bf16_f32 v87, v88, v89
	v_cvt_pk_bf16_f32 v88, v82, v83
	v_cvt_pk_bf16_f32 v89, v84, v85
	s_lshl_b32 s27, 32, s13
	v_add_u32_e32 v237, s27, v236
	global_store_dwordx4 v237, v[94:97], s[48:49] sc1
	global_store_dwordx4 v237, v[86:89], s[48:49] offset:64 sc1
	v_add_u32_e32 v234, 0x4800, v235
	global_load_dwordx4 v[82:85], v234, s[78:79] offset:0
	global_load_dwordx4 v[86:89], v234, s[78:79] offset:16
	global_load_dwordx4 v[90:93], v234, s[22:23] offset:0
	global_load_dwordx4 v[94:97], v234, s[22:23] offset:16
	s_waitcnt vmcnt(12)
	v_pk_mul_f32 v[78:79], v[78:79], v[180:181] op_sel:[0,1] op_sel_hi:[1,1]
	v_pk_mul_f32 v[80:81], v[80:81], v[180:181] op_sel:[0,1] op_sel_hi:[1,1]
	v_pk_mul_f32 v[74:75], v[74:75], v[180:181] op_sel:[0,1] op_sel_hi:[1,1]
	v_pk_mul_f32 v[76:77], v[76:77], v[180:181] op_sel:[0,1] op_sel_hi:[1,1]
	v_pk_mul_f32 v[70:71], v[70:71], v[180:181] op_sel:[0,1] op_sel_hi:[1,1]
	v_pk_mul_f32 v[72:73], v[72:73], v[180:181] op_sel:[0,1] op_sel_hi:[1,1]
	v_pk_mul_f32 v[66:67], v[66:67], v[180:181] op_sel:[0,1] op_sel_hi:[1,1]
	v_pk_mul_f32 v[68:69], v[68:69], v[180:181] op_sel:[0,1] op_sel_hi:[1,1]
	v_pk_mul_f32 v[78:79], v[78:79], v[142:143]
	v_pk_mul_f32 v[80:81], v[80:81], v[144:145]
	v_pk_mul_f32 v[74:75], v[74:75], v[138:139]
	v_pk_mul_f32 v[76:77], v[76:77], v[140:141]
	v_pk_mul_f32 v[70:71], v[70:71], v[134:135]
	v_pk_mul_f32 v[72:73], v[72:73], v[136:137]
	v_pk_mul_f32 v[66:67], v[66:67], v[130:131]
	v_pk_mul_f32 v[68:69], v[68:69], v[132:133]
	s_cmp_eq_u32 s20, 0
	s_cbranch_scc1 .Lwin_norope_3
	v_pk_mul_f32 v[192:193], v[70:71], v[122:123]
	v_pk_mul_f32 v[194:195], v[72:73], v[124:125]
	v_pk_mul_f32 v[70:71], v[70:71], v[114:115]
	v_pk_mul_f32 v[72:73], v[72:73], v[116:117]
	v_pk_fma_f32 v[70:71], v[78:79], v[122:123], v[70:71]
	v_pk_fma_f32 v[72:73], v[80:81], v[124:125], v[72:73]
	v_pk_fma_f32 v[78:79], v[78:79], v[114:115], v[192:193] neg_lo:[0,0,1] neg_hi:[0,0,1]
	v_pk_fma_f32 v[80:81], v[80:81], v[116:117], v[194:195] neg_lo:[0,0,1] neg_hi:[0,0,1]
	v_pk_mul_f32 v[192:193], v[66:67], v[126:127]
	v_pk_mul_f32 v[194:195], v[68:69], v[128:129]
	v_pk_mul_f32 v[66:67], v[66:67], v[118:119]
	v_pk_mul_f32 v[68:69], v[68:69], v[120:121]
	v_pk_fma_f32 v[66:67], v[74:75], v[126:127], v[66:67]
	v_pk_fma_f32 v[68:69], v[76:77], v[128:129], v[68:69]
	v_pk_fma_f32 v[74:75], v[74:75], v[118:119], v[192:193] neg_lo:[0,0,1] neg_hi:[0,0,1]
	v_pk_fma_f32 v[76:77], v[76:77], v[120:121], v[194:195] neg_lo:[0,0,1] neg_hi:[0,0,1]
.Lwin_norope_3:
	v_cvt_pk_bf16_f32 v78, v78, v79
	v_cvt_pk_bf16_f32 v79, v80, v81
	v_cvt_pk_bf16_f32 v80, v74, v75
	v_cvt_pk_bf16_f32 v81, v76, v77
	v_cvt_pk_bf16_f32 v70, v70, v71
	v_cvt_pk_bf16_f32 v71, v72, v73
	v_cvt_pk_bf16_f32 v72, v66, v67
	v_cvt_pk_bf16_f32 v73, v68, v69
	s_lshl_b32 s27, 48, s13
	v_add_u32_e32 v237, s27, v236
	global_store_dwordx4 v237, v[78:81], s[48:49] sc1
	global_store_dwordx4 v237, v[70:73], s[48:49] offset:64 sc1
	v_add_u32_e32 v234, 0x5000, v235
	global_load_dwordx4 v[66:69], v234, s[78:79] offset:0
	global_load_dwordx4 v[70:73], v234, s[78:79] offset:16
	global_load_dwordx4 v[74:77], v234, s[22:23] offset:0
	global_load_dwordx4 v[78:81], v234, s[22:23] offset:16
	s_waitcnt vmcnt(12)
	v_pk_mul_f32 v[62:63], v[62:63], v[182:183] op_sel_hi:[1,0]
	v_pk_mul_f32 v[64:65], v[64:65], v[182:183] op_sel_hi:[1,0]
	v_pk_mul_f32 v[58:59], v[58:59], v[182:183] op_sel_hi:[1,0]
	v_pk_mul_f32 v[60:61], v[60:61], v[182:183] op_sel_hi:[1,0]
	v_pk_mul_f32 v[54:55], v[54:55], v[182:183] op_sel_hi:[1,0]
	v_pk_mul_f32 v[56:57], v[56:57], v[182:183] op_sel_hi:[1,0]
	v_pk_mul_f32 v[50:51], v[50:51], v[182:183] op_sel_hi:[1,0]
	v_pk_mul_f32 v[52:53], v[52:53], v[182:183] op_sel_hi:[1,0]
	v_pk_mul_f32 v[62:63], v[62:63], v[142:143]
	v_pk_mul_f32 v[64:65], v[64:65], v[144:145]
	v_pk_mul_f32 v[58:59], v[58:59], v[138:139]
	v_pk_mul_f32 v[60:61], v[60:61], v[140:141]
	v_pk_mul_f32 v[54:55], v[54:55], v[134:135]
	v_pk_mul_f32 v[56:57], v[56:57], v[136:137]
	v_pk_mul_f32 v[50:51], v[50:51], v[130:131]
	v_pk_mul_f32 v[52:53], v[52:53], v[132:133]
	s_cmp_eq_u32 s20, 0
	s_cbranch_scc1 .Lwin_norope_4
	v_pk_mul_f32 v[192:193], v[54:55], v[106:107]
	v_pk_mul_f32 v[194:195], v[56:57], v[108:109]
	v_pk_mul_f32 v[54:55], v[54:55], v[98:99]
	v_pk_mul_f32 v[56:57], v[56:57], v[100:101]
	v_pk_fma_f32 v[54:55], v[62:63], v[106:107], v[54:55]
	v_pk_fma_f32 v[56:57], v[64:65], v[108:109], v[56:57]
	v_pk_fma_f32 v[62:63], v[62:63], v[98:99], v[192:193] neg_lo:[0,0,1] neg_hi:[0,0,1]
	v_pk_fma_f32 v[64:65], v[64:65], v[100:101], v[194:195] neg_lo:[0,0,1] neg_hi:[0,0,1]
	v_pk_mul_f32 v[192:193], v[50:51], v[110:111]
	v_pk_mul_f32 v[194:195], v[52:53], v[112:113]
	v_pk_mul_f32 v[50:51], v[50:51], v[102:103]
	v_pk_mul_f32 v[52:53], v[52:53], v[104:105]
	v_pk_fma_f32 v[50:51], v[58:59], v[110:111], v[50:51]
	v_pk_fma_f32 v[52:53], v[60:61], v[112:113], v[52:53]
	v_pk_fma_f32 v[58:59], v[58:59], v[102:103], v[192:193] neg_lo:[0,0,1] neg_hi:[0,0,1]
	v_pk_fma_f32 v[60:61], v[60:61], v[104:105], v[194:195] neg_lo:[0,0,1] neg_hi:[0,0,1]
.Lwin_norope_4:
	v_cvt_pk_bf16_f32 v62, v62, v63
	v_cvt_pk_bf16_f32 v63, v64, v65
	v_cvt_pk_bf16_f32 v64, v58, v59
	v_cvt_pk_bf16_f32 v65, v60, v61
	v_cvt_pk_bf16_f32 v54, v54, v55
	v_cvt_pk_bf16_f32 v55, v56, v57
	v_cvt_pk_bf16_f32 v56, v50, v51
	v_cvt_pk_bf16_f32 v57, v52, v53
	s_lshl_b32 s27, 128, s13
	v_add_u32_e32 v237, s27, v236
	global_store_dwordx4 v237, v[62:65], s[48:49] sc1
	global_store_dwordx4 v237, v[54:57], s[48:49] offset:64 sc1
	v_add_u32_e32 v234, 0x5800, v235
	global_load_dwordx4 v[50:53], v234, s[78:79] offset:0
	global_load_dwordx4 v[54:57], v234, s[78:79] offset:16
	global_load_dwordx4 v[58:61], v234, s[22:23] offset:0
	global_load_dwordx4 v[62:65], v234, s[22:23] offset:16
	s_waitcnt vmcnt(12)
	v_pk_mul_f32 v[46:47], v[46:47], v[182:183] op_sel:[0,1] op_sel_hi:[1,1]
	v_pk_mul_f32 v[48:49], v[48:49], v[182:183] op_sel:[0,1] op_sel_hi:[1,1]
	v_pk_mul_f32 v[42:43], v[42:43], v[182:183] op_sel:[0,1] op_sel_hi:[1,1]
	v_pk_mul_f32 v[44:45], v[44:45], v[182:183] op_sel:[0,1] op_sel_hi:[1,1]
	v_pk_mul_f32 v[38:39], v[38:39], v[182:183] op_sel:[0,1] op_sel_hi:[1,1]
	v_pk_mul_f32 v[40:41], v[40:41], v[182:183] op_sel:[0,1] op_sel_hi:[1,1]
	v_pk_mul_f32 v[34:35], v[34:35], v[182:183] op_sel:[0,1] op_sel_hi:[1,1]
	v_pk_mul_f32 v[36:37], v[36:37], v[182:183] op_sel:[0,1] op_sel_hi:[1,1]
	v_pk_mul_f32 v[46:47], v[46:47], v[142:143]
	v_pk_mul_f32 v[48:49], v[48:49], v[144:145]
	v_pk_mul_f32 v[42:43], v[42:43], v[138:139]
	v_pk_mul_f32 v[44:45], v[44:45], v[140:141]
	v_pk_mul_f32 v[38:39], v[38:39], v[134:135]
	v_pk_mul_f32 v[40:41], v[40:41], v[136:137]
	v_pk_mul_f32 v[34:35], v[34:35], v[130:131]
	v_pk_mul_f32 v[36:37], v[36:37], v[132:133]
	s_cmp_eq_u32 s20, 0
	s_cbranch_scc1 .Lwin_norope_5
	v_pk_mul_f32 v[192:193], v[38:39], v[90:91]
	v_pk_mul_f32 v[194:195], v[40:41], v[92:93]
	v_pk_mul_f32 v[38:39], v[38:39], v[82:83]
	v_pk_mul_f32 v[40:41], v[40:41], v[84:85]
	v_pk_fma_f32 v[38:39], v[46:47], v[90:91], v[38:39]
	v_pk_fma_f32 v[40:41], v[48:49], v[92:93], v[40:41]
	v_pk_fma_f32 v[46:47], v[46:47], v[82:83], v[192:193] neg_lo:[0,0,1] neg_hi:[0,0,1]
	v_pk_fma_f32 v[48:49], v[48:49], v[84:85], v[194:195] neg_lo:[0,0,1] neg_hi:[0,0,1]
	v_pk_mul_f32 v[192:193], v[34:35], v[94:95]
	v_pk_mul_f32 v[194:195], v[36:37], v[96:97]
	v_pk_mul_f32 v[34:35], v[34:35], v[86:87]
	v_pk_mul_f32 v[36:37], v[36:37], v[88:89]
	v_pk_fma_f32 v[34:35], v[42:43], v[94:95], v[34:35]
	v_pk_fma_f32 v[36:37], v[44:45], v[96:97], v[36:37]
	v_pk_fma_f32 v[42:43], v[42:43], v[86:87], v[192:193] neg_lo:[0,0,1] neg_hi:[0,0,1]
	v_pk_fma_f32 v[44:45], v[44:45], v[88:89], v[194:195] neg_lo:[0,0,1] neg_hi:[0,0,1]
.Lwin_norope_5:
	v_cvt_pk_bf16_f32 v46, v46, v47
	v_cvt_pk_bf16_f32 v47, v48, v49
	v_cvt_pk_bf16_f32 v48, v42, v43
	v_cvt_pk_bf16_f32 v49, v44, v45
	v_cvt_pk_bf16_f32 v38, v38, v39
	v_cvt_pk_bf16_f32 v39, v40, v41
	v_cvt_pk_bf16_f32 v40, v34, v35
	v_cvt_pk_bf16_f32 v41, v36, v37
	s_lshl_b32 s27, 144, s13
	v_add_u32_e32 v237, s27, v236
	global_store_dwordx4 v237, v[46:49], s[48:49] sc1
	global_store_dwordx4 v237, v[38:41], s[48:49] offset:64 sc1
	s_waitcnt vmcnt(8)
	v_pk_mul_f32 v[30:31], v[30:31], v[184:185] op_sel_hi:[1,0]
	v_pk_mul_f32 v[32:33], v[32:33], v[184:185] op_sel_hi:[1,0]
	v_pk_mul_f32 v[26:27], v[26:27], v[184:185] op_sel_hi:[1,0]
	v_pk_mul_f32 v[28:29], v[28:29], v[184:185] op_sel_hi:[1,0]
	v_pk_mul_f32 v[22:23], v[22:23], v[184:185] op_sel_hi:[1,0]
	v_pk_mul_f32 v[24:25], v[24:25], v[184:185] op_sel_hi:[1,0]
	v_pk_mul_f32 v[18:19], v[18:19], v[184:185] op_sel_hi:[1,0]
	v_pk_mul_f32 v[20:21], v[20:21], v[184:185] op_sel_hi:[1,0]
	v_pk_mul_f32 v[30:31], v[30:31], v[142:143]
	v_pk_mul_f32 v[32:33], v[32:33], v[144:145]
	v_pk_mul_f32 v[26:27], v[26:27], v[138:139]
	v_pk_mul_f32 v[28:29], v[28:29], v[140:141]
	v_pk_mul_f32 v[22:23], v[22:23], v[134:135]
	v_pk_mul_f32 v[24:25], v[24:25], v[136:137]
	v_pk_mul_f32 v[18:19], v[18:19], v[130:131]
	v_pk_mul_f32 v[20:21], v[20:21], v[132:133]
	s_cmp_eq_u32 s20, 0
	s_cbranch_scc1 .Lwin_norope_6
	v_pk_mul_f32 v[192:193], v[22:23], v[74:75]
	v_pk_mul_f32 v[194:195], v[24:25], v[76:77]
	v_pk_mul_f32 v[22:23], v[22:23], v[66:67]
	v_pk_mul_f32 v[24:25], v[24:25], v[68:69]
	v_pk_fma_f32 v[22:23], v[30:31], v[74:75], v[22:23]
	v_pk_fma_f32 v[24:25], v[32:33], v[76:77], v[24:25]
	v_pk_fma_f32 v[30:31], v[30:31], v[66:67], v[192:193] neg_lo:[0,0,1] neg_hi:[0,0,1]
	v_pk_fma_f32 v[32:33], v[32:33], v[68:69], v[194:195] neg_lo:[0,0,1] neg_hi:[0,0,1]
	v_pk_mul_f32 v[192:193], v[18:19], v[78:79]
	v_pk_mul_f32 v[194:195], v[20:21], v[80:81]
	v_pk_mul_f32 v[18:19], v[18:19], v[70:71]
	v_pk_mul_f32 v[20:21], v[20:21], v[72:73]
	v_pk_fma_f32 v[18:19], v[26:27], v[78:79], v[18:19]
	v_pk_fma_f32 v[20:21], v[28:29], v[80:81], v[20:21]
	v_pk_fma_f32 v[26:27], v[26:27], v[70:71], v[192:193] neg_lo:[0,0,1] neg_hi:[0,0,1]
	v_pk_fma_f32 v[28:29], v[28:29], v[72:73], v[194:195] neg_lo:[0,0,1] neg_hi:[0,0,1]
.Lwin_norope_6:
	v_cvt_pk_bf16_f32 v30, v30, v31
	v_cvt_pk_bf16_f32 v31, v32, v33
	v_cvt_pk_bf16_f32 v32, v26, v27
	v_cvt_pk_bf16_f32 v33, v28, v29
	v_cvt_pk_bf16_f32 v22, v22, v23
	v_cvt_pk_bf16_f32 v23, v24, v25
	v_cvt_pk_bf16_f32 v24, v18, v19
	v_cvt_pk_bf16_f32 v25, v20, v21
	s_lshl_b32 s27, 160, s13
	v_add_u32_e32 v237, s27, v236
	global_store_dwordx4 v237, v[30:33], s[48:49] sc1
	global_store_dwordx4 v237, v[22:25], s[48:49] offset:64 sc1
	s_waitcnt vmcnt(4)
	v_pk_mul_f32 v[14:15], v[14:15], v[184:185] op_sel:[0,1] op_sel_hi:[1,1]
	v_pk_mul_f32 v[16:17], v[16:17], v[184:185] op_sel:[0,1] op_sel_hi:[1,1]
	v_pk_mul_f32 v[10:11], v[10:11], v[184:185] op_sel:[0,1] op_sel_hi:[1,1]
	v_pk_mul_f32 v[12:13], v[12:13], v[184:185] op_sel:[0,1] op_sel_hi:[1,1]
	v_pk_mul_f32 v[6:7], v[6:7], v[184:185] op_sel:[0,1] op_sel_hi:[1,1]
	v_pk_mul_f32 v[8:9], v[8:9], v[184:185] op_sel:[0,1] op_sel_hi:[1,1]
	v_pk_mul_f32 v[2:3], v[2:3], v[184:185] op_sel:[0,1] op_sel_hi:[1,1]
	v_pk_mul_f32 v[4:5], v[4:5], v[184:185] op_sel:[0,1] op_sel_hi:[1,1]
	v_pk_mul_f32 v[14:15], v[14:15], v[142:143]
	v_pk_mul_f32 v[16:17], v[16:17], v[144:145]
	v_pk_mul_f32 v[10:11], v[10:11], v[138:139]
	v_pk_mul_f32 v[12:13], v[12:13], v[140:141]
	v_pk_mul_f32 v[6:7], v[6:7], v[134:135]
	v_pk_mul_f32 v[8:9], v[8:9], v[136:137]
	v_pk_mul_f32 v[2:3], v[2:3], v[130:131]
	v_pk_mul_f32 v[4:5], v[4:5], v[132:133]
	s_cmp_eq_u32 s20, 0
	s_cbranch_scc1 .Lwin_norope_7
	v_pk_mul_f32 v[192:193], v[6:7], v[58:59]
	v_pk_mul_f32 v[194:195], v[8:9], v[60:61]
	v_pk_mul_f32 v[6:7], v[6:7], v[50:51]
	v_pk_mul_f32 v[8:9], v[8:9], v[52:53]
	v_pk_fma_f32 v[6:7], v[14:15], v[58:59], v[6:7]
	v_pk_fma_f32 v[8:9], v[16:17], v[60:61], v[8:9]
	v_pk_fma_f32 v[14:15], v[14:15], v[50:51], v[192:193] neg_lo:[0,0,1] neg_hi:[0,0,1]
	v_pk_fma_f32 v[16:17], v[16:17], v[52:53], v[194:195] neg_lo:[0,0,1] neg_hi:[0,0,1]
	v_pk_mul_f32 v[192:193], v[2:3], v[62:63]
	v_pk_mul_f32 v[194:195], v[4:5], v[64:65]
	v_pk_mul_f32 v[2:3], v[2:3], v[54:55]
	v_pk_mul_f32 v[4:5], v[4:5], v[56:57]
	v_pk_fma_f32 v[2:3], v[10:11], v[62:63], v[2:3]
	v_pk_fma_f32 v[4:5], v[12:13], v[64:65], v[4:5]
	v_pk_fma_f32 v[10:11], v[10:11], v[54:55], v[192:193] neg_lo:[0,0,1] neg_hi:[0,0,1]
	v_pk_fma_f32 v[12:13], v[12:13], v[56:57], v[194:195] neg_lo:[0,0,1] neg_hi:[0,0,1]
.Lwin_norope_7:
	v_cvt_pk_bf16_f32 v14, v14, v15
	v_cvt_pk_bf16_f32 v15, v16, v17
	v_cvt_pk_bf16_f32 v16, v10, v11
	v_cvt_pk_bf16_f32 v17, v12, v13
	v_cvt_pk_bf16_f32 v6, v6, v7
	v_cvt_pk_bf16_f32 v7, v8, v9
	v_cvt_pk_bf16_f32 v8, v2, v3
	v_cvt_pk_bf16_f32 v9, v4, v5
	s_lshl_b32 s27, 176, s13
	v_add_u32_e32 v237, s27, v236
	global_store_dwordx4 v237, v[14:17], s[48:49] sc1
	global_store_dwordx4 v237, v[6:9], s[48:49] offset:64 sc1
	s_mov_b64 s[58:59], 0
.LBB0_483:
	s_and_b64 vcc, exec, s[58:59]
	s_cbranch_vccz .LBB0_485
	s_add_i32 s8, s3, 0xffffc000
	s_ashr_i32 s9, s3, 12
	s_lshr_b32 s8, s8, 8
	s_mulk_i32 s9, 0x1100
	s_mulk_i32 s8, 0x1100
	s_addk_i32 s9, 0x100
	v_and_b32_e32 v0, 0xfcf, v204
	v_and_b32_e32 v130, 0xcf, v204
	s_movk_i32 s10, 0x4000
	v_add_u32_e32 v0, s9, v0
	v_or_b32_e32 v130, s8, v130
	v_cmp_gt_i32_e32 vcc, s10, v204
	s_mov_b64 s[14:15], 0x71fff00
	s_mov_b32 s13, 0x71ff000
	v_cndmask_b32_e32 v130, v130, v0, vcc
	v_ashrrev_i32_e32 v131, 31, v130
	v_lshlrev_b64 v[130:131], 8, v[130:131]
	v_lshl_add_u64 v[130:131], s[24:25], 0, v[130:131]
	v_lshlrev_b32_e32 v0, 1, v247
	v_lshl_add_u64 v[134:135], v[130:131], 0, v[0:1]
	v_lshl_add_u64 v[136:137], v[134:135], 0, s[14:15]
	v_add_co_u32_e32 v134, vcc, s13, v134
	v_cvt_pk_bf16_f32 v130, v126, v127
	v_cvt_pk_bf16_f32 v131, v128, v129
	v_cvt_pk_bf16_f32 v132, v122, v123
	v_cvt_pk_bf16_f32 v133, v124, v125
	v_addc_co_u32_e32 v135, vcc, 0, v135, vcc
	global_store_dwordx4 v[134:135], v[130:133], off offset:3840 sc1
	s_movk_i32 s11, 0xfdf
	s_movk_i32 s81, 0x4000
	v_cvt_pk_bf16_f32 v130, v118, v119
	v_cvt_pk_bf16_f32 v131, v120, v121
	v_cvt_pk_bf16_f32 v132, v114, v115
	v_cvt_pk_bf16_f32 v133, v116, v117
	global_store_dwordx4 v[136:137], v[130:133], off offset:64 sc1
	s_nop 1
	v_bitop3_b32 v131, v204, s11, 16 bitop3:0xc8
	s_movk_i32 s11, 0xdf
	v_or_b32_e32 v130, 16, v204
	v_bitop3_b32 v132, v204, s11, 16 bitop3:0xc8
	v_add_u32_e32 v131, s9, v131
	v_or_b32_e32 v132, s8, v132
	v_cmp_gt_i32_e32 vcc, s10, v130
	v_cvt_pk_bf16_f32 v133, v108, v109
	s_movk_i32 s11, 0xfef
	v_cndmask_b32_e32 v130, v132, v131, vcc
	v_ashrrev_i32_e32 v131, 31, v130
	v_lshlrev_b64 v[130:131], 8, v[130:131]
	v_lshl_add_u64 v[130:131], s[24:25], 0, v[130:131]
	v_lshl_add_u64 v[134:135], v[130:131], 0, v[0:1]
	v_lshl_add_u64 v[136:137], v[134:135], 0, s[14:15]
	v_add_co_u32_e32 v134, vcc, s13, v134
	v_cvt_pk_bf16_f32 v130, v110, v111
	v_cvt_pk_bf16_f32 v131, v112, v113
	v_cvt_pk_bf16_f32 v132, v106, v107
	v_addc_co_u32_e32 v135, vcc, 0, v135, vcc
	global_store_dwordx4 v[134:135], v[130:133], off offset:3840 sc1
	s_nop 1
	v_cvt_pk_bf16_f32 v130, v102, v103
	v_cvt_pk_bf16_f32 v131, v104, v105
	v_cvt_pk_bf16_f32 v132, v98, v99
	v_cvt_pk_bf16_f32 v133, v100, v101
	global_store_dwordx4 v[136:137], v[130:133], off offset:64 sc1
	s_nop 1
	v_bitop3_b32 v131, v204, s11, 32 bitop3:0xc8
	s_movk_i32 s11, 0xef
	v_or_b32_e32 v130, 32, v204
	v_bitop3_b32 v132, v204, s11, 32 bitop3:0xc8
	v_add_u32_e32 v131, s9, v131
	v_or_b32_e32 v132, s8, v132
	v_cmp_gt_i32_e32 vcc, s10, v130
	v_cvt_pk_bf16_f32 v133, v92, v93
	s_nop 0
	v_cndmask_b32_e32 v130, v132, v131, vcc
	v_ashrrev_i32_e32 v131, 31, v130
	v_lshlrev_b64 v[130:131], 8, v[130:131]
	v_lshl_add_u64 v[130:131], s[24:25], 0, v[130:131]
	v_lshl_add_u64 v[134:135], v[130:131], 0, v[0:1]
	v_lshl_add_u64 v[136:137], v[134:135], 0, s[14:15]
	v_add_co_u32_e32 v134, vcc, s13, v134
	v_cvt_pk_bf16_f32 v130, v94, v95
	v_cvt_pk_bf16_f32 v131, v96, v97
	v_cvt_pk_bf16_f32 v132, v90, v91
	v_addc_co_u32_e32 v135, vcc, 0, v135, vcc
	global_store_dwordx4 v[134:135], v[130:133], off offset:3840 sc1
	s_nop 1
	v_cvt_pk_bf16_f32 v130, v86, v87
	v_cvt_pk_bf16_f32 v131, v88, v89
	v_cvt_pk_bf16_f32 v132, v82, v83
	v_cvt_pk_bf16_f32 v133, v84, v85
	global_store_dwordx4 v[136:137], v[130:133], off offset:64 sc1
	s_nop 1
	v_bitop3_b32 v131, v204, s82, 48 bitop3:0xc8
	v_add_u32_e32 v131, s9, v131
	s_movk_i32 s9, 0xff
	v_or_b32_e32 v130, 48, v204
	v_bitop3_b32 v132, v204, s9, 48 bitop3:0xc8
	v_or_b32_e32 v132, s8, v132
	v_cmp_gt_i32_e32 vcc, s10, v130
	v_cvt_pk_bf16_f32 v133, v76, v77
	s_add_i32 s8, s3, 0xffffc080
	v_cndmask_b32_e32 v130, v132, v131, vcc
	v_ashrrev_i32_e32 v131, 31, v130
	v_lshlrev_b64 v[130:131], 8, v[130:131]
	v_lshl_add_u64 v[130:131], s[24:25], 0, v[130:131]
	v_lshl_add_u64 v[134:135], v[130:131], 0, v[0:1]
	v_lshl_add_u64 v[136:137], v[134:135], 0, s[14:15]
	v_add_co_u32_e32 v134, vcc, s13, v134
	v_cvt_pk_bf16_f32 v130, v78, v79
	v_cvt_pk_bf16_f32 v131, v80, v81
	v_cvt_pk_bf16_f32 v132, v74, v75
	v_addc_co_u32_e32 v135, vcc, 0, v135, vcc
	global_store_dwordx4 v[134:135], v[130:133], off offset:3840 sc1
	s_lshr_b32 s8, s8, 8
	s_movk_i32 s9, 0x1100
	v_cvt_pk_bf16_f32 v130, v70, v71
	v_cvt_pk_bf16_f32 v131, v72, v73
	v_cvt_pk_bf16_f32 v132, v66, v67
	v_cvt_pk_bf16_f32 v133, v68, v69
	global_store_dwordx4 v[136:137], v[130:133], off offset:64 sc1
	s_mulk_i32 s8, 0x1100
	s_nop 0
	v_add_u32_e32 v130, 0x80, v204
	v_ashrrev_i32_e32 v131, 12, v130
	v_mov_b32_e32 v132, 0x100
	v_mad_i32_i24 v138, v131, s9, v132
	v_and_b32_e32 v131, 0xfcf, v130
	v_and_b32_e32 v130, 0xcf, v130
	s_movk_i32 s9, 0x3f80
	v_add_u32_e32 v131, v138, v131
	v_or_b32_e32 v130, s8, v130
	v_cmp_gt_i32_e32 vcc, s9, v204
	v_cvt_pk_bf16_f32 v132, v58, v59
	v_cvt_pk_bf16_f32 v133, v60, v61
	v_cndmask_b32_e32 v130, v130, v131, vcc
	v_ashrrev_i32_e32 v131, 31, v130
	v_lshlrev_b64 v[130:131], 8, v[130:131]
	v_lshl_add_u64 v[130:131], s[24:25], 0, v[130:131]
	v_lshl_add_u64 v[134:135], v[130:131], 0, v[0:1]
	v_lshl_add_u64 v[136:137], v[134:135], 0, s[14:15]
	v_add_co_u32_e32 v134, vcc, s13, v134
	v_cvt_pk_bf16_f32 v130, v62, v63
	v_cvt_pk_bf16_f32 v131, v64, v65
	v_addc_co_u32_e32 v135, vcc, 0, v135, vcc
	global_store_dwordx4 v[134:135], v[130:133], off offset:3840 sc1
	s_movk_i32 s9, 0x3f70
	v_cmp_gt_i32_e32 vcc, s9, v204
	v_cvt_pk_bf16_f32 v130, v54, v55
	v_cvt_pk_bf16_f32 v131, v56, v57
	v_cvt_pk_bf16_f32 v132, v50, v51
	v_cvt_pk_bf16_f32 v133, v52, v53
	global_store_dwordx4 v[136:137], v[130:133], off offset:64 sc1
	s_movk_i32 s9, 0x3f60
	s_nop 0
	v_add_u32_e32 v130, 0x90, v204
	v_and_b32_e32 v131, 0xfdf, v130
	v_and_b32_e32 v130, 0xdf, v130
	v_add_u32_e32 v131, v138, v131
	v_or_b32_e32 v130, s8, v130
	v_cndmask_b32_e32 v130, v130, v131, vcc
	v_ashrrev_i32_e32 v131, 31, v130
	v_lshlrev_b64 v[130:131], 8, v[130:131]
	v_lshl_add_u64 v[130:131], s[24:25], 0, v[130:131]
	v_lshl_add_u64 v[134:135], v[130:131], 0, v[0:1]
	v_lshl_add_u64 v[136:137], v[134:135], 0, s[14:15]
	v_add_co_u32_e32 v134, vcc, s13, v134
	v_cvt_pk_bf16_f32 v130, v46, v47
	v_cvt_pk_bf16_f32 v131, v48, v49
	v_cvt_pk_bf16_f32 v132, v42, v43
	v_cvt_pk_bf16_f32 v133, v44, v45
	v_addc_co_u32_e32 v135, vcc, 0, v135, vcc
	global_store_dwordx4 v[134:135], v[130:133], off offset:3840 sc1
	v_cmp_gt_i32_e32 vcc, s9, v204
	s_nop 0
	v_cvt_pk_bf16_f32 v130, v38, v39
	v_cvt_pk_bf16_f32 v131, v40, v41
	v_cvt_pk_bf16_f32 v132, v34, v35
	v_cvt_pk_bf16_f32 v133, v36, v37
	global_store_dwordx4 v[136:137], v[130:133], off offset:64 sc1
	s_nop 1
	v_add_u32_e32 v130, 0xa0, v204
	v_and_b32_e32 v131, 0xfef, v130
	v_and_b32_e32 v130, 0xef, v130
	v_add_u32_e32 v131, v138, v131
	v_or_b32_e32 v130, s8, v130
	v_cndmask_b32_e32 v130, v130, v131, vcc
	v_ashrrev_i32_e32 v131, 31, v130
	v_lshlrev_b64 v[130:131], 8, v[130:131]
	v_lshl_add_u64 v[130:131], s[24:25], 0, v[130:131]
	v_lshl_add_u64 v[134:135], v[130:131], 0, v[0:1]
	v_lshl_add_u64 v[136:137], v[134:135], 0, s[14:15]
	v_add_co_u32_e32 v134, vcc, s13, v134
	v_cvt_pk_bf16_f32 v130, v30, v31
	v_cvt_pk_bf16_f32 v131, v32, v33
	v_cvt_pk_bf16_f32 v132, v26, v27
	v_cvt_pk_bf16_f32 v133, v28, v29
	v_addc_co_u32_e32 v135, vcc, 0, v135, vcc
	global_store_dwordx4 v[134:135], v[130:133], off offset:3840 sc1
	s_nop 1
	v_cvt_pk_bf16_f32 v130, v22, v23
	v_cvt_pk_bf16_f32 v131, v24, v25
	v_cvt_pk_bf16_f32 v132, v18, v19
	v_cvt_pk_bf16_f32 v133, v20, v21
	global_store_dwordx4 v[136:137], v[130:133], off offset:64 sc1
	s_nop 1
	v_add_u32_e32 v130, 0xb0, v204
	v_and_b32_e32 v131, 0xfff, v130
	v_or_b32_sdwa v130, v130, s8 dst_sel:DWORD dst_unused:UNUSED_PAD src0_sel:BYTE_0 src1_sel:DWORD
	s_movk_i32 s8, 0x3f50
	v_add_u32_e32 v131, v138, v131
	v_cmp_gt_i32_e32 vcc, s8, v204
	v_cvt_pk_bf16_f32 v132, v10, v11
	v_cvt_pk_bf16_f32 v133, v12, v13
	v_cndmask_b32_e32 v130, v130, v131, vcc
	v_ashrrev_i32_e32 v131, 31, v130
	v_lshlrev_b64 v[130:131], 8, v[130:131]
	v_lshl_add_u64 v[130:131], s[24:25], 0, v[130:131]
	v_lshl_add_u64 v[134:135], v[130:131], 0, v[0:1]
	v_lshl_add_u64 v[136:137], v[134:135], 0, s[14:15]
	v_add_co_u32_e32 v134, vcc, s13, v134
	v_cvt_pk_bf16_f32 v130, v14, v15
	v_cvt_pk_bf16_f32 v131, v16, v17
	v_addc_co_u32_e32 v135, vcc, 0, v135, vcc
	global_store_dwordx4 v[134:135], v[130:133], off offset:3840 sc1
	s_nop 1
	v_cvt_pk_bf16_f32 v130, v6, v7
	v_cvt_pk_bf16_f32 v131, v8, v9
	v_cvt_pk_bf16_f32 v132, v2, v3
	v_cvt_pk_bf16_f32 v133, v4, v5
	global_store_dwordx4 v[136:137], v[130:133], off offset:64 sc1

.LBB0_486:
	s_load_dwordx2 s[14:15], s[0:1], 0xc8
	s_lshr_b32 s13, s57, 5
	s_cmp_gt_u32 s44, 4
	s_cbranch_scc1 .Lwing_g
	s_sub_i32 s8, s44, 3
	s_lshl_b32 s8, s8, 8
	s_or_b32 s8, s8, s57
	s_lshl_b32 s8, s8, 1
	s_lshl_b32 s9, s3, 10
	s_add_u32 s8, s8, s9
	s_add_u32 s8, s8, 0x7700000
	v_lshlrev_b32_e32 v139, 10, v205
	v_lshl_add_u32 v139, v247, 1, v139
	s_waitcnt lgkmcnt(0)
	s_add_u32 s66, s14, s8
	s_addc_u32 s67, s15, 0
	v_cvt_pk_bf16_f32 v126, v126, v127
	v_cvt_pk_bf16_f32 v127, v128, v129
	v_cvt_pk_bf16_f32 v128, v122, v123
	v_cvt_pk_bf16_f32 v129, v124, v125
	global_store_dwordx4 v139, v[126:129], s[66:67] sc1
	v_cvt_pk_bf16_f32 v118, v118, v119
	v_cvt_pk_bf16_f32 v119, v120, v121
	v_cvt_pk_bf16_f32 v120, v114, v115
	v_cvt_pk_bf16_f32 v121, v116, v117
	global_store_dwordx4 v139, v[118:121], s[66:67] offset:256 sc1
	s_add_u32 s66, s66, 0x4000
	s_addc_u32 s67, s67, 0
	v_cvt_pk_bf16_f32 v110, v110, v111
	v_cvt_pk_bf16_f32 v111, v112, v113
	v_cvt_pk_bf16_f32 v112, v106, v107
	v_cvt_pk_bf16_f32 v113, v108, v109
	global_store_dwordx4 v139, v[110:113], s[66:67] sc1
	v_cvt_pk_bf16_f32 v102, v102, v103
	v_cvt_pk_bf16_f32 v103, v104, v105
	v_cvt_pk_bf16_f32 v104, v98, v99
	v_cvt_pk_bf16_f32 v105, v100, v101
	global_store_dwordx4 v139, v[102:105], s[66:67] offset:256 sc1
	s_add_u32 s66, s66, 0x4000
	s_addc_u32 s67, s67, 0
	v_cvt_pk_bf16_f32 v94, v94, v95
	v_cvt_pk_bf16_f32 v95, v96, v97
	v_cvt_pk_bf16_f32 v96, v90, v91
	v_cvt_pk_bf16_f32 v97, v92, v93
	global_store_dwordx4 v139, v[94:97], s[66:67] sc1
	v_cvt_pk_bf16_f32 v86, v86, v87
	v_cvt_pk_bf16_f32 v87, v88, v89
	v_cvt_pk_bf16_f32 v88, v82, v83
	v_cvt_pk_bf16_f32 v89, v84, v85
	global_store_dwordx4 v139, v[86:89], s[66:67] offset:256 sc1
	s_add_u32 s66, s66, 0x4000
	s_addc_u32 s67, s67, 0
	v_cvt_pk_bf16_f32 v78, v78, v79
	v_cvt_pk_bf16_f32 v79, v80, v81
	v_cvt_pk_bf16_f32 v80, v74, v75
	v_cvt_pk_bf16_f32 v81, v76, v77
	global_store_dwordx4 v139, v[78:81], s[66:67] sc1
	v_cvt_pk_bf16_f32 v70, v70, v71
	v_cvt_pk_bf16_f32 v71, v72, v73
	v_cvt_pk_bf16_f32 v72, v66, v67
	v_cvt_pk_bf16_f32 v73, v68, v69
	global_store_dwordx4 v139, v[70:73], s[66:67] offset:256 sc1
	s_add_u32 s66, s66, 0x14000
	s_addc_u32 s67, s67, 0
	v_cvt_pk_bf16_f32 v62, v62, v63
	v_cvt_pk_bf16_f32 v63, v64, v65
	v_cvt_pk_bf16_f32 v64, v58, v59
	v_cvt_pk_bf16_f32 v65, v60, v61
	global_store_dwordx4 v139, v[62:65], s[66:67] sc1
	v_cvt_pk_bf16_f32 v54, v54, v55
	v_cvt_pk_bf16_f32 v55, v56, v57
	v_cvt_pk_bf16_f32 v56, v50, v51
	v_cvt_pk_bf16_f32 v57, v52, v53
	global_store_dwordx4 v139, v[54:57], s[66:67] offset:256 sc1
	s_add_u32 s66, s66, 0x4000
	s_addc_u32 s67, s67, 0
	v_cvt_pk_bf16_f32 v46, v46, v47
	v_cvt_pk_bf16_f32 v47, v48, v49
	v_cvt_pk_bf16_f32 v48, v42, v43
	v_cvt_pk_bf16_f32 v49, v44, v45
	global_store_dwordx4 v139, v[46:49], s[66:67] sc1
	v_cvt_pk_bf16_f32 v38, v38, v39
	v_cvt_pk_bf16_f32 v39, v40, v41
	v_cvt_pk_bf16_f32 v40, v34, v35
	v_cvt_pk_bf16_f32 v41, v36, v37
	global_store_dwordx4 v139, v[38:41], s[66:67] offset:256 sc1
	s_add_u32 s66, s66, 0x4000
	s_addc_u32 s67, s67, 0
	v_cvt_pk_bf16_f32 v30, v30, v31
	v_cvt_pk_bf16_f32 v31, v32, v33
	v_cvt_pk_bf16_f32 v32, v26, v27
	v_cvt_pk_bf16_f32 v33, v28, v29
	global_store_dwordx4 v139, v[30:33], s[66:67] sc1
	v_cvt_pk_bf16_f32 v22, v22, v23
	v_cvt_pk_bf16_f32 v23, v24, v25
	v_cvt_pk_bf16_f32 v24, v18, v19
	v_cvt_pk_bf16_f32 v25, v20, v21
	global_store_dwordx4 v139, v[22:25], s[66:67] offset:256 sc1
	s_add_u32 s66, s66, 0x4000
	s_addc_u32 s67, s67, 0
	v_cvt_pk_bf16_f32 v14, v14, v15
	v_cvt_pk_bf16_f32 v15, v16, v17
	v_cvt_pk_bf16_f32 v16, v10, v11
	v_cvt_pk_bf16_f32 v17, v12, v13
	global_store_dwordx4 v139, v[14:17], s[66:67] sc1
	v_cvt_pk_bf16_f32 v6, v6, v7
	v_cvt_pk_bf16_f32 v7, v8, v9
	v_cvt_pk_bf16_f32 v8, v2, v3
	v_cvt_pk_bf16_f32 v9, v4, v5
	global_store_dwordx4 v139, v[6:9], s[66:67] offset:256 sc1
	s_branch .Lwing_done
.Lwing_g:
	s_sub_i32 s8, s44, 5
	s_lshl_b32 s8, s8, 2
	s_lshr_b32 s9, s13, 1
	s_add_i32 s8, s8, s9
	s_lshl_b32 s8, s8, 11
	s_and_b32 s9, s13, 1
	s_lshl_b32 s9, s9, 10
	s_add_i32 s8, s8, s9
	s_lshr_b32 s9, s3, 4
	s_lshl_b32 s9, s9, 14
	s_add_u32 s8, s8, s9
	s_add_u32 s8, s8, 0x8801000
	v_lshrrev_b32_e32 v139, 4, v247
	v_lshlrev_b32_e32 v139, 9, v139
	v_lshl_add_u32 v139, v205, 5, v139
	v_and_b32_e32 v0, 8, v247
	v_lshl_add_u32 v139, v0, 1, v139
	v_mov_b32_e32 v138, 0xc0135761
	s_waitcnt lgkmcnt(0)
	s_add_u32 s66, s14, s8
	s_addc_u32 s67, s15, 0
	v_mul_f32_e32 v130, v126, v126
	v_mul_f32_e32 v131, v127, v127
	v_mul_f32_e32 v132, v128, v128
	v_mul_f32_e32 v133, v129, v129
	v_mul_f32_e32 v134, v122, v122
	v_mul_f32_e32 v135, v123, v123
	v_mul_f32_e32 v136, v124, v124
	v_mul_f32_e32 v137, v125, v125
	v_fmamk_f32 v130, v130, 0xbdd2d3e7, v138
	v_fmamk_f32 v131, v131, 0xbdd2d3e7, v138
	v_fmamk_f32 v132, v132, 0xbdd2d3e7, v138
	v_fmamk_f32 v133, v133, 0xbdd2d3e7, v138
	v_fmamk_f32 v134, v134, 0xbdd2d3e7, v138
	v_fmamk_f32 v135, v135, 0xbdd2d3e7, v138
	v_fmamk_f32 v136, v136, 0xbdd2d3e7, v138
	v_fmamk_f32 v137, v137, 0xbdd2d3e7, v138
	v_mul_f32_e32 v130, v126, v130
	v_mul_f32_e32 v131, v127, v131
	v_mul_f32_e32 v132, v128, v132
	v_mul_f32_e32 v133, v129, v133
	v_mul_f32_e32 v134, v122, v134
	v_mul_f32_e32 v135, v123, v135
	v_mul_f32_e32 v136, v124, v136
	v_mul_f32_e32 v137, v125, v137
	v_exp_f32_e32 v130, v130
	v_exp_f32_e32 v131, v131
	v_exp_f32_e32 v132, v132
	v_exp_f32_e32 v133, v133
	v_exp_f32_e32 v134, v134
	v_exp_f32_e32 v135, v135
	v_exp_f32_e32 v136, v136
	v_exp_f32_e32 v137, v137
	v_add_f32_e32 v130, 1.0, v130
	v_add_f32_e32 v131, 1.0, v131
	v_add_f32_e32 v132, 1.0, v132
	v_add_f32_e32 v133, 1.0, v133
	v_add_f32_e32 v134, 1.0, v134
	v_add_f32_e32 v135, 1.0, v135
	v_add_f32_e32 v136, 1.0, v136
	v_add_f32_e32 v137, 1.0, v137
	v_rcp_f32_e32 v130, v130
	v_rcp_f32_e32 v131, v131
	v_rcp_f32_e32 v132, v132
	v_rcp_f32_e32 v133, v133
	v_rcp_f32_e32 v134, v134
	v_rcp_f32_e32 v135, v135
	v_rcp_f32_e32 v136, v136
	v_rcp_f32_e32 v137, v137
	v_mul_f32_e32 v126, v126, v130
	v_mul_f32_e32 v127, v127, v131
	v_mul_f32_e32 v128, v128, v132
	v_mul_f32_e32 v129, v129, v133
	v_mul_f32_e32 v122, v122, v134
	v_mul_f32_e32 v123, v123, v135
	v_mul_f32_e32 v124, v124, v136
	v_mul_f32_e32 v125, v125, v137
	v_cvt_pk_bf16_f32 v126, v126, v127
	v_cvt_pk_bf16_f32 v127, v128, v129
	v_cvt_pk_bf16_f32 v128, v122, v123
	v_cvt_pk_bf16_f32 v129, v124, v125
	global_store_dwordx4 v139, v[126:129], s[66:67] offset:-4096 sc1
	v_mul_f32_e32 v130, v118, v118
	v_mul_f32_e32 v131, v119, v119
	v_mul_f32_e32 v132, v120, v120
	v_mul_f32_e32 v133, v121, v121
	v_mul_f32_e32 v134, v114, v114
	v_mul_f32_e32 v135, v115, v115
	v_mul_f32_e32 v136, v116, v116
	v_mul_f32_e32 v137, v117, v117
	v_fmamk_f32 v130, v130, 0xbdd2d3e7, v138
	v_fmamk_f32 v131, v131, 0xbdd2d3e7, v138
	v_fmamk_f32 v132, v132, 0xbdd2d3e7, v138
	v_fmamk_f32 v133, v133, 0xbdd2d3e7, v138
	v_fmamk_f32 v134, v134, 0xbdd2d3e7, v138
	v_fmamk_f32 v135, v135, 0xbdd2d3e7, v138
	v_fmamk_f32 v136, v136, 0xbdd2d3e7, v138
	v_fmamk_f32 v137, v137, 0xbdd2d3e7, v138
	v_mul_f32_e32 v130, v118, v130
	v_mul_f32_e32 v131, v119, v131
	v_mul_f32_e32 v132, v120, v132
	v_mul_f32_e32 v133, v121, v133
	v_mul_f32_e32 v134, v114, v134
	v_mul_f32_e32 v135, v115, v135
	v_mul_f32_e32 v136, v116, v136
	v_mul_f32_e32 v137, v117, v137
	v_exp_f32_e32 v130, v130
	v_exp_f32_e32 v131, v131
	v_exp_f32_e32 v132, v132
	v_exp_f32_e32 v133, v133
	v_exp_f32_e32 v134, v134
	v_exp_f32_e32 v135, v135
	v_exp_f32_e32 v136, v136
	v_exp_f32_e32 v137, v137
	v_add_f32_e32 v130, 1.0, v130
	v_add_f32_e32 v131, 1.0, v131
	v_add_f32_e32 v132, 1.0, v132
	v_add_f32_e32 v133, 1.0, v133
	v_add_f32_e32 v134, 1.0, v134
	v_add_f32_e32 v135, 1.0, v135
	v_add_f32_e32 v136, 1.0, v136
	v_add_f32_e32 v137, 1.0, v137
	v_rcp_f32_e32 v130, v130
	v_rcp_f32_e32 v131, v131
	v_rcp_f32_e32 v132, v132
	v_rcp_f32_e32 v133, v133
	v_rcp_f32_e32 v134, v134
	v_rcp_f32_e32 v135, v135
	v_rcp_f32_e32 v136, v136
	v_rcp_f32_e32 v137, v137
	v_mul_f32_e32 v118, v118, v130
	v_mul_f32_e32 v119, v119, v131
	v_mul_f32_e32 v120, v120, v132
	v_mul_f32_e32 v121, v121, v133
	v_mul_f32_e32 v114, v114, v134
	v_mul_f32_e32 v115, v115, v135
	v_mul_f32_e32 v116, v116, v136
	v_mul_f32_e32 v117, v117, v137
	v_cvt_pk_bf16_f32 v118, v118, v119
	v_cvt_pk_bf16_f32 v119, v120, v121
	v_cvt_pk_bf16_f32 v120, v114, v115
	v_cvt_pk_bf16_f32 v121, v116, v117
	global_store_dwordx4 v139, v[118:121], s[66:67] sc1
	s_add_u32 s66, s66, 0x4000
	s_addc_u32 s67, s67, 0
	v_mul_f32_e32 v130, v110, v110
	v_mul_f32_e32 v131, v111, v111
	v_mul_f32_e32 v132, v112, v112
	v_mul_f32_e32 v133, v113, v113
	v_mul_f32_e32 v134, v106, v106
	v_mul_f32_e32 v135, v107, v107
	v_mul_f32_e32 v136, v108, v108
	v_mul_f32_e32 v137, v109, v109
	v_fmamk_f32 v130, v130, 0xbdd2d3e7, v138
	v_fmamk_f32 v131, v131, 0xbdd2d3e7, v138
	v_fmamk_f32 v132, v132, 0xbdd2d3e7, v138
	v_fmamk_f32 v133, v133, 0xbdd2d3e7, v138
	v_fmamk_f32 v134, v134, 0xbdd2d3e7, v138
	v_fmamk_f32 v135, v135, 0xbdd2d3e7, v138
	v_fmamk_f32 v136, v136, 0xbdd2d3e7, v138
	v_fmamk_f32 v137, v137, 0xbdd2d3e7, v138
	v_mul_f32_e32 v130, v110, v130
	v_mul_f32_e32 v131, v111, v131
	v_mul_f32_e32 v132, v112, v132
	v_mul_f32_e32 v133, v113, v133
	v_mul_f32_e32 v134, v106, v134
	v_mul_f32_e32 v135, v107, v135
	v_mul_f32_e32 v136, v108, v136
	v_mul_f32_e32 v137, v109, v137
	v_exp_f32_e32 v130, v130
	v_exp_f32_e32 v131, v131
	v_exp_f32_e32 v132, v132
	v_exp_f32_e32 v133, v133
	v_exp_f32_e32 v134, v134
	v_exp_f32_e32 v135, v135
	v_exp_f32_e32 v136, v136
	v_exp_f32_e32 v137, v137
	v_add_f32_e32 v130, 1.0, v130
	v_add_f32_e32 v131, 1.0, v131
	v_add_f32_e32 v132, 1.0, v132
	v_add_f32_e32 v133, 1.0, v133
	v_add_f32_e32 v134, 1.0, v134
	v_add_f32_e32 v135, 1.0, v135
	v_add_f32_e32 v136, 1.0, v136
	v_add_f32_e32 v137, 1.0, v137
	v_rcp_f32_e32 v130, v130
	v_rcp_f32_e32 v131, v131
	v_rcp_f32_e32 v132, v132
	v_rcp_f32_e32 v133, v133
	v_rcp_f32_e32 v134, v134
	v_rcp_f32_e32 v135, v135
	v_rcp_f32_e32 v136, v136
	v_rcp_f32_e32 v137, v137
	v_mul_f32_e32 v110, v110, v130
	v_mul_f32_e32 v111, v111, v131
	v_mul_f32_e32 v112, v112, v132
	v_mul_f32_e32 v113, v113, v133
	v_mul_f32_e32 v106, v106, v134
	v_mul_f32_e32 v107, v107, v135
	v_mul_f32_e32 v108, v108, v136
	v_mul_f32_e32 v109, v109, v137
	v_cvt_pk_bf16_f32 v110, v110, v111
	v_cvt_pk_bf16_f32 v111, v112, v113
	v_cvt_pk_bf16_f32 v112, v106, v107
	v_cvt_pk_bf16_f32 v113, v108, v109
	global_store_dwordx4 v139, v[110:113], s[66:67] offset:-4096 sc1
	v_mul_f32_e32 v130, v102, v102
	v_mul_f32_e32 v131, v103, v103
	v_mul_f32_e32 v132, v104, v104
	v_mul_f32_e32 v133, v105, v105
	v_mul_f32_e32 v134, v98, v98
	v_mul_f32_e32 v135, v99, v99
	v_mul_f32_e32 v136, v100, v100
	v_mul_f32_e32 v137, v101, v101
	v_fmamk_f32 v130, v130, 0xbdd2d3e7, v138
	v_fmamk_f32 v131, v131, 0xbdd2d3e7, v138
	v_fmamk_f32 v132, v132, 0xbdd2d3e7, v138
	v_fmamk_f32 v133, v133, 0xbdd2d3e7, v138
	v_fmamk_f32 v134, v134, 0xbdd2d3e7, v138
	v_fmamk_f32 v135, v135, 0xbdd2d3e7, v138
	v_fmamk_f32 v136, v136, 0xbdd2d3e7, v138
	v_fmamk_f32 v137, v137, 0xbdd2d3e7, v138
	v_mul_f32_e32 v130, v102, v130
	v_mul_f32_e32 v131, v103, v131
	v_mul_f32_e32 v132, v104, v132
	v_mul_f32_e32 v133, v105, v133
	v_mul_f32_e32 v134, v98, v134
	v_mul_f32_e32 v135, v99, v135
	v_mul_f32_e32 v136, v100, v136
	v_mul_f32_e32 v137, v101, v137
	v_exp_f32_e32 v130, v130
	v_exp_f32_e32 v131, v131
	v_exp_f32_e32 v132, v132
	v_exp_f32_e32 v133, v133
	v_exp_f32_e32 v134, v134
	v_exp_f32_e32 v135, v135
	v_exp_f32_e32 v136, v136
	v_exp_f32_e32 v137, v137
	v_add_f32_e32 v130, 1.0, v130
	v_add_f32_e32 v131, 1.0, v131
	v_add_f32_e32 v132, 1.0, v132
	v_add_f32_e32 v133, 1.0, v133
	v_add_f32_e32 v134, 1.0, v134
	v_add_f32_e32 v135, 1.0, v135
	v_add_f32_e32 v136, 1.0, v136
	v_add_f32_e32 v137, 1.0, v137
	v_rcp_f32_e32 v130, v130
	v_rcp_f32_e32 v131, v131
	v_rcp_f32_e32 v132, v132
	v_rcp_f32_e32 v133, v133
	v_rcp_f32_e32 v134, v134
	v_rcp_f32_e32 v135, v135
	v_rcp_f32_e32 v136, v136
	v_rcp_f32_e32 v137, v137
	v_mul_f32_e32 v102, v102, v130
	v_mul_f32_e32 v103, v103, v131
	v_mul_f32_e32 v104, v104, v132
	v_mul_f32_e32 v105, v105, v133
	v_mul_f32_e32 v98, v98, v134
	v_mul_f32_e32 v99, v99, v135
	v_mul_f32_e32 v100, v100, v136
	v_mul_f32_e32 v101, v101, v137
	v_cvt_pk_bf16_f32 v102, v102, v103
	v_cvt_pk_bf16_f32 v103, v104, v105
	v_cvt_pk_bf16_f32 v104, v98, v99
	v_cvt_pk_bf16_f32 v105, v100, v101
	global_store_dwordx4 v139, v[102:105], s[66:67] sc1
	s_add_u32 s66, s66, 0x4000
	s_addc_u32 s67, s67, 0
	v_mul_f32_e32 v130, v94, v94
	v_mul_f32_e32 v131, v95, v95
	v_mul_f32_e32 v132, v96, v96
	v_mul_f32_e32 v133, v97, v97
	v_mul_f32_e32 v134, v90, v90
	v_mul_f32_e32 v135, v91, v91
	v_mul_f32_e32 v136, v92, v92
	v_mul_f32_e32 v137, v93, v93
	v_fmamk_f32 v130, v130, 0xbdd2d3e7, v138
	v_fmamk_f32 v131, v131, 0xbdd2d3e7, v138
	v_fmamk_f32 v132, v132, 0xbdd2d3e7, v138
	v_fmamk_f32 v133, v133, 0xbdd2d3e7, v138
	v_fmamk_f32 v134, v134, 0xbdd2d3e7, v138
	v_fmamk_f32 v135, v135, 0xbdd2d3e7, v138
	v_fmamk_f32 v136, v136, 0xbdd2d3e7, v138
	v_fmamk_f32 v137, v137, 0xbdd2d3e7, v138
	v_mul_f32_e32 v130, v94, v130
	v_mul_f32_e32 v131, v95, v131
	v_mul_f32_e32 v132, v96, v132
	v_mul_f32_e32 v133, v97, v133
	v_mul_f32_e32 v134, v90, v134
	v_mul_f32_e32 v135, v91, v135
	v_mul_f32_e32 v136, v92, v136
	v_mul_f32_e32 v137, v93, v137
	v_exp_f32_e32 v130, v130
	v_exp_f32_e32 v131, v131
	v_exp_f32_e32 v132, v132
	v_exp_f32_e32 v133, v133
	v_exp_f32_e32 v134, v134
	v_exp_f32_e32 v135, v135
	v_exp_f32_e32 v136, v136
	v_exp_f32_e32 v137, v137
	v_add_f32_e32 v130, 1.0, v130
	v_add_f32_e32 v131, 1.0, v131
	v_add_f32_e32 v132, 1.0, v132
	v_add_f32_e32 v133, 1.0, v133
	v_add_f32_e32 v134, 1.0, v134
	v_add_f32_e32 v135, 1.0, v135
	v_add_f32_e32 v136, 1.0, v136
	v_add_f32_e32 v137, 1.0, v137
	v_rcp_f32_e32 v130, v130
	v_rcp_f32_e32 v131, v131
	v_rcp_f32_e32 v132, v132
	v_rcp_f32_e32 v133, v133
	v_rcp_f32_e32 v134, v134
	v_rcp_f32_e32 v135, v135
	v_rcp_f32_e32 v136, v136
	v_rcp_f32_e32 v137, v137
	v_mul_f32_e32 v94, v94, v130
	v_mul_f32_e32 v95, v95, v131
	v_mul_f32_e32 v96, v96, v132
	v_mul_f32_e32 v97, v97, v133
	v_mul_f32_e32 v90, v90, v134
	v_mul_f32_e32 v91, v91, v135
	v_mul_f32_e32 v92, v92, v136
	v_mul_f32_e32 v93, v93, v137
	v_cvt_pk_bf16_f32 v94, v94, v95
	v_cvt_pk_bf16_f32 v95, v96, v97
	v_cvt_pk_bf16_f32 v96, v90, v91
	v_cvt_pk_bf16_f32 v97, v92, v93
	global_store_dwordx4 v139, v[94:97], s[66:67] offset:-4096 sc1
	v_mul_f32_e32 v130, v86, v86
	v_mul_f32_e32 v131, v87, v87
	v_mul_f32_e32 v132, v88, v88
	v_mul_f32_e32 v133, v89, v89
	v_mul_f32_e32 v134, v82, v82
	v_mul_f32_e32 v135, v83, v83
	v_mul_f32_e32 v136, v84, v84
	v_mul_f32_e32 v137, v85, v85
	v_fmamk_f32 v130, v130, 0xbdd2d3e7, v138
	v_fmamk_f32 v131, v131, 0xbdd2d3e7, v138
	v_fmamk_f32 v132, v132, 0xbdd2d3e7, v138
	v_fmamk_f32 v133, v133, 0xbdd2d3e7, v138
	v_fmamk_f32 v134, v134, 0xbdd2d3e7, v138
	v_fmamk_f32 v135, v135, 0xbdd2d3e7, v138
	v_fmamk_f32 v136, v136, 0xbdd2d3e7, v138
	v_fmamk_f32 v137, v137, 0xbdd2d3e7, v138
	v_mul_f32_e32 v130, v86, v130
	v_mul_f32_e32 v131, v87, v131
	v_mul_f32_e32 v132, v88, v132
	v_mul_f32_e32 v133, v89, v133
	v_mul_f32_e32 v134, v82, v134
	v_mul_f32_e32 v135, v83, v135
	v_mul_f32_e32 v136, v84, v136
	v_mul_f32_e32 v137, v85, v137
	v_exp_f32_e32 v130, v130
	v_exp_f32_e32 v131, v131
	v_exp_f32_e32 v132, v132
	v_exp_f32_e32 v133, v133
	v_exp_f32_e32 v134, v134
	v_exp_f32_e32 v135, v135
	v_exp_f32_e32 v136, v136
	v_exp_f32_e32 v137, v137
	v_add_f32_e32 v130, 1.0, v130
	v_add_f32_e32 v131, 1.0, v131
	v_add_f32_e32 v132, 1.0, v132
	v_add_f32_e32 v133, 1.0, v133
	v_add_f32_e32 v134, 1.0, v134
	v_add_f32_e32 v135, 1.0, v135
	v_add_f32_e32 v136, 1.0, v136
	v_add_f32_e32 v137, 1.0, v137
	v_rcp_f32_e32 v130, v130
	v_rcp_f32_e32 v131, v131
	v_rcp_f32_e32 v132, v132
	v_rcp_f32_e32 v133, v133
	v_rcp_f32_e32 v134, v134
	v_rcp_f32_e32 v135, v135
	v_rcp_f32_e32 v136, v136
	v_rcp_f32_e32 v137, v137
	v_mul_f32_e32 v86, v86, v130
	v_mul_f32_e32 v87, v87, v131
	v_mul_f32_e32 v88, v88, v132
	v_mul_f32_e32 v89, v89, v133
	v_mul_f32_e32 v82, v82, v134
	v_mul_f32_e32 v83, v83, v135
	v_mul_f32_e32 v84, v84, v136
	v_mul_f32_e32 v85, v85, v137
	v_cvt_pk_bf16_f32 v86, v86, v87
	v_cvt_pk_bf16_f32 v87, v88, v89
	v_cvt_pk_bf16_f32 v88, v82, v83
	v_cvt_pk_bf16_f32 v89, v84, v85
	global_store_dwordx4 v139, v[86:89], s[66:67] sc1
	s_add_u32 s66, s66, 0x4000
	s_addc_u32 s67, s67, 0
	v_mul_f32_e32 v130, v78, v78
	v_mul_f32_e32 v131, v79, v79
	v_mul_f32_e32 v132, v80, v80
	v_mul_f32_e32 v133, v81, v81
	v_mul_f32_e32 v134, v74, v74
	v_mul_f32_e32 v135, v75, v75
	v_mul_f32_e32 v136, v76, v76
	v_mul_f32_e32 v137, v77, v77
	v_fmamk_f32 v130, v130, 0xbdd2d3e7, v138
	v_fmamk_f32 v131, v131, 0xbdd2d3e7, v138
	v_fmamk_f32 v132, v132, 0xbdd2d3e7, v138
	v_fmamk_f32 v133, v133, 0xbdd2d3e7, v138
	v_fmamk_f32 v134, v134, 0xbdd2d3e7, v138
	v_fmamk_f32 v135, v135, 0xbdd2d3e7, v138
	v_fmamk_f32 v136, v136, 0xbdd2d3e7, v138
	v_fmamk_f32 v137, v137, 0xbdd2d3e7, v138
	v_mul_f32_e32 v130, v78, v130
	v_mul_f32_e32 v131, v79, v131
	v_mul_f32_e32 v132, v80, v132
	v_mul_f32_e32 v133, v81, v133
	v_mul_f32_e32 v134, v74, v134
	v_mul_f32_e32 v135, v75, v135
	v_mul_f32_e32 v136, v76, v136
	v_mul_f32_e32 v137, v77, v137
	v_exp_f32_e32 v130, v130
	v_exp_f32_e32 v131, v131
	v_exp_f32_e32 v132, v132
	v_exp_f32_e32 v133, v133
	v_exp_f32_e32 v134, v134
	v_exp_f32_e32 v135, v135
	v_exp_f32_e32 v136, v136
	v_exp_f32_e32 v137, v137
	v_add_f32_e32 v130, 1.0, v130
	v_add_f32_e32 v131, 1.0, v131
	v_add_f32_e32 v132, 1.0, v132
	v_add_f32_e32 v133, 1.0, v133
	v_add_f32_e32 v134, 1.0, v134
	v_add_f32_e32 v135, 1.0, v135
	v_add_f32_e32 v136, 1.0, v136
	v_add_f32_e32 v137, 1.0, v137
	v_rcp_f32_e32 v130, v130
	v_rcp_f32_e32 v131, v131
	v_rcp_f32_e32 v132, v132
	v_rcp_f32_e32 v133, v133
	v_rcp_f32_e32 v134, v134
	v_rcp_f32_e32 v135, v135
	v_rcp_f32_e32 v136, v136
	v_rcp_f32_e32 v137, v137
	v_mul_f32_e32 v78, v78, v130
	v_mul_f32_e32 v79, v79, v131
	v_mul_f32_e32 v80, v80, v132
	v_mul_f32_e32 v81, v81, v133
	v_mul_f32_e32 v74, v74, v134
	v_mul_f32_e32 v75, v75, v135
	v_mul_f32_e32 v76, v76, v136
	v_mul_f32_e32 v77, v77, v137
	v_cvt_pk_bf16_f32 v78, v78, v79
	v_cvt_pk_bf16_f32 v79, v80, v81
	v_cvt_pk_bf16_f32 v80, v74, v75
	v_cvt_pk_bf16_f32 v81, v76, v77
	global_store_dwordx4 v139, v[78:81], s[66:67] offset:-4096 sc1
	v_mul_f32_e32 v130, v70, v70
	v_mul_f32_e32 v131, v71, v71
	v_mul_f32_e32 v132, v72, v72
	v_mul_f32_e32 v133, v73, v73
	v_mul_f32_e32 v134, v66, v66
	v_mul_f32_e32 v135, v67, v67
	v_mul_f32_e32 v136, v68, v68
	v_mul_f32_e32 v137, v69, v69
	v_fmamk_f32 v130, v130, 0xbdd2d3e7, v138
	v_fmamk_f32 v131, v131, 0xbdd2d3e7, v138
	v_fmamk_f32 v132, v132, 0xbdd2d3e7, v138
	v_fmamk_f32 v133, v133, 0xbdd2d3e7, v138
	v_fmamk_f32 v134, v134, 0xbdd2d3e7, v138
	v_fmamk_f32 v135, v135, 0xbdd2d3e7, v138
	v_fmamk_f32 v136, v136, 0xbdd2d3e7, v138
	v_fmamk_f32 v137, v137, 0xbdd2d3e7, v138
	v_mul_f32_e32 v130, v70, v130
	v_mul_f32_e32 v131, v71, v131
	v_mul_f32_e32 v132, v72, v132
	v_mul_f32_e32 v133, v73, v133
	v_mul_f32_e32 v134, v66, v134
	v_mul_f32_e32 v135, v67, v135
	v_mul_f32_e32 v136, v68, v136
	v_mul_f32_e32 v137, v69, v137
	v_exp_f32_e32 v130, v130
	v_exp_f32_e32 v131, v131
	v_exp_f32_e32 v132, v132
	v_exp_f32_e32 v133, v133
	v_exp_f32_e32 v134, v134
	v_exp_f32_e32 v135, v135
	v_exp_f32_e32 v136, v136
	v_exp_f32_e32 v137, v137
	v_add_f32_e32 v130, 1.0, v130
	v_add_f32_e32 v131, 1.0, v131
	v_add_f32_e32 v132, 1.0, v132
	v_add_f32_e32 v133, 1.0, v133
	v_add_f32_e32 v134, 1.0, v134
	v_add_f32_e32 v135, 1.0, v135
	v_add_f32_e32 v136, 1.0, v136
	v_add_f32_e32 v137, 1.0, v137
	v_rcp_f32_e32 v130, v130
	v_rcp_f32_e32 v131, v131
	v_rcp_f32_e32 v132, v132
	v_rcp_f32_e32 v133, v133
	v_rcp_f32_e32 v134, v134
	v_rcp_f32_e32 v135, v135
	v_rcp_f32_e32 v136, v136
	v_rcp_f32_e32 v137, v137
	v_mul_f32_e32 v70, v70, v130
	v_mul_f32_e32 v71, v71, v131
	v_mul_f32_e32 v72, v72, v132
	v_mul_f32_e32 v73, v73, v133
	v_mul_f32_e32 v66, v66, v134
	v_mul_f32_e32 v67, v67, v135
	v_mul_f32_e32 v68, v68, v136
	v_mul_f32_e32 v69, v69, v137
	v_cvt_pk_bf16_f32 v70, v70, v71
	v_cvt_pk_bf16_f32 v71, v72, v73
	v_cvt_pk_bf16_f32 v72, v66, v67
	v_cvt_pk_bf16_f32 v73, v68, v69
	global_store_dwordx4 v139, v[70:73], s[66:67] sc1
	s_add_u32 s66, s66, 0x14000
	s_addc_u32 s67, s67, 0
	v_mul_f32_e32 v130, v62, v62
	v_mul_f32_e32 v131, v63, v63
	v_mul_f32_e32 v132, v64, v64
	v_mul_f32_e32 v133, v65, v65
	v_mul_f32_e32 v134, v58, v58
	v_mul_f32_e32 v135, v59, v59
	v_mul_f32_e32 v136, v60, v60
	v_mul_f32_e32 v137, v61, v61
	v_fmamk_f32 v130, v130, 0xbdd2d3e7, v138
	v_fmamk_f32 v131, v131, 0xbdd2d3e7, v138
	v_fmamk_f32 v132, v132, 0xbdd2d3e7, v138
	v_fmamk_f32 v133, v133, 0xbdd2d3e7, v138
	v_fmamk_f32 v134, v134, 0xbdd2d3e7, v138
	v_fmamk_f32 v135, v135, 0xbdd2d3e7, v138
	v_fmamk_f32 v136, v136, 0xbdd2d3e7, v138
	v_fmamk_f32 v137, v137, 0xbdd2d3e7, v138
	v_mul_f32_e32 v130, v62, v130
	v_mul_f32_e32 v131, v63, v131
	v_mul_f32_e32 v132, v64, v132
	v_mul_f32_e32 v133, v65, v133
	v_mul_f32_e32 v134, v58, v134
	v_mul_f32_e32 v135, v59, v135
	v_mul_f32_e32 v136, v60, v136
	v_mul_f32_e32 v137, v61, v137
	v_exp_f32_e32 v130, v130
	v_exp_f32_e32 v131, v131
	v_exp_f32_e32 v132, v132
	v_exp_f32_e32 v133, v133
	v_exp_f32_e32 v134, v134
	v_exp_f32_e32 v135, v135
	v_exp_f32_e32 v136, v136
	v_exp_f32_e32 v137, v137
	v_add_f32_e32 v130, 1.0, v130
	v_add_f32_e32 v131, 1.0, v131
	v_add_f32_e32 v132, 1.0, v132
	v_add_f32_e32 v133, 1.0, v133
	v_add_f32_e32 v134, 1.0, v134
	v_add_f32_e32 v135, 1.0, v135
	v_add_f32_e32 v136, 1.0, v136
	v_add_f32_e32 v137, 1.0, v137
	v_rcp_f32_e32 v130, v130
	v_rcp_f32_e32 v131, v131
	v_rcp_f32_e32 v132, v132
	v_rcp_f32_e32 v133, v133
	v_rcp_f32_e32 v134, v134
	v_rcp_f32_e32 v135, v135
	v_rcp_f32_e32 v136, v136
	v_rcp_f32_e32 v137, v137
	v_mul_f32_e32 v62, v62, v130
	v_mul_f32_e32 v63, v63, v131
	v_mul_f32_e32 v64, v64, v132
	v_mul_f32_e32 v65, v65, v133
	v_mul_f32_e32 v58, v58, v134
	v_mul_f32_e32 v59, v59, v135
	v_mul_f32_e32 v60, v60, v136
	v_mul_f32_e32 v61, v61, v137
	v_cvt_pk_bf16_f32 v62, v62, v63
	v_cvt_pk_bf16_f32 v63, v64, v65
	v_cvt_pk_bf16_f32 v64, v58, v59
	v_cvt_pk_bf16_f32 v65, v60, v61
	global_store_dwordx4 v139, v[62:65], s[66:67] offset:-4096 sc1
	v_mul_f32_e32 v130, v54, v54
	v_mul_f32_e32 v131, v55, v55
	v_mul_f32_e32 v132, v56, v56
	v_mul_f32_e32 v133, v57, v57
	v_mul_f32_e32 v134, v50, v50
	v_mul_f32_e32 v135, v51, v51
	v_mul_f32_e32 v136, v52, v52
	v_mul_f32_e32 v137, v53, v53
	v_fmamk_f32 v130, v130, 0xbdd2d3e7, v138
	v_fmamk_f32 v131, v131, 0xbdd2d3e7, v138
	v_fmamk_f32 v132, v132, 0xbdd2d3e7, v138
	v_fmamk_f32 v133, v133, 0xbdd2d3e7, v138
	v_fmamk_f32 v134, v134, 0xbdd2d3e7, v138
	v_fmamk_f32 v135, v135, 0xbdd2d3e7, v138
	v_fmamk_f32 v136, v136, 0xbdd2d3e7, v138
	v_fmamk_f32 v137, v137, 0xbdd2d3e7, v138
	v_mul_f32_e32 v130, v54, v130
	v_mul_f32_e32 v131, v55, v131
	v_mul_f32_e32 v132, v56, v132
	v_mul_f32_e32 v133, v57, v133
	v_mul_f32_e32 v134, v50, v134
	v_mul_f32_e32 v135, v51, v135
	v_mul_f32_e32 v136, v52, v136
	v_mul_f32_e32 v137, v53, v137
	v_exp_f32_e32 v130, v130
	v_exp_f32_e32 v131, v131
	v_exp_f32_e32 v132, v132
	v_exp_f32_e32 v133, v133
	v_exp_f32_e32 v134, v134
	v_exp_f32_e32 v135, v135
	v_exp_f32_e32 v136, v136
	v_exp_f32_e32 v137, v137
	v_add_f32_e32 v130, 1.0, v130
	v_add_f32_e32 v131, 1.0, v131
	v_add_f32_e32 v132, 1.0, v132
	v_add_f32_e32 v133, 1.0, v133
	v_add_f32_e32 v134, 1.0, v134
	v_add_f32_e32 v135, 1.0, v135
	v_add_f32_e32 v136, 1.0, v136
	v_add_f32_e32 v137, 1.0, v137
	v_rcp_f32_e32 v130, v130
	v_rcp_f32_e32 v131, v131
	v_rcp_f32_e32 v132, v132
	v_rcp_f32_e32 v133, v133
	v_rcp_f32_e32 v134, v134
	v_rcp_f32_e32 v135, v135
	v_rcp_f32_e32 v136, v136
	v_rcp_f32_e32 v137, v137
	v_mul_f32_e32 v54, v54, v130
	v_mul_f32_e32 v55, v55, v131
	v_mul_f32_e32 v56, v56, v132
	v_mul_f32_e32 v57, v57, v133
	v_mul_f32_e32 v50, v50, v134
	v_mul_f32_e32 v51, v51, v135
	v_mul_f32_e32 v52, v52, v136
	v_mul_f32_e32 v53, v53, v137
	v_cvt_pk_bf16_f32 v54, v54, v55
	v_cvt_pk_bf16_f32 v55, v56, v57
	v_cvt_pk_bf16_f32 v56, v50, v51
	v_cvt_pk_bf16_f32 v57, v52, v53
	global_store_dwordx4 v139, v[54:57], s[66:67] sc1
	s_add_u32 s66, s66, 0x4000
	s_addc_u32 s67, s67, 0
	v_mul_f32_e32 v130, v46, v46
	v_mul_f32_e32 v131, v47, v47
	v_mul_f32_e32 v132, v48, v48
	v_mul_f32_e32 v133, v49, v49
	v_mul_f32_e32 v134, v42, v42
	v_mul_f32_e32 v135, v43, v43
	v_mul_f32_e32 v136, v44, v44
	v_mul_f32_e32 v137, v45, v45
	v_fmamk_f32 v130, v130, 0xbdd2d3e7, v138
	v_fmamk_f32 v131, v131, 0xbdd2d3e7, v138
	v_fmamk_f32 v132, v132, 0xbdd2d3e7, v138
	v_fmamk_f32 v133, v133, 0xbdd2d3e7, v138
	v_fmamk_f32 v134, v134, 0xbdd2d3e7, v138
	v_fmamk_f32 v135, v135, 0xbdd2d3e7, v138
	v_fmamk_f32 v136, v136, 0xbdd2d3e7, v138
	v_fmamk_f32 v137, v137, 0xbdd2d3e7, v138
	v_mul_f32_e32 v130, v46, v130
	v_mul_f32_e32 v131, v47, v131
	v_mul_f32_e32 v132, v48, v132
	v_mul_f32_e32 v133, v49, v133
	v_mul_f32_e32 v134, v42, v134
	v_mul_f32_e32 v135, v43, v135
	v_mul_f32_e32 v136, v44, v136
	v_mul_f32_e32 v137, v45, v137
	v_exp_f32_e32 v130, v130
	v_exp_f32_e32 v131, v131
	v_exp_f32_e32 v132, v132
	v_exp_f32_e32 v133, v133
	v_exp_f32_e32 v134, v134
	v_exp_f32_e32 v135, v135
	v_exp_f32_e32 v136, v136
	v_exp_f32_e32 v137, v137
	v_add_f32_e32 v130, 1.0, v130
	v_add_f32_e32 v131, 1.0, v131
	v_add_f32_e32 v132, 1.0, v132
	v_add_f32_e32 v133, 1.0, v133
	v_add_f32_e32 v134, 1.0, v134
	v_add_f32_e32 v135, 1.0, v135
	v_add_f32_e32 v136, 1.0, v136
	v_add_f32_e32 v137, 1.0, v137
	v_rcp_f32_e32 v130, v130
	v_rcp_f32_e32 v131, v131
	v_rcp_f32_e32 v132, v132
	v_rcp_f32_e32 v133, v133
	v_rcp_f32_e32 v134, v134
	v_rcp_f32_e32 v135, v135
	v_rcp_f32_e32 v136, v136
	v_rcp_f32_e32 v137, v137
	v_mul_f32_e32 v46, v46, v130
	v_mul_f32_e32 v47, v47, v131
	v_mul_f32_e32 v48, v48, v132
	v_mul_f32_e32 v49, v49, v133
	v_mul_f32_e32 v42, v42, v134
	v_mul_f32_e32 v43, v43, v135
	v_mul_f32_e32 v44, v44, v136
	v_mul_f32_e32 v45, v45, v137
	v_cvt_pk_bf16_f32 v46, v46, v47
	v_cvt_pk_bf16_f32 v47, v48, v49
	v_cvt_pk_bf16_f32 v48, v42, v43
	v_cvt_pk_bf16_f32 v49, v44, v45
	global_store_dwordx4 v139, v[46:49], s[66:67] offset:-4096 sc1
	v_mul_f32_e32 v130, v38, v38
	v_mul_f32_e32 v131, v39, v39
	v_mul_f32_e32 v132, v40, v40
	v_mul_f32_e32 v133, v41, v41
	v_mul_f32_e32 v134, v34, v34
	v_mul_f32_e32 v135, v35, v35
	v_mul_f32_e32 v136, v36, v36
	v_mul_f32_e32 v137, v37, v37
	v_fmamk_f32 v130, v130, 0xbdd2d3e7, v138
	v_fmamk_f32 v131, v131, 0xbdd2d3e7, v138
	v_fmamk_f32 v132, v132, 0xbdd2d3e7, v138
	v_fmamk_f32 v133, v133, 0xbdd2d3e7, v138
	v_fmamk_f32 v134, v134, 0xbdd2d3e7, v138
	v_fmamk_f32 v135, v135, 0xbdd2d3e7, v138
	v_fmamk_f32 v136, v136, 0xbdd2d3e7, v138
	v_fmamk_f32 v137, v137, 0xbdd2d3e7, v138
	v_mul_f32_e32 v130, v38, v130
	v_mul_f32_e32 v131, v39, v131
	v_mul_f32_e32 v132, v40, v132
	v_mul_f32_e32 v133, v41, v133
	v_mul_f32_e32 v134, v34, v134
	v_mul_f32_e32 v135, v35, v135
	v_mul_f32_e32 v136, v36, v136
	v_mul_f32_e32 v137, v37, v137
	v_exp_f32_e32 v130, v130
	v_exp_f32_e32 v131, v131
	v_exp_f32_e32 v132, v132
	v_exp_f32_e32 v133, v133
	v_exp_f32_e32 v134, v134
	v_exp_f32_e32 v135, v135
	v_exp_f32_e32 v136, v136
	v_exp_f32_e32 v137, v137
	v_add_f32_e32 v130, 1.0, v130
	v_add_f32_e32 v131, 1.0, v131
	v_add_f32_e32 v132, 1.0, v132
	v_add_f32_e32 v133, 1.0, v133
	v_add_f32_e32 v134, 1.0, v134
	v_add_f32_e32 v135, 1.0, v135
	v_add_f32_e32 v136, 1.0, v136
	v_add_f32_e32 v137, 1.0, v137
	v_rcp_f32_e32 v130, v130
	v_rcp_f32_e32 v131, v131
	v_rcp_f32_e32 v132, v132
	v_rcp_f32_e32 v133, v133
	v_rcp_f32_e32 v134, v134
	v_rcp_f32_e32 v135, v135
	v_rcp_f32_e32 v136, v136
	v_rcp_f32_e32 v137, v137
	v_mul_f32_e32 v38, v38, v130
	v_mul_f32_e32 v39, v39, v131
	v_mul_f32_e32 v40, v40, v132
	v_mul_f32_e32 v41, v41, v133
	v_mul_f32_e32 v34, v34, v134
	v_mul_f32_e32 v35, v35, v135
	v_mul_f32_e32 v36, v36, v136
	v_mul_f32_e32 v37, v37, v137
	v_cvt_pk_bf16_f32 v38, v38, v39
	v_cvt_pk_bf16_f32 v39, v40, v41
	v_cvt_pk_bf16_f32 v40, v34, v35
	v_cvt_pk_bf16_f32 v41, v36, v37
	global_store_dwordx4 v139, v[38:41], s[66:67] sc1
	s_add_u32 s66, s66, 0x4000
	s_addc_u32 s67, s67, 0
	v_mul_f32_e32 v130, v30, v30
	v_mul_f32_e32 v131, v31, v31
	v_mul_f32_e32 v132, v32, v32
	v_mul_f32_e32 v133, v33, v33
	v_mul_f32_e32 v134, v26, v26
	v_mul_f32_e32 v135, v27, v27
	v_mul_f32_e32 v136, v28, v28
	v_mul_f32_e32 v137, v29, v29
	v_fmamk_f32 v130, v130, 0xbdd2d3e7, v138
	v_fmamk_f32 v131, v131, 0xbdd2d3e7, v138
	v_fmamk_f32 v132, v132, 0xbdd2d3e7, v138
	v_fmamk_f32 v133, v133, 0xbdd2d3e7, v138
	v_fmamk_f32 v134, v134, 0xbdd2d3e7, v138
	v_fmamk_f32 v135, v135, 0xbdd2d3e7, v138
	v_fmamk_f32 v136, v136, 0xbdd2d3e7, v138
	v_fmamk_f32 v137, v137, 0xbdd2d3e7, v138
	v_mul_f32_e32 v130, v30, v130
	v_mul_f32_e32 v131, v31, v131
	v_mul_f32_e32 v132, v32, v132
	v_mul_f32_e32 v133, v33, v133
	v_mul_f32_e32 v134, v26, v134
	v_mul_f32_e32 v135, v27, v135
	v_mul_f32_e32 v136, v28, v136
	v_mul_f32_e32 v137, v29, v137
	v_exp_f32_e32 v130, v130
	v_exp_f32_e32 v131, v131
	v_exp_f32_e32 v132, v132
	v_exp_f32_e32 v133, v133
	v_exp_f32_e32 v134, v134
	v_exp_f32_e32 v135, v135
	v_exp_f32_e32 v136, v136
	v_exp_f32_e32 v137, v137
	v_add_f32_e32 v130, 1.0, v130
	v_add_f32_e32 v131, 1.0, v131
	v_add_f32_e32 v132, 1.0, v132
	v_add_f32_e32 v133, 1.0, v133
	v_add_f32_e32 v134, 1.0, v134
	v_add_f32_e32 v135, 1.0, v135
	v_add_f32_e32 v136, 1.0, v136
	v_add_f32_e32 v137, 1.0, v137
	v_rcp_f32_e32 v130, v130
	v_rcp_f32_e32 v131, v131
	v_rcp_f32_e32 v132, v132
	v_rcp_f32_e32 v133, v133
	v_rcp_f32_e32 v134, v134
	v_rcp_f32_e32 v135, v135
	v_rcp_f32_e32 v136, v136
	v_rcp_f32_e32 v137, v137
	v_mul_f32_e32 v30, v30, v130
	v_mul_f32_e32 v31, v31, v131
	v_mul_f32_e32 v32, v32, v132
	v_mul_f32_e32 v33, v33, v133
	v_mul_f32_e32 v26, v26, v134
	v_mul_f32_e32 v27, v27, v135
	v_mul_f32_e32 v28, v28, v136
	v_mul_f32_e32 v29, v29, v137
	v_cvt_pk_bf16_f32 v30, v30, v31
	v_cvt_pk_bf16_f32 v31, v32, v33
	v_cvt_pk_bf16_f32 v32, v26, v27
	v_cvt_pk_bf16_f32 v33, v28, v29
	global_store_dwordx4 v139, v[30:33], s[66:67] offset:-4096 sc1
	v_mul_f32_e32 v130, v22, v22
	v_mul_f32_e32 v131, v23, v23
	v_mul_f32_e32 v132, v24, v24
	v_mul_f32_e32 v133, v25, v25
	v_mul_f32_e32 v134, v18, v18
	v_mul_f32_e32 v135, v19, v19
	v_mul_f32_e32 v136, v20, v20
	v_mul_f32_e32 v137, v21, v21
	v_fmamk_f32 v130, v130, 0xbdd2d3e7, v138
	v_fmamk_f32 v131, v131, 0xbdd2d3e7, v138
	v_fmamk_f32 v132, v132, 0xbdd2d3e7, v138
	v_fmamk_f32 v133, v133, 0xbdd2d3e7, v138
	v_fmamk_f32 v134, v134, 0xbdd2d3e7, v138
	v_fmamk_f32 v135, v135, 0xbdd2d3e7, v138
	v_fmamk_f32 v136, v136, 0xbdd2d3e7, v138
	v_fmamk_f32 v137, v137, 0xbdd2d3e7, v138
	v_mul_f32_e32 v130, v22, v130
	v_mul_f32_e32 v131, v23, v131
	v_mul_f32_e32 v132, v24, v132
	v_mul_f32_e32 v133, v25, v133
	v_mul_f32_e32 v134, v18, v134
	v_mul_f32_e32 v135, v19, v135
	v_mul_f32_e32 v136, v20, v136
	v_mul_f32_e32 v137, v21, v137
	v_exp_f32_e32 v130, v130
	v_exp_f32_e32 v131, v131
	v_exp_f32_e32 v132, v132
	v_exp_f32_e32 v133, v133
	v_exp_f32_e32 v134, v134
	v_exp_f32_e32 v135, v135
	v_exp_f32_e32 v136, v136
	v_exp_f32_e32 v137, v137
	v_add_f32_e32 v130, 1.0, v130
	v_add_f32_e32 v131, 1.0, v131
	v_add_f32_e32 v132, 1.0, v132
	v_add_f32_e32 v133, 1.0, v133
	v_add_f32_e32 v134, 1.0, v134
	v_add_f32_e32 v135, 1.0, v135
	v_add_f32_e32 v136, 1.0, v136
	v_add_f32_e32 v137, 1.0, v137
	v_rcp_f32_e32 v130, v130
	v_rcp_f32_e32 v131, v131
	v_rcp_f32_e32 v132, v132
	v_rcp_f32_e32 v133, v133
	v_rcp_f32_e32 v134, v134
	v_rcp_f32_e32 v135, v135
	v_rcp_f32_e32 v136, v136
	v_rcp_f32_e32 v137, v137
	v_mul_f32_e32 v22, v22, v130
	v_mul_f32_e32 v23, v23, v131
	v_mul_f32_e32 v24, v24, v132
	v_mul_f32_e32 v25, v25, v133
	v_mul_f32_e32 v18, v18, v134
	v_mul_f32_e32 v19, v19, v135
	v_mul_f32_e32 v20, v20, v136
	v_mul_f32_e32 v21, v21, v137
	v_cvt_pk_bf16_f32 v22, v22, v23
	v_cvt_pk_bf16_f32 v23, v24, v25
	v_cvt_pk_bf16_f32 v24, v18, v19
	v_cvt_pk_bf16_f32 v25, v20, v21
	global_store_dwordx4 v139, v[22:25], s[66:67] sc1
	s_add_u32 s66, s66, 0x4000
	s_addc_u32 s67, s67, 0
	v_mul_f32_e32 v130, v14, v14
	v_mul_f32_e32 v131, v15, v15
	v_mul_f32_e32 v132, v16, v16
	v_mul_f32_e32 v133, v17, v17
	v_mul_f32_e32 v134, v10, v10
	v_mul_f32_e32 v135, v11, v11
	v_mul_f32_e32 v136, v12, v12
	v_mul_f32_e32 v137, v13, v13
	v_fmamk_f32 v130, v130, 0xbdd2d3e7, v138
	v_fmamk_f32 v131, v131, 0xbdd2d3e7, v138
	v_fmamk_f32 v132, v132, 0xbdd2d3e7, v138
	v_fmamk_f32 v133, v133, 0xbdd2d3e7, v138
	v_fmamk_f32 v134, v134, 0xbdd2d3e7, v138
	v_fmamk_f32 v135, v135, 0xbdd2d3e7, v138
	v_fmamk_f32 v136, v136, 0xbdd2d3e7, v138
	v_fmamk_f32 v137, v137, 0xbdd2d3e7, v138
	v_mul_f32_e32 v130, v14, v130
	v_mul_f32_e32 v131, v15, v131
	v_mul_f32_e32 v132, v16, v132
	v_mul_f32_e32 v133, v17, v133
	v_mul_f32_e32 v134, v10, v134
	v_mul_f32_e32 v135, v11, v135
	v_mul_f32_e32 v136, v12, v136
	v_mul_f32_e32 v137, v13, v137
	v_exp_f32_e32 v130, v130
	v_exp_f32_e32 v131, v131
	v_exp_f32_e32 v132, v132
	v_exp_f32_e32 v133, v133
	v_exp_f32_e32 v134, v134
	v_exp_f32_e32 v135, v135
	v_exp_f32_e32 v136, v136
	v_exp_f32_e32 v137, v137
	v_add_f32_e32 v130, 1.0, v130
	v_add_f32_e32 v131, 1.0, v131
	v_add_f32_e32 v132, 1.0, v132
	v_add_f32_e32 v133, 1.0, v133
	v_add_f32_e32 v134, 1.0, v134
	v_add_f32_e32 v135, 1.0, v135
	v_add_f32_e32 v136, 1.0, v136
	v_add_f32_e32 v137, 1.0, v137
	v_rcp_f32_e32 v130, v130
	v_rcp_f32_e32 v131, v131
	v_rcp_f32_e32 v132, v132
	v_rcp_f32_e32 v133, v133
	v_rcp_f32_e32 v134, v134
	v_rcp_f32_e32 v135, v135
	v_rcp_f32_e32 v136, v136
	v_rcp_f32_e32 v137, v137
	v_mul_f32_e32 v14, v14, v130
	v_mul_f32_e32 v15, v15, v131
	v_mul_f32_e32 v16, v16, v132
	v_mul_f32_e32 v17, v17, v133
	v_mul_f32_e32 v10, v10, v134
	v_mul_f32_e32 v11, v11, v135
	v_mul_f32_e32 v12, v12, v136
	v_mul_f32_e32 v13, v13, v137
	v_cvt_pk_bf16_f32 v14, v14, v15
	v_cvt_pk_bf16_f32 v15, v16, v17
	v_cvt_pk_bf16_f32 v16, v10, v11
	v_cvt_pk_bf16_f32 v17, v12, v13
	global_store_dwordx4 v139, v[14:17], s[66:67] offset:-4096 sc1
	v_mul_f32_e32 v130, v6, v6
	v_mul_f32_e32 v131, v7, v7
	v_mul_f32_e32 v132, v8, v8
	v_mul_f32_e32 v133, v9, v9
	v_mul_f32_e32 v134, v2, v2
	v_mul_f32_e32 v135, v3, v3
	v_mul_f32_e32 v136, v4, v4
	v_mul_f32_e32 v137, v5, v5
	v_fmamk_f32 v130, v130, 0xbdd2d3e7, v138
	v_fmamk_f32 v131, v131, 0xbdd2d3e7, v138
	v_fmamk_f32 v132, v132, 0xbdd2d3e7, v138
	v_fmamk_f32 v133, v133, 0xbdd2d3e7, v138
	v_fmamk_f32 v134, v134, 0xbdd2d3e7, v138
	v_fmamk_f32 v135, v135, 0xbdd2d3e7, v138
	v_fmamk_f32 v136, v136, 0xbdd2d3e7, v138
	v_fmamk_f32 v137, v137, 0xbdd2d3e7, v138
	v_mul_f32_e32 v130, v6, v130
	v_mul_f32_e32 v131, v7, v131
	v_mul_f32_e32 v132, v8, v132
	v_mul_f32_e32 v133, v9, v133
	v_mul_f32_e32 v134, v2, v134
	v_mul_f32_e32 v135, v3, v135
	v_mul_f32_e32 v136, v4, v136
	v_mul_f32_e32 v137, v5, v137
	v_exp_f32_e32 v130, v130
	v_exp_f32_e32 v131, v131
	v_exp_f32_e32 v132, v132
	v_exp_f32_e32 v133, v133
	v_exp_f32_e32 v134, v134
	v_exp_f32_e32 v135, v135
	v_exp_f32_e32 v136, v136
	v_exp_f32_e32 v137, v137
	v_add_f32_e32 v130, 1.0, v130
	v_add_f32_e32 v131, 1.0, v131
	v_add_f32_e32 v132, 1.0, v132
	v_add_f32_e32 v133, 1.0, v133
	v_add_f32_e32 v134, 1.0, v134
	v_add_f32_e32 v135, 1.0, v135
	v_add_f32_e32 v136, 1.0, v136
	v_add_f32_e32 v137, 1.0, v137
	v_rcp_f32_e32 v130, v130
	v_rcp_f32_e32 v131, v131
	v_rcp_f32_e32 v132, v132
	v_rcp_f32_e32 v133, v133
	v_rcp_f32_e32 v134, v134
	v_rcp_f32_e32 v135, v135
	v_rcp_f32_e32 v136, v136
	v_rcp_f32_e32 v137, v137
	v_mul_f32_e32 v6, v6, v130
	v_mul_f32_e32 v7, v7, v131
	v_mul_f32_e32 v8, v8, v132
	v_mul_f32_e32 v9, v9, v133
	v_mul_f32_e32 v2, v2, v134
	v_mul_f32_e32 v3, v3, v135
	v_mul_f32_e32 v4, v4, v136
	v_mul_f32_e32 v5, v5, v137
	v_cvt_pk_bf16_f32 v6, v6, v7
	v_cvt_pk_bf16_f32 v7, v8, v9
	v_cvt_pk_bf16_f32 v8, v2, v3
	v_cvt_pk_bf16_f32 v9, v4, v5
	global_store_dwordx4 v139, v[6:9], s[66:67] sc1

.LBB0_579:
	s_mov_b64 s[10:11], s[8:9]
	v_mov_b32_e32 v86, s13
	global_load_dword v6, v62, s[10:11] nt
	s_add_u32 s10, s10, 0x6000
	s_addc_u32 s11, s11, 0
	global_load_dword v7, v62, s[10:11] nt
	s_add_u32 s10, s10, 0x6000
	s_addc_u32 s11, s11, 0
	global_load_dword v8, v62, s[10:11] nt
	s_add_u32 s10, s10, 0x6000
	s_addc_u32 s11, s11, 0
	global_load_dword v9, v62, s[10:11] nt
	s_add_u32 s10, s10, 0x6000
	s_addc_u32 s11, s11, 0
	global_load_dword v10, v62, s[10:11] nt
	s_add_u32 s10, s10, 0x6000
	s_addc_u32 s11, s11, 0
	global_load_dword v11, v62, s[10:11] nt
	s_add_u32 s10, s10, 0x6000
	s_addc_u32 s11, s11, 0
	global_load_dword v12, v62, s[10:11] nt
	s_add_u32 s10, s10, 0x6000
	s_addc_u32 s11, s11, 0
	global_load_dword v13, v62, s[10:11] nt
	s_add_u32 s10, s10, 0x6000
	s_addc_u32 s11, s11, 0
	global_load_dword v14, v62, s[10:11] nt
	s_add_u32 s10, s10, 0x6000
	s_addc_u32 s11, s11, 0
	global_load_dword v15, v62, s[10:11] nt
	s_add_u32 s10, s10, 0x6000
	s_addc_u32 s11, s11, 0
	global_load_dword v16, v62, s[10:11] nt
	s_add_u32 s10, s10, 0x6000
	s_addc_u32 s11, s11, 0
	global_load_dword v17, v62, s[10:11] nt
	s_add_u32 s10, s10, 0x6000
	s_addc_u32 s11, s11, 0
	global_load_dword v18, v62, s[10:11] nt
	s_add_u32 s10, s10, 0x6000
	s_addc_u32 s11, s11, 0
	global_load_dword v19, v62, s[10:11] nt
	s_add_u32 s10, s10, 0x6000
	s_addc_u32 s11, s11, 0
	global_load_dword v20, v62, s[10:11] nt
	s_add_u32 s10, s10, 0x6000
	s_addc_u32 s11, s11, 0
	global_load_dword v21, v62, s[10:11] nt
	s_add_u32 s10, s10, 0x6000
	s_addc_u32 s11, s11, 0
	global_load_dword v22, v62, s[10:11] nt
	s_add_u32 s10, s10, 0x6000
	s_addc_u32 s11, s11, 0
	global_load_dword v23, v62, s[10:11] nt
	s_add_u32 s10, s10, 0x6000
	s_addc_u32 s11, s11, 0
	global_load_dword v24, v62, s[10:11] nt
	s_add_u32 s10, s10, 0x6000
	s_addc_u32 s11, s11, 0
	global_load_dword v25, v62, s[10:11] nt
	s_add_u32 s10, s10, 0x6000
	s_addc_u32 s11, s11, 0
	global_load_dword v26, v62, s[10:11] nt
	s_add_u32 s10, s10, 0x6000
	s_addc_u32 s11, s11, 0
	global_load_dword v27, v62, s[10:11] nt
	s_add_u32 s10, s10, 0x6000
	s_addc_u32 s11, s11, 0
	global_load_dword v28, v62, s[10:11] nt
	s_add_u32 s10, s10, 0x6000
	s_addc_u32 s11, s11, 0
	global_load_dword v29, v62, s[10:11] nt
	s_add_u32 s10, s10, 0x6000
	s_addc_u32 s11, s11, 0
	global_load_dword v30, v62, s[10:11] nt
	s_add_u32 s10, s10, 0x6000
	s_addc_u32 s11, s11, 0
	global_load_dword v31, v62, s[10:11] nt
	s_add_u32 s10, s10, 0x6000
	s_addc_u32 s11, s11, 0
	global_load_dword v32, v62, s[10:11] nt
	s_add_u32 s10, s10, 0x6000
	s_addc_u32 s11, s11, 0
	global_load_dword v33, v62, s[10:11] nt
	s_add_u32 s10, s10, 0x6000
	s_addc_u32 s11, s11, 0
	global_load_dword v34, v62, s[10:11] nt
	s_add_u32 s10, s10, 0x6000
	s_addc_u32 s11, s11, 0
	global_load_dword v35, v62, s[10:11] nt
	s_add_u32 s10, s10, 0x6000
	s_addc_u32 s11, s11, 0
	global_load_dword v36, v62, s[10:11] nt
	s_add_u32 s10, s10, 0x6000
	s_addc_u32 s11, s11, 0
	global_load_dword v37, v62, s[10:11] nt
	s_add_u32 s10, s10, 0x6000
	s_addc_u32 s11, s11, 0
	global_load_dword v70, v62, s[10:11] nt
	s_add_u32 s10, s10, 0x6000
	s_addc_u32 s11, s11, 0
	global_load_dword v71, v62, s[10:11] nt
	s_add_u32 s10, s10, 0x6000
	s_addc_u32 s11, s11, 0
	global_load_dword v72, v62, s[10:11] nt
	s_add_u32 s10, s10, 0x6000
	s_addc_u32 s11, s11, 0
	global_load_dword v73, v62, s[10:11] nt
	s_add_u32 s10, s10, 0x6000
	s_addc_u32 s11, s11, 0
	global_load_dword v74, v62, s[10:11] nt
	s_add_u32 s10, s10, 0x6000
	s_addc_u32 s11, s11, 0
	global_load_dword v75, v62, s[10:11] nt
	s_add_u32 s10, s10, 0x6000
	s_addc_u32 s11, s11, 0
	global_load_dword v76, v62, s[10:11] nt
	s_add_u32 s10, s10, 0x6000
	s_addc_u32 s11, s11, 0
	global_load_dword v77, v62, s[10:11] nt
	s_add_u32 s10, s10, 0x6000
	s_addc_u32 s11, s11, 0
	global_load_dword v78, v62, s[10:11] nt
	s_add_u32 s10, s10, 0x6000
	s_addc_u32 s11, s11, 0
	global_load_dword v79, v62, s[10:11] nt
	s_add_u32 s10, s10, 0x6000
	s_addc_u32 s11, s11, 0
	global_load_dword v80, v62, s[10:11] nt
	s_add_u32 s10, s10, 0x6000
	s_addc_u32 s11, s11, 0
	global_load_dword v81, v62, s[10:11] nt
	s_add_u32 s10, s10, 0x6000
	s_addc_u32 s11, s11, 0
	global_load_dword v82, v62, s[10:11] nt
	s_add_u32 s10, s10, 0x6000
	s_addc_u32 s11, s11, 0
	global_load_dword v83, v62, s[10:11] nt
	s_add_u32 s10, s10, 0x6000
	s_addc_u32 s11, s11, 0
	global_load_dword v84, v62, s[10:11] nt
	s_add_u32 s10, s10, 0x6000
	s_addc_u32 s11, s11, 0
	global_load_dword v85, v62, s[10:11] nt
	s_add_u32 s10, s10, 0x6000
	s_addc_u32 s11, s11, 0
	ds_read_b128 v[38:41], v86 offset:0
	ds_read_b128 v[42:45], v86 offset:4096
	ds_read_b128 v[46:49], v86 offset:8192
	ds_read_b128 v[50:53], v86 offset:12288
	ds_read_b128 v[66:69], v86 offset:16384
	s_waitcnt vmcnt(32)
	s_waitcnt lgkmcnt(4)
	v_fmac_f32_e32 v2, v6, v38
	v_fmac_f32_e32 v2, v7, v39
	v_fmac_f32_e32 v2, v8, v40
	v_fmac_f32_e32 v2, v9, v41
	ds_read_b128 v[38:41], v86 offset:16
	s_waitcnt lgkmcnt(4)
	v_fmac_f32_e32 v3, v6, v42
	v_fmac_f32_e32 v3, v7, v43
	v_fmac_f32_e32 v3, v8, v44
	v_fmac_f32_e32 v3, v9, v45
	ds_read_b128 v[42:45], v86 offset:4112
	s_waitcnt lgkmcnt(4)
	v_fmac_f32_e32 v4, v6, v46
	v_fmac_f32_e32 v4, v7, v47
	v_fmac_f32_e32 v4, v8, v48
	v_fmac_f32_e32 v4, v9, v49
	ds_read_b128 v[46:49], v86 offset:8208
	s_waitcnt lgkmcnt(4)
	v_fmac_f32_e32 v5, v6, v50
	v_fmac_f32_e32 v5, v7, v51
	v_fmac_f32_e32 v5, v8, v52
	v_fmac_f32_e32 v5, v9, v53
	ds_read_b128 v[50:53], v86 offset:12304
	s_waitcnt lgkmcnt(4)
	v_fmac_f32_e32 v63, v6, v66
	v_fmac_f32_e32 v63, v7, v67
	v_fmac_f32_e32 v63, v8, v68
	v_fmac_f32_e32 v63, v9, v69
	ds_read_b128 v[66:69], v86 offset:16400
	global_load_dword v6, v62, s[10:11] nt
	s_add_u32 s10, s10, 0x6000
	s_addc_u32 s11, s11, 0
	global_load_dword v7, v62, s[10:11] nt
	s_add_u32 s10, s10, 0x6000
	s_addc_u32 s11, s11, 0
	global_load_dword v8, v62, s[10:11] nt
	s_add_u32 s10, s10, 0x6000
	s_addc_u32 s11, s11, 0
	global_load_dword v9, v62, s[10:11] nt
	s_add_u32 s10, s10, 0x6000
	s_addc_u32 s11, s11, 0
	s_waitcnt lgkmcnt(4)
	v_fmac_f32_e32 v2, v10, v38
	v_fmac_f32_e32 v2, v11, v39
	v_fmac_f32_e32 v2, v12, v40
	v_fmac_f32_e32 v2, v13, v41
	ds_read_b128 v[38:41], v86 offset:32
	s_waitcnt lgkmcnt(4)
	v_fmac_f32_e32 v3, v10, v42
	v_fmac_f32_e32 v3, v11, v43
	v_fmac_f32_e32 v3, v12, v44
	v_fmac_f32_e32 v3, v13, v45
	ds_read_b128 v[42:45], v86 offset:4128
	s_waitcnt lgkmcnt(4)
	v_fmac_f32_e32 v4, v10, v46
	v_fmac_f32_e32 v4, v11, v47
	v_fmac_f32_e32 v4, v12, v48
	v_fmac_f32_e32 v4, v13, v49
	ds_read_b128 v[46:49], v86 offset:8224
	s_waitcnt lgkmcnt(4)
	v_fmac_f32_e32 v5, v10, v50
	v_fmac_f32_e32 v5, v11, v51
	v_fmac_f32_e32 v5, v12, v52
	v_fmac_f32_e32 v5, v13, v53
	ds_read_b128 v[50:53], v86 offset:12320
	s_waitcnt lgkmcnt(4)
	v_fmac_f32_e32 v63, v10, v66
	v_fmac_f32_e32 v63, v11, v67
	v_fmac_f32_e32 v63, v12, v68
	v_fmac_f32_e32 v63, v13, v69
	ds_read_b128 v[66:69], v86 offset:16416
	global_load_dword v10, v62, s[10:11] nt
	s_add_u32 s10, s10, 0x6000
	s_addc_u32 s11, s11, 0
	global_load_dword v11, v62, s[10:11] nt
	s_add_u32 s10, s10, 0x6000
	s_addc_u32 s11, s11, 0
	global_load_dword v12, v62, s[10:11] nt
	s_add_u32 s10, s10, 0x6000
	s_addc_u32 s11, s11, 0
	global_load_dword v13, v62, s[10:11] nt
	s_add_u32 s10, s10, 0x6000
	s_addc_u32 s11, s11, 0
	s_waitcnt lgkmcnt(4)
	v_fmac_f32_e32 v2, v14, v38
	v_fmac_f32_e32 v2, v15, v39
	v_fmac_f32_e32 v2, v16, v40
	v_fmac_f32_e32 v2, v17, v41
	ds_read_b128 v[38:41], v86 offset:48
	s_waitcnt lgkmcnt(4)
	v_fmac_f32_e32 v3, v14, v42
	v_fmac_f32_e32 v3, v15, v43
	v_fmac_f32_e32 v3, v16, v44
	v_fmac_f32_e32 v3, v17, v45
	ds_read_b128 v[42:45], v86 offset:4144
	s_waitcnt lgkmcnt(4)
	v_fmac_f32_e32 v4, v14, v46
	v_fmac_f32_e32 v4, v15, v47
	v_fmac_f32_e32 v4, v16, v48
	v_fmac_f32_e32 v4, v17, v49
	ds_read_b128 v[46:49], v86 offset:8240
	s_waitcnt lgkmcnt(4)
	v_fmac_f32_e32 v5, v14, v50
	v_fmac_f32_e32 v5, v15, v51
	v_fmac_f32_e32 v5, v16, v52
	v_fmac_f32_e32 v5, v17, v53
	ds_read_b128 v[50:53], v86 offset:12336
	s_waitcnt lgkmcnt(4)
	v_fmac_f32_e32 v63, v14, v66
	v_fmac_f32_e32 v63, v15, v67
	v_fmac_f32_e32 v63, v16, v68
	v_fmac_f32_e32 v63, v17, v69
	ds_read_b128 v[66:69], v86 offset:16432
	global_load_dword v14, v62, s[10:11] nt
	s_add_u32 s10, s10, 0x6000
	s_addc_u32 s11, s11, 0
	global_load_dword v15, v62, s[10:11] nt
	s_add_u32 s10, s10, 0x6000
	s_addc_u32 s11, s11, 0
	global_load_dword v16, v62, s[10:11] nt
	s_add_u32 s10, s10, 0x6000
	s_addc_u32 s11, s11, 0
	global_load_dword v17, v62, s[10:11] nt
	s_add_u32 s10, s10, 0x6000
	s_addc_u32 s11, s11, 0
	s_waitcnt lgkmcnt(4)
	v_fmac_f32_e32 v2, v18, v38
	v_fmac_f32_e32 v2, v19, v39
	v_fmac_f32_e32 v2, v20, v40
	v_fmac_f32_e32 v2, v21, v41
	ds_read_b128 v[38:41], v86 offset:64
	s_waitcnt lgkmcnt(4)
	v_fmac_f32_e32 v3, v18, v42
	v_fmac_f32_e32 v3, v19, v43
	v_fmac_f32_e32 v3, v20, v44
	v_fmac_f32_e32 v3, v21, v45
	ds_read_b128 v[42:45], v86 offset:4160
	s_waitcnt lgkmcnt(4)
	v_fmac_f32_e32 v4, v18, v46
	v_fmac_f32_e32 v4, v19, v47
	v_fmac_f32_e32 v4, v20, v48
	v_fmac_f32_e32 v4, v21, v49
	ds_read_b128 v[46:49], v86 offset:8256
	s_waitcnt lgkmcnt(4)
	v_fmac_f32_e32 v5, v18, v50
	v_fmac_f32_e32 v5, v19, v51
	v_fmac_f32_e32 v5, v20, v52
	v_fmac_f32_e32 v5, v21, v53
	ds_read_b128 v[50:53], v86 offset:12352
	s_waitcnt lgkmcnt(4)
	v_fmac_f32_e32 v63, v18, v66
	v_fmac_f32_e32 v63, v19, v67
	v_fmac_f32_e32 v63, v20, v68
	v_fmac_f32_e32 v63, v21, v69
	ds_read_b128 v[66:69], v86 offset:16448
	global_load_dword v18, v62, s[10:11] nt
	s_add_u32 s10, s10, 0x6000
	s_addc_u32 s11, s11, 0
	global_load_dword v19, v62, s[10:11] nt
	s_add_u32 s10, s10, 0x6000
	s_addc_u32 s11, s11, 0
	global_load_dword v20, v62, s[10:11] nt
	s_add_u32 s10, s10, 0x6000
	s_addc_u32 s11, s11, 0
	global_load_dword v21, v62, s[10:11] nt
	s_add_u32 s10, s10, 0x6000
	s_addc_u32 s11, s11, 0
	s_waitcnt vmcnt(32)
	s_waitcnt lgkmcnt(4)
	v_fmac_f32_e32 v2, v22, v38
	v_fmac_f32_e32 v2, v23, v39
	v_fmac_f32_e32 v2, v24, v40
	v_fmac_f32_e32 v2, v25, v41
	ds_read_b128 v[38:41], v86 offset:80
	s_waitcnt lgkmcnt(4)
	v_fmac_f32_e32 v3, v22, v42
	v_fmac_f32_e32 v3, v23, v43
	v_fmac_f32_e32 v3, v24, v44
	v_fmac_f32_e32 v3, v25, v45
	ds_read_b128 v[42:45], v86 offset:4176
	s_waitcnt lgkmcnt(4)
	v_fmac_f32_e32 v4, v22, v46
	v_fmac_f32_e32 v4, v23, v47
	v_fmac_f32_e32 v4, v24, v48
	v_fmac_f32_e32 v4, v25, v49
	ds_read_b128 v[46:49], v86 offset:8272
	s_waitcnt lgkmcnt(4)
	v_fmac_f32_e32 v5, v22, v50
	v_fmac_f32_e32 v5, v23, v51
	v_fmac_f32_e32 v5, v24, v52
	v_fmac_f32_e32 v5, v25, v53
	ds_read_b128 v[50:53], v86 offset:12368
	s_waitcnt lgkmcnt(4)
	v_fmac_f32_e32 v63, v22, v66
	v_fmac_f32_e32 v63, v23, v67
	v_fmac_f32_e32 v63, v24, v68
	v_fmac_f32_e32 v63, v25, v69
	ds_read_b128 v[66:69], v86 offset:16464
	global_load_dword v22, v62, s[10:11] nt
	s_add_u32 s10, s10, 0x6000
	s_addc_u32 s11, s11, 0
	global_load_dword v23, v62, s[10:11] nt
	s_add_u32 s10, s10, 0x6000
	s_addc_u32 s11, s11, 0
	global_load_dword v24, v62, s[10:11] nt
	s_add_u32 s10, s10, 0x6000
	s_addc_u32 s11, s11, 0
	global_load_dword v25, v62, s[10:11] nt
	s_add_u32 s10, s10, 0x6000
	s_addc_u32 s11, s11, 0
	s_waitcnt lgkmcnt(4)
	v_fmac_f32_e32 v2, v26, v38
	v_fmac_f32_e32 v2, v27, v39
	v_fmac_f32_e32 v2, v28, v40
	v_fmac_f32_e32 v2, v29, v41
	ds_read_b128 v[38:41], v86 offset:96
	s_waitcnt lgkmcnt(4)
	v_fmac_f32_e32 v3, v26, v42
	v_fmac_f32_e32 v3, v27, v43
	v_fmac_f32_e32 v3, v28, v44
	v_fmac_f32_e32 v3, v29, v45
	ds_read_b128 v[42:45], v86 offset:4192
	s_waitcnt lgkmcnt(4)
	v_fmac_f32_e32 v4, v26, v46
	v_fmac_f32_e32 v4, v27, v47
	v_fmac_f32_e32 v4, v28, v48
	v_fmac_f32_e32 v4, v29, v49
	ds_read_b128 v[46:49], v86 offset:8288
	s_waitcnt lgkmcnt(4)
	v_fmac_f32_e32 v5, v26, v50
	v_fmac_f32_e32 v5, v27, v51
	v_fmac_f32_e32 v5, v28, v52
	v_fmac_f32_e32 v5, v29, v53
	ds_read_b128 v[50:53], v86 offset:12384
	s_waitcnt lgkmcnt(4)
	v_fmac_f32_e32 v63, v26, v66
	v_fmac_f32_e32 v63, v27, v67
	v_fmac_f32_e32 v63, v28, v68
	v_fmac_f32_e32 v63, v29, v69
	ds_read_b128 v[66:69], v86 offset:16480
	global_load_dword v26, v62, s[10:11] nt
	s_add_u32 s10, s10, 0x6000
	s_addc_u32 s11, s11, 0
	global_load_dword v27, v62, s[10:11] nt
	s_add_u32 s10, s10, 0x6000
	s_addc_u32 s11, s11, 0
	global_load_dword v28, v62, s[10:11] nt
	s_add_u32 s10, s10, 0x6000
	s_addc_u32 s11, s11, 0
	global_load_dword v29, v62, s[10:11] nt
	s_add_u32 s10, s10, 0x6000
	s_addc_u32 s11, s11, 0
	s_waitcnt lgkmcnt(4)
	v_fmac_f32_e32 v2, v30, v38
	v_fmac_f32_e32 v2, v31, v39
	v_fmac_f32_e32 v2, v32, v40
	v_fmac_f32_e32 v2, v33, v41
	ds_read_b128 v[38:41], v86 offset:112
	s_waitcnt lgkmcnt(4)
	v_fmac_f32_e32 v3, v30, v42
	v_fmac_f32_e32 v3, v31, v43
	v_fmac_f32_e32 v3, v32, v44
	v_fmac_f32_e32 v3, v33, v45
	ds_read_b128 v[42:45], v86 offset:4208
	s_waitcnt lgkmcnt(4)
	v_fmac_f32_e32 v4, v30, v46
	v_fmac_f32_e32 v4, v31, v47
	v_fmac_f32_e32 v4, v32, v48
	v_fmac_f32_e32 v4, v33, v49
	ds_read_b128 v[46:49], v86 offset:8304
	s_waitcnt lgkmcnt(4)
	v_fmac_f32_e32 v5, v30, v50
	v_fmac_f32_e32 v5, v31, v51
	v_fmac_f32_e32 v5, v32, v52
	v_fmac_f32_e32 v5, v33, v53
	ds_read_b128 v[50:53], v86 offset:12400
	s_waitcnt lgkmcnt(4)
	v_fmac_f32_e32 v63, v30, v66
	v_fmac_f32_e32 v63, v31, v67
	v_fmac_f32_e32 v63, v32, v68
	v_fmac_f32_e32 v63, v33, v69
	ds_read_b128 v[66:69], v86 offset:16496
	global_load_dword v30, v62, s[10:11] nt
	s_add_u32 s10, s10, 0x6000
	s_addc_u32 s11, s11, 0
	global_load_dword v31, v62, s[10:11] nt
	s_add_u32 s10, s10, 0x6000
	s_addc_u32 s11, s11, 0
	global_load_dword v32, v62, s[10:11] nt
	s_add_u32 s10, s10, 0x6000
	s_addc_u32 s11, s11, 0
	global_load_dword v33, v62, s[10:11] nt
	s_add_u32 s10, s10, 0x6000
	s_addc_u32 s11, s11, 0
	s_waitcnt lgkmcnt(4)
	v_fmac_f32_e32 v2, v34, v38
	v_fmac_f32_e32 v2, v35, v39
	v_fmac_f32_e32 v2, v36, v40
	v_fmac_f32_e32 v2, v37, v41
	ds_read_b128 v[38:41], v86 offset:128
	s_waitcnt lgkmcnt(4)
	v_fmac_f32_e32 v3, v34, v42
	v_fmac_f32_e32 v3, v35, v43
	v_fmac_f32_e32 v3, v36, v44
	v_fmac_f32_e32 v3, v37, v45
	ds_read_b128 v[42:45], v86 offset:4224
	s_waitcnt lgkmcnt(4)
	v_fmac_f32_e32 v4, v34, v46
	v_fmac_f32_e32 v4, v35, v47
	v_fmac_f32_e32 v4, v36, v48
	v_fmac_f32_e32 v4, v37, v49
	ds_read_b128 v[46:49], v86 offset:8320
	s_waitcnt lgkmcnt(4)
	v_fmac_f32_e32 v5, v34, v50
	v_fmac_f32_e32 v5, v35, v51
	v_fmac_f32_e32 v5, v36, v52
	v_fmac_f32_e32 v5, v37, v53
	ds_read_b128 v[50:53], v86 offset:12416
	s_waitcnt lgkmcnt(4)
	v_fmac_f32_e32 v63, v34, v66
	v_fmac_f32_e32 v63, v35, v67
	v_fmac_f32_e32 v63, v36, v68
	v_fmac_f32_e32 v63, v37, v69
	ds_read_b128 v[66:69], v86 offset:16512
	global_load_dword v34, v62, s[10:11] nt
	s_add_u32 s10, s10, 0x6000
	s_addc_u32 s11, s11, 0
	global_load_dword v35, v62, s[10:11] nt
	s_add_u32 s10, s10, 0x6000
	s_addc_u32 s11, s11, 0
	global_load_dword v36, v62, s[10:11] nt
	s_add_u32 s10, s10, 0x6000
	s_addc_u32 s11, s11, 0
	global_load_dword v37, v62, s[10:11] nt
	s_add_u32 s10, s10, 0x6000
	s_addc_u32 s11, s11, 0
	s_waitcnt vmcnt(32)
	s_waitcnt lgkmcnt(4)
	v_fmac_f32_e32 v2, v70, v38
	v_fmac_f32_e32 v2, v71, v39
	v_fmac_f32_e32 v2, v72, v40
	v_fmac_f32_e32 v2, v73, v41
	ds_read_b128 v[38:41], v86 offset:144
	s_waitcnt lgkmcnt(4)
	v_fmac_f32_e32 v3, v70, v42
	v_fmac_f32_e32 v3, v71, v43
	v_fmac_f32_e32 v3, v72, v44
	v_fmac_f32_e32 v3, v73, v45
	ds_read_b128 v[42:45], v86 offset:4240
	s_waitcnt lgkmcnt(4)
	v_fmac_f32_e32 v4, v70, v46
	v_fmac_f32_e32 v4, v71, v47
	v_fmac_f32_e32 v4, v72, v48
	v_fmac_f32_e32 v4, v73, v49
	ds_read_b128 v[46:49], v86 offset:8336
	s_waitcnt lgkmcnt(4)
	v_fmac_f32_e32 v5, v70, v50
	v_fmac_f32_e32 v5, v71, v51
	v_fmac_f32_e32 v5, v72, v52
	v_fmac_f32_e32 v5, v73, v53
	ds_read_b128 v[50:53], v86 offset:12432
	s_waitcnt lgkmcnt(4)
	v_fmac_f32_e32 v63, v70, v66
	v_fmac_f32_e32 v63, v71, v67
	v_fmac_f32_e32 v63, v72, v68
	v_fmac_f32_e32 v63, v73, v69
	ds_read_b128 v[66:69], v86 offset:16528
	global_load_dword v70, v62, s[10:11] nt
	s_add_u32 s10, s10, 0x6000
	s_addc_u32 s11, s11, 0
	global_load_dword v71, v62, s[10:11] nt
	s_add_u32 s10, s10, 0x6000
	s_addc_u32 s11, s11, 0
	global_load_dword v72, v62, s[10:11] nt
	s_add_u32 s10, s10, 0x6000
	s_addc_u32 s11, s11, 0
	global_load_dword v73, v62, s[10:11] nt
	s_add_u32 s10, s10, 0x6000
	s_addc_u32 s11, s11, 0
	s_waitcnt lgkmcnt(4)
	v_fmac_f32_e32 v2, v74, v38
	v_fmac_f32_e32 v2, v75, v39
	v_fmac_f32_e32 v2, v76, v40
	v_fmac_f32_e32 v2, v77, v41
	ds_read_b128 v[38:41], v86 offset:160
	s_waitcnt lgkmcnt(4)
	v_fmac_f32_e32 v3, v74, v42
	v_fmac_f32_e32 v3, v75, v43
	v_fmac_f32_e32 v3, v76, v44
	v_fmac_f32_e32 v3, v77, v45
	ds_read_b128 v[42:45], v86 offset:4256
	s_waitcnt lgkmcnt(4)
	v_fmac_f32_e32 v4, v74, v46
	v_fmac_f32_e32 v4, v75, v47
	v_fmac_f32_e32 v4, v76, v48
	v_fmac_f32_e32 v4, v77, v49
	ds_read_b128 v[46:49], v86 offset:8352
	s_waitcnt lgkmcnt(4)
	v_fmac_f32_e32 v5, v74, v50
	v_fmac_f32_e32 v5, v75, v51
	v_fmac_f32_e32 v5, v76, v52
	v_fmac_f32_e32 v5, v77, v53
	ds_read_b128 v[50:53], v86 offset:12448
	s_waitcnt lgkmcnt(4)
	v_fmac_f32_e32 v63, v74, v66
	v_fmac_f32_e32 v63, v75, v67
	v_fmac_f32_e32 v63, v76, v68
	v_fmac_f32_e32 v63, v77, v69
	ds_read_b128 v[66:69], v86 offset:16544
	global_load_dword v74, v62, s[10:11] nt
	s_add_u32 s10, s10, 0x6000
	s_addc_u32 s11, s11, 0
	global_load_dword v75, v62, s[10:11] nt
	s_add_u32 s10, s10, 0x6000
	s_addc_u32 s11, s11, 0
	global_load_dword v76, v62, s[10:11] nt
	s_add_u32 s10, s10, 0x6000
	s_addc_u32 s11, s11, 0
	global_load_dword v77, v62, s[10:11] nt
	s_add_u32 s10, s10, 0x6000
	s_addc_u32 s11, s11, 0
	s_waitcnt lgkmcnt(4)
	v_fmac_f32_e32 v2, v78, v38
	v_fmac_f32_e32 v2, v79, v39
	v_fmac_f32_e32 v2, v80, v40
	v_fmac_f32_e32 v2, v81, v41
	ds_read_b128 v[38:41], v86 offset:176
	s_waitcnt lgkmcnt(4)
	v_fmac_f32_e32 v3, v78, v42
	v_fmac_f32_e32 v3, v79, v43
	v_fmac_f32_e32 v3, v80, v44
	v_fmac_f32_e32 v3, v81, v45
	ds_read_b128 v[42:45], v86 offset:4272
	s_waitcnt lgkmcnt(4)
	v_fmac_f32_e32 v4, v78, v46
	v_fmac_f32_e32 v4, v79, v47
	v_fmac_f32_e32 v4, v80, v48
	v_fmac_f32_e32 v4, v81, v49
	ds_read_b128 v[46:49], v86 offset:8368
	s_waitcnt lgkmcnt(4)
	v_fmac_f32_e32 v5, v78, v50
	v_fmac_f32_e32 v5, v79, v51
	v_fmac_f32_e32 v5, v80, v52
	v_fmac_f32_e32 v5, v81, v53
	ds_read_b128 v[50:53], v86 offset:12464
	s_waitcnt lgkmcnt(4)
	v_fmac_f32_e32 v63, v78, v66
	v_fmac_f32_e32 v63, v79, v67
	v_fmac_f32_e32 v63, v80, v68
	v_fmac_f32_e32 v63, v81, v69
	ds_read_b128 v[66:69], v86 offset:16560
	global_load_dword v78, v62, s[10:11] nt
	s_add_u32 s10, s10, 0x6000
	s_addc_u32 s11, s11, 0
	global_load_dword v79, v62, s[10:11] nt
	s_add_u32 s10, s10, 0x6000
	s_addc_u32 s11, s11, 0
	global_load_dword v80, v62, s[10:11] nt
	s_add_u32 s10, s10, 0x6000
	s_addc_u32 s11, s11, 0
	global_load_dword v81, v62, s[10:11] nt
	s_add_u32 s10, s10, 0x6000
	s_addc_u32 s11, s11, 0
	s_waitcnt lgkmcnt(4)
	v_fmac_f32_e32 v2, v82, v38
	v_fmac_f32_e32 v2, v83, v39
	v_fmac_f32_e32 v2, v84, v40
	v_fmac_f32_e32 v2, v85, v41
	ds_read_b128 v[38:41], v86 offset:192
	s_waitcnt lgkmcnt(4)
	v_fmac_f32_e32 v3, v82, v42
	v_fmac_f32_e32 v3, v83, v43
	v_fmac_f32_e32 v3, v84, v44
	v_fmac_f32_e32 v3, v85, v45
	ds_read_b128 v[42:45], v86 offset:4288
	s_waitcnt lgkmcnt(4)
	v_fmac_f32_e32 v4, v82, v46
	v_fmac_f32_e32 v4, v83, v47
	v_fmac_f32_e32 v4, v84, v48
	v_fmac_f32_e32 v4, v85, v49
	ds_read_b128 v[46:49], v86 offset:8384
	s_waitcnt lgkmcnt(4)
	v_fmac_f32_e32 v5, v82, v50
	v_fmac_f32_e32 v5, v83, v51
	v_fmac_f32_e32 v5, v84, v52
	v_fmac_f32_e32 v5, v85, v53
	ds_read_b128 v[50:53], v86 offset:12480
	s_waitcnt lgkmcnt(4)
	v_fmac_f32_e32 v63, v82, v66
	v_fmac_f32_e32 v63, v83, v67
	v_fmac_f32_e32 v63, v84, v68
	v_fmac_f32_e32 v63, v85, v69
	ds_read_b128 v[66:69], v86 offset:16576
	global_load_dword v82, v62, s[10:11] nt
	s_add_u32 s10, s10, 0x6000
	s_addc_u32 s11, s11, 0
	global_load_dword v83, v62, s[10:11] nt
	s_add_u32 s10, s10, 0x6000
	s_addc_u32 s11, s11, 0
	global_load_dword v84, v62, s[10:11] nt
	s_add_u32 s10, s10, 0x6000
	s_addc_u32 s11, s11, 0
	global_load_dword v85, v62, s[10:11] nt
	s_add_u32 s10, s10, 0x6000
	s_addc_u32 s11, s11, 0
	s_waitcnt vmcnt(32)
	s_waitcnt lgkmcnt(4)
	v_fmac_f32_e32 v2, v6, v38
	v_fmac_f32_e32 v2, v7, v39
	v_fmac_f32_e32 v2, v8, v40
	v_fmac_f32_e32 v2, v9, v41
	ds_read_b128 v[38:41], v86 offset:208
	s_waitcnt lgkmcnt(4)
	v_fmac_f32_e32 v3, v6, v42
	v_fmac_f32_e32 v3, v7, v43
	v_fmac_f32_e32 v3, v8, v44
	v_fmac_f32_e32 v3, v9, v45
	ds_read_b128 v[42:45], v86 offset:4304
	s_waitcnt lgkmcnt(4)
	v_fmac_f32_e32 v4, v6, v46
	v_fmac_f32_e32 v4, v7, v47
	v_fmac_f32_e32 v4, v8, v48
	v_fmac_f32_e32 v4, v9, v49
	ds_read_b128 v[46:49], v86 offset:8400
	s_waitcnt lgkmcnt(4)
	v_fmac_f32_e32 v5, v6, v50
	v_fmac_f32_e32 v5, v7, v51
	v_fmac_f32_e32 v5, v8, v52
	v_fmac_f32_e32 v5, v9, v53
	ds_read_b128 v[50:53], v86 offset:12496
	s_waitcnt lgkmcnt(4)
	v_fmac_f32_e32 v63, v6, v66
	v_fmac_f32_e32 v63, v7, v67
	v_fmac_f32_e32 v63, v8, v68
	v_fmac_f32_e32 v63, v9, v69
	ds_read_b128 v[66:69], v86 offset:16592
	global_load_dword v6, v62, s[10:11] nt
	s_add_u32 s10, s10, 0x6000
	s_addc_u32 s11, s11, 0
	global_load_dword v7, v62, s[10:11] nt
	s_add_u32 s10, s10, 0x6000
	s_addc_u32 s11, s11, 0
	global_load_dword v8, v62, s[10:11] nt
	s_add_u32 s10, s10, 0x6000
	s_addc_u32 s11, s11, 0
	global_load_dword v9, v62, s[10:11] nt
	s_add_u32 s10, s10, 0x6000
	s_addc_u32 s11, s11, 0
	s_waitcnt lgkmcnt(4)
	v_fmac_f32_e32 v2, v10, v38
	v_fmac_f32_e32 v2, v11, v39
	v_fmac_f32_e32 v2, v12, v40
	v_fmac_f32_e32 v2, v13, v41
	ds_read_b128 v[38:41], v86 offset:224
	s_waitcnt lgkmcnt(4)
	v_fmac_f32_e32 v3, v10, v42
	v_fmac_f32_e32 v3, v11, v43
	v_fmac_f32_e32 v3, v12, v44
	v_fmac_f32_e32 v3, v13, v45
	ds_read_b128 v[42:45], v86 offset:4320
	s_waitcnt lgkmcnt(4)
	v_fmac_f32_e32 v4, v10, v46
	v_fmac_f32_e32 v4, v11, v47
	v_fmac_f32_e32 v4, v12, v48
	v_fmac_f32_e32 v4, v13, v49
	ds_read_b128 v[46:49], v86 offset:8416
	s_waitcnt lgkmcnt(4)
	v_fmac_f32_e32 v5, v10, v50
	v_fmac_f32_e32 v5, v11, v51
	v_fmac_f32_e32 v5, v12, v52
	v_fmac_f32_e32 v5, v13, v53
	ds_read_b128 v[50:53], v86 offset:12512
	s_waitcnt lgkmcnt(4)
	v_fmac_f32_e32 v63, v10, v66
	v_fmac_f32_e32 v63, v11, v67
	v_fmac_f32_e32 v63, v12, v68
	v_fmac_f32_e32 v63, v13, v69
	ds_read_b128 v[66:69], v86 offset:16608
	global_load_dword v10, v62, s[10:11] nt
	s_add_u32 s10, s10, 0x6000
	s_addc_u32 s11, s11, 0
	global_load_dword v11, v62, s[10:11] nt
	s_add_u32 s10, s10, 0x6000
	s_addc_u32 s11, s11, 0
	global_load_dword v12, v62, s[10:11] nt
	s_add_u32 s10, s10, 0x6000
	s_addc_u32 s11, s11, 0
	global_load_dword v13, v62, s[10:11] nt
	s_add_u32 s10, s10, 0x6000
	s_addc_u32 s11, s11, 0
	s_waitcnt lgkmcnt(4)
	v_fmac_f32_e32 v2, v14, v38
	v_fmac_f32_e32 v2, v15, v39
	v_fmac_f32_e32 v2, v16, v40
	v_fmac_f32_e32 v2, v17, v41
	ds_read_b128 v[38:41], v86 offset:240
	s_waitcnt lgkmcnt(4)
	v_fmac_f32_e32 v3, v14, v42
	v_fmac_f32_e32 v3, v15, v43
	v_fmac_f32_e32 v3, v16, v44
	v_fmac_f32_e32 v3, v17, v45
	ds_read_b128 v[42:45], v86 offset:4336
	s_waitcnt lgkmcnt(4)
	v_fmac_f32_e32 v4, v14, v46
	v_fmac_f32_e32 v4, v15, v47
	v_fmac_f32_e32 v4, v16, v48
	v_fmac_f32_e32 v4, v17, v49
	ds_read_b128 v[46:49], v86 offset:8432
	s_waitcnt lgkmcnt(4)
	v_fmac_f32_e32 v5, v14, v50
	v_fmac_f32_e32 v5, v15, v51
	v_fmac_f32_e32 v5, v16, v52
	v_fmac_f32_e32 v5, v17, v53
	ds_read_b128 v[50:53], v86 offset:12528
	s_waitcnt lgkmcnt(4)
	v_fmac_f32_e32 v63, v14, v66
	v_fmac_f32_e32 v63, v15, v67
	v_fmac_f32_e32 v63, v16, v68
	v_fmac_f32_e32 v63, v17, v69
	ds_read_b128 v[66:69], v86 offset:16624
	global_load_dword v14, v62, s[10:11] nt
	s_add_u32 s10, s10, 0x6000
	s_addc_u32 s11, s11, 0
	global_load_dword v15, v62, s[10:11] nt
	s_add_u32 s10, s10, 0x6000
	s_addc_u32 s11, s11, 0
	global_load_dword v16, v62, s[10:11] nt
	s_add_u32 s10, s10, 0x6000
	s_addc_u32 s11, s11, 0
	global_load_dword v17, v62, s[10:11] nt
	s_add_u32 s10, s10, 0x6000
	s_addc_u32 s11, s11, 0
	s_waitcnt lgkmcnt(4)
	v_fmac_f32_e32 v2, v18, v38
	v_fmac_f32_e32 v2, v19, v39
	v_fmac_f32_e32 v2, v20, v40
	v_fmac_f32_e32 v2, v21, v41
	ds_read_b128 v[38:41], v86 offset:256
	s_waitcnt lgkmcnt(4)
	v_fmac_f32_e32 v3, v18, v42
	v_fmac_f32_e32 v3, v19, v43
	v_fmac_f32_e32 v3, v20, v44
	v_fmac_f32_e32 v3, v21, v45
	ds_read_b128 v[42:45], v86 offset:4352
	s_waitcnt lgkmcnt(4)
	v_fmac_f32_e32 v4, v18, v46
	v_fmac_f32_e32 v4, v19, v47
	v_fmac_f32_e32 v4, v20, v48
	v_fmac_f32_e32 v4, v21, v49
	ds_read_b128 v[46:49], v86 offset:8448
	s_waitcnt lgkmcnt(4)
	v_fmac_f32_e32 v5, v18, v50
	v_fmac_f32_e32 v5, v19, v51
	v_fmac_f32_e32 v5, v20, v52
	v_fmac_f32_e32 v5, v21, v53
	ds_read_b128 v[50:53], v86 offset:12544
	s_waitcnt lgkmcnt(4)
	v_fmac_f32_e32 v63, v18, v66
	v_fmac_f32_e32 v63, v19, v67
	v_fmac_f32_e32 v63, v20, v68
	v_fmac_f32_e32 v63, v21, v69
	ds_read_b128 v[66:69], v86 offset:16640
	global_load_dword v18, v62, s[10:11] nt
	s_add_u32 s10, s10, 0x6000
	s_addc_u32 s11, s11, 0
	global_load_dword v19, v62, s[10:11] nt
	s_add_u32 s10, s10, 0x6000
	s_addc_u32 s11, s11, 0
	global_load_dword v20, v62, s[10:11] nt
	s_add_u32 s10, s10, 0x6000
	s_addc_u32 s11, s11, 0
	global_load_dword v21, v62, s[10:11] nt
	s_add_u32 s10, s10, 0x6000
	s_addc_u32 s11, s11, 0
	s_waitcnt vmcnt(32)
	s_waitcnt lgkmcnt(4)
	v_fmac_f32_e32 v2, v22, v38
	v_fmac_f32_e32 v2, v23, v39
	v_fmac_f32_e32 v2, v24, v40
	v_fmac_f32_e32 v2, v25, v41
	ds_read_b128 v[38:41], v86 offset:272
	s_waitcnt lgkmcnt(4)
	v_fmac_f32_e32 v3, v22, v42
	v_fmac_f32_e32 v3, v23, v43
	v_fmac_f32_e32 v3, v24, v44
	v_fmac_f32_e32 v3, v25, v45
	ds_read_b128 v[42:45], v86 offset:4368
	s_waitcnt lgkmcnt(4)
	v_fmac_f32_e32 v4, v22, v46
	v_fmac_f32_e32 v4, v23, v47
	v_fmac_f32_e32 v4, v24, v48
	v_fmac_f32_e32 v4, v25, v49
	ds_read_b128 v[46:49], v86 offset:8464
	s_waitcnt lgkmcnt(4)
	v_fmac_f32_e32 v5, v22, v50
	v_fmac_f32_e32 v5, v23, v51
	v_fmac_f32_e32 v5, v24, v52
	v_fmac_f32_e32 v5, v25, v53
	ds_read_b128 v[50:53], v86 offset:12560
	s_waitcnt lgkmcnt(4)
	v_fmac_f32_e32 v63, v22, v66
	v_fmac_f32_e32 v63, v23, v67
	v_fmac_f32_e32 v63, v24, v68
	v_fmac_f32_e32 v63, v25, v69
	ds_read_b128 v[66:69], v86 offset:16656
	global_load_dword v22, v62, s[10:11] nt
	s_add_u32 s10, s10, 0x6000
	s_addc_u32 s11, s11, 0
	global_load_dword v23, v62, s[10:11] nt
	s_add_u32 s10, s10, 0x6000
	s_addc_u32 s11, s11, 0
	global_load_dword v24, v62, s[10:11] nt
	s_add_u32 s10, s10, 0x6000
	s_addc_u32 s11, s11, 0
	global_load_dword v25, v62, s[10:11] nt
	s_add_u32 s10, s10, 0x6000
	s_addc_u32 s11, s11, 0
	s_waitcnt lgkmcnt(4)
	v_fmac_f32_e32 v2, v26, v38
	v_fmac_f32_e32 v2, v27, v39
	v_fmac_f32_e32 v2, v28, v40
	v_fmac_f32_e32 v2, v29, v41
	ds_read_b128 v[38:41], v86 offset:288
	s_waitcnt lgkmcnt(4)
	v_fmac_f32_e32 v3, v26, v42
	v_fmac_f32_e32 v3, v27, v43
	v_fmac_f32_e32 v3, v28, v44
	v_fmac_f32_e32 v3, v29, v45
	ds_read_b128 v[42:45], v86 offset:4384
	s_waitcnt lgkmcnt(4)
	v_fmac_f32_e32 v4, v26, v46
	v_fmac_f32_e32 v4, v27, v47
	v_fmac_f32_e32 v4, v28, v48
	v_fmac_f32_e32 v4, v29, v49
	ds_read_b128 v[46:49], v86 offset:8480
	s_waitcnt lgkmcnt(4)
	v_fmac_f32_e32 v5, v26, v50
	v_fmac_f32_e32 v5, v27, v51
	v_fmac_f32_e32 v5, v28, v52
	v_fmac_f32_e32 v5, v29, v53
	ds_read_b128 v[50:53], v86 offset:12576
	s_waitcnt lgkmcnt(4)
	v_fmac_f32_e32 v63, v26, v66
	v_fmac_f32_e32 v63, v27, v67
	v_fmac_f32_e32 v63, v28, v68
	v_fmac_f32_e32 v63, v29, v69
	ds_read_b128 v[66:69], v86 offset:16672
	global_load_dword v26, v62, s[10:11] nt
	s_add_u32 s10, s10, 0x6000
	s_addc_u32 s11, s11, 0
	global_load_dword v27, v62, s[10:11] nt
	s_add_u32 s10, s10, 0x6000
	s_addc_u32 s11, s11, 0
	global_load_dword v28, v62, s[10:11] nt
	s_add_u32 s10, s10, 0x6000
	s_addc_u32 s11, s11, 0
	global_load_dword v29, v62, s[10:11] nt
	s_add_u32 s10, s10, 0x6000
	s_addc_u32 s11, s11, 0
	s_waitcnt lgkmcnt(4)
	v_fmac_f32_e32 v2, v30, v38
	v_fmac_f32_e32 v2, v31, v39
	v_fmac_f32_e32 v2, v32, v40
	v_fmac_f32_e32 v2, v33, v41
	ds_read_b128 v[38:41], v86 offset:304
	s_waitcnt lgkmcnt(4)
	v_fmac_f32_e32 v3, v30, v42
	v_fmac_f32_e32 v3, v31, v43
	v_fmac_f32_e32 v3, v32, v44
	v_fmac_f32_e32 v3, v33, v45
	ds_read_b128 v[42:45], v86 offset:4400
	s_waitcnt lgkmcnt(4)
	v_fmac_f32_e32 v4, v30, v46
	v_fmac_f32_e32 v4, v31, v47
	v_fmac_f32_e32 v4, v32, v48
	v_fmac_f32_e32 v4, v33, v49
	ds_read_b128 v[46:49], v86 offset:8496
	s_waitcnt lgkmcnt(4)
	v_fmac_f32_e32 v5, v30, v50
	v_fmac_f32_e32 v5, v31, v51
	v_fmac_f32_e32 v5, v32, v52
	v_fmac_f32_e32 v5, v33, v53
	ds_read_b128 v[50:53], v86 offset:12592
	s_waitcnt lgkmcnt(4)
	v_fmac_f32_e32 v63, v30, v66
	v_fmac_f32_e32 v63, v31, v67
	v_fmac_f32_e32 v63, v32, v68
	v_fmac_f32_e32 v63, v33, v69
	ds_read_b128 v[66:69], v86 offset:16688
	global_load_dword v30, v62, s[10:11] nt
	s_add_u32 s10, s10, 0x6000
	s_addc_u32 s11, s11, 0
	global_load_dword v31, v62, s[10:11] nt
	s_add_u32 s10, s10, 0x6000
	s_addc_u32 s11, s11, 0
	global_load_dword v32, v62, s[10:11] nt
	s_add_u32 s10, s10, 0x6000
	s_addc_u32 s11, s11, 0
	global_load_dword v33, v62, s[10:11] nt
	s_add_u32 s10, s10, 0x6000
	s_addc_u32 s11, s11, 0
	s_waitcnt lgkmcnt(4)
	v_fmac_f32_e32 v2, v34, v38
	v_fmac_f32_e32 v2, v35, v39
	v_fmac_f32_e32 v2, v36, v40
	v_fmac_f32_e32 v2, v37, v41
	ds_read_b128 v[38:41], v86 offset:320
	s_waitcnt lgkmcnt(4)
	v_fmac_f32_e32 v3, v34, v42
	v_fmac_f32_e32 v3, v35, v43
	v_fmac_f32_e32 v3, v36, v44
	v_fmac_f32_e32 v3, v37, v45
	ds_read_b128 v[42:45], v86 offset:4416
	s_waitcnt lgkmcnt(4)
	v_fmac_f32_e32 v4, v34, v46
	v_fmac_f32_e32 v4, v35, v47
	v_fmac_f32_e32 v4, v36, v48
	v_fmac_f32_e32 v4, v37, v49
	ds_read_b128 v[46:49], v86 offset:8512
	s_waitcnt lgkmcnt(4)
	v_fmac_f32_e32 v5, v34, v50
	v_fmac_f32_e32 v5, v35, v51
	v_fmac_f32_e32 v5, v36, v52
	v_fmac_f32_e32 v5, v37, v53
	ds_read_b128 v[50:53], v86 offset:12608
	s_waitcnt lgkmcnt(4)
	v_fmac_f32_e32 v63, v34, v66
	v_fmac_f32_e32 v63, v35, v67
	v_fmac_f32_e32 v63, v36, v68
	v_fmac_f32_e32 v63, v37, v69
	ds_read_b128 v[66:69], v86 offset:16704
	global_load_dword v34, v62, s[10:11] nt
	s_add_u32 s10, s10, 0x6000
	s_addc_u32 s11, s11, 0
	global_load_dword v35, v62, s[10:11] nt
	s_add_u32 s10, s10, 0x6000
	s_addc_u32 s11, s11, 0
	global_load_dword v36, v62, s[10:11] nt
	s_add_u32 s10, s10, 0x6000
	s_addc_u32 s11, s11, 0
	global_load_dword v37, v62, s[10:11] nt
	s_add_u32 s10, s10, 0x6000
	s_addc_u32 s11, s11, 0
	s_waitcnt vmcnt(32)
	s_waitcnt lgkmcnt(4)
	v_fmac_f32_e32 v2, v70, v38
	v_fmac_f32_e32 v2, v71, v39
	v_fmac_f32_e32 v2, v72, v40
	v_fmac_f32_e32 v2, v73, v41
	ds_read_b128 v[38:41], v86 offset:336
	s_waitcnt lgkmcnt(4)
	v_fmac_f32_e32 v3, v70, v42
	v_fmac_f32_e32 v3, v71, v43
	v_fmac_f32_e32 v3, v72, v44
	v_fmac_f32_e32 v3, v73, v45
	ds_read_b128 v[42:45], v86 offset:4432
	s_waitcnt lgkmcnt(4)
	v_fmac_f32_e32 v4, v70, v46
	v_fmac_f32_e32 v4, v71, v47
	v_fmac_f32_e32 v4, v72, v48
	v_fmac_f32_e32 v4, v73, v49
	ds_read_b128 v[46:49], v86 offset:8528
	s_waitcnt lgkmcnt(4)
	v_fmac_f32_e32 v5, v70, v50
	v_fmac_f32_e32 v5, v71, v51
	v_fmac_f32_e32 v5, v72, v52
	v_fmac_f32_e32 v5, v73, v53
	ds_read_b128 v[50:53], v86 offset:12624
	s_waitcnt lgkmcnt(4)
	v_fmac_f32_e32 v63, v70, v66
	v_fmac_f32_e32 v63, v71, v67
	v_fmac_f32_e32 v63, v72, v68
	v_fmac_f32_e32 v63, v73, v69
	ds_read_b128 v[66:69], v86 offset:16720
	s_waitcnt lgkmcnt(4)
	v_fmac_f32_e32 v2, v74, v38
	v_fmac_f32_e32 v2, v75, v39
	v_fmac_f32_e32 v2, v76, v40
	v_fmac_f32_e32 v2, v77, v41
	ds_read_b128 v[38:41], v86 offset:352
	s_waitcnt lgkmcnt(4)
	v_fmac_f32_e32 v3, v74, v42
	v_fmac_f32_e32 v3, v75, v43
	v_fmac_f32_e32 v3, v76, v44
	v_fmac_f32_e32 v3, v77, v45
	ds_read_b128 v[42:45], v86 offset:4448
	s_waitcnt lgkmcnt(4)
	v_fmac_f32_e32 v4, v74, v46
	v_fmac_f32_e32 v4, v75, v47
	v_fmac_f32_e32 v4, v76, v48
	v_fmac_f32_e32 v4, v77, v49
	ds_read_b128 v[46:49], v86 offset:8544
	s_waitcnt lgkmcnt(4)
	v_fmac_f32_e32 v5, v74, v50
	v_fmac_f32_e32 v5, v75, v51
	v_fmac_f32_e32 v5, v76, v52
	v_fmac_f32_e32 v5, v77, v53
	ds_read_b128 v[50:53], v86 offset:12640
	s_waitcnt lgkmcnt(4)
	v_fmac_f32_e32 v63, v74, v66
	v_fmac_f32_e32 v63, v75, v67
	v_fmac_f32_e32 v63, v76, v68
	v_fmac_f32_e32 v63, v77, v69
	ds_read_b128 v[66:69], v86 offset:16736
	s_waitcnt lgkmcnt(4)
	v_fmac_f32_e32 v2, v78, v38
	v_fmac_f32_e32 v2, v79, v39
	v_fmac_f32_e32 v2, v80, v40
	v_fmac_f32_e32 v2, v81, v41
	ds_read_b128 v[38:41], v86 offset:368
	s_waitcnt lgkmcnt(4)
	v_fmac_f32_e32 v3, v78, v42
	v_fmac_f32_e32 v3, v79, v43
	v_fmac_f32_e32 v3, v80, v44
	v_fmac_f32_e32 v3, v81, v45
	ds_read_b128 v[42:45], v86 offset:4464
	s_waitcnt lgkmcnt(4)
	v_fmac_f32_e32 v4, v78, v46
	v_fmac_f32_e32 v4, v79, v47
	v_fmac_f32_e32 v4, v80, v48
	v_fmac_f32_e32 v4, v81, v49
	ds_read_b128 v[46:49], v86 offset:8560
	s_waitcnt lgkmcnt(4)
	v_fmac_f32_e32 v5, v78, v50
	v_fmac_f32_e32 v5, v79, v51
	v_fmac_f32_e32 v5, v80, v52
	v_fmac_f32_e32 v5, v81, v53
	ds_read_b128 v[50:53], v86 offset:12656
	s_waitcnt lgkmcnt(4)
	v_fmac_f32_e32 v63, v78, v66
	v_fmac_f32_e32 v63, v79, v67
	v_fmac_f32_e32 v63, v80, v68
	v_fmac_f32_e32 v63, v81, v69
	ds_read_b128 v[66:69], v86 offset:16752
	s_waitcnt lgkmcnt(4)
	v_fmac_f32_e32 v2, v82, v38
	v_fmac_f32_e32 v2, v83, v39
	v_fmac_f32_e32 v2, v84, v40
	v_fmac_f32_e32 v2, v85, v41
	ds_read_b128 v[38:41], v86 offset:384
	s_waitcnt lgkmcnt(4)
	v_fmac_f32_e32 v3, v82, v42
	v_fmac_f32_e32 v3, v83, v43
	v_fmac_f32_e32 v3, v84, v44
	v_fmac_f32_e32 v3, v85, v45
	ds_read_b128 v[42:45], v86 offset:4480
	s_waitcnt lgkmcnt(4)
	v_fmac_f32_e32 v4, v82, v46
	v_fmac_f32_e32 v4, v83, v47
	v_fmac_f32_e32 v4, v84, v48
	v_fmac_f32_e32 v4, v85, v49
	ds_read_b128 v[46:49], v86 offset:8576
	s_waitcnt lgkmcnt(4)
	v_fmac_f32_e32 v5, v82, v50
	v_fmac_f32_e32 v5, v83, v51
	v_fmac_f32_e32 v5, v84, v52
	v_fmac_f32_e32 v5, v85, v53
	ds_read_b128 v[50:53], v86 offset:12672
	s_waitcnt lgkmcnt(4)
	v_fmac_f32_e32 v63, v82, v66
	v_fmac_f32_e32 v63, v83, v67
	v_fmac_f32_e32 v63, v84, v68
	v_fmac_f32_e32 v63, v85, v69
	ds_read_b128 v[66:69], v86 offset:16768
	s_waitcnt vmcnt(16)
	s_waitcnt lgkmcnt(4)
	v_fmac_f32_e32 v2, v6, v38
	v_fmac_f32_e32 v2, v7, v39
	v_fmac_f32_e32 v2, v8, v40
	v_fmac_f32_e32 v2, v9, v41
	ds_read_b128 v[38:41], v86 offset:400
	s_waitcnt lgkmcnt(4)
	v_fmac_f32_e32 v3, v6, v42
	v_fmac_f32_e32 v3, v7, v43
	v_fmac_f32_e32 v3, v8, v44
	v_fmac_f32_e32 v3, v9, v45
	ds_read_b128 v[42:45], v86 offset:4496
	s_waitcnt lgkmcnt(4)
	v_fmac_f32_e32 v4, v6, v46
	v_fmac_f32_e32 v4, v7, v47
	v_fmac_f32_e32 v4, v8, v48
	v_fmac_f32_e32 v4, v9, v49
	ds_read_b128 v[46:49], v86 offset:8592
	s_waitcnt lgkmcnt(4)
	v_fmac_f32_e32 v5, v6, v50
	v_fmac_f32_e32 v5, v7, v51
	v_fmac_f32_e32 v5, v8, v52
	v_fmac_f32_e32 v5, v9, v53
	ds_read_b128 v[50:53], v86 offset:12688
	s_waitcnt lgkmcnt(4)
	v_fmac_f32_e32 v63, v6, v66
	v_fmac_f32_e32 v63, v7, v67
	v_fmac_f32_e32 v63, v8, v68
	v_fmac_f32_e32 v63, v9, v69
	ds_read_b128 v[66:69], v86 offset:16784
	s_waitcnt lgkmcnt(4)
	v_fmac_f32_e32 v2, v10, v38
	v_fmac_f32_e32 v2, v11, v39
	v_fmac_f32_e32 v2, v12, v40
	v_fmac_f32_e32 v2, v13, v41
	ds_read_b128 v[38:41], v86 offset:416
	s_waitcnt lgkmcnt(4)
	v_fmac_f32_e32 v3, v10, v42
	v_fmac_f32_e32 v3, v11, v43
	v_fmac_f32_e32 v3, v12, v44
	v_fmac_f32_e32 v3, v13, v45
	ds_read_b128 v[42:45], v86 offset:4512
	s_waitcnt lgkmcnt(4)
	v_fmac_f32_e32 v4, v10, v46
	v_fmac_f32_e32 v4, v11, v47
	v_fmac_f32_e32 v4, v12, v48
	v_fmac_f32_e32 v4, v13, v49
	ds_read_b128 v[46:49], v86 offset:8608
	s_waitcnt lgkmcnt(4)
	v_fmac_f32_e32 v5, v10, v50
	v_fmac_f32_e32 v5, v11, v51
	v_fmac_f32_e32 v5, v12, v52
	v_fmac_f32_e32 v5, v13, v53
	ds_read_b128 v[50:53], v86 offset:12704
	s_waitcnt lgkmcnt(4)
	v_fmac_f32_e32 v63, v10, v66
	v_fmac_f32_e32 v63, v11, v67
	v_fmac_f32_e32 v63, v12, v68
	v_fmac_f32_e32 v63, v13, v69
	ds_read_b128 v[66:69], v86 offset:16800
	s_waitcnt lgkmcnt(4)
	v_fmac_f32_e32 v2, v14, v38
	v_fmac_f32_e32 v2, v15, v39
	v_fmac_f32_e32 v2, v16, v40
	v_fmac_f32_e32 v2, v17, v41
	ds_read_b128 v[38:41], v86 offset:432
	s_waitcnt lgkmcnt(4)
	v_fmac_f32_e32 v3, v14, v42
	v_fmac_f32_e32 v3, v15, v43
	v_fmac_f32_e32 v3, v16, v44
	v_fmac_f32_e32 v3, v17, v45
	ds_read_b128 v[42:45], v86 offset:4528
	s_waitcnt lgkmcnt(4)
	v_fmac_f32_e32 v4, v14, v46
	v_fmac_f32_e32 v4, v15, v47
	v_fmac_f32_e32 v4, v16, v48
	v_fmac_f32_e32 v4, v17, v49
	ds_read_b128 v[46:49], v86 offset:8624
	s_waitcnt lgkmcnt(4)
	v_fmac_f32_e32 v5, v14, v50
	v_fmac_f32_e32 v5, v15, v51
	v_fmac_f32_e32 v5, v16, v52
	v_fmac_f32_e32 v5, v17, v53
	ds_read_b128 v[50:53], v86 offset:12720
	s_waitcnt lgkmcnt(4)
	v_fmac_f32_e32 v63, v14, v66
	v_fmac_f32_e32 v63, v15, v67
	v_fmac_f32_e32 v63, v16, v68
	v_fmac_f32_e32 v63, v17, v69
	ds_read_b128 v[66:69], v86 offset:16816
	s_waitcnt lgkmcnt(4)
	v_fmac_f32_e32 v2, v18, v38
	v_fmac_f32_e32 v2, v19, v39
	v_fmac_f32_e32 v2, v20, v40
	v_fmac_f32_e32 v2, v21, v41
	ds_read_b128 v[38:41], v86 offset:448
	s_waitcnt lgkmcnt(4)
	v_fmac_f32_e32 v3, v18, v42
	v_fmac_f32_e32 v3, v19, v43
	v_fmac_f32_e32 v3, v20, v44
	v_fmac_f32_e32 v3, v21, v45
	ds_read_b128 v[42:45], v86 offset:4544
	s_waitcnt lgkmcnt(4)
	v_fmac_f32_e32 v4, v18, v46
	v_fmac_f32_e32 v4, v19, v47
	v_fmac_f32_e32 v4, v20, v48
	v_fmac_f32_e32 v4, v21, v49
	ds_read_b128 v[46:49], v86 offset:8640
	s_waitcnt lgkmcnt(4)
	v_fmac_f32_e32 v5, v18, v50
	v_fmac_f32_e32 v5, v19, v51
	v_fmac_f32_e32 v5, v20, v52
	v_fmac_f32_e32 v5, v21, v53
	ds_read_b128 v[50:53], v86 offset:12736
	s_waitcnt lgkmcnt(4)
	v_fmac_f32_e32 v63, v18, v66
	v_fmac_f32_e32 v63, v19, v67
	v_fmac_f32_e32 v63, v20, v68
	v_fmac_f32_e32 v63, v21, v69
	ds_read_b128 v[66:69], v86 offset:16832
	s_waitcnt vmcnt(0)
	s_waitcnt lgkmcnt(4)
	v_fmac_f32_e32 v2, v22, v38
	v_fmac_f32_e32 v2, v23, v39
	v_fmac_f32_e32 v2, v24, v40
	v_fmac_f32_e32 v2, v25, v41
	ds_read_b128 v[38:41], v86 offset:464
	s_waitcnt lgkmcnt(4)
	v_fmac_f32_e32 v3, v22, v42
	v_fmac_f32_e32 v3, v23, v43
	v_fmac_f32_e32 v3, v24, v44
	v_fmac_f32_e32 v3, v25, v45
	ds_read_b128 v[42:45], v86 offset:4560
	s_waitcnt lgkmcnt(4)
	v_fmac_f32_e32 v4, v22, v46
	v_fmac_f32_e32 v4, v23, v47
	v_fmac_f32_e32 v4, v24, v48
	v_fmac_f32_e32 v4, v25, v49
	ds_read_b128 v[46:49], v86 offset:8656
	s_waitcnt lgkmcnt(4)
	v_fmac_f32_e32 v5, v22, v50
	v_fmac_f32_e32 v5, v23, v51
	v_fmac_f32_e32 v5, v24, v52
	v_fmac_f32_e32 v5, v25, v53
	ds_read_b128 v[50:53], v86 offset:12752
	s_waitcnt lgkmcnt(4)
	v_fmac_f32_e32 v63, v22, v66
	v_fmac_f32_e32 v63, v23, v67
	v_fmac_f32_e32 v63, v24, v68
	v_fmac_f32_e32 v63, v25, v69
	ds_read_b128 v[66:69], v86 offset:16848
	s_waitcnt lgkmcnt(4)
	v_fmac_f32_e32 v2, v26, v38
	v_fmac_f32_e32 v2, v27, v39
	v_fmac_f32_e32 v2, v28, v40
	v_fmac_f32_e32 v2, v29, v41
	ds_read_b128 v[38:41], v86 offset:480
	s_waitcnt lgkmcnt(4)
	v_fmac_f32_e32 v3, v26, v42
	v_fmac_f32_e32 v3, v27, v43
	v_fmac_f32_e32 v3, v28, v44
	v_fmac_f32_e32 v3, v29, v45
	ds_read_b128 v[42:45], v86 offset:4576
	s_waitcnt lgkmcnt(4)
	v_fmac_f32_e32 v4, v26, v46
	v_fmac_f32_e32 v4, v27, v47
	v_fmac_f32_e32 v4, v28, v48
	v_fmac_f32_e32 v4, v29, v49
	ds_read_b128 v[46:49], v86 offset:8672
	s_waitcnt lgkmcnt(4)
	v_fmac_f32_e32 v5, v26, v50
	v_fmac_f32_e32 v5, v27, v51
	v_fmac_f32_e32 v5, v28, v52
	v_fmac_f32_e32 v5, v29, v53
	ds_read_b128 v[50:53], v86 offset:12768
	s_waitcnt lgkmcnt(4)
	v_fmac_f32_e32 v63, v26, v66
	v_fmac_f32_e32 v63, v27, v67
	v_fmac_f32_e32 v63, v28, v68
	v_fmac_f32_e32 v63, v29, v69
	ds_read_b128 v[66:69], v86 offset:16864
	s_waitcnt lgkmcnt(4)
	v_fmac_f32_e32 v2, v30, v38
	v_fmac_f32_e32 v2, v31, v39
	v_fmac_f32_e32 v2, v32, v40
	v_fmac_f32_e32 v2, v33, v41
	ds_read_b128 v[38:41], v86 offset:496
	s_waitcnt lgkmcnt(4)
	v_fmac_f32_e32 v3, v30, v42
	v_fmac_f32_e32 v3, v31, v43
	v_fmac_f32_e32 v3, v32, v44
	v_fmac_f32_e32 v3, v33, v45
	ds_read_b128 v[42:45], v86 offset:4592
	s_waitcnt lgkmcnt(4)
	v_fmac_f32_e32 v4, v30, v46
	v_fmac_f32_e32 v4, v31, v47
	v_fmac_f32_e32 v4, v32, v48
	v_fmac_f32_e32 v4, v33, v49
	ds_read_b128 v[46:49], v86 offset:8688
	s_waitcnt lgkmcnt(4)
	v_fmac_f32_e32 v5, v30, v50
	v_fmac_f32_e32 v5, v31, v51
	v_fmac_f32_e32 v5, v32, v52
	v_fmac_f32_e32 v5, v33, v53
	ds_read_b128 v[50:53], v86 offset:12784
	s_waitcnt lgkmcnt(4)
	v_fmac_f32_e32 v63, v30, v66
	v_fmac_f32_e32 v63, v31, v67
	v_fmac_f32_e32 v63, v32, v68
	v_fmac_f32_e32 v63, v33, v69
	ds_read_b128 v[66:69], v86 offset:16880
	s_waitcnt lgkmcnt(4)
	v_fmac_f32_e32 v2, v34, v38
	v_fmac_f32_e32 v2, v35, v39
	v_fmac_f32_e32 v2, v36, v40
	v_fmac_f32_e32 v2, v37, v41
	s_waitcnt lgkmcnt(3)
	v_fmac_f32_e32 v3, v34, v42
	v_fmac_f32_e32 v3, v35, v43
	v_fmac_f32_e32 v3, v36, v44
	v_fmac_f32_e32 v3, v37, v45
	s_waitcnt lgkmcnt(2)
	v_fmac_f32_e32 v4, v34, v46
	v_fmac_f32_e32 v4, v35, v47
	v_fmac_f32_e32 v4, v36, v48
	v_fmac_f32_e32 v4, v37, v49
	s_waitcnt lgkmcnt(1)
	v_fmac_f32_e32 v5, v34, v50
	v_fmac_f32_e32 v5, v35, v51
	v_fmac_f32_e32 v5, v36, v52
	v_fmac_f32_e32 v5, v37, v53
	s_waitcnt lgkmcnt(0)
	v_fmac_f32_e32 v63, v34, v66
	v_fmac_f32_e32 v63, v35, v67
	v_fmac_f32_e32 v63, v36, v68
	v_fmac_f32_e32 v63, v37, v69
	s_mul_i32 s5, s18, 0x500
	v_add_u32_e32 v0, s5, v55
	ds_write2st64_b32 v0, v2, v3 offset0:80 offset1:81
	ds_write2st64_b32 v0, v4, v5 offset0:82 offset1:83
	ds_write_b32 v0, v63 offset:21504
	s_waitcnt lgkmcnt(0)
	s_barrier
	s_and_saveexec_b64 s[8:9], s[6:7]
	s_cbranch_execz .LBB0_570
	s_load_dwordx2 s[10:11], s[0:1], 0x28
	s_mul_i32 s5, s15, 0x1800
	s_add_i32 s5, s5, s4
	v_or_b32_e32 v2, s5, v54
	v_ashrrev_i32_e32 v3, 31, v2
	s_waitcnt lgkmcnt(0)
	v_lshl_add_u64 v[2:3], v[2:3], 2, s[10:11]
	global_load_dword v0, v[2:3], off
	ds_read2st64_b32 v[2:3], v59 offset0:80 offset1:85
	ds_read2st64_b32 v[4:5], v59 offset0:90 offset1:95
	ds_read2st64_b32 v[6:7], v59 offset0:100 offset1:105
	ds_read2st64_b32 v[8:9], v59 offset0:110 offset1:115
	v_mad_u64_u32 v[10:11], s[10:11], s15, 5, v[58:59]
	s_movk_i32 s5, 0x1800
	v_mul_lo_u32 v10, v10, s5
	v_add_u32_e32 v10, s4, v10
	v_or_b32_e32 v10, v10, v54
	v_readlane_b32 s4, v255, 48
	v_ashrrev_i32_e32 v11, 31, v10
	v_readlane_b32 s5, v255, 49
	s_waitcnt vmcnt(0) lgkmcnt(3)
	v_add_f32_e32 v0, v0, v2
	v_add_f32_e32 v0, v0, v3
	s_waitcnt lgkmcnt(2)
	v_add_f32_e32 v0, v0, v4
	v_add_f32_e32 v0, v0, v5
	s_waitcnt lgkmcnt(1)
	v_add_f32_e32 v0, v0, v6
	v_add_f32_e32 v0, v0, v7
	s_waitcnt lgkmcnt(0)
	v_add_f32_e32 v0, v0, v8
	v_add_f32_e32 v0, v0, v9
	v_lshl_add_u64 v[2:3], v[10:11], 2, s[4:5]
	global_store_dword v[2:3], v0, off sc1
	s_branch .LBB0_570

.LBB0_584:
	s_or_b64 exec, exec, s[8:9]
	v_mul_f32_e32 v0, v13, v13
	v_fmamk_f32 v10, v0, 0xb94c1982, v238
	v_fmaak_f32 v10, v0, v10, 0xbe2aaa9d
	v_mul_f32_e32 v10, v0, v10
	v_fmac_f32_e32 v13, v13, v10
	v_fmamk_f32 v10, v0, 0x37d75334, v232
	v_fmaak_f32 v10, v0, v10, 0x3d2aabf7
	v_fmaak_f32 v10, v0, v10, 0xbf000004
	v_fma_f32 v0, v0, v10, 1.0
	v_and_b32_e32 v10, 1, v12
	v_cmp_eq_u32_e32 vcc, 0, v10
	v_lshlrev_b32_e32 v10, 30, v12
	v_and_b32_e32 v10, 0x80000000, v10
	v_xor_b32_e32 v8, v9, v8
	v_cndmask_b32_e32 v0, v0, v13, vcc
	v_xor_b32_e32 v8, v8, v10
	v_xor_b32_e32 v0, v8, v0
	v_cndmask_b32_e64 v0, v242, v0, s[6:7]
	v_add_u32_e32 v7, s22, v7
	s_mov_b32 s3, 0x1ffff
	v_readlane_b32 s6, v254, 54
	v_cmp_lt_i32_e32 vcc, s3, v7
	v_readlane_b32 s7, v254, 55
	global_store_dword v[4:5], v0, off sc1
	s_or_b64 s[14:15], vcc, s[14:15]
	v_lshl_add_u64 v[4:5], v[4:5], 0, s[6:7]
	s_andn2_b64 exec, exec, s[14:15]
	s_cbranch_execz .LBB0_593

.LBB0_587:
	s_or_saveexec_b64 s[6:7], s[16:17]
	s_mov_b32 s3, 0x3f22f983
	v_mul_f32_e64 v0, |v8|, s3
	v_rndne_f32_e32 v0, v0
	s_xor_b64 exec, exec, s[6:7]
	v_cvt_i32_f32_e32 v12, v0
	v_fma_f32 v13, v0, s30, |v8|
	v_fmac_f32_e32 v13, 0xb3a22168, v0
	v_fmac_f32_e32 v13, 0xa7c234c4, v0
	s_or_b64 exec, exec, s[6:7]
	v_mul_f32_e32 v14, v13, v13
	v_fmamk_f32 v15, v14, 0xb94c1982, v238
	v_fmaak_f32 v15, v14, v15, 0xbe2aaa9d
	v_mul_f32_e32 v15, v14, v15
	v_fmac_f32_e32 v13, v13, v15
	v_fmamk_f32 v15, v14, 0x37d75334, v232
	v_fmaak_f32 v15, v14, v15, 0x3d2aabf7
	v_fmaak_f32 v15, v14, v15, 0xbf000004
	v_fma_f32 v14, v14, v15, 1.0
	v_and_b32_e32 v15, 1, v12
	v_cmp_eq_u32_e32 vcc, 0, v15
	v_lshlrev_b32_e32 v12, 30, v12
	s_brev_b32 s3, 1
	v_cndmask_b32_e64 v13, -v13, v14, vcc
	v_bitop3_b32 v12, v12, v13, s3 bitop3:0x6c
	s_movk_i32 s3, 0x1f8
	v_cmp_class_f32_e64 s[6:7], v8, s3
	s_nop 1
	v_cndmask_b32_e64 v14, v242, v12, s[6:7]
	v_add_co_u32_e32 v12, vcc, 0xfff80000, v4
	s_nop 1
	v_addc_co_u32_e32 v13, vcc, -1, v5, vcc
	global_store_dword v[12:13], v14, off sc1
	s_and_saveexec_b64 s[8:9], s[12:13]
	s_xor_b64 s[16:17], exec, s[8:9]
	s_cbranch_execz .LBB0_591
	v_cmp_lt_u32_e32 vcc, 63, v11
	v_mad_u64_u32 v[12:13], s[12:13], v10, s19, 0
	s_nop 0
	v_cndmask_b32_e32 v0, 0, v229, vcc
	v_add_u32_e32 v0, v0, v11
	v_cmp_lt_u32_e64 s[8:9], 31, v0
	s_nop 1
	v_cndmask_b32_e64 v11, 0, v239, s[8:9]
	v_add_u32_e32 v0, v11, v0
	v_cmp_lt_u32_e64 s[10:11], 31, v0
	s_nop 1
	v_cndmask_b32_e64 v11, 0, v239, s[10:11]
	v_add_u32_e32 v24, v11, v0
	v_mov_b32_e32 v0, v13
	v_mad_u64_u32 v[14:15], s[12:13], v10, s23, v[0:1]
	v_mov_b32_e32 v0, v15
	v_mad_u64_u32 v[16:17], s[12:13], v10, s24, v[0:1]
	v_mov_b32_e32 v0, v17
	v_mad_u64_u32 v[18:19], s[12:13], v10, s25, v[0:1]
	v_mov_b32_e32 v0, v19
	v_mad_u64_u32 v[20:21], s[12:13], v10, s26, v[0:1]
	v_mov_b32_e32 v0, v21
	v_mad_u64_u32 v[22:23], s[12:13], v10, s27, v[0:1]
	v_mov_b32_e32 v0, v23
	v_mad_u64_u32 v[10:11], s[12:13], v10, s28, v[0:1]
	v_cndmask_b32_e32 v13, v22, v18, vcc
	v_cndmask_b32_e32 v0, v10, v20, vcc
	v_cndmask_b32_e32 v11, v11, v22, vcc
	v_cndmask_b32_e64 v10, v0, v13, s[8:9]
	v_cndmask_b32_e64 v0, v11, v0, s[8:9]
	v_cndmask_b32_e32 v11, v20, v16, vcc
	v_cndmask_b32_e64 v13, v13, v11, s[8:9]
	v_cndmask_b32_e32 v14, v18, v14, vcc
	v_cndmask_b32_e64 v0, v0, v10, s[10:11]
	v_cndmask_b32_e64 v10, v10, v13, s[10:11]
	v_sub_u32_e32 v15, 32, v24
	v_cndmask_b32_e64 v11, v11, v14, s[8:9]
	v_alignbit_b32 v17, v0, v10, v15
	v_cmp_eq_u32_e64 s[12:13], 0, v24
	v_cndmask_b32_e64 v13, v13, v11, s[10:11]
	v_cndmask_b32_e32 v12, v16, v12, vcc
	v_cndmask_b32_e64 v0, v17, v0, s[12:13]
	v_alignbit_b32 v17, v10, v13, v15
	v_cndmask_b32_e64 v10, v17, v10, s[12:13]
	v_bfe_u32 v19, v0, 29, 1
	v_cndmask_b32_e64 v12, v14, v12, s[8:9]
	v_alignbit_b32 v17, v0, v10, 30
	v_sub_u32_e32 v20, 0, v19
	v_cndmask_b32_e64 v11, v11, v12, s[10:11]
	v_xor_b32_e32 v17, v17, v20
	v_alignbit_b32 v12, v13, v11, v15
	v_cndmask_b32_e64 v12, v12, v13, s[12:13]
	v_ffbh_u32_e32 v13, v17
	v_alignbit_b32 v10, v10, v12, 30
	v_min_u32_e32 v13, 32, v13
	v_alignbit_b32 v11, v12, v11, 30
	v_xor_b32_e32 v10, v10, v20
	v_sub_u32_e32 v14, 31, v13
	v_xor_b32_e32 v11, v11, v20
	v_alignbit_b32 v15, v17, v10, v14
	v_alignbit_b32 v10, v10, v11, v14
	v_alignbit_b32 v11, v15, v10, 9
	v_ffbh_u32_e32 v12, v11
	v_min_u32_e32 v12, 32, v12
	v_lshrrev_b32_e32 v18, 29, v0
	v_not_b32_e32 v14, v12
	v_alignbit_b32 v10, v11, v10, v14
	v_lshlrev_b32_e32 v11, 31, v18
	v_or_b32_e32 v14, 0x33000000, v11
	v_add_lshl_u32 v12, v12, v13, 23
	v_lshrrev_b32_e32 v10, 9, v10
	v_sub_u32_e32 v12, v14, v12
	v_or_b32_e32 v11, 0.5, v11
	v_lshlrev_b32_e32 v13, 23, v13
	v_or_b32_e32 v10, v12, v10
	v_lshrrev_b32_e32 v12, 9, v15
	v_sub_u32_e32 v11, v11, v13
	v_or_b32_e32 v11, v12, v11
	v_mul_f32_e32 v12, 0x3fc90fda, v11
	v_fma_f32 v13, v11, s29, -v12
	v_fmac_f32_e32 v13, 0x33a22168, v11
	v_fmac_f32_e32 v13, 0x3fc90fda, v10
	v_lshrrev_b32_e32 v0, 30, v0
	v_add_f32_e32 v13, v12, v13
	v_add_u32_e32 v12, v19, v0

.LBB0_593:
	s_or_b64 exec, exec, s[4:5]
	s_mov_b32 s3, 0x40000
	v_cmp_gt_i32_e32 vcc, s3, v2
	s_and_saveexec_b64 s[4:5], vcc
	s_cbranch_execz .LBB0_596
	s_load_dwordx2 s[6:7], s[0:1], 0xc8
	s_load_dwordx2 s[8:9], s[0:1], 0x58
	s_load_dwordx2 s[10:11], s[0:1], 0x68
	v_readlane_b32 s3, v254, 44
	v_lshrrev_b32_e32 v0, 13, v2
	v_and_b32_e32 v0, 8, v0
	v_bfe_u32 v6, v2, 12, 3
	v_or_b32_e32 v0, v0, v6
	v_lshlrev_b32_e32 v0, 14, v0
	v_lshl_add_u32 v6, v56, 6, s3
	v_and_b32_e32 v6, 0xfc0, v6
	v_lshl_add_u32 v0, v6, 2, v0
	v_lshrrev_b32_e32 v6, 4, v2
	v_and_b32_e32 v6, 0xfc, v6
	v_add_u32_e32 v0, v0, v6
	v_and_b32_e32 v6, 0x8000, v2
	v_cmp_eq_u32_e32 vcc, 0, v6
	s_waitcnt lgkmcnt(0)
	v_lshl_add_u64 v[4:5], v[2:3], 1, s[6:7]
	s_mov_b64 s[6:7], 0x300000
	v_lshl_add_u64 v[4:5], v[4:5], 0, s[6:7]
	v_mov_b32_e32 v8, s10
	v_mov_b32_e32 v9, s11
	v_mov_b32_e32 v10, s8
	v_mov_b32_e32 v11, s9
	v_cndmask_b32_e32 v8, v8, v10, vcc
	v_cndmask_b32_e32 v9, v9, v11, vcc
	v_lshl_add_u64 v[8:9], v[8:9], 0, v[0:1]
	v_lshl_add_u64 v[12:13], v[8:9], 0, s[66:67]
	global_load_dword v10, v[8:9], off
	global_load_dword v11, v[12:13], off
	v_lshl_add_u64 v[6:7], v[4:5], 0, s[66:67]
	v_add_u32_e32 v2, 0x40000, v2
	s_waitcnt vmcnt(0)
	v_cvt_pk_bf16_f32 v10, v10, v10
	v_cvt_pk_bf16_f32 v11, v11, v11
	global_store_short v[4:5], v10, off sc1
	global_store_short v[6:7], v11, off sc1

.LBB0_598:
	s_or_b64 exec, exec, s[4:5]
	v_ashrrev_i32_e32 v17, 31, v16
	s_waitcnt lgkmcnt(3)
	v_cvt_pk_bf16_f32 v28, v4, v5
	v_lshlrev_b64 v[4:5], 11, v[16:17]
	s_waitcnt lgkmcnt(2)
	v_cvt_pk_bf16_f32 v29, v10, v11
	s_waitcnt lgkmcnt(1)
	v_cvt_pk_bf16_f32 v30, v12, v13
	s_waitcnt lgkmcnt(0)
	v_cvt_pk_bf16_f32 v31, v14, v15
	v_lshl_add_u64 v[2:3], v[2:3], 0, v[4:5]
	global_store_dwordx4 v[2:3], v[28:31], off sc1
	s_waitcnt lgkmcnt(0)

.LBB0_600:
	s_mul_hi_i32 s4, s3, 0x2e8ba2e9
	s_lshr_b32 s5, s4, 31
	s_ashr_i32 s4, s4, 10
	s_add_i32 s4, s4, s5
	s_mul_i32 s5, s4, 0xffffea00
	s_add_i32 s20, s3, s5
	s_ashr_i32 s5, s4, 31
	s_mul_i32 s9, s4, 0x1600000
	s_mul_hi_i32 s8, s4, 0x1600000
	s_add_u32 s18, s12, s9
	s_addc_u32 s19, s13, s8
	s_cmpk_gt_i32 s20, 0x37f
	s_mov_b64 s[6:7], -1
	s_cbranch_scc0 .LBB0_626
	s_cmpk_gt_u32 s20, 0x57f
	s_cbranch_scc0 .LBB0_623
	s_cmpk_gt_u32 s20, 0x107f
	s_cbranch_scc0 .LBB0_604
	s_load_dwordx2 s[6:7], s[0:1], 0xb0
	s_mul_i32 s11, s4, 0xb00000
	s_mul_hi_i32 s10, s4, 0xb00000
	s_mul_i32 s21, s4, 0xffffd400
	v_lshlrev_b32_e32 v0, 2, v6
	s_waitcnt lgkmcnt(0)
	s_add_u32 s11, s6, s11
	s_addc_u32 s22, s7, s10
	s_add_i32 s6, s16, s21
	s_addk_i32 s6, 0xe600
	s_and_b32 s7, s6, 0xfc0
	s_add_i32 s6, s14, 0xfffe6000
	s_and_b32 s6, s6, 0x3e0
	s_lshl_b32 s10, s6, 2
	s_add_u32 s10, s11, s10
	v_or_b32_e32 v4, s7, v7
	s_addc_u32 s11, s22, 0
	v_lshl_add_u64 v[2:3], s[10:11], 0, v[0:1]
	v_lshlrev_b32_e32 v0, 12, v4
	v_lshl_add_u64 v[2:3], v[2:3], 0, v[0:1]
	v_add_co_u32_e32 v4, vcc, s29, v2
	s_mov_b32 s10, 0x20000
	s_nop 0
	v_addc_co_u32_e32 v5, vcc, 0, v3, vcc
	v_add_co_u32_e32 v10, vcc, s49, v2
	s_lshl_b32 s7, s7, 1
	s_nop 0
	v_addc_co_u32_e32 v11, vcc, 0, v3, vcc
	v_add_co_u32_e32 v12, vcc, s65, v2
	s_nop 1
	v_addc_co_u32_e32 v13, vcc, 0, v3, vcc
	v_add_co_u32_e32 v14, vcc, s31, v2
	s_nop 1
	v_addc_co_u32_e32 v15, vcc, 0, v3, vcc
	v_add_co_u32_e32 v16, vcc, s56, v2
	s_nop 1
	v_addc_co_u32_e32 v17, vcc, 0, v3, vcc
	v_add_co_u32_e32 v28, vcc, s90, v2
	s_nop 1
	v_addc_co_u32_e32 v29, vcc, 0, v3, vcc
	v_add_co_u32_e32 v30, vcc, s78, v2
	s_nop 1
	v_addc_co_u32_e32 v31, vcc, 0, v3, vcc
	global_load_dword v0, v[2:3], off nt
	global_load_dword v34, v[4:5], off nt
	global_load_dword v35, v[10:11], off nt
	global_load_dword v36, v[12:13], off nt
	global_load_dword v37, v[14:15], off nt
	global_load_dword v38, v[16:17], off nt
	global_load_dword v39, v[28:29], off nt
	global_load_dword v40, v[30:31], off nt
	v_add_co_u32_e32 v4, vcc, s28, v2
	s_nop 1
	v_addc_co_u32_e32 v5, vcc, 0, v3, vcc
	v_add_co_u32_e32 v10, vcc, s54, v2
	s_nop 1
	v_addc_co_u32_e32 v11, vcc, 0, v3, vcc
	v_add_co_u32_e32 v12, vcc, s30, v2
	s_nop 1
	v_addc_co_u32_e32 v13, vcc, 0, v3, vcc
	v_add_co_u32_e32 v14, vcc, s45, v2
	s_nop 1
	v_addc_co_u32_e32 v15, vcc, 0, v3, vcc
	v_add_co_u32_e32 v16, vcc, s95, v2
	s_nop 1
	v_addc_co_u32_e32 v17, vcc, 0, v3, vcc
	v_add_co_u32_e32 v28, vcc, s46, v2
	s_nop 1
	v_addc_co_u32_e32 v29, vcc, 0, v3, vcc
	v_add_co_u32_e32 v30, vcc, s77, v2
	s_nop 1
	v_addc_co_u32_e32 v31, vcc, 0, v3, vcc
	v_add_co_u32_e32 v32, vcc, s64, v2
	s_nop 1
	v_addc_co_u32_e32 v33, vcc, 0, v3, vcc
	global_load_dword v41, v[4:5], off nt
	global_load_dword v42, v[10:11], off nt
	global_load_dword v43, v[12:13], off nt
	global_load_dword v44, v[14:15], off nt
	global_load_dword v45, v[16:17], off nt
	global_load_dword v46, v[28:29], off nt
	global_load_dword v47, v[30:31], off nt
	global_load_dword v48, v[32:33], off nt
	v_add_co_u32_e32 v4, vcc, s10, v2
	s_mov_b32 s10, 0x22000
	s_nop 0
	v_addc_co_u32_e32 v5, vcc, 0, v3, vcc
	v_add_co_u32_e32 v10, vcc, s10, v2
	s_mov_b32 s10, 0x28000
	s_nop 0
	v_addc_co_u32_e32 v11, vcc, 0, v3, vcc
	v_add_co_u32_e32 v12, vcc, s97, v2
	s_nop 1
	v_addc_co_u32_e32 v13, vcc, 0, v3, vcc
	v_add_co_u32_e32 v14, vcc, s79, v2
	s_nop 1
	v_addc_co_u32_e32 v15, vcc, 0, v3, vcc
	v_add_co_u32_e32 v16, vcc, s10, v2
	s_mov_b32 s10, 0x2c000
	s_nop 0
	v_addc_co_u32_e32 v17, vcc, 0, v3, vcc
	v_add_co_u32_e32 v28, vcc, s55, v2
	s_nop 1
	v_addc_co_u32_e32 v29, vcc, 0, v3, vcc
	v_add_co_u32_e32 v30, vcc, s10, v2
	s_mov_b32 s10, 0x2e000
	s_nop 0
	v_addc_co_u32_e32 v31, vcc, 0, v3, vcc
	v_add_co_u32_e32 v32, vcc, s10, v2
	s_mov_b32 s10, 0x32000
	s_nop 0
	v_addc_co_u32_e32 v33, vcc, 0, v3, vcc
	global_load_dword v49, v[4:5], off nt
	global_load_dword v50, v[10:11], off nt
	global_load_dword v51, v[12:13], off nt
	global_load_dword v52, v[14:15], off nt
	global_load_dword v53, v[16:17], off nt
	global_load_dword v54, v[28:29], off nt
	global_load_dword v55, v[30:31], off nt
	s_nop 0
	global_load_dword v32, v[32:33], off nt
	v_add_co_u32_e32 v4, vcc, s91, v2
	s_nop 1
	v_addc_co_u32_e32 v5, vcc, 0, v3, vcc
	v_add_co_u32_e32 v10, vcc, s10, v2
	s_mov_b32 s10, 0x3a000
	s_nop 0
	v_addc_co_u32_e32 v11, vcc, 0, v3, vcc
	v_add_co_u32_e32 v12, vcc, s85, v2
	s_nop 1
	v_addc_co_u32_e32 v13, vcc, 0, v3, vcc
	v_add_co_u32_e32 v14, vcc, s94, v2
	s_nop 1
	v_addc_co_u32_e32 v15, vcc, 0, v3, vcc
	v_add_co_u32_e32 v16, vcc, s93, v2
	s_nop 1
	v_addc_co_u32_e32 v17, vcc, 0, v3, vcc
	v_add_co_u32_e32 v28, vcc, s10, v2
	s_mov_b32 s10, 0x3e000
	s_nop 0
	v_addc_co_u32_e32 v29, vcc, 0, v3, vcc
	v_add_co_u32_e32 v30, vcc, s92, v2
	s_nop 1
	v_addc_co_u32_e32 v31, vcc, 0, v3, vcc
	v_add_co_u32_e32 v2, vcc, s10, v2
	s_add_u32 s10, s18, s7
	s_nop 0
	v_addc_co_u32_e32 v3, vcc, 0, v3, vcc
	global_load_dword v4, v[4:5], off nt
	s_nop 0
	global_load_dword v5, v[10:11], off nt
	s_nop 0
	global_load_dword v10, v[12:13], off nt
	global_load_dword v11, v[14:15], off nt
	s_nop 0
	global_load_dword v12, v[16:17], off nt
	global_load_dword v13, v[28:29], off nt
	global_load_dword v14, v[30:31], off nt
	s_nop 0
	global_load_dword v2, v[2:3], off nt
	s_waitcnt vmcnt(30)
	ds_write2_b32 v9, v0, v34 offset1:66
	s_waitcnt vmcnt(28)
	ds_write2_b32 v9, v35, v36 offset0:132 offset1:198
	v_add_u32_e32 v0, 0x400, v9
	s_waitcnt vmcnt(26)
	ds_write2_b32 v0, v37, v38 offset0:8 offset1:74
	s_waitcnt vmcnt(24)
	ds_write2_b32 v0, v39, v40 offset0:140 offset1:206
	v_add_u32_e32 v0, 0x800, v9
	s_waitcnt vmcnt(22)
	ds_write2_b32 v0, v41, v42 offset0:16 offset1:82
	s_waitcnt vmcnt(20)
	ds_write2_b32 v0, v43, v44 offset0:148 offset1:214
	v_add_u32_e32 v0, 0xc00, v9
	s_waitcnt vmcnt(18)
	ds_write2_b32 v0, v45, v46 offset0:24 offset1:90
	s_waitcnt vmcnt(16)
	ds_write2_b32 v0, v47, v48 offset0:156 offset1:222
	v_add_u32_e32 v0, 0x1000, v9
	s_waitcnt vmcnt(14)
	ds_write2_b32 v0, v49, v50 offset0:32 offset1:98
	s_waitcnt vmcnt(12)
	ds_write2_b32 v0, v51, v52 offset0:164 offset1:230
	v_add_u32_e32 v0, 0x1400, v9
	s_waitcnt vmcnt(10)
	ds_write2_b32 v0, v53, v54 offset0:40 offset1:106
	s_waitcnt vmcnt(8)
	ds_write2_b32 v0, v55, v32 offset0:172 offset1:238
	v_add_u32_e32 v0, 0x1800, v9
	s_waitcnt vmcnt(6)
	ds_write2_b32 v0, v4, v5 offset0:48 offset1:114
	s_waitcnt vmcnt(4)
	ds_write2_b32 v0, v10, v11 offset0:180 offset1:246
	v_add_u32_e32 v0, 0x1c00, v9
	s_waitcnt vmcnt(2)
	ds_write2_b32 v0, v12, v13 offset0:56 offset1:122
	s_waitcnt vmcnt(0)
	ds_write2_b32 v0, v14, v2 offset0:188 offset1:254
	s_waitcnt lgkmcnt(0)
	s_addc_u32 s11, s19, 0
	v_lshlrev_b32_e32 v0, 1, v8
	ds_read2_b32 v[10:11], v19 offset0:33 offset1:41
	ds_read2_b32 v[12:13], v19 offset1:8
	ds_read2_b32 v[14:15], v19 offset0:66 offset1:74
	ds_read2_b32 v[16:17], v19 offset0:99 offset1:107
	ds_read2_b32 v[28:29], v19 offset0:132 offset1:140
	ds_read2_b32 v[30:31], v19 offset0:165 offset1:173
	ds_read2_b32 v[32:33], v19 offset0:198 offset1:206
	ds_read2_b32 v[34:35], v19 offset0:231 offset1:239
	v_lshl_add_u64 v[2:3], s[10:11], 0, v[0:1]
	v_or_b32_e32 v0, s6, v18
	s_mov_b64 s[10:11], 0x1080000
	v_mul_u32_u24_e32 v0, 0xb00, v0
	v_lshl_add_u64 v[36:37], v[2:3], 0, s[10:11]
	v_lshlrev_b32_e32 v0, 1, v0
	v_lshl_add_u64 v[38:39], v[36:37], 0, v[0:1]
	v_or_b32_e32 v0, s6, v20
	s_waitcnt lgkmcnt(6)
	v_cvt_pk_bf16_f32 v2, v12, v10
	s_waitcnt lgkmcnt(4)
	v_cvt_pk_bf16_f32 v3, v14, v16
	s_waitcnt lgkmcnt(2)
	v_cvt_pk_bf16_f32 v4, v28, v30
	s_waitcnt lgkmcnt(0)
	v_cvt_pk_bf16_f32 v5, v32, v34
	v_mul_u32_u24_e32 v0, 0xb00, v0
	global_store_dwordx4 v[38:39], v[2:5], off sc1
	v_lshlrev_b32_e32 v0, 1, v0
	s_nop 0
	v_cvt_pk_bf16_f32 v2, v13, v11
	v_cvt_pk_bf16_f32 v3, v15, v17
	v_cvt_pk_bf16_f32 v4, v29, v31
	v_cvt_pk_bf16_f32 v5, v33, v35
	v_lshl_add_u64 v[10:11], v[36:37], 0, v[0:1]
	ds_read2_b32 v[12:13], v19 offset0:16 offset1:24
	ds_read2_b32 v[14:15], v19 offset0:49 offset1:57
	ds_read2_b32 v[16:17], v19 offset0:82 offset1:90
	ds_read2_b32 v[28:29], v19 offset0:115 offset1:123
	ds_read2_b32 v[30:31], v19 offset0:148 offset1:156
	ds_read2_b32 v[32:33], v19 offset0:181 offset1:189
	ds_read2_b32 v[34:35], v19 offset0:214 offset1:222
	ds_read2_b32 v[38:39], v19 offset0:247 offset1:255
	v_or_b32_e32 v0, s6, v21
	v_mul_u32_u24_e32 v0, 0xb00, v0
	v_lshlrev_b32_e32 v0, 1, v0
	global_store_dwordx4 v[10:11], v[2:5], off sc1
	v_lshl_add_u64 v[10:11], v[36:37], 0, v[0:1]
	v_or_b32_e32 v0, s6, v22
	v_mul_u32_u24_e32 v0, 0xb00, v0
	s_waitcnt lgkmcnt(6)
	v_cvt_pk_bf16_f32 v2, v12, v14
	s_waitcnt lgkmcnt(4)
	v_cvt_pk_bf16_f32 v3, v16, v28
	s_waitcnt lgkmcnt(2)
	v_cvt_pk_bf16_f32 v4, v30, v32
	s_waitcnt lgkmcnt(0)
	v_cvt_pk_bf16_f32 v5, v34, v38
	v_lshlrev_b32_e32 v0, 1, v0
	global_store_dwordx4 v[10:11], v[2:5], off sc1
	v_lshl_add_u64 v[10:11], v[36:37], 0, v[0:1]
	s_mov_b64 s[6:7], 0
	v_cvt_pk_bf16_f32 v2, v13, v15
	v_cvt_pk_bf16_f32 v3, v17, v29
	v_cvt_pk_bf16_f32 v4, v31, v33
	v_cvt_pk_bf16_f32 v5, v35, v39
	global_store_dwordx4 v[10:11], v[2:5], off sc1
	s_waitcnt lgkmcnt(0)

.LBB0_609:
	s_and_b32 s6, 0xffff, s10
	s_lshl_b32 s6, s6, 1
	s_add_u32 s6, s18, s6
	s_addc_u32 s7, s19, 0
	v_lshlrev_b32_e32 v0, 1, v8
	v_lshl_add_u64 v[2:3], s[6:7], 0, v[0:1]
	s_mov_b64 s[6:7], 0x580000
	v_mov_b32_e32 v17, v1
	v_lshl_add_u64 v[2:3], v[2:3], 0, s[6:7]
	s_waitcnt lgkmcnt(3)
	v_cvt_pk_bf16_f32 v28, v4, v5
	v_lshlrev_b64 v[4:5], 11, v[16:17]
	s_waitcnt lgkmcnt(2)
	v_cvt_pk_bf16_f32 v29, v10, v11
	s_waitcnt lgkmcnt(1)
	v_cvt_pk_bf16_f32 v30, v12, v13
	s_waitcnt lgkmcnt(0)
	v_cvt_pk_bf16_f32 v31, v14, v15
	v_lshl_add_u64 v[4:5], v[2:3], 0, v[4:5]
	global_store_dwordx4 v[4:5], v[28:31], off sc1
	ds_read2_b32 v[4:5], v19 offset0:8 offset1:41
	ds_read2_b32 v[10:11], v19 offset0:74 offset1:107
	ds_read2_b32 v[12:13], v19 offset0:140 offset1:173
	ds_read2_b32 v[14:15], v19 offset0:206 offset1:239
	v_or_b32_e32 v0, s21, v20
	v_cndmask_b32_e64 v17, 0, 1, s[8:9]
	v_lshlrev_b32_e32 v16, 1, v0
	s_mov_b64 s[10:11], -1
	v_cmp_ne_u32_e64 s[6:7], 1, v17
	s_andn2_b64 vcc, exec, s[8:9]
	v_and_b32_e32 v17, 0x6f, v0
	s_cbranch_vccnz .LBB0_611
	v_add_u32_e32 v0, 0x7fffea00, v16
	v_and_b32_e32 v0, 0x7fffff00, v0
	s_movk_i32 s8, 0x80
	v_or3_b32 v0, v17, v0, s8
	s_mov_b64 s[10:11], 0

.LBB0_613:
	s_waitcnt lgkmcnt(3)
	v_cvt_pk_bf16_f32 v28, v4, v5
	v_lshlrev_b64 v[4:5], 11, v[0:1]
	s_waitcnt lgkmcnt(2)
	v_cvt_pk_bf16_f32 v29, v10, v11
	s_waitcnt lgkmcnt(1)
	v_cvt_pk_bf16_f32 v30, v12, v13
	s_waitcnt lgkmcnt(0)
	v_cvt_pk_bf16_f32 v31, v14, v15
	v_lshl_add_u64 v[4:5], v[2:3], 0, v[4:5]
	global_store_dwordx4 v[4:5], v[28:31], off sc1
	ds_read2_b32 v[4:5], v19 offset0:16 offset1:49
	ds_read2_b32 v[10:11], v19 offset0:82 offset1:115
	ds_read2_b32 v[12:13], v19 offset0:148 offset1:181
	ds_read2_b32 v[14:15], v19 offset0:214 offset1:247
	v_or_b32_e32 v0, s21, v21
	v_lshlrev_b32_e32 v16, 1, v0
	s_mov_b64 s[8:9], -1
	s_and_b64 vcc, exec, s[6:7]
	v_and_b32_e32 v17, 0x77, v0
	s_cbranch_vccnz .LBB0_615
	v_add_u32_e32 v0, 0x7fffea00, v16
	v_and_b32_e32 v0, 0x7fffff00, v0
	s_movk_i32 s8, 0x80
	v_or3_b32 v0, v17, v0, s8
	s_mov_b64 s[8:9], 0

.LBB0_617:
	s_waitcnt lgkmcnt(3)
	v_cvt_pk_bf16_f32 v28, v4, v5
	v_lshlrev_b64 v[4:5], 11, v[0:1]
	s_waitcnt lgkmcnt(2)
	v_cvt_pk_bf16_f32 v29, v10, v11
	s_waitcnt lgkmcnt(1)
	v_cvt_pk_bf16_f32 v30, v12, v13
	s_waitcnt lgkmcnt(0)
	v_cvt_pk_bf16_f32 v31, v14, v15
	v_lshl_add_u64 v[4:5], v[2:3], 0, v[4:5]
	global_store_dwordx4 v[4:5], v[28:31], off sc1
	ds_read2_b32 v[4:5], v19 offset0:24 offset1:57
	ds_read2_b32 v[10:11], v19 offset0:90 offset1:123
	ds_read2_b32 v[12:13], v19 offset0:156 offset1:189
	ds_read2_b32 v[14:15], v19 offset0:222 offset1:255
	v_or_b32_e32 v0, s21, v22
	v_lshlrev_b32_e32 v16, 1, v0
	s_mov_b64 s[8:9], -1
	s_and_b64 vcc, exec, s[6:7]
	v_and_b32_e32 v17, 0x7f, v0
	s_cbranch_vccnz .LBB0_619
	v_add_u32_e32 v0, 0x7fffea00, v16
	v_and_b32_e32 v0, 0x7fffff00, v0
	s_movk_i32 s6, 0x80
	v_or3_b32 v0, v17, v0, s6
	s_mov_b64 s[8:9], 0

.LBB0_621:
	s_waitcnt lgkmcnt(3)
	v_cvt_pk_bf16_f32 v28, v4, v5
	v_lshlrev_b64 v[4:5], 11, v[0:1]
	s_waitcnt lgkmcnt(2)
	v_cvt_pk_bf16_f32 v29, v10, v11
	s_waitcnt lgkmcnt(1)
	v_cvt_pk_bf16_f32 v30, v12, v13
	s_waitcnt lgkmcnt(0)
	v_cvt_pk_bf16_f32 v31, v14, v15
	v_lshl_add_u64 v[2:3], v[2:3], 0, v[4:5]
	global_store_dwordx4 v[2:3], v[28:31], off sc1
	s_waitcnt lgkmcnt(0)

.LBB0_623:
	s_andn2_b64 vcc, exec, s[6:7]
	s_cbranch_vccnz .LBB0_625
	s_load_dwordx4 s[24:27], s[0:1], 0x80
	s_load_dwordx2 s[6:7], s[0:1], 0x90
	s_add_i32 s11, s20, 0xfffffc80
	s_lshl_b64 s[8:9], s[4:5], 22
	v_lshlrev_b32_e32 v0, 2, v6
	s_waitcnt lgkmcnt(0)
	s_add_u32 s21, s6, s8
	s_addc_u32 s23, s7, s9
	s_lshl_b32 s6, s4, 9
	s_ashr_i32 s7, s6, 31
	s_lshl_b64 s[8:9], s[6:7], 2
	s_add_u32 s6, s24, s8
	s_addc_u32 s7, s25, s9
	s_add_u32 s8, s26, s8
	s_addc_u32 s9, s27, s9
	s_and_b32 s5, s14, 0x3e0
	s_and_b32 s10, s16, 0x3c0
	s_lshl_b32 s22, s5, 2
	s_add_u32 s22, s21, s22
	v_or_b32_e32 v36, s10, v7
	s_addc_u32 s23, s23, 0
	v_lshl_add_u64 v[2:3], s[22:23], 0, v[0:1]
	v_lshlrev_b32_e32 v0, 12, v36
	v_lshl_add_u64 v[2:3], v[2:3], 0, v[0:1]
	v_add_co_u32_e32 v4, vcc, s29, v2
	global_load_dword v38, v[2:3], off nt
	s_nop 0
	v_addc_co_u32_e32 v5, vcc, 0, v3, vcc
	global_load_dword v40, v[4:5], off nt
	v_add_co_u32_e32 v4, vcc, s49, v2
	s_mov_b32 s21, 0x20000
	s_nop 0
	v_addc_co_u32_e32 v5, vcc, 0, v3, vcc
	global_load_dword v41, v[4:5], off nt
	v_add_co_u32_e32 v4, vcc, s65, v2
	v_lshlrev_b32_e32 v0, 2, v36
	s_nop 0
	v_addc_co_u32_e32 v5, vcc, 0, v3, vcc
	global_load_dword v42, v[4:5], off nt
	v_add_co_u32_e32 v4, vcc, s31, v2
	s_cmpk_lt_u32 s11, 0x100
	s_nop 0
	v_addc_co_u32_e32 v5, vcc, 0, v3, vcc
	global_load_dword v43, v[4:5], off nt
	v_add_co_u32_e32 v4, vcc, s56, v2
	s_nop 1
	v_addc_co_u32_e32 v5, vcc, 0, v3, vcc
	global_load_dword v44, v[4:5], off nt
	v_add_co_u32_e32 v4, vcc, s90, v2
	s_nop 1
	v_addc_co_u32_e32 v5, vcc, 0, v3, vcc
	global_load_dword v45, v[4:5], off nt
	v_add_co_u32_e32 v4, vcc, s78, v2
	s_nop 1
	v_addc_co_u32_e32 v5, vcc, 0, v3, vcc
	global_load_dword v46, v[4:5], off nt
	v_add_co_u32_e32 v4, vcc, s28, v2
	s_nop 1
	v_addc_co_u32_e32 v5, vcc, 0, v3, vcc
	global_load_dword v47, v[4:5], off nt
	v_add_co_u32_e32 v4, vcc, s54, v2
	s_nop 1
	v_addc_co_u32_e32 v5, vcc, 0, v3, vcc
	global_load_dword v48, v[4:5], off nt
	v_add_co_u32_e32 v4, vcc, s30, v2
	s_nop 1
	v_addc_co_u32_e32 v5, vcc, 0, v3, vcc
	global_load_dword v49, v[4:5], off nt
	v_add_co_u32_e32 v4, vcc, s45, v2
	s_nop 1
	v_addc_co_u32_e32 v5, vcc, 0, v3, vcc
	global_load_dword v50, v[4:5], off nt
	v_add_co_u32_e32 v4, vcc, s95, v2
	s_nop 1
	v_addc_co_u32_e32 v5, vcc, 0, v3, vcc
	global_load_dword v51, v[4:5], off nt
	v_add_co_u32_e32 v4, vcc, s46, v2
	s_nop 1
	v_addc_co_u32_e32 v5, vcc, 0, v3, vcc
	global_load_dword v52, v[4:5], off nt
	v_add_co_u32_e32 v4, vcc, s77, v2
	s_nop 1
	v_addc_co_u32_e32 v5, vcc, 0, v3, vcc
	global_load_dword v53, v[4:5], off nt
	v_add_co_u32_e32 v4, vcc, s64, v2
	s_nop 1
	v_addc_co_u32_e32 v5, vcc, 0, v3, vcc
	global_load_dword v54, v[4:5], off nt
	v_add_co_u32_e32 v4, vcc, s21, v2
	s_mov_b32 s21, 0x22000
	s_nop 0
	v_addc_co_u32_e32 v5, vcc, 0, v3, vcc
	global_load_dword v35, v[4:5], off nt
	v_add_co_u32_e32 v4, vcc, s21, v2
	s_mov_b32 s21, 0x28000
	s_nop 0
	v_addc_co_u32_e32 v5, vcc, 0, v3, vcc
	global_load_dword v34, v[4:5], off nt
	v_add_co_u32_e32 v4, vcc, s97, v2
	s_nop 1
	v_addc_co_u32_e32 v5, vcc, 0, v3, vcc
	global_load_dword v33, v[4:5], off nt
	v_add_co_u32_e32 v4, vcc, s79, v2
	s_nop 1
	v_addc_co_u32_e32 v5, vcc, 0, v3, vcc
	global_load_dword v32, v[4:5], off nt
	v_add_co_u32_e32 v4, vcc, s21, v2
	s_mov_b32 s21, 0x2c000
	s_nop 0
	v_addc_co_u32_e32 v5, vcc, 0, v3, vcc
	global_load_dword v31, v[4:5], off nt
	v_add_co_u32_e32 v4, vcc, s55, v2
	s_nop 1
	v_addc_co_u32_e32 v5, vcc, 0, v3, vcc
	global_load_dword v30, v[4:5], off nt
	v_add_co_u32_e32 v4, vcc, s21, v2
	s_mov_b32 s21, 0x2e000
	s_nop 0
	v_addc_co_u32_e32 v5, vcc, 0, v3, vcc
	global_load_dword v29, v[4:5], off nt
	v_add_co_u32_e32 v4, vcc, s21, v2
	s_mov_b32 s21, 0x32000
	s_nop 0
	v_addc_co_u32_e32 v5, vcc, 0, v3, vcc
	global_load_dword v28, v[4:5], off nt
	v_add_co_u32_e32 v4, vcc, s91, v2
	s_nop 1
	v_addc_co_u32_e32 v5, vcc, 0, v3, vcc
	global_load_dword v17, v[4:5], off nt
	v_add_co_u32_e32 v4, vcc, s21, v2
	s_mov_b32 s21, 0x3a000
	s_nop 0
	v_addc_co_u32_e32 v5, vcc, 0, v3, vcc
	global_load_dword v16, v[4:5], off nt
	v_add_co_u32_e32 v4, vcc, s85, v2
	s_nop 1
	v_addc_co_u32_e32 v5, vcc, 0, v3, vcc
	global_load_dword v15, v[4:5], off nt
	v_add_co_u32_e32 v4, vcc, s94, v2
	s_nop 1
	v_addc_co_u32_e32 v5, vcc, 0, v3, vcc
	global_load_dword v14, v[4:5], off nt
	v_add_co_u32_e32 v4, vcc, s93, v2
	s_nop 1
	v_addc_co_u32_e32 v5, vcc, 0, v3, vcc
	global_load_dword v13, v[4:5], off nt
	v_add_co_u32_e32 v4, vcc, s21, v2
	s_mov_b32 s21, 0x3e000
	s_nop 0
	v_addc_co_u32_e32 v5, vcc, 0, v3, vcc
	global_load_dword v12, v[4:5], off nt
	v_add_co_u32_e32 v4, vcc, s92, v2
	s_nop 1
	v_addc_co_u32_e32 v5, vcc, 0, v3, vcc
	v_add_co_u32_e32 v2, vcc, s21, v2
	global_load_dword v11, v[4:5], off nt
	s_nop 0
	v_addc_co_u32_e32 v3, vcc, 0, v3, vcc
	global_load_dword v10, v[2:3], off nt
	v_lshl_add_u64 v[2:3], s[8:9], 0, v[0:1]
	s_movk_i32 s8, 0xf800
	s_mov_b32 s9, -1
	s_cselect_b64 vcc, -1, 0
	v_lshl_add_u64 v[36:37], v[2:3], 0, s[8:9]
	v_lshl_add_u64 v[4:5], s[6:7], 0, v[0:1]
	s_waitcnt vmcnt(30)
	v_lshl_add_u64 v[96:97], v[2:3], 0, s[8:9]
	v_cndmask_b32_e32 v97, v97, v5, vcc
	v_cndmask_b32_e32 v96, v96, v4, vcc
	global_load_dword v64, v[96:97], off
	global_load_dword v65, v[96:97], off offset:8
	global_load_dword v66, v[96:97], off offset:16
	global_load_dword v67, v[96:97], off offset:24
	global_load_dword v68, v[96:97], off offset:32
	global_load_dword v69, v[96:97], off offset:40
	global_load_dword v70, v[96:97], off offset:48
	global_load_dword v71, v[96:97], off offset:56
	global_load_dword v72, v[96:97], off offset:64
	global_load_dword v73, v[96:97], off offset:72
	global_load_dword v74, v[96:97], off offset:80
	global_load_dword v75, v[96:97], off offset:88
	global_load_dword v76, v[96:97], off offset:96
	global_load_dword v77, v[96:97], off offset:104
	global_load_dword v78, v[96:97], off offset:112
	global_load_dword v79, v[96:97], off offset:120
	global_load_dword v80, v[96:97], off offset:128
	global_load_dword v81, v[96:97], off offset:136
	global_load_dword v82, v[96:97], off offset:144
	global_load_dword v83, v[96:97], off offset:152
	global_load_dword v84, v[96:97], off offset:160
	global_load_dword v85, v[96:97], off offset:168
	global_load_dword v86, v[96:97], off offset:176
	global_load_dword v87, v[96:97], off offset:184
	global_load_dword v88, v[96:97], off offset:192
	global_load_dword v89, v[96:97], off offset:200
	global_load_dword v90, v[96:97], off offset:208
	global_load_dword v91, v[96:97], off offset:216
	global_load_dword v92, v[96:97], off offset:224
	global_load_dword v93, v[96:97], off offset:232
	global_load_dword v94, v[96:97], off offset:240
	global_load_dword v95, v[96:97], off offset:248
	v_cndmask_b32_e32 v37, v37, v5, vcc
	v_cndmask_b32_e32 v36, v36, v4, vcc
	s_nop 0
	s_movk_i32 s6, 0xf808
	s_mov_b32 s7, -1
	v_lshl_add_u64 v[36:37], v[4:5], 0, 8
	s_waitcnt vmcnt(0)
	v_mul_f32_e32 v0, v38, v64
	v_lshl_add_u64 v[38:39], v[2:3], 0, s[6:7]
	s_movk_i32 s6, 0xf810
	v_cndmask_b32_e32 v37, v39, v37, vcc
	v_cndmask_b32_e32 v36, v38, v36, vcc
	s_mov_b32 s7, -1
	ds_write_b32 v9, v0
	s_nop 0
	v_lshl_add_u64 v[36:37], v[4:5], 0, 16
	v_lshl_add_u64 v[38:39], v[2:3], 0, s[6:7]
	v_cndmask_b32_e32 v37, v39, v37, vcc
	v_cndmask_b32_e32 v36, v38, v36, vcc
	s_nop 0
	s_movk_i32 s6, 0xf818
	s_mov_b32 s7, -1
	v_lshl_add_u64 v[38:39], v[2:3], 0, s[6:7]
	s_movk_i32 s6, 0xf820
	s_mov_b32 s7, -1
	s_waitcnt vmcnt(1)
	v_mul_f32_e32 v0, v40, v65
	v_add_u32_e32 v40, 0x400, v27
	s_waitcnt vmcnt(0)
	v_mul_f32_e32 v36, v41, v66
	ds_write2_b32 v27, v0, v36 offset1:66
	v_lshl_add_u64 v[36:37], v[4:5], 0, 24
	v_cndmask_b32_e32 v37, v39, v37, vcc
	v_cndmask_b32_e32 v36, v38, v36, vcc
	s_nop 0
	v_lshl_add_u64 v[36:37], v[4:5], 0, 32
	v_lshl_add_u64 v[38:39], v[2:3], 0, s[6:7]
	v_cndmask_b32_e32 v37, v39, v37, vcc
	v_cndmask_b32_e32 v36, v38, v36, vcc
	s_nop 0
	s_movk_i32 s6, 0xf828
	s_mov_b32 s7, -1
	v_lshl_add_u64 v[38:39], v[2:3], 0, s[6:7]
	s_movk_i32 s6, 0xf830
	s_mov_b32 s7, -1
	s_waitcnt vmcnt(1)
	v_mul_f32_e32 v0, v42, v67
	s_waitcnt vmcnt(0)
	v_mul_f32_e32 v36, v43, v68
	ds_write2_b32 v27, v0, v36 offset0:132 offset1:198
	v_lshl_add_u64 v[36:37], v[4:5], 0, 40
	v_cndmask_b32_e32 v37, v39, v37, vcc
	v_cndmask_b32_e32 v36, v38, v36, vcc
	s_nop 0
	v_lshl_add_u64 v[36:37], v[4:5], 0, 48
	v_lshl_add_u64 v[38:39], v[2:3], 0, s[6:7]
	v_cndmask_b32_e32 v37, v39, v37, vcc
	v_cndmask_b32_e32 v36, v38, v36, vcc
	s_nop 0
	s_movk_i32 s6, 0xf838
	s_mov_b32 s7, -1
	v_lshl_add_u64 v[38:39], v[2:3], 0, s[6:7]
	s_movk_i32 s6, 0xf840
	s_mov_b32 s7, -1
	s_waitcnt vmcnt(1)
	v_mul_f32_e32 v0, v44, v69
	s_waitcnt vmcnt(0)
	v_mul_f32_e32 v36, v45, v70
	ds_write2_b32 v40, v0, v36 offset0:8 offset1:74
	v_lshl_add_u64 v[36:37], v[4:5], 0, 56
	v_cndmask_b32_e32 v37, v39, v37, vcc
	v_cndmask_b32_e32 v36, v38, v36, vcc
	s_nop 0
	v_lshl_add_u64 v[36:37], v[4:5], 0, 64
	v_lshl_add_u64 v[38:39], v[2:3], 0, s[6:7]
	v_cndmask_b32_e32 v37, v39, v37, vcc
	v_cndmask_b32_e32 v36, v38, v36, vcc
	s_nop 0
	s_mov_b64 s[6:7], 0x48
	s_waitcnt vmcnt(1)
	v_mul_f32_e32 v0, v46, v71
	s_waitcnt vmcnt(0)
	v_mul_f32_e32 v36, v47, v72
	ds_write2_b32 v40, v0, v36 offset0:140 offset1:206
	v_lshl_add_u64 v[36:37], v[4:5], 0, s[6:7]
	s_movk_i32 s6, 0xf848
	s_mov_b32 s7, -1
	v_lshl_add_u64 v[38:39], v[2:3], 0, s[6:7]
	v_cndmask_b32_e32 v37, v39, v37, vcc
	v_cndmask_b32_e32 v36, v38, v36, vcc
	s_mov_b64 s[6:7], 0x50
	s_nop 0
	v_lshl_add_u64 v[36:37], v[4:5], 0, s[6:7]
	s_movk_i32 s6, 0xf850
	s_mov_b32 s7, -1
	v_lshl_add_u64 v[38:39], v[2:3], 0, s[6:7]
	v_cndmask_b32_e32 v37, v39, v37, vcc
	v_cndmask_b32_e32 v36, v38, v36, vcc
	s_nop 0
	v_add_u32_e32 v40, 0x800, v27
	s_mov_b64 s[6:7], 0x58
	s_waitcnt vmcnt(1)
	v_mul_f32_e32 v0, v48, v73
	s_waitcnt vmcnt(0)
	v_mul_f32_e32 v36, v49, v74
	ds_write2_b32 v40, v0, v36 offset0:16 offset1:82
	v_lshl_add_u64 v[36:37], v[4:5], 0, s[6:7]
	s_movk_i32 s6, 0xf858
	s_mov_b32 s7, -1
	v_lshl_add_u64 v[38:39], v[2:3], 0, s[6:7]
	v_cndmask_b32_e32 v37, v39, v37, vcc
	v_cndmask_b32_e32 v36, v38, v36, vcc
	s_mov_b64 s[6:7], 0x60
	s_nop 0
	v_lshl_add_u64 v[36:37], v[4:5], 0, s[6:7]
	s_movk_i32 s6, 0xf860
	s_mov_b32 s7, -1
	v_lshl_add_u64 v[38:39], v[2:3], 0, s[6:7]
	v_cndmask_b32_e32 v37, v39, v37, vcc
	v_cndmask_b32_e32 v36, v38, v36, vcc
	s_nop 0
	s_mov_b64 s[6:7], 0x68
	s_waitcnt vmcnt(1)
	v_mul_f32_e32 v0, v50, v75
	s_waitcnt vmcnt(0)
	v_mul_f32_e32 v36, v51, v76
	ds_write2_b32 v40, v0, v36 offset0:148 offset1:214
	v_lshl_add_u64 v[36:37], v[4:5], 0, s[6:7]
	s_movk_i32 s6, 0xf868
	s_mov_b32 s7, -1
	v_lshl_add_u64 v[38:39], v[2:3], 0, s[6:7]
	v_cndmask_b32_e32 v37, v39, v37, vcc
	v_cndmask_b32_e32 v36, v38, v36, vcc
	s_mov_b64 s[6:7], 0x70
	s_nop 0
	v_lshl_add_u64 v[36:37], v[4:5], 0, s[6:7]
	s_movk_i32 s6, 0xf870
	s_mov_b32 s7, -1
	v_lshl_add_u64 v[38:39], v[2:3], 0, s[6:7]
	v_cndmask_b32_e32 v37, v39, v37, vcc
	v_cndmask_b32_e32 v36, v38, v36, vcc
	s_nop 0
	v_add_u32_e32 v40, 0xc00, v27
	s_mov_b64 s[6:7], 0x78
	s_waitcnt vmcnt(1)
	v_mul_f32_e32 v0, v52, v77
	s_waitcnt vmcnt(0)
	v_mul_f32_e32 v36, v53, v78
	ds_write2_b32 v40, v0, v36 offset0:24 offset1:90
	v_lshl_add_u64 v[36:37], v[4:5], 0, s[6:7]
	s_movk_i32 s6, 0xf878
	s_mov_b32 s7, -1
	v_lshl_add_u64 v[38:39], v[2:3], 0, s[6:7]
	s_movk_i32 s6, 0xf880
	v_cndmask_b32_e32 v37, v39, v37, vcc
	v_cndmask_b32_e32 v36, v38, v36, vcc
	s_mov_b32 s7, -1
	s_nop 0
	v_lshl_add_u64 v[36:37], v[4:5], 0, s[86:87]
	v_lshl_add_u64 v[38:39], v[2:3], 0, s[6:7]
	v_cndmask_b32_e32 v37, v39, v37, vcc
	v_cndmask_b32_e32 v36, v38, v36, vcc
	s_nop 0
	s_mov_b64 s[6:7], 0x88
	s_waitcnt vmcnt(1)
	v_mul_f32_e32 v0, v54, v79
	s_waitcnt vmcnt(0)
	v_mul_f32_e32 v35, v35, v80
	v_lshl_add_u64 v[36:37], v[4:5], 0, s[6:7]
	s_movk_i32 s6, 0xf888
	s_mov_b32 s7, -1
	v_lshl_add_u64 v[38:39], v[2:3], 0, s[6:7]
	v_cndmask_b32_e32 v37, v39, v37, vcc
	v_cndmask_b32_e32 v36, v38, v36, vcc
	ds_write2_b32 v40, v0, v35 offset0:156 offset1:222
	s_nop 0
	s_mov_b64 s[6:7], 0x90
	v_add_u32_e32 v38, 0x1000, v27
	s_waitcnt vmcnt(0)
	v_mul_f32_e32 v0, v34, v81
	v_lshl_add_u64 v[34:35], v[4:5], 0, s[6:7]
	s_movk_i32 s6, 0xf890
	s_mov_b32 s7, -1
	v_lshl_add_u64 v[36:37], v[2:3], 0, s[6:7]
	v_cndmask_b32_e32 v35, v37, v35, vcc
	v_cndmask_b32_e32 v34, v36, v34, vcc
	s_nop 0
	s_mov_b64 s[6:7], 0x98
	s_waitcnt vmcnt(0)
	v_mul_f32_e32 v33, v33, v82
	v_lshl_add_u64 v[34:35], v[4:5], 0, s[6:7]
	s_movk_i32 s6, 0xf898
	s_mov_b32 s7, -1
	v_lshl_add_u64 v[36:37], v[2:3], 0, s[6:7]
	v_cndmask_b32_e32 v35, v37, v35, vcc
	v_cndmask_b32_e32 v34, v36, v34, vcc
	ds_write2_b32 v38, v0, v33 offset0:32 offset1:98
	s_nop 0
	s_mov_b64 s[6:7], 0xa0
	s_waitcnt vmcnt(0)
	v_mul_f32_e32 v0, v32, v83
	v_lshl_add_u64 v[32:33], v[4:5], 0, s[6:7]
	s_movk_i32 s6, 0xf8a0
	s_mov_b32 s7, -1
	v_lshl_add_u64 v[34:35], v[2:3], 0, s[6:7]
	v_cndmask_b32_e32 v33, v35, v33, vcc
	v_cndmask_b32_e32 v32, v34, v32, vcc
	s_nop 0
	s_mov_b64 s[6:7], 0xa8
	s_waitcnt vmcnt(0)
	v_mul_f32_e32 v31, v31, v84
	v_lshl_add_u64 v[32:33], v[4:5], 0, s[6:7]
	s_movk_i32 s6, 0xf8a8
	s_mov_b32 s7, -1
	v_lshl_add_u64 v[34:35], v[2:3], 0, s[6:7]
	v_cndmask_b32_e32 v33, v35, v33, vcc
	v_cndmask_b32_e32 v32, v34, v32, vcc
	ds_write2_b32 v38, v0, v31 offset0:164 offset1:230
	s_nop 0
	s_mov_b64 s[6:7], 0xb0
	v_add_u32_e32 v34, 0x1400, v27
	s_waitcnt vmcnt(0)
	v_mul_f32_e32 v0, v30, v85
	v_lshl_add_u64 v[30:31], v[4:5], 0, s[6:7]
	s_movk_i32 s6, 0xf8b0
	s_mov_b32 s7, -1
	v_lshl_add_u64 v[32:33], v[2:3], 0, s[6:7]
	v_cndmask_b32_e32 v31, v33, v31, vcc
	v_cndmask_b32_e32 v30, v32, v30, vcc
	s_nop 0
	s_mov_b64 s[6:7], 0xb8
	s_waitcnt vmcnt(0)
	v_mul_f32_e32 v29, v29, v86
	v_lshl_add_u64 v[30:31], v[4:5], 0, s[6:7]
	s_movk_i32 s6, 0xf8b8
	s_mov_b32 s7, -1
	v_lshl_add_u64 v[32:33], v[2:3], 0, s[6:7]
	v_cndmask_b32_e32 v31, v33, v31, vcc
	v_cndmask_b32_e32 v30, v32, v30, vcc
	ds_write2_b32 v34, v0, v29 offset0:40 offset1:106
	s_nop 0
	s_mov_b64 s[6:7], 0xc0
	s_waitcnt vmcnt(0)
	v_mul_f32_e32 v0, v28, v87
	v_lshl_add_u64 v[28:29], v[4:5], 0, s[6:7]
	s_movk_i32 s6, 0xf8c0
	s_mov_b32 s7, -1
	v_lshl_add_u64 v[30:31], v[2:3], 0, s[6:7]
	v_cndmask_b32_e32 v29, v31, v29, vcc
	v_cndmask_b32_e32 v28, v30, v28, vcc
	s_nop 0
	s_mov_b64 s[6:7], 0xc8
	s_waitcnt vmcnt(0)
	v_mul_f32_e32 v17, v17, v88
	v_lshl_add_u64 v[28:29], v[4:5], 0, s[6:7]
	s_movk_i32 s6, 0xf8c8
	s_mov_b32 s7, -1
	v_lshl_add_u64 v[30:31], v[2:3], 0, s[6:7]
	v_cndmask_b32_e32 v29, v31, v29, vcc
	v_cndmask_b32_e32 v28, v30, v28, vcc
	ds_write2_b32 v34, v0, v17 offset0:172 offset1:238
	s_nop 0
	s_mov_b64 s[6:7], 0xd0
	v_add_u32_e32 v30, 0x1800, v27
	s_waitcnt vmcnt(0)
	v_mul_f32_e32 v0, v16, v89
	v_lshl_add_u64 v[16:17], v[4:5], 0, s[6:7]
	s_movk_i32 s6, 0xf8d0
	s_mov_b32 s7, -1
	v_lshl_add_u64 v[28:29], v[2:3], 0, s[6:7]
	v_cndmask_b32_e32 v17, v29, v17, vcc
	v_cndmask_b32_e32 v16, v28, v16, vcc
	s_nop 0
	s_mov_b64 s[6:7], 0xd8
	s_waitcnt vmcnt(0)
	v_mul_f32_e32 v15, v15, v90
	v_lshl_add_u64 v[16:17], v[4:5], 0, s[6:7]
	s_movk_i32 s6, 0xf8d8
	s_mov_b32 s7, -1
	v_lshl_add_u64 v[28:29], v[2:3], 0, s[6:7]
	v_cndmask_b32_e32 v17, v29, v17, vcc
	v_cndmask_b32_e32 v16, v28, v16, vcc
	ds_write2_b32 v30, v0, v15 offset0:48 offset1:114
	s_nop 0
	s_mov_b64 s[6:7], 0xe0
	s_waitcnt vmcnt(0)
	v_mul_f32_e32 v0, v14, v91
	v_lshl_add_u64 v[14:15], v[4:5], 0, s[6:7]
	s_movk_i32 s6, 0xf8e0
	s_mov_b32 s7, -1
	v_lshl_add_u64 v[16:17], v[2:3], 0, s[6:7]
	v_cndmask_b32_e32 v15, v17, v15, vcc
	v_cndmask_b32_e32 v14, v16, v14, vcc
	s_nop 0
	s_mov_b64 s[6:7], 0xe8
	s_waitcnt vmcnt(0)
	v_mul_f32_e32 v13, v13, v92
	v_lshl_add_u64 v[14:15], v[4:5], 0, s[6:7]
	s_movk_i32 s6, 0xf8e8
	s_mov_b32 s7, -1
	v_lshl_add_u64 v[16:17], v[2:3], 0, s[6:7]
	v_cndmask_b32_e32 v15, v17, v15, vcc
	v_cndmask_b32_e32 v14, v16, v14, vcc
	ds_write2_b32 v30, v0, v13 offset0:180 offset1:246
	s_nop 0
	s_mov_b64 s[6:7], 0xf0
	s_waitcnt vmcnt(0)
	v_mul_f32_e32 v0, v12, v93
	v_lshl_add_u64 v[12:13], v[4:5], 0, s[6:7]
	s_movk_i32 s6, 0xf8f0
	s_mov_b32 s7, -1
	v_lshl_add_u64 v[14:15], v[2:3], 0, s[6:7]
	v_cndmask_b32_e32 v13, v15, v13, vcc
	v_cndmask_b32_e32 v12, v14, v12, vcc
	s_nop 0
	s_mov_b64 s[6:7], 0xf8
	v_lshl_add_u64 v[4:5], v[4:5], 0, s[6:7]
	s_movk_i32 s6, 0xf8f8
	s_mov_b32 s7, -1
	v_lshl_add_u64 v[2:3], v[2:3], 0, s[6:7]
	v_cndmask_b32_e32 v3, v3, v5, vcc
	v_cndmask_b32_e32 v2, v2, v4, vcc
	s_lshl_b32 s6, s10, 1
	s_add_u32 s6, s18, s6
	s_addc_u32 s7, s19, 0
	s_waitcnt vmcnt(0)
	v_mul_f32_e32 v11, v11, v94
	v_add_u32_e32 v12, 0x1c00, v27
	ds_write2_b32 v12, v0, v11 offset0:56 offset1:122
	s_nop 0
	s_waitcnt vmcnt(0)
	v_mul_f32_e32 v0, v10, v95
	ds_write_b32 v27, v0 offset:7920
	s_waitcnt lgkmcnt(0)
	ds_read2_b32 v[12:13], v19 offset0:33 offset1:41
	ds_read2_b32 v[14:15], v19 offset1:8
	ds_read2_b32 v[16:17], v19 offset0:66 offset1:74
	ds_read2_b32 v[28:29], v19 offset0:99 offset1:107
	ds_read2_b32 v[30:31], v19 offset0:132 offset1:140
	ds_read2_b32 v[32:33], v19 offset0:165 offset1:173
	ds_read2_b32 v[34:35], v19 offset0:198 offset1:206
	ds_read2_b32 v[36:37], v19 offset0:231 offset1:239
	v_lshlrev_b32_e32 v0, 1, v8
	v_lshl_add_u64 v[2:3], s[6:7], 0, v[0:1]
	s_mov_b64 s[6:7], 0x380000
	v_or_b32_e32 v0, s5, v18
	v_lshl_add_u64 v[10:11], v[2:3], 0, s[6:7]
	v_lshlrev_b32_e32 v0, 11, v0
	v_lshl_add_u64 v[38:39], v[10:11], 0, v[0:1]
	v_or_b32_e32 v0, s5, v20
	s_waitcnt lgkmcnt(6)
	v_cvt_pk_bf16_f32 v2, v14, v12
	s_waitcnt lgkmcnt(4)
	v_cvt_pk_bf16_f32 v3, v16, v28
	s_waitcnt lgkmcnt(2)
	v_cvt_pk_bf16_f32 v4, v30, v32
	s_waitcnt lgkmcnt(0)
	v_cvt_pk_bf16_f32 v5, v34, v36
	v_lshlrev_b32_e32 v0, 11, v0
	global_store_dwordx4 v[38:39], v[2:5], off sc1
	s_nop 1
	v_cvt_pk_bf16_f32 v2, v15, v13
	v_cvt_pk_bf16_f32 v3, v17, v29
	v_cvt_pk_bf16_f32 v4, v31, v33
	v_cvt_pk_bf16_f32 v5, v35, v37
	v_lshl_add_u64 v[12:13], v[10:11], 0, v[0:1]
	global_store_dwordx4 v[12:13], v[2:5], off sc1
	ds_read2_b32 v[12:13], v19 offset0:49 offset1:57
	ds_read2_b32 v[14:15], v19 offset0:16 offset1:24
	ds_read2_b32 v[16:17], v19 offset0:82 offset1:90
	ds_read2_b32 v[28:29], v19 offset0:115 offset1:123
	ds_read2_b32 v[30:31], v19 offset0:148 offset1:156
	ds_read2_b32 v[32:33], v19 offset0:181 offset1:189
	ds_read2_b32 v[34:35], v19 offset0:214 offset1:222
	ds_read2_b32 v[36:37], v19 offset0:247 offset1:255
	v_or_b32_e32 v0, s5, v21
	v_lshlrev_b32_e32 v0, 11, v0
	v_lshl_add_u64 v[38:39], v[10:11], 0, v[0:1]
	v_or_b32_e32 v0, s5, v22
	s_waitcnt lgkmcnt(6)
	v_cvt_pk_bf16_f32 v2, v14, v12
	s_waitcnt lgkmcnt(4)
	v_cvt_pk_bf16_f32 v3, v16, v28
	s_waitcnt lgkmcnt(2)
	v_cvt_pk_bf16_f32 v4, v30, v32
	s_waitcnt lgkmcnt(0)
	v_cvt_pk_bf16_f32 v5, v34, v36
	v_lshlrev_b32_e32 v0, 11, v0
	global_store_dwordx4 v[38:39], v[2:5], off sc1
	v_lshl_add_u64 v[10:11], v[10:11], 0, v[0:1]
	s_nop 0
	v_cvt_pk_bf16_f32 v2, v15, v13
	v_cvt_pk_bf16_f32 v3, v17, v29
	v_cvt_pk_bf16_f32 v4, v31, v33
	v_cvt_pk_bf16_f32 v5, v35, v37
	global_store_dwordx4 v[10:11], v[2:5], off sc1
	s_waitcnt lgkmcnt(0)

.LBB0_626:
	s_andn2_b64 vcc, exec, s[6:7]
	s_cbranch_vccnz .LBB0_599
	s_load_dwordx2 s[6:7], s[0:1], 0x30
	s_mul_hi_i32 s5, s4, 0x700000
	s_mul_i32 s4, s4, 0x700000
	s_mul_i32 s8, s20, 0x4925
	v_lshlrev_b32_e32 v0, 2, v6
	s_waitcnt lgkmcnt(0)
	s_add_u32 s10, s6, s4
	s_addc_u32 s11, s7, s5
	s_lshr_b32 s4, s8, 31
	s_ashr_i32 s5, s8, 20
	s_add_i32 s4, s5, s4
	s_mul_i32 s5, s4, 56
	s_sub_i32 s5, s20, s5
	s_sext_i32_i16 s7, s5
	s_lshl_b32 s6, s4, 6
	s_lshl_b32 s4, s7, 5
	s_ashr_i32 s5, s4, 31
	s_lshl_b64 s[8:9], s[4:5], 2
	v_or_b32_e32 v4, s6, v7
	s_add_u32 s8, s10, s8
	s_addc_u32 s9, s11, s9
	v_mul_i32_i24_e32 v4, 0x1c00, v4
	v_lshl_add_u64 v[2:3], s[8:9], 0, v[0:1]
	v_ashrrev_i32_e32 v5, 31, v4
	v_lshl_add_u64 v[2:3], v[2:3], 0, v[4:5]
	s_movk_i32 s5, 0x3000
	v_add_co_u32_e32 v4, vcc, s5, v2
	s_movk_i32 s5, 0x7000
	s_nop 0
	v_addc_co_u32_e32 v5, vcc, 0, v3, vcc
	v_add_co_u32_e32 v10, vcc, s5, v2
	s_mov_b32 s5, 0x11000
	s_nop 0
	v_addc_co_u32_e32 v11, vcc, 0, v3, vcc
	v_add_co_u32_e32 v12, vcc, s56, v2
	s_nop 1
	v_addc_co_u32_e32 v13, vcc, 0, v3, vcc
	v_add_co_u32_e32 v14, vcc, s78, v2
	s_nop 1
	v_addc_co_u32_e32 v15, vcc, 0, v3, vcc
	v_add_co_u32_e32 v16, vcc, s5, v2
	s_mov_b32 s5, 0x15000
	s_nop 0
	v_addc_co_u32_e32 v17, vcc, 0, v3, vcc
	v_add_co_u32_e32 v28, vcc, s5, v2
	s_mov_b32 s5, 0x1f000
	s_nop 0
	v_addc_co_u32_e32 v29, vcc, 0, v3, vcc
	v_add_co_u32_e32 v30, vcc, s95, v2
	s_nop 1
	v_addc_co_u32_e32 v31, vcc, 0, v3, vcc
	global_load_dword v0, v[2:3], off nt
	global_load_dword v34, v[4:5], off offset:2048 nt
	global_load_dword v35, v[10:11], off nt
	global_load_dword v36, v[12:13], off offset:2048 nt
	global_load_dword v37, v[14:15], off nt
	global_load_dword v38, v[16:17], off offset:2048 nt
	global_load_dword v39, v[28:29], off nt
	global_load_dword v40, v[30:31], off offset:2048 nt
	v_add_co_u32_e32 v4, vcc, s77, v2
	s_nop 1
	v_addc_co_u32_e32 v5, vcc, 0, v3, vcc
	v_add_co_u32_e32 v10, vcc, s5, v2
	s_mov_b32 s5, 0x23000
	s_nop 0
	v_addc_co_u32_e32 v11, vcc, 0, v3, vcc
	v_add_co_u32_e32 v12, vcc, s5, v2
	s_mov_b32 s5, 0x2d000
	s_nop 0
	v_addc_co_u32_e32 v13, vcc, 0, v3, vcc
	v_add_co_u32_e32 v14, vcc, s79, v2
	s_nop 1
	v_addc_co_u32_e32 v15, vcc, 0, v3, vcc
	v_add_co_u32_e32 v16, vcc, s55, v2
	s_nop 1
	v_addc_co_u32_e32 v17, vcc, 0, v3, vcc
	v_add_co_u32_e32 v28, vcc, s5, v2
	s_mov_b32 s5, 0x31000
	s_nop 0
	v_addc_co_u32_e32 v29, vcc, 0, v3, vcc
	v_add_co_u32_e32 v30, vcc, s5, v2
	s_mov_b32 s5, 0x3b000
	s_nop 0
	v_addc_co_u32_e32 v31, vcc, 0, v3, vcc
	v_add_co_u32_e32 v32, vcc, s85, v2
	s_nop 1
	v_addc_co_u32_e32 v33, vcc, 0, v3, vcc
	global_load_dword v41, v[4:5], off nt
	global_load_dword v42, v[10:11], off offset:2048 nt
	global_load_dword v43, v[12:13], off nt
	global_load_dword v44, v[14:15], off offset:2048 nt
	global_load_dword v45, v[16:17], off nt
	global_load_dword v46, v[28:29], off offset:2048 nt
	global_load_dword v47, v[30:31], off nt
	global_load_dword v48, v[32:33], off offset:2048 nt
	v_add_co_u32_e32 v4, vcc, s93, v2
	s_nop 1
	v_addc_co_u32_e32 v5, vcc, 0, v3, vcc
	v_add_co_u32_e32 v10, vcc, s5, v2
	s_mov_b32 s5, 0x3f000
	s_nop 0
	v_addc_co_u32_e32 v11, vcc, 0, v3, vcc
	v_add_co_u32_e32 v12, vcc, s5, v2
	s_mov_b32 s5, 0x46000
	s_nop 0
	v_addc_co_u32_e32 v13, vcc, 0, v3, vcc
	v_add_co_u32_e32 v14, vcc, s84, v2
	s_nop 1
	v_addc_co_u32_e32 v15, vcc, 0, v3, vcc
	v_add_co_u32_e32 v16, vcc, s5, v2
	s_mov_b32 s5, 0x49000
	s_nop 0
	v_addc_co_u32_e32 v17, vcc, 0, v3, vcc
	v_add_co_u32_e32 v28, vcc, s5, v2
	s_mov_b32 s5, 0x50000
	s_nop 0
	v_addc_co_u32_e32 v29, vcc, 0, v3, vcc
	v_add_co_u32_e32 v30, vcc, s76, v2
	s_nop 1
	v_addc_co_u32_e32 v31, vcc, 0, v3, vcc
	v_add_co_u32_e32 v32, vcc, s5, v2
	s_mov_b32 s5, 0x57000
	s_nop 0
	v_addc_co_u32_e32 v33, vcc, 0, v3, vcc
	global_load_dword v49, v[4:5], off nt
	global_load_dword v50, v[10:11], off offset:2048 nt
	global_load_dword v51, v[12:13], off nt
	global_load_dword v52, v[14:15], off offset:2048 nt
	global_load_dword v53, v[16:17], off nt
	global_load_dword v54, v[28:29], off offset:2048 nt
	global_load_dword v55, v[30:31], off nt
	s_nop 0
	global_load_dword v32, v[32:33], off offset:2048 nt
	v_add_co_u32_e32 v4, vcc, s83, v2
	s_nop 1
	v_addc_co_u32_e32 v5, vcc, 0, v3, vcc
	v_add_co_u32_e32 v10, vcc, s5, v2
	s_mov_b32 s5, 0x5b000
	s_nop 0
	v_addc_co_u32_e32 v11, vcc, 0, v3, vcc
	v_add_co_u32_e32 v12, vcc, s5, v2
	s_mov_b32 s5, 0x5e000
	s_nop 0
	v_addc_co_u32_e32 v13, vcc, 0, v3, vcc
	v_add_co_u32_e32 v14, vcc, s5, v2
	s_mov_b32 s5, 0x62000
	s_nop 0
	v_addc_co_u32_e32 v15, vcc, 0, v3, vcc
	v_add_co_u32_e32 v16, vcc, s5, v2
	s_mov_b32 s5, 0x65000
	s_nop 0
	v_addc_co_u32_e32 v17, vcc, 0, v3, vcc
	v_add_co_u32_e32 v28, vcc, s5, v2
	s_mov_b32 s5, 0x69000
	s_nop 0
	v_addc_co_u32_e32 v29, vcc, 0, v3, vcc
	v_add_co_u32_e32 v30, vcc, s5, v2
	s_lshl_b32 s5, s7, 7
	s_nop 0
	v_addc_co_u32_e32 v31, vcc, 0, v3, vcc
	v_add_co_u32_e32 v2, vcc, s34, v2
	s_and_b32 s5, s5, 0x80
	s_nop 0
	v_addc_co_u32_e32 v3, vcc, 0, v3, vcc
	global_load_dword v4, v[4:5], off nt
	s_nop 0
	global_load_dword v5, v[10:11], off offset:2048 nt
	s_nop 0
	global_load_dword v10, v[12:13], off nt
	global_load_dword v11, v[14:15], off offset:2048 nt
	s_nop 0
	global_load_dword v12, v[16:17], off nt
	global_load_dword v13, v[28:29], off offset:2048 nt
	global_load_dword v14, v[30:31], off nt
	s_nop 0
	global_load_dword v2, v[2:3], off offset:2048 nt
	s_waitcnt vmcnt(30)
	ds_write2_b32 v9, v0, v34 offset1:66
	s_waitcnt vmcnt(28)
	ds_write2_b32 v9, v35, v36 offset0:132 offset1:198
	v_add_u32_e32 v0, 0x400, v9
	s_waitcnt vmcnt(26)
	ds_write2_b32 v0, v37, v38 offset0:8 offset1:74
	s_waitcnt vmcnt(24)
	ds_write2_b32 v0, v39, v40 offset0:140 offset1:206
	v_add_u32_e32 v0, 0x800, v9
	s_waitcnt vmcnt(22)
	ds_write2_b32 v0, v41, v42 offset0:16 offset1:82
	s_waitcnt vmcnt(20)
	ds_write2_b32 v0, v43, v44 offset0:148 offset1:214
	v_add_u32_e32 v0, 0xc00, v9
	s_waitcnt vmcnt(18)
	ds_write2_b32 v0, v45, v46 offset0:24 offset1:90
	s_waitcnt vmcnt(16)
	ds_write2_b32 v0, v47, v48 offset0:156 offset1:222
	v_add_u32_e32 v0, 0x1000, v9
	s_waitcnt vmcnt(14)
	ds_write2_b32 v0, v49, v50 offset0:32 offset1:98
	s_waitcnt vmcnt(12)
	ds_write2_b32 v0, v51, v52 offset0:164 offset1:230
	v_add_u32_e32 v0, 0x1400, v9
	s_waitcnt vmcnt(10)
	ds_write2_b32 v0, v53, v54 offset0:40 offset1:106
	s_waitcnt vmcnt(8)
	ds_write2_b32 v0, v55, v32 offset0:172 offset1:238
	v_add_u32_e32 v0, 0x1800, v9
	s_waitcnt vmcnt(6)
	ds_write2_b32 v0, v4, v5 offset0:48 offset1:114
	s_waitcnt vmcnt(4)
	ds_write2_b32 v0, v10, v11 offset0:180 offset1:246
	v_add_u32_e32 v0, 0x1c00, v9
	s_waitcnt vmcnt(2)
	ds_write2_b32 v0, v12, v13 offset0:56 offset1:122
	s_waitcnt vmcnt(0)
	ds_write2_b32 v0, v14, v2 offset0:188 offset1:254
	s_waitcnt lgkmcnt(0)
	ds_read2_b32 v[4:5], v19 offset1:33
	ds_read2_b32 v[10:11], v19 offset0:66 offset1:99
	ds_read2_b32 v[12:13], v19 offset0:132 offset1:165
	ds_read2_b32 v[14:15], v19 offset0:198 offset1:231
	v_or_b32_e32 v0, s4, v18
	v_cmp_lt_i32_e32 vcc, s57, v0
	s_and_saveexec_b64 s[8:9], vcc
	s_xor_b64 s[8:9], exec, s[8:9]
	s_cmpk_lt_u32 s4, 0x300
	s_cselect_b64 vcc, -1, 0
	s_add_i32 s10, s4, 0xfffffe00
	s_lshr_b32 s10, s10, 1
	s_and_b32 s10, s10, 0x7fffffe0
	v_or_b32_e32 v2, s5, v23
	v_add_u32_e32 v2, s10, v2
	v_cndmask_b32_e32 v16, v0, v2, vcc
	s_or_saveexec_b64 s[8:9], s[8:9]
	s_lshl_b32 s7, s7, 4
	s_and_b32 s7, s7, 0x60
	s_or_b32 s10, s7, s5
	s_xor_b64 exec, exec, s[8:9]
	v_and_b32_e32 v0, 0xffffff07, v0
	v_or_b32_e32 v16, s10, v0
	s_or_b64 exec, exec, s[8:9]
	s_waitcnt lgkmcnt(3)
	v_cvt_pk_bf16_f32 v28, v4, v5
	s_waitcnt lgkmcnt(2)
	v_cvt_pk_bf16_f32 v29, v10, v11
	s_waitcnt lgkmcnt(1)
	v_cvt_pk_bf16_f32 v30, v12, v13
	s_waitcnt lgkmcnt(0)
	v_cvt_pk_bf16_f32 v31, v14, v15
	ds_read2_b32 v[4:5], v19 offset0:8 offset1:41
	ds_read2_b32 v[10:11], v19 offset0:74 offset1:107
	ds_read2_b32 v[12:13], v19 offset0:140 offset1:173
	ds_read2_b32 v[14:15], v19 offset0:206 offset1:239
	s_ashr_i32 s7, s6, 31
	s_lshl_b64 s[6:7], s[6:7], 1
	s_add_u32 s6, s18, s6
	s_addc_u32 s7, s19, s7
	v_lshlrev_b32_e32 v0, 1, v8
	v_ashrrev_i32_e32 v17, 31, v16
	v_lshl_add_u64 v[2:3], s[6:7], 0, v[0:1]
	v_lshlrev_b64 v[16:17], 11, v[16:17]
	v_or_b32_e32 v0, s4, v20
	v_lshl_add_u64 v[16:17], v[2:3], 0, v[16:17]
	v_cmp_lt_i32_e32 vcc, s57, v0
	global_store_dwordx4 v[16:17], v[28:31], off sc1
	s_and_saveexec_b64 s[6:7], vcc
	s_xor_b64 s[6:7], exec, s[6:7]
	s_cmpk_lt_u32 s4, 0x300
	s_cselect_b64 vcc, -1, 0
	s_add_i32 s8, s4, 0xfffffe00
	s_lshr_b32 s8, s8, 1
	s_and_b32 s8, s8, 0x7fffffe0
	v_or_b32_e32 v16, s5, v24
	v_add_u32_e32 v16, s8, v16
	v_cndmask_b32_e32 v16, v0, v16, vcc
	s_andn2_saveexec_b64 s[6:7], s[6:7]
	v_and_b32_e32 v0, 0xffffff0f, v0
	v_or_b32_e32 v16, s10, v0
	s_or_b64 exec, exec, s[6:7]
	s_waitcnt lgkmcnt(3)
	v_cvt_pk_bf16_f32 v28, v4, v5
	s_waitcnt lgkmcnt(2)
	v_cvt_pk_bf16_f32 v29, v10, v11
	s_waitcnt lgkmcnt(1)
	v_cvt_pk_bf16_f32 v30, v12, v13
	s_waitcnt lgkmcnt(0)
	v_cvt_pk_bf16_f32 v31, v14, v15
	ds_read2_b32 v[4:5], v19 offset0:16 offset1:49
	ds_read2_b32 v[10:11], v19 offset0:82 offset1:115
	ds_read2_b32 v[12:13], v19 offset0:148 offset1:181
	ds_read2_b32 v[14:15], v19 offset0:214 offset1:247
	v_ashrrev_i32_e32 v17, 31, v16
	v_lshlrev_b64 v[16:17], 11, v[16:17]
	v_or_b32_e32 v0, s4, v21
	v_lshl_add_u64 v[16:17], v[2:3], 0, v[16:17]
	v_cmp_lt_i32_e32 vcc, s57, v0
	global_store_dwordx4 v[16:17], v[28:31], off sc1
	s_and_saveexec_b64 s[6:7], vcc
	s_xor_b64 s[6:7], exec, s[6:7]
	s_cmpk_lt_u32 s4, 0x300
	s_cselect_b64 vcc, -1, 0
	s_add_i32 s8, s4, 0xfffffe00
	s_lshr_b32 s8, s8, 1
	s_and_b32 s8, s8, 0x7fffffe0
	v_or_b32_e32 v16, s5, v25
	v_add_u32_e32 v16, s8, v16
	v_cndmask_b32_e32 v16, v0, v16, vcc
	s_andn2_saveexec_b64 s[6:7], s[6:7]
	v_and_b32_e32 v0, 0xffffff17, v0
	v_or_b32_e32 v16, s10, v0
	s_or_b64 exec, exec, s[6:7]
	s_waitcnt lgkmcnt(3)
	v_cvt_pk_bf16_f32 v28, v4, v5
	s_waitcnt lgkmcnt(2)
	v_cvt_pk_bf16_f32 v29, v10, v11
	s_waitcnt lgkmcnt(1)
	v_cvt_pk_bf16_f32 v30, v12, v13
	s_waitcnt lgkmcnt(0)
	v_cvt_pk_bf16_f32 v31, v14, v15
	ds_read2_b32 v[4:5], v19 offset0:24 offset1:57
	ds_read2_b32 v[10:11], v19 offset0:90 offset1:123
	ds_read2_b32 v[12:13], v19 offset0:156 offset1:189
	ds_read2_b32 v[14:15], v19 offset0:222 offset1:255
	v_ashrrev_i32_e32 v17, 31, v16
	v_lshlrev_b64 v[16:17], 11, v[16:17]
	v_or_b32_e32 v0, s4, v22
	v_lshl_add_u64 v[16:17], v[2:3], 0, v[16:17]
	v_cmp_lt_i32_e32 vcc, s57, v0
	global_store_dwordx4 v[16:17], v[28:31], off sc1
	s_and_saveexec_b64 s[6:7], vcc
	s_xor_b64 s[6:7], exec, s[6:7]
	s_cmpk_lt_u32 s4, 0x300
	s_cselect_b64 vcc, -1, 0
	s_addk_i32 s4, 0xfe00
	s_lshr_b32 s4, s4, 1
	s_and_b32 s4, s4, 0x7fffffe0
	v_or_b32_e32 v16, s5, v26
	v_add_u32_e32 v16, s4, v16
	v_cndmask_b32_e32 v16, v0, v16, vcc
	s_andn2_saveexec_b64 s[4:5], s[6:7]
	s_cbranch_execz .LBB0_598
	v_and_b32_e32 v0, 0xffffff1f, v0
	v_or_b32_e32 v16, s10, v0
	s_branch .LBB0_598
